# balanced LDS-DMA staging in up-GEMM K-loops: A half-tiles staged in SP1 (4 loads) and B half-tiles in SP2 (4 loads) instead of 2+6, extra counted vmcnt(4)
# speedup vs baseline: 1.0054x; 1.0054x over previous
.LBB0_779:
	s_mov_b64 s[12:13], 0x80
	s_add_i32 m0, s47, 0x18000
	v_lshl_add_u64 v[22:23], v[22:23], 0, s[12:13]
	s_waitcnt vmcnt(2)
	s_barrier
	global_load_lds_dwordx4 v[22:23], off
	v_lshl_add_u64 v[20:21], v[20:21], 0, s[12:13]
	s_add_i32 m0, s47, 0x1a000
	s_add_i32 s51, s47, 0x8000
	s_add_i32 s52, s47, 0xa000
	global_load_lds_dwordx4 v[20:21], off
	v_lshl_add_u64 v[16:17], v[16:17], 0, s[12:13]
	s_mov_b32 m0, s51
	s_add_u32 s14, s10, 0x80080
	global_load_lds_dwordx4 v[16:17], off
	v_lshl_add_u64 v[16:17], v[18:19], 0, s[12:13]
	s_mov_b32 m0, s52
	s_addc_u32 s15, s11, 0
	global_load_lds_dwordx4 v[16:17], off
	s_add_i32 m0, s47, 0x1c000
	v_lshl_add_u64 v[16:17], s[14:15], 0, v[130:131]
	global_load_lds_dwordx4 v[16:17], off
	v_lshl_add_u64 v[16:17], s[14:15], 0, v[134:135]
	s_add_i32 m0, s47, 0x1e000
	s_nop 0
	global_load_lds_dwordx4 v[16:17], off
	s_waitcnt vmcnt(6)
	s_barrier
	s_and_saveexec_b64 s[14:15], s[2:3]
	s_cbranch_execz .LBB0_781
	v_pk_add_f32 v[10:11], v[10:11], v[14:15]
	v_pk_add_f32 v[8:9], v[8:9], v[12:13]
	s_waitcnt vmcnt(0)
	v_pk_add_f32 v[4:5], v[6:7], v[4:5]
	v_pk_add_f32 v[0:1], v[2:3], v[0:1]
	v_pk_add_f32 v[2:3], v[4:5], v[10:11]
	v_pk_add_f32 v[0:1], v[0:1], v[8:9]
	s_nop 0
	v_pk_mov_b32 v[4:5], v[2:3], v[0:1] op_sel:[1,0]
	v_mov_b32_e32 v3, v1
	v_pk_add_f32 v[0:1], v[4:5], v[2:3]
	s_nop 0
	v_add_f32_e32 v0, v0, v1
	v_mov_b32_e32 v1, 0x358637bd
	v_fmac_f32_e32 v1, 0x3a000000, v0
	v_rsq_f32_e32 v0, v1
	v_lshl_add_u32 v1, v25, 2, 0
	v_add_u32_e32 v1, 0x20000, v1
	ds_write_b32 v1, v0

.LBB0_785:
	ds_read_b128 v[140:143], v148
	ds_read_b128 v[154:157], v148 offset:1024
	ds_read_b128 v[158:161], v148 offset:2048
	ds_read_b128 v[162:165], v148 offset:3072
	ds_read_b128 v[166:169], v149
	ds_read_b128 v[170:173], v149 offset:1024
	ds_read_b128 v[174:177], v149 offset:2048
	ds_read_b128 v[178:181], v149 offset:3072
	s_add_u32 s38, s36, 0xfff80080
	s_addc_u32 s39, s37, -1
	s_cmp_eq_u32 s75, 28
	s_cselect_b32 s41, s69, s39
	s_cselect_b32 s40, s70, s38
	s_cselect_b32 s39, s71, s74
	s_cselect_b32 s38, s72, s73
	v_lshl_add_u64 v[144:145], s[36:37], 0, v[136:137]
	s_add_i32 m0, s47, 0xc000
	ds_read_b128 v[182:185], v150
	ds_read_b128 v[186:189], v150 offset:1024
	ds_read_b128 v[190:193], v150 offset:2048
	ds_read_b128 v[194:197], v150 offset:3072
	ds_read_b128 v[198:201], v150 offset:4096
	ds_read_b128 v[202:205], v150 offset:5120
	ds_read_b128 v[206:209], v150 offset:6144
	ds_read_b128 v[210:213], v150 offset:7168
	global_load_lds_dwordx4 v[144:145], off
	v_lshl_add_u64 v[144:145], s[36:37], 0, v[138:139]
	s_add_i32 m0, s47, 0xe000
	s_nop 0
	global_load_lds_dwordx4 v[144:145], off
	s_waitcnt vmcnt(8)
	s_waitcnt lgkmcnt(0)
	s_barrier
	s_setprio 1
	s_waitcnt lgkmcnt(0)
	v_mfma_f32_16x16x32_bf16 v[124:127], v[140:143], v[182:185], v[124:127]
	v_mfma_f32_16x16x32_bf16 v[120:123], v[158:161], v[182:185], v[120:123]
	v_mfma_f32_16x16x32_bf16 v[112:115], v[140:143], v[190:193], v[112:115]
	v_mfma_f32_16x16x32_bf16 v[104:107], v[158:161], v[190:193], v[104:107]
	v_mfma_f32_16x16x32_bf16 v[96:99], v[140:143], v[198:201], v[96:99]
	v_mfma_f32_16x16x32_bf16 v[88:91], v[158:161], v[198:201], v[88:91]
	v_mfma_f32_16x16x32_bf16 v[80:83], v[140:143], v[206:209], v[80:83]
	v_mfma_f32_16x16x32_bf16 v[72:75], v[158:161], v[206:209], v[72:75]
	v_mfma_f32_16x16x32_bf16 v[124:127], v[154:157], v[186:189], v[124:127]
	v_mfma_f32_16x16x32_bf16 v[120:123], v[162:165], v[186:189], v[120:123]
	v_mfma_f32_16x16x32_bf16 v[112:115], v[154:157], v[194:197], v[112:115]
	v_mfma_f32_16x16x32_bf16 v[104:107], v[162:165], v[194:197], v[104:107]
	v_mfma_f32_16x16x32_bf16 v[96:99], v[154:157], v[202:205], v[96:99]
	v_mfma_f32_16x16x32_bf16 v[88:91], v[162:165], v[202:205], v[88:91]
	v_mfma_f32_16x16x32_bf16 v[80:83], v[154:157], v[210:213], v[80:83]
	v_mfma_f32_16x16x32_bf16 v[72:75], v[162:165], v[210:213], v[72:75]
	s_setprio 0
	s_setprio 1
	v_mfma_f32_16x16x32_bf16 v[116:119], v[166:169], v[182:185], v[116:119]
	v_mfma_f32_16x16x32_bf16 v[108:111], v[174:177], v[182:185], v[108:111]
	v_mfma_f32_16x16x32_bf16 v[100:103], v[166:169], v[190:193], v[100:103]
	v_mfma_f32_16x16x32_bf16 v[92:95], v[174:177], v[190:193], v[92:95]
	v_mfma_f32_16x16x32_bf16 v[84:87], v[166:169], v[198:201], v[84:87]
	v_mfma_f32_16x16x32_bf16 v[76:79], v[174:177], v[198:201], v[76:79]
	v_mfma_f32_16x16x32_bf16 v[68:71], v[166:169], v[206:209], v[68:71]
	v_mfma_f32_16x16x32_bf16 v[64:67], v[174:177], v[206:209], v[64:67]
	v_mfma_f32_16x16x32_bf16 v[116:119], v[170:173], v[186:189], v[116:119]
	v_mfma_f32_16x16x32_bf16 v[108:111], v[178:181], v[186:189], v[108:111]
	v_mfma_f32_16x16x32_bf16 v[100:103], v[170:173], v[194:197], v[100:103]
	v_mfma_f32_16x16x32_bf16 v[92:95], v[178:181], v[194:197], v[92:95]
	v_mfma_f32_16x16x32_bf16 v[84:87], v[170:173], v[202:205], v[84:87]
	v_mfma_f32_16x16x32_bf16 v[76:79], v[178:181], v[202:205], v[76:79]
	v_mfma_f32_16x16x32_bf16 v[68:71], v[170:173], v[210:213], v[68:71]
	v_mfma_f32_16x16x32_bf16 v[64:67], v[178:181], v[210:213], v[64:67]
	s_setprio 0
	s_barrier
	s_add_i32 s76, s59, s5
	v_lshl_add_u64 v[144:145], s[38:39], 0, v[130:131]
	s_mov_b32 m0, s76
	ds_read_b128 v[182:185], v150 offset:16384
	ds_read_b128 v[186:189], v150 offset:17408
	ds_read_b128 v[190:193], v150 offset:18432
	ds_read_b128 v[194:197], v150 offset:19456
	ds_read_b128 v[198:201], v150 offset:20480
	ds_read_b128 v[202:205], v150 offset:21504
	ds_read_b128 v[206:209], v150 offset:22528
	ds_read_b128 v[210:213], v150 offset:23552
	global_load_lds_dwordx4 v[144:145], off
	s_add_i32 m0, s76, 0x2000
	s_add_u32 s76, s38, 0x80000
	v_lshl_add_u64 v[214:215], s[38:39], 0, v[134:135]
	s_addc_u32 s77, s39, 0
	s_add_i32 s78, s60, s5
	global_load_lds_dwordx4 v[214:215], off
	v_lshl_add_u64 v[216:217], s[76:77], 0, v[130:131]
	s_mov_b32 m0, s78
	v_lshl_add_u64 v[218:219], s[40:41], 0, v[132:133]
	global_load_lds_dwordx4 v[216:217], off
	v_lshl_add_u64 v[216:217], s[76:77], 0, v[134:135]
	s_add_i32 m0, s78, 0x2000
	s_nop 0
	global_load_lds_dwordx4 v[216:217], off
	v_lshl_add_u64 v[216:217], s[40:41], 0, v[128:129]
	s_mov_b32 m0, s47
	s_nop 0
	global_load_lds_dwordx4 v[216:217], off
	s_mov_b32 m0, s48
	s_nop 0
	global_load_lds_dwordx4 v[218:219], off
	s_waitcnt vmcnt(8)
	s_waitcnt lgkmcnt(0)
	s_barrier
	s_setprio 1
	s_waitcnt lgkmcnt(0)
	v_mfma_f32_16x16x32_bf16 v[60:63], v[140:143], v[182:185], v[60:63]
	v_mfma_f32_16x16x32_bf16 v[56:59], v[158:161], v[182:185], v[56:59]
	v_mfma_f32_16x16x32_bf16 v[48:51], v[140:143], v[190:193], v[48:51]
	v_mfma_f32_16x16x32_bf16 v[40:43], v[158:161], v[190:193], v[40:43]
	v_mfma_f32_16x16x32_bf16 v[32:35], v[140:143], v[198:201], v[32:35]
	v_mfma_f32_16x16x32_bf16 v[24:27], v[158:161], v[198:201], v[24:27]
	v_mfma_f32_16x16x32_bf16 v[16:19], v[140:143], v[206:209], v[16:19]
	v_mfma_f32_16x16x32_bf16 v[8:11], v[158:161], v[206:209], v[8:11]
	v_mfma_f32_16x16x32_bf16 v[60:63], v[154:157], v[186:189], v[60:63]
	v_mfma_f32_16x16x32_bf16 v[56:59], v[162:165], v[186:189], v[56:59]
	v_mfma_f32_16x16x32_bf16 v[48:51], v[154:157], v[194:197], v[48:51]
	v_mfma_f32_16x16x32_bf16 v[40:43], v[162:165], v[194:197], v[40:43]
	v_mfma_f32_16x16x32_bf16 v[32:35], v[154:157], v[202:205], v[32:35]
	v_mfma_f32_16x16x32_bf16 v[24:27], v[162:165], v[202:205], v[24:27]
	v_mfma_f32_16x16x32_bf16 v[16:19], v[154:157], v[210:213], v[16:19]
	v_mfma_f32_16x16x32_bf16 v[8:11], v[162:165], v[210:213], v[8:11]
	s_setprio 0
	s_setprio 1
	v_mfma_f32_16x16x32_bf16 v[52:55], v[166:169], v[182:185], v[52:55]
	v_mfma_f32_16x16x32_bf16 v[44:47], v[174:177], v[182:185], v[44:47]
	v_mfma_f32_16x16x32_bf16 v[36:39], v[166:169], v[190:193], v[36:39]
	v_mfma_f32_16x16x32_bf16 v[28:31], v[174:177], v[190:193], v[28:31]
	v_mfma_f32_16x16x32_bf16 v[20:23], v[166:169], v[198:201], v[20:23]
	v_mfma_f32_16x16x32_bf16 v[12:15], v[174:177], v[198:201], v[12:15]
	v_mfma_f32_16x16x32_bf16 v[4:7], v[166:169], v[206:209], v[4:7]
	v_mfma_f32_16x16x32_bf16 v[0:3], v[174:177], v[206:209], v[0:3]
	v_mfma_f32_16x16x32_bf16 v[52:55], v[170:173], v[186:189], v[52:55]
	v_mfma_f32_16x16x32_bf16 v[44:47], v[178:181], v[186:189], v[44:47]
	v_mfma_f32_16x16x32_bf16 v[36:39], v[170:173], v[194:197], v[36:39]
	v_mfma_f32_16x16x32_bf16 v[28:31], v[178:181], v[194:197], v[28:31]
	v_mfma_f32_16x16x32_bf16 v[20:23], v[170:173], v[202:205], v[20:23]
	v_mfma_f32_16x16x32_bf16 v[12:15], v[178:181], v[202:205], v[12:15]
	v_mfma_f32_16x16x32_bf16 v[4:7], v[170:173], v[210:213], v[4:7]
	v_mfma_f32_16x16x32_bf16 v[0:3], v[178:181], v[210:213], v[0:3]
	s_setprio 0
	s_barrier
	ds_read_b128 v[140:143], v151
	ds_read_b128 v[154:157], v151 offset:1024
	ds_read_b128 v[158:161], v151 offset:2048
	ds_read_b128 v[162:165], v151 offset:3072
	ds_read_b128 v[166:169], v152
	ds_read_b128 v[170:173], v152 offset:1024
	ds_read_b128 v[174:177], v152 offset:2048
	ds_read_b128 v[178:181], v152 offset:3072
	s_add_u32 s40, s40, 0x80000
	s_addc_u32 s41, s41, 0
	s_mov_b32 m0, s49
	v_lshl_add_u64 v[220:221], s[40:41], 0, v[128:129]
	ds_read_b128 v[182:185], v150 offset:32768
	ds_read_b128 v[186:189], v150 offset:33792
	ds_read_b128 v[190:193], v150 offset:34816
	ds_read_b128 v[194:197], v150 offset:35840
	ds_read_b128 v[198:201], v150 offset:36864
	ds_read_b128 v[202:205], v150 offset:37888
	ds_read_b128 v[206:209], v150 offset:38912
	ds_read_b128 v[210:213], v150 offset:39936
	global_load_lds_dwordx4 v[220:221], off
	v_lshl_add_u64 v[220:221], s[40:41], 0, v[132:133]
	s_mov_b32 m0, s50
	s_nop 0
	global_load_lds_dwordx4 v[220:221], off
	s_waitcnt vmcnt(8)
	s_waitcnt lgkmcnt(0)
	s_barrier
	s_setprio 1
	s_waitcnt lgkmcnt(0)
	v_mfma_f32_16x16x32_bf16 v[124:127], v[140:143], v[182:185], v[124:127]
	v_mfma_f32_16x16x32_bf16 v[120:123], v[158:161], v[182:185], v[120:123]
	v_mfma_f32_16x16x32_bf16 v[112:115], v[140:143], v[190:193], v[112:115]
	v_mfma_f32_16x16x32_bf16 v[104:107], v[158:161], v[190:193], v[104:107]
	v_mfma_f32_16x16x32_bf16 v[96:99], v[140:143], v[198:201], v[96:99]
	v_mfma_f32_16x16x32_bf16 v[88:91], v[158:161], v[198:201], v[88:91]
	v_mfma_f32_16x16x32_bf16 v[80:83], v[140:143], v[206:209], v[80:83]
	v_mfma_f32_16x16x32_bf16 v[72:75], v[158:161], v[206:209], v[72:75]
	v_mfma_f32_16x16x32_bf16 v[124:127], v[154:157], v[186:189], v[124:127]
	v_mfma_f32_16x16x32_bf16 v[120:123], v[162:165], v[186:189], v[120:123]
	v_mfma_f32_16x16x32_bf16 v[112:115], v[154:157], v[194:197], v[112:115]
	v_mfma_f32_16x16x32_bf16 v[104:107], v[162:165], v[194:197], v[104:107]
	v_mfma_f32_16x16x32_bf16 v[96:99], v[154:157], v[202:205], v[96:99]
	v_mfma_f32_16x16x32_bf16 v[88:91], v[162:165], v[202:205], v[88:91]
	v_mfma_f32_16x16x32_bf16 v[80:83], v[154:157], v[210:213], v[80:83]
	v_mfma_f32_16x16x32_bf16 v[72:75], v[162:165], v[210:213], v[72:75]
	s_setprio 0
	s_setprio 1
	v_mfma_f32_16x16x32_bf16 v[116:119], v[166:169], v[182:185], v[116:119]
	v_mfma_f32_16x16x32_bf16 v[108:111], v[174:177], v[182:185], v[108:111]
	v_mfma_f32_16x16x32_bf16 v[100:103], v[166:169], v[190:193], v[100:103]
	v_mfma_f32_16x16x32_bf16 v[92:95], v[174:177], v[190:193], v[92:95]
	v_mfma_f32_16x16x32_bf16 v[84:87], v[166:169], v[198:201], v[84:87]
	v_mfma_f32_16x16x32_bf16 v[76:79], v[174:177], v[198:201], v[76:79]
	v_mfma_f32_16x16x32_bf16 v[68:71], v[166:169], v[206:209], v[68:71]
	v_mfma_f32_16x16x32_bf16 v[64:67], v[174:177], v[206:209], v[64:67]
	v_mfma_f32_16x16x32_bf16 v[116:119], v[170:173], v[186:189], v[116:119]
	v_mfma_f32_16x16x32_bf16 v[108:111], v[178:181], v[186:189], v[108:111]
	v_mfma_f32_16x16x32_bf16 v[100:103], v[170:173], v[194:197], v[100:103]
	v_mfma_f32_16x16x32_bf16 v[92:95], v[178:181], v[194:197], v[92:95]
	v_mfma_f32_16x16x32_bf16 v[84:87], v[170:173], v[202:205], v[84:87]
	v_mfma_f32_16x16x32_bf16 v[76:79], v[178:181], v[202:205], v[76:79]
	v_mfma_f32_16x16x32_bf16 v[68:71], v[170:173], v[210:213], v[68:71]
	v_mfma_f32_16x16x32_bf16 v[64:67], v[178:181], v[210:213], v[64:67]
	s_setprio 0
	s_barrier
	s_add_i32 s40, s61, s5
	v_lshl_add_u64 v[144:145], v[144:145], 0, s[12:13]
	s_mov_b32 m0, s40
	ds_read_b128 v[182:185], v150 offset:49152
	ds_read_b128 v[186:189], v150 offset:50176
	ds_read_b128 v[190:193], v150 offset:51200
	ds_read_b128 v[194:197], v150 offset:52224
	ds_read_b128 v[198:201], v150 offset:53248
	ds_read_b128 v[202:205], v150 offset:54272
	ds_read_b128 v[206:209], v150 offset:55296
	ds_read_b128 v[210:213], v150 offset:56320
	global_load_lds_dwordx4 v[144:145], off
	s_add_i32 m0, s40, 0x2000
	s_add_u32 s38, s38, 0x80080
	v_lshl_add_u64 v[144:145], v[214:215], 0, s[12:13]
	s_addc_u32 s39, s39, 0
	s_add_i32 s40, s62, s5
	global_load_lds_dwordx4 v[144:145], off
	v_lshl_add_u64 v[144:145], s[38:39], 0, v[130:131]
	s_mov_b32 m0, s40
	s_nop 0
	global_load_lds_dwordx4 v[144:145], off
	v_lshl_add_u64 v[144:145], s[38:39], 0, v[134:135]
	s_add_i32 m0, s40, 0x2000
	s_nop 0
	global_load_lds_dwordx4 v[144:145], off
	v_lshl_add_u64 v[144:145], v[216:217], 0, s[12:13]
	s_mov_b32 m0, s51
	s_nop 0
	global_load_lds_dwordx4 v[144:145], off
	v_lshl_add_u64 v[144:145], v[218:219], 0, s[12:13]
	s_mov_b32 m0, s52
	s_nop 0
	global_load_lds_dwordx4 v[144:145], off
	s_waitcnt vmcnt(8)
	s_waitcnt lgkmcnt(0)
	s_barrier
	s_setprio 1
	s_waitcnt lgkmcnt(0)
	v_mfma_f32_16x16x32_bf16 v[60:63], v[140:143], v[182:185], v[60:63]
	v_mfma_f32_16x16x32_bf16 v[56:59], v[158:161], v[182:185], v[56:59]
	v_mfma_f32_16x16x32_bf16 v[48:51], v[140:143], v[190:193], v[48:51]
	v_mfma_f32_16x16x32_bf16 v[40:43], v[158:161], v[190:193], v[40:43]
	v_mfma_f32_16x16x32_bf16 v[32:35], v[140:143], v[198:201], v[32:35]
	v_mfma_f32_16x16x32_bf16 v[24:27], v[158:161], v[198:201], v[24:27]
	v_mfma_f32_16x16x32_bf16 v[16:19], v[140:143], v[206:209], v[16:19]
	v_mfma_f32_16x16x32_bf16 v[8:11], v[158:161], v[206:209], v[8:11]
	v_mfma_f32_16x16x32_bf16 v[60:63], v[154:157], v[186:189], v[60:63]
	v_mfma_f32_16x16x32_bf16 v[56:59], v[162:165], v[186:189], v[56:59]
	v_mfma_f32_16x16x32_bf16 v[48:51], v[154:157], v[194:197], v[48:51]
	v_mfma_f32_16x16x32_bf16 v[40:43], v[162:165], v[194:197], v[40:43]
	v_mfma_f32_16x16x32_bf16 v[32:35], v[154:157], v[202:205], v[32:35]
	v_mfma_f32_16x16x32_bf16 v[24:27], v[162:165], v[202:205], v[24:27]
	v_mfma_f32_16x16x32_bf16 v[16:19], v[154:157], v[210:213], v[16:19]
	v_mfma_f32_16x16x32_bf16 v[8:11], v[162:165], v[210:213], v[8:11]
	s_setprio 0
	s_setprio 1
	v_mfma_f32_16x16x32_bf16 v[52:55], v[166:169], v[182:185], v[52:55]
	v_mfma_f32_16x16x32_bf16 v[44:47], v[174:177], v[182:185], v[44:47]
	v_mfma_f32_16x16x32_bf16 v[36:39], v[166:169], v[190:193], v[36:39]
	v_mfma_f32_16x16x32_bf16 v[28:31], v[174:177], v[190:193], v[28:31]
	v_mfma_f32_16x16x32_bf16 v[20:23], v[166:169], v[198:201], v[20:23]
	v_mfma_f32_16x16x32_bf16 v[12:15], v[174:177], v[198:201], v[12:15]
	v_mfma_f32_16x16x32_bf16 v[4:7], v[166:169], v[206:209], v[4:7]
	v_mfma_f32_16x16x32_bf16 v[0:3], v[174:177], v[206:209], v[0:3]
	v_mfma_f32_16x16x32_bf16 v[52:55], v[170:173], v[186:189], v[52:55]
	v_mfma_f32_16x16x32_bf16 v[44:47], v[178:181], v[186:189], v[44:47]
	v_mfma_f32_16x16x32_bf16 v[36:39], v[170:173], v[194:197], v[36:39]
	v_mfma_f32_16x16x32_bf16 v[28:31], v[178:181], v[194:197], v[28:31]
	v_mfma_f32_16x16x32_bf16 v[20:23], v[170:173], v[202:205], v[20:23]
	v_mfma_f32_16x16x32_bf16 v[12:15], v[178:181], v[202:205], v[12:15]
	v_mfma_f32_16x16x32_bf16 v[4:7], v[170:173], v[210:213], v[4:7]
	v_mfma_f32_16x16x32_bf16 v[0:3], v[178:181], v[210:213], v[0:3]
	s_setprio 0
	s_barrier
	s_add_i32 s75, s75, 2
	s_add_u32 s36, s36, 0x100
	s_addc_u32 s37, s37, 0
	s_add_u32 s73, s73, 0x100
	s_addc_u32 s74, s74, 0
	s_cmp_gt_u32 s75, 29
	s_cbranch_scc0 .LBB0_785
	s_and_b64 vcc, exec, s[14:15]
	s_cbranch_vccz .LBB0_788
	s_barrier

.LBB0_868:
.LBB0_869:
	s_add_i32 s0, 0, 0x23f94
	s_waitcnt vmcnt(0)
	v_mov_b32_e32 v0, s0
	v_mbcnt_lo_u32_b32 v58, -1, 0
	v_mbcnt_hi_u32_b32 v58, -1, v58
	ds_read_b32 v0, v0
	v_lshlrev_b32_e32 v71, 4, v58
	v_and_b32_e32 v59, 15, v58
	s_mov_b32 s1, 0
	v_ashrrev_i32_e32 v70, 4, v58
	s_waitcnt lgkmcnt(0)
	v_readfirstlane_b32 s0, v0
	s_and_b32 s4, s0, 7
	s_mul_i32 s5, s4, 0x1400000
	s_add_u32 s5, s94, s5
	s_addc_u32 s6, s95, 0
	s_lshl_b32 s4, s4, 22
	s_sub_u32 s4, 0, s4
	s_subb_u32 s7, 0, 0
	s_add_u32 s4, s5, s4
	s_addc_u32 s5, s6, s7
	s_lshl_b32 s8, s88, 10
	v_add_u32_e32 v0, s8, v71
	v_ashrrev_i32_e32 v1, 31, v0
	v_lshrrev_b32_e32 v1, 22, v1
	v_add_u32_e32 v1, v0, v1
	v_ashrrev_i32_e32 v1, 10, v1
	v_mul_i32_i24_e32 v2, 0x400, v1
	v_sub_u32_e32 v2, v0, v2
	v_lshrrev_b32_e32 v3, 4, v2
	v_bitop3_b32 v2, v3, v2, 32 bitop3:0x6c
	v_ashrrev_i32_e32 v4, 31, v2
	v_lshrrev_b32_e32 v4, 26, v4
	v_lshlrev_b32_e32 v3, 3, v1
	v_add_u32_e32 v4, v2, v4
	v_and_b32_e32 v3, -16, v3
	v_ashrrev_i32_e32 v5, 6, v4
	v_add_u32_e32 v104, v5, v3
	v_and_b32_e32 v3, 0xc0, v4
	v_lshlrev_b32_e32 v1, 5, v1
	v_sub_u32_e32 v2, v2, v3
	v_mov_b32_e32 v3, 1
	v_and_b32_e32 v1, 32, v1
	v_ashrrev_i16_sdwa v2, v3, sext(v2) dst_sel:DWORD dst_unused:UNUSED_PAD src0_sel:DWORD src1_sel:BYTE_0
	v_add_u32_sdwa v1, v1, sext(v2) dst_sel:DWORD dst_unused:UNUSED_PAD src0_sel:DWORD src1_sel:WORD_0
	v_lshlrev_b32_e32 v2, 10, v104
	v_add_u32_e32 v0, 0x2000, v0
	v_lshl_add_u32 v62, v1, 1, v2
	v_ashrrev_i32_e32 v1, 31, v0
	v_lshrrev_b32_e32 v1, 22, v1
	v_add_u32_e32 v1, v0, v1
	v_ashrrev_i32_e32 v1, 10, v1
	v_mul_i32_i24_e32 v2, 0x400, v1
	v_sub_u32_e32 v0, v0, v2
	v_lshrrev_b32_e32 v2, 4, v0
	s_lshl_b32 s6, s0, 3
	v_bitop3_b32 v0, v2, v0, 32 bitop3:0x6c
	s_and_b32 s6, s6, 56
	s_ashr_i32 s7, s0, 5
	v_ashrrev_i32_e32 v4, 31, v0
	s_add_i32 s9, s6, s7
	v_lshrrev_b32_e32 v4, 26, v4
	s_ashr_i32 s12, s9, 5
	v_lshlrev_b32_e32 v2, 3, v1
	v_add_u32_e32 v4, v0, v4
	s_bfe_u32 s0, s0, 0x20003
	s_lshl_b32 s6, s12, 2
	v_and_b32_e32 v2, -16, v2
	v_ashrrev_i32_e32 v5, 6, v4
	s_or_b32 s6, s6, s0
	v_add_u32_e32 v108, v5, v2
	v_and_b32_e32 v2, 0xffc0, v4
	s_ashr_i32 s7, s6, 31
	v_sub_u32_e32 v0, v0, v2
	s_lshl_b64 s[6:7], s[6:7], 18
	v_lshrrev_b16_e32 v2, 7, v0
	s_add_u32 s10, s94, s6
	v_and_b32_e32 v2, 1, v2
	s_addc_u32 s11, s95, s7
	v_lshlrev_b32_e32 v1, 5, v1
	v_add_u16_e32 v0, v0, v2
	s_add_u32 s6, s10, 0x11400000
	v_and_b32_e32 v1, 32, v1
	v_ashrrev_i16_sdwa v0, v3, sext(v0) dst_sel:DWORD dst_unused:UNUSED_PAD src0_sel:DWORD src1_sel:BYTE_0
	s_addc_u32 s7, s11, 0
	s_lshl_b32 s9, s9, 7
	v_add_u32_sdwa v0, v1, sext(v0) dst_sel:DWORD dst_unused:UNUSED_PAD src0_sel:DWORD src1_sel:WORD_0
	v_lshlrev_b32_e32 v1, 10, v108
	s_lshl_b32 s12, s12, 12
	s_and_b32 s9, s9, 0xf80
	v_lshl_add_u32 v64, v0, 1, v1
	v_lshl_or_b32 v1, s88, 4, v59
	s_or_b32 s9, s12, s9
	v_add_u32_e32 v2, s9, v1
	v_ashrrev_i32_e32 v3, 31, v2
	v_lshlrev_b64 v[2:3], 12, v[2:3]
	s_lshl_b32 s0, s0, 10
	v_lshl_add_u64 v[2:3], s[4:5], 0, v[2:3]
	v_lshlrev_b32_e32 v0, 3, v70
	v_lshl_add_u64 v[2:3], v[2:3], 0, s[0:1]
	s_mov_b64 s[0:1], 0x13000000
	v_ashrrev_i32_e32 v1, 31, v0
	v_lshl_add_u64 v[60:61], v[2:3], 0, s[0:1]
	v_lshl_add_u64 v[0:1], v[0:1], 1, v[60:61]
	s_mov_b64 s[0:1], 0xc00000
	v_lshl_add_u64 v[2:3], v[0:1], 0, s[0:1]
	s_mov_b32 s0, 0xc00000
	v_add_co_u32_e32 v0, vcc, s0, v0
	s_add_i32 s22, s8, 0
	s_nop 0
	v_addc_co_u32_e32 v1, vcc, 0, v1, vcc
	v_mov_b32_e32 v63, 0
	s_mov_b32 m0, s22
	s_add_i32 s21, s22, 0x2000
	global_load_dwordx4 v[72:75], v[2:3], off offset:64
	global_load_dwordx4 v[52:55], v[2:3], off offset:128
	global_load_dwordx4 v[48:51], v[2:3], off offset:192
	global_load_dwordx4 v[44:47], v[2:3], off offset:256
	global_load_dwordx4 v[40:43], v[2:3], off offset:320
	global_load_dwordx4 v[36:39], v[2:3], off offset:384
	global_load_dwordx4 v[32:35], v[2:3], off offset:448
	global_load_dwordx4 v[28:31], v[2:3], off offset:512
	global_load_dwordx4 v[24:27], v[2:3], off offset:576
	global_load_dwordx4 v[20:23], v[2:3], off offset:640
	global_load_dwordx4 v[16:19], v[2:3], off offset:704
	global_load_dwordx4 v[12:15], v[2:3], off offset:768
	global_load_dwordx4 v[8:11], v[2:3], off offset:832
	global_load_dwordx4 v[4:7], v[2:3], off offset:896
	global_load_dwordx4 v[76:79], v[0:1], off
	s_nop 0
	global_load_dwordx4 v[0:3], v[2:3], off offset:960
	v_mov_b32_e32 v65, v63
	global_load_lds_dwordx4 v62, s[6:7]
	s_mov_b32 m0, s21
	v_lshl_add_u64 v[66:67], s[6:7], 0, v[62:63]
	v_lshl_add_u64 v[68:69], s[6:7], 0, v[64:65]
	global_load_lds_dwordx4 v64, s[6:7]
	s_add_i32 s20, s22, 0x4000
	s_mov_b64 s[6:7], 0x80
	s_add_i32 s23, s22, 0x6000
	v_lshl_add_u64 v[56:57], v[66:67], 0, s[6:7]
	s_mov_b32 m0, s20
	s_add_u32 s0, s10, 0x11420000
	global_load_lds_dwordx4 v[56:57], off
	v_lshl_add_u64 v[56:57], v[68:69], 0, s[6:7]
	s_mov_b32 m0, s23
	s_addc_u32 s1, s11, 0
	s_add_i32 s24, s22, 0x8000
	global_load_lds_dwordx4 v[56:57], off
	s_mov_b32 m0, s24
	s_add_i32 s25, s22, 0xa000
	global_load_lds_dwordx4 v62, s[0:1]
	s_mov_b32 m0, s25
	s_mov_b64 s[4:5], 0x180
	global_load_lds_dwordx4 v64, s[0:1]
	s_add_u32 s0, s10, 0x11420080
	s_addc_u32 s1, s11, 0
	s_add_i32 s26, s22, 0xc000
	s_mov_b32 m0, s26
	s_add_i32 s27, s22, 0xe000
	global_load_lds_dwordx4 v62, s[0:1]
	s_mov_b32 m0, s27
	s_add_u32 s8, s10, 0x11c00000
	global_load_lds_dwordx4 v64, s[0:1]
	s_addc_u32 s9, s11, 0
	s_add_i32 s19, s22, 0x10000
	s_mov_b64 s[0:1], 0x100
	v_lshl_add_u64 v[56:57], v[66:67], 0, s[0:1]
	s_mov_b32 m0, s19
	s_add_i32 s13, s22, 0x12000
	s_waitcnt vmcnt(0)
	s_waitcnt vmcnt(0) lgkmcnt(0)
	s_barrier
	global_load_lds_dwordx4 v[56:57], off
	v_lshl_add_u64 v[56:57], v[68:69], 0, s[0:1]
	s_mov_b32 m0, s13
	s_add_i32 s12, s22, 0x14000
	s_add_i32 s14, s22, 0x16000
	global_load_lds_dwordx4 v[56:57], off
	v_lshl_add_u64 v[56:57], v[66:67], 0, s[4:5]
	s_mov_b32 m0, s12
	s_add_u32 s28, s10, 0x11420100
	global_load_lds_dwordx4 v[56:57], off
	v_lshl_add_u64 v[56:57], v[68:69], 0, s[4:5]
	s_mov_b32 m0, s14
	s_addc_u32 s29, s11, 0
	s_add_i32 s15, s22, 0x18000
	global_load_lds_dwordx4 v[56:57], off
	s_mov_b32 m0, s15
	s_add_i32 s16, s22, 0x1a000
	global_load_lds_dwordx4 v62, s[28:29]
	s_mov_b32 m0, s16
	v_and_b32_e32 v57, 48, v58
	global_load_lds_dwordx4 v64, s[28:29]
	s_add_u32 s28, s10, 0x11420180
	s_addc_u32 s29, s11, 0
	s_add_i32 s17, s22, 0x1c000
	s_mov_b32 m0, s17
	s_add_i32 s18, s22, 0x1e000
	global_load_lds_dwordx4 v62, s[28:29]
	s_mov_b32 m0, s18
	v_lshlrev_b32_e32 v58, 2, v58
	global_load_lds_dwordx4 v64, s[28:29]
	v_lshlrev_b32_e32 v56, 6, v59
	v_and_b32_e32 v58, 32, v58
	v_bitop3_b32 v56, v56, v58, v57 bitop3:0x36
	v_and_b32_e32 v57, 0xfffffc00, v71
	v_add3_u32 v65, 0, v56, v57
	v_mov_b32_e32 v71, v65
	ds_read_b128 v[56:59], v71
	ds_read_b128 v[80:83], v71 offset:2048
	s_waitcnt lgkmcnt(0)
	v_mfma_f32_16x16x32_bf16 v[84:87], v[56:59], v[76:79], 0
	ds_read_b128 v[56:59], v71 offset:4096
	ds_read_b128 v[88:91], v71 offset:6144
	ds_read_b128 v[96:99], v71 offset:8192
	ds_read_b128 v[100:103], v71 offset:10240
	s_waitcnt lgkmcnt(0)
	v_mfma_f32_16x16x32_bf16 v[92:95], v[56:59], v[76:79], 0
	v_lshlrev_b32_e32 v56, 9, v104
	ds_read_b128 v[104:107], v71 offset:12288
	v_lshlrev_b32_e32 v57, 9, v108
	ds_read_b128 v[108:111], v71 offset:14336
	ds_read_b128 v[112:115], v71 offset:32768
	ds_read_b128 v[116:119], v71 offset:34816
	ds_read_b128 v[120:123], v71 offset:36864
	ds_read_b128 v[124:127], v71 offset:38912
	ds_read_b128 v[128:131], v71 offset:40960
	ds_read_b128 v[132:135], v71 offset:43008
	ds_read_b128 v[136:139], v71 offset:45056
	ds_read_b128 v[140:143], v71 offset:47104
	v_mfma_f32_16x16x32_bf16 v[80:83], v[80:83], v[76:79], 0
	v_sub_u32_e32 v56, v62, v56
	v_sub_u32_e32 v58, v64, v57
	v_mfma_f32_16x16x32_bf16 v[88:91], v[88:91], v[76:79], 0
	v_mfma_f32_16x16x32_bf16 v[96:99], v[96:99], v[76:79], 0
	v_mfma_f32_16x16x32_bf16 v[100:103], v[100:103], v[76:79], 0
	s_waitcnt lgkmcnt(0)
	v_mfma_f32_16x16x32_bf16 v[104:107], v[104:107], v[76:79], 0
	v_mfma_f32_16x16x32_bf16 v[108:111], v[108:111], v[76:79], 0
	ds_read_b128 v[144:147], v71 offset:15360
	ds_read_b128 v[148:151], v71 offset:13312
	ds_read_b128 v[152:155], v71 offset:11264
	ds_read_b128 v[156:159], v71 offset:9216
	ds_read_b128 v[160:163], v71 offset:7168
	ds_read_b128 v[164:167], v71 offset:5120
	ds_read_b128 v[168:171], v71 offset:3072
	ds_read_b128 v[172:175], v71 offset:1024
	v_mfma_f32_16x16x32_bf16 v[112:115], v[112:115], v[76:79], 0
	v_mfma_f32_16x16x32_bf16 v[116:119], v[116:119], v[76:79], 0
	v_mfma_f32_16x16x32_bf16 v[120:123], v[120:123], v[76:79], 0
	v_mfma_f32_16x16x32_bf16 v[124:127], v[124:127], v[76:79], 0
	v_mfma_f32_16x16x32_bf16 v[128:131], v[128:131], v[76:79], 0
	v_mfma_f32_16x16x32_bf16 v[132:135], v[132:135], v[76:79], 0
	v_mfma_f32_16x16x32_bf16 v[136:139], v[136:139], v[76:79], 0
	v_mfma_f32_16x16x32_bf16 v[76:79], v[140:143], v[76:79], 0
	s_waitcnt lgkmcnt(0)
	v_mfma_f32_16x16x32_bf16 v[84:87], v[172:175], v[72:75], v[84:87]
	v_mfma_f32_16x16x32_bf16 v[80:83], v[168:171], v[72:75], v[80:83]
	v_mfma_f32_16x16x32_bf16 v[92:95], v[164:167], v[72:75], v[92:95]
	v_mfma_f32_16x16x32_bf16 v[88:91], v[160:163], v[72:75], v[88:91]
	v_mfma_f32_16x16x32_bf16 v[96:99], v[156:159], v[72:75], v[96:99]
	v_mfma_f32_16x16x32_bf16 v[100:103], v[152:155], v[72:75], v[100:103]
	ds_read_b128 v[140:143], v71 offset:33792
	ds_read_b128 v[152:155], v71 offset:35840
	ds_read_b128 v[156:159], v71 offset:37888
	ds_read_b128 v[160:163], v71 offset:39936
	v_mfma_f32_16x16x32_bf16 v[104:107], v[148:151], v[72:75], v[104:107]
	ds_read_b128 v[148:151], v71 offset:41984
	ds_read_b128 v[164:167], v71 offset:44032
	ds_read_b128 v[168:171], v71 offset:46080
	ds_read_b128 v[172:175], v71 offset:48128
	v_mfma_f32_16x16x32_bf16 v[108:111], v[144:147], v[72:75], v[108:111]
	s_waitcnt lgkmcnt(0)
	v_mfma_f32_16x16x32_bf16 v[112:115], v[140:143], v[72:75], v[112:115]
	v_mfma_f32_16x16x32_bf16 v[116:119], v[152:155], v[72:75], v[116:119]
	v_mfma_f32_16x16x32_bf16 v[120:123], v[156:159], v[72:75], v[120:123]
	v_mfma_f32_16x16x32_bf16 v[124:127], v[160:163], v[72:75], v[124:127]
	v_mfma_f32_16x16x32_bf16 v[128:131], v[148:151], v[72:75], v[128:131]
	ds_read_b128 v[140:143], v71 offset:30720
	ds_read_b128 v[144:147], v71 offset:28672
	ds_read_b128 v[148:151], v71 offset:26624
	ds_read_b128 v[152:155], v71 offset:24576
	v_mfma_f32_16x16x32_bf16 v[132:135], v[164:167], v[72:75], v[132:135]
	v_mfma_f32_16x16x32_bf16 v[136:139], v[168:171], v[72:75], v[136:139]
	ds_read_b128 v[156:159], v71 offset:22528
	ds_read_b128 v[160:163], v71 offset:20480
	ds_read_b128 v[164:167], v71 offset:18432
	ds_read_b128 v[168:171], v71 offset:16384
	v_mfma_f32_16x16x32_bf16 v[72:75], v[172:175], v[72:75], v[76:79]
	s_waitcnt lgkmcnt(0)
	v_mfma_f32_16x16x32_bf16 v[76:79], v[168:171], v[52:55], v[84:87]
	v_mfma_f32_16x16x32_bf16 v[80:83], v[164:167], v[52:55], v[80:83]
	v_mfma_f32_16x16x32_bf16 v[84:87], v[160:163], v[52:55], v[92:95]
	v_mfma_f32_16x16x32_bf16 v[88:91], v[156:159], v[52:55], v[88:91]
	v_mfma_f32_16x16x32_bf16 v[92:95], v[152:155], v[52:55], v[96:99]
	v_mfma_f32_16x16x32_bf16 v[96:99], v[148:151], v[52:55], v[100:103]
	s_nop 2
	ds_read_b128 v[100:103], v71 offset:49152
	ds_read_b128 v[148:151], v71 offset:51200
	ds_read_b128 v[152:155], v71 offset:53248
	ds_read_b128 v[156:159], v71 offset:55296
	v_mfma_f32_16x16x32_bf16 v[104:107], v[144:147], v[52:55], v[104:107]
	ds_read_b128 v[144:147], v71 offset:57344
	ds_read_b128 v[160:163], v71 offset:59392
	ds_read_b128 v[164:167], v71 offset:61440
	ds_read_b128 v[168:171], v71 offset:63488
	v_mfma_f32_16x16x32_bf16 v[108:111], v[140:143], v[52:55], v[108:111]
	s_waitcnt lgkmcnt(0)
	v_mfma_f32_16x16x32_bf16 v[100:103], v[100:103], v[52:55], v[112:115]
	v_mfma_f32_16x16x32_bf16 v[112:115], v[148:151], v[52:55], v[116:119]
	v_mfma_f32_16x16x32_bf16 v[116:119], v[152:155], v[52:55], v[120:123]
	v_mfma_f32_16x16x32_bf16 v[120:123], v[156:159], v[52:55], v[124:127]
	v_mfma_f32_16x16x32_bf16 v[124:127], v[144:147], v[52:55], v[128:131]
	v_mfma_f32_16x16x32_bf16 v[128:131], v[160:163], v[52:55], v[132:135]
	s_nop 2
	ds_read_b128 v[132:135], v71 offset:31744
	ds_read_b128 v[140:143], v71 offset:29696
	ds_read_b128 v[144:147], v71 offset:27648
	ds_read_b128 v[148:151], v71 offset:25600
	v_mfma_f32_16x16x32_bf16 v[136:139], v[164:167], v[52:55], v[136:139]
	ds_read_b128 v[152:155], v71 offset:23552
	ds_read_b128 v[156:159], v71 offset:21504
	ds_read_b128 v[160:163], v71 offset:19456
	ds_read_b128 v[164:167], v71 offset:17408
	v_mfma_f32_16x16x32_bf16 v[52:55], v[168:171], v[52:55], v[72:75]
	s_waitcnt lgkmcnt(0)
	v_mfma_f32_16x16x32_bf16 v[72:75], v[164:167], v[48:51], v[76:79]
	v_mfma_f32_16x16x32_bf16 v[76:79], v[160:163], v[48:51], v[80:83]
	v_mfma_f32_16x16x32_bf16 v[80:83], v[156:159], v[48:51], v[84:87]
	v_mfma_f32_16x16x32_bf16 v[84:87], v[152:155], v[48:51], v[88:91]
	v_mfma_f32_16x16x32_bf16 v[88:91], v[148:151], v[48:51], v[92:95]
	v_mfma_f32_16x16x32_bf16 v[92:95], v[144:147], v[48:51], v[96:99]
	s_nop 2
	ds_read_b128 v[96:99], v71 offset:50176
	ds_read_b128 v[144:147], v71 offset:52224
	ds_read_b128 v[148:151], v71 offset:54272
	ds_read_b128 v[152:155], v71 offset:56320
	v_mfma_f32_16x16x32_bf16 v[104:107], v[140:143], v[48:51], v[104:107]
	ds_read_b128 v[140:143], v71 offset:58368
	ds_read_b128 v[156:159], v71 offset:60416
	ds_read_b128 v[160:163], v71 offset:62464
	ds_read_b128 v[164:167], v71 offset:64512
	v_mfma_f32_16x16x32_bf16 v[108:111], v[132:135], v[48:51], v[108:111]
	s_waitcnt lgkmcnt(0)
	v_mfma_f32_16x16x32_bf16 v[96:99], v[96:99], v[48:51], v[100:103]
	v_mfma_f32_16x16x32_bf16 v[100:103], v[144:147], v[48:51], v[112:115]
	v_mfma_f32_16x16x32_bf16 v[112:115], v[148:151], v[48:51], v[116:119]
	v_mfma_f32_16x16x32_bf16 v[116:119], v[152:155], v[48:51], v[120:123]
	v_mfma_f32_16x16x32_bf16 v[120:123], v[140:143], v[48:51], v[124:127]
	v_mfma_f32_16x16x32_bf16 v[124:127], v[156:159], v[48:51], v[128:131]
	v_mfma_f32_16x16x32_bf16 v[128:131], v[160:163], v[48:51], v[136:139]
	v_mfma_f32_16x16x32_bf16 v[50:53], v[164:167], v[48:51], v[52:55]
	s_mov_b64 s[28:29], 0x200
	s_mov_b32 m0, s22
	v_lshl_add_u64 v[48:49], v[66:67], 0, s[28:29]
	s_waitcnt vmcnt(0)
	s_waitcnt vmcnt(0)
	s_barrier
	global_load_lds_dwordx4 v[48:49], off
	v_lshl_add_u64 v[48:49], v[68:69], 0, s[28:29]
	s_mov_b32 m0, s21
	s_mov_b64 s[28:29], 0x280
	global_load_lds_dwordx4 v[48:49], off
	v_lshl_add_u64 v[48:49], v[66:67], 0, s[28:29]
	s_mov_b32 m0, s20
	s_nop 0
	global_load_lds_dwordx4 v[48:49], off
	v_lshl_add_u64 v[48:49], v[68:69], 0, s[28:29]
	s_mov_b32 m0, s23
	s_add_u32 s28, s10, 0x11420200
	global_load_lds_dwordx4 v[48:49], off
	s_addc_u32 s29, s11, 0
	s_mov_b32 m0, s24
	v_add_u32_e32 v48, 0x10000, v65
	global_load_lds_dwordx4 v62, s[28:29]
	s_mov_b32 m0, s25
	v_mov_b32_e32 v49, v48
	global_load_lds_dwordx4 v64, s[28:29]
	s_add_u32 s28, s10, 0x11420280
	s_addc_u32 s29, s11, 0
	s_mov_b32 m0, s26
	s_nop 0
	global_load_lds_dwordx4 v62, s[28:29]
	s_mov_b32 m0, s27
	s_nop 0
	global_load_lds_dwordx4 v64, s[28:29]
	ds_read_b128 v[132:135], v49
	ds_read_b128 v[136:139], v49 offset:2048
	s_waitcnt lgkmcnt(0)
	v_mfma_f32_16x16x32_bf16 v[72:75], v[132:135], v[44:47], v[72:75]
	ds_read_b128 v[132:135], v49 offset:4096
	v_mfma_f32_16x16x32_bf16 v[76:79], v[136:139], v[44:47], v[76:79]
	ds_read_b128 v[136:139], v49 offset:6144
	s_waitcnt lgkmcnt(0)
	v_mfma_f32_16x16x32_bf16 v[80:83], v[132:135], v[44:47], v[80:83]
	ds_read_b128 v[132:135], v49 offset:8192
	v_mfma_f32_16x16x32_bf16 v[84:87], v[136:139], v[44:47], v[84:87]
	ds_read_b128 v[136:139], v49 offset:10240
	s_waitcnt lgkmcnt(0)
	v_mfma_f32_16x16x32_bf16 v[88:91], v[132:135], v[44:47], v[88:91]
	ds_read_b128 v[132:135], v49 offset:12288
	ds_read_b128 v[140:143], v49 offset:14336
	v_mfma_f32_16x16x32_bf16 v[92:95], v[136:139], v[44:47], v[92:95]
	ds_read_b128 v[136:139], v49 offset:32768
	ds_read_b128 v[144:147], v49 offset:34816
	ds_read_b128 v[148:151], v49 offset:36864
	ds_read_b128 v[152:155], v49 offset:38912
	s_waitcnt lgkmcnt(0)
	v_mfma_f32_16x16x32_bf16 v[104:107], v[132:135], v[44:47], v[104:107]
	ds_read_b128 v[132:135], v49 offset:40960
	ds_read_b128 v[156:159], v49 offset:43008
	ds_read_b128 v[160:163], v49 offset:45056
	ds_read_b128 v[164:167], v49 offset:47104
	v_mfma_f32_16x16x32_bf16 v[108:111], v[140:143], v[44:47], v[108:111]
	v_mfma_f32_16x16x32_bf16 v[96:99], v[136:139], v[44:47], v[96:99]
	v_mfma_f32_16x16x32_bf16 v[100:103], v[144:147], v[44:47], v[100:103]
	v_mfma_f32_16x16x32_bf16 v[112:115], v[148:151], v[44:47], v[112:115]
	v_mfma_f32_16x16x32_bf16 v[116:119], v[152:155], v[44:47], v[116:119]
	s_waitcnt lgkmcnt(0)
	v_mfma_f32_16x16x32_bf16 v[120:123], v[132:135], v[44:47], v[120:123]
	ds_read_b128 v[132:135], v49 offset:15360
	ds_read_b128 v[136:139], v49 offset:13312
	ds_read_b128 v[140:143], v49 offset:11264
	ds_read_b128 v[144:147], v49 offset:9216
	v_mfma_f32_16x16x32_bf16 v[124:127], v[156:159], v[44:47], v[124:127]
	v_mfma_f32_16x16x32_bf16 v[128:131], v[160:163], v[44:47], v[128:131]
	ds_read_b128 v[148:151], v49 offset:7168
	ds_read_b128 v[152:155], v49 offset:5120
	ds_read_b128 v[156:159], v49 offset:3072
	ds_read_b128 v[160:163], v49 offset:1024
	v_mfma_f32_16x16x32_bf16 v[44:47], v[164:167], v[44:47], v[50:53]
	s_waitcnt lgkmcnt(0)
	v_mfma_f32_16x16x32_bf16 v[50:53], v[160:163], v[40:43], v[72:75]
	v_mfma_f32_16x16x32_bf16 v[72:75], v[156:159], v[40:43], v[76:79]
	v_mfma_f32_16x16x32_bf16 v[76:79], v[152:155], v[40:43], v[80:83]
	v_mfma_f32_16x16x32_bf16 v[80:83], v[148:151], v[40:43], v[84:87]
	v_mfma_f32_16x16x32_bf16 v[84:87], v[144:147], v[40:43], v[88:91]
	v_mfma_f32_16x16x32_bf16 v[88:91], v[140:143], v[40:43], v[92:95]
	s_nop 2
	ds_read_b128 v[92:95], v49 offset:33792
	ds_read_b128 v[140:143], v49 offset:35840
	ds_read_b128 v[144:147], v49 offset:37888
	ds_read_b128 v[148:151], v49 offset:39936
	v_mfma_f32_16x16x32_bf16 v[104:107], v[136:139], v[40:43], v[104:107]
	ds_read_b128 v[136:139], v49 offset:41984
	ds_read_b128 v[152:155], v49 offset:44032
	ds_read_b128 v[156:159], v49 offset:46080
	ds_read_b128 v[160:163], v49 offset:48128
	v_mfma_f32_16x16x32_bf16 v[108:111], v[132:135], v[40:43], v[108:111]
	s_waitcnt lgkmcnt(0)
	v_mfma_f32_16x16x32_bf16 v[92:95], v[92:95], v[40:43], v[96:99]
	v_mfma_f32_16x16x32_bf16 v[96:99], v[140:143], v[40:43], v[100:103]
	v_mfma_f32_16x16x32_bf16 v[100:103], v[144:147], v[40:43], v[112:115]
	v_mfma_f32_16x16x32_bf16 v[112:115], v[148:151], v[40:43], v[116:119]
	v_mfma_f32_16x16x32_bf16 v[116:119], v[136:139], v[40:43], v[120:123]
	v_mfma_f32_16x16x32_bf16 v[120:123], v[152:155], v[40:43], v[124:127]
	s_nop 2
	ds_read_b128 v[124:127], v49 offset:30720
	ds_read_b128 v[132:135], v49 offset:28672
	ds_read_b128 v[136:139], v49 offset:26624
	ds_read_b128 v[140:143], v49 offset:24576
	v_mfma_f32_16x16x32_bf16 v[128:131], v[156:159], v[40:43], v[128:131]
	ds_read_b128 v[144:147], v49 offset:22528
	ds_read_b128 v[148:151], v49 offset:20480
	ds_read_b128 v[152:155], v49 offset:18432
	ds_read_b128 v[156:159], v49 offset:16384
	v_mfma_f32_16x16x32_bf16 v[40:43], v[160:163], v[40:43], v[44:47]
	s_waitcnt lgkmcnt(0)
	v_mfma_f32_16x16x32_bf16 v[44:47], v[156:159], v[36:39], v[50:53]
	v_mfma_f32_16x16x32_bf16 v[50:53], v[152:155], v[36:39], v[72:75]
	v_mfma_f32_16x16x32_bf16 v[72:75], v[148:151], v[36:39], v[76:79]
	v_mfma_f32_16x16x32_bf16 v[76:79], v[144:147], v[36:39], v[80:83]
	v_mfma_f32_16x16x32_bf16 v[80:83], v[140:143], v[36:39], v[84:87]
	v_mfma_f32_16x16x32_bf16 v[84:87], v[136:139], v[36:39], v[88:91]
	s_nop 2
	ds_read_b128 v[88:91], v49 offset:49152
	ds_read_b128 v[136:139], v49 offset:51200
	ds_read_b128 v[140:143], v49 offset:53248
	ds_read_b128 v[144:147], v49 offset:55296
	v_mfma_f32_16x16x32_bf16 v[104:107], v[132:135], v[36:39], v[104:107]
	ds_read_b128 v[132:135], v49 offset:57344
	ds_read_b128 v[148:151], v49 offset:59392
	ds_read_b128 v[152:155], v49 offset:61440
	ds_read_b128 v[156:159], v49 offset:63488
	v_mfma_f32_16x16x32_bf16 v[108:111], v[124:127], v[36:39], v[108:111]
	s_waitcnt lgkmcnt(0)
	v_mfma_f32_16x16x32_bf16 v[88:91], v[88:91], v[36:39], v[92:95]
	v_mfma_f32_16x16x32_bf16 v[92:95], v[136:139], v[36:39], v[96:99]
	v_mfma_f32_16x16x32_bf16 v[96:99], v[140:143], v[36:39], v[100:103]
	v_mfma_f32_16x16x32_bf16 v[100:103], v[144:147], v[36:39], v[112:115]
	v_mfma_f32_16x16x32_bf16 v[112:115], v[132:135], v[36:39], v[116:119]
	v_mfma_f32_16x16x32_bf16 v[116:119], v[148:151], v[36:39], v[120:123]
	s_nop 2
	ds_read_b128 v[120:123], v49 offset:31744
	ds_read_b128 v[124:127], v49 offset:29696
	ds_read_b128 v[132:135], v49 offset:27648
	ds_read_b128 v[136:139], v49 offset:25600
	v_mfma_f32_16x16x32_bf16 v[128:131], v[152:155], v[36:39], v[128:131]
	ds_read_b128 v[140:143], v49 offset:23552
	ds_read_b128 v[144:147], v49 offset:21504
	ds_read_b128 v[148:151], v49 offset:19456
	ds_read_b128 v[152:155], v49 offset:17408
	v_mfma_f32_16x16x32_bf16 v[36:39], v[156:159], v[36:39], v[40:43]
	s_waitcnt lgkmcnt(0)
	v_mfma_f32_16x16x32_bf16 v[40:43], v[152:155], v[32:35], v[44:47]
	v_mfma_f32_16x16x32_bf16 v[44:47], v[148:151], v[32:35], v[50:53]
	v_mfma_f32_16x16x32_bf16 v[50:53], v[144:147], v[32:35], v[72:75]
	v_mfma_f32_16x16x32_bf16 v[72:75], v[140:143], v[32:35], v[76:79]
	v_mfma_f32_16x16x32_bf16 v[76:79], v[136:139], v[32:35], v[80:83]
	v_mfma_f32_16x16x32_bf16 v[80:83], v[132:135], v[32:35], v[84:87]
	s_nop 2
	ds_read_b128 v[84:87], v49 offset:50176
	ds_read_b128 v[132:135], v49 offset:52224
	ds_read_b128 v[136:139], v49 offset:54272
	ds_read_b128 v[140:143], v49 offset:56320
	v_mfma_f32_16x16x32_bf16 v[104:107], v[124:127], v[32:35], v[104:107]
	ds_read_b128 v[124:127], v49 offset:58368
	ds_read_b128 v[144:147], v49 offset:60416
	ds_read_b128 v[148:151], v49 offset:62464
	ds_read_b128 v[152:155], v49 offset:64512
	v_mfma_f32_16x16x32_bf16 v[108:111], v[120:123], v[32:35], v[108:111]
	s_waitcnt lgkmcnt(0)
	v_mfma_f32_16x16x32_bf16 v[84:87], v[84:87], v[32:35], v[88:91]
	v_mfma_f32_16x16x32_bf16 v[88:91], v[132:135], v[32:35], v[92:95]
	v_mfma_f32_16x16x32_bf16 v[92:95], v[136:139], v[32:35], v[96:99]
	v_mfma_f32_16x16x32_bf16 v[96:99], v[140:143], v[32:35], v[100:103]
	v_mfma_f32_16x16x32_bf16 v[100:103], v[124:127], v[32:35], v[112:115]
	v_mfma_f32_16x16x32_bf16 v[112:115], v[144:147], v[32:35], v[116:119]
	v_mfma_f32_16x16x32_bf16 v[116:119], v[148:151], v[32:35], v[128:131]
	v_mfma_f32_16x16x32_bf16 v[32:35], v[152:155], v[32:35], v[36:39]
	s_mov_b64 s[28:29], 0x300
	s_mov_b32 m0, s19
	s_nop 0
	v_lshl_add_u64 v[36:37], v[66:67], 0, s[28:29]
	s_waitcnt vmcnt(0)
	s_waitcnt vmcnt(0)
	s_barrier
	global_load_lds_dwordx4 v[36:37], off
	v_lshl_add_u64 v[36:37], v[68:69], 0, s[28:29]
	s_mov_b32 m0, s13
	s_mov_b64 s[28:29], 0x380
	global_load_lds_dwordx4 v[36:37], off
	v_lshl_add_u64 v[36:37], v[66:67], 0, s[28:29]
	s_mov_b32 m0, s12
	v_mov_b32_e32 v49, v65
	global_load_lds_dwordx4 v[36:37], off
	v_lshl_add_u64 v[36:37], v[68:69], 0, s[28:29]
	s_mov_b32 m0, s14
	s_add_u32 s28, s10, 0x11420300
	global_load_lds_dwordx4 v[36:37], off
	s_addc_u32 s29, s11, 0
	s_mov_b32 m0, s15
	s_nop 0
	global_load_lds_dwordx4 v62, s[28:29]
	s_mov_b32 m0, s16
	s_nop 0
	global_load_lds_dwordx4 v64, s[28:29]
	s_add_u32 s28, s10, 0x11420380
	s_addc_u32 s29, s11, 0
	s_mov_b32 m0, s17
	s_nop 0
	global_load_lds_dwordx4 v62, s[28:29]
	s_mov_b32 m0, s18
	s_nop 0
	global_load_lds_dwordx4 v64, s[28:29]
	ds_read_b128 v[36:39], v49
	ds_read_b128 v[66:69], v49 offset:2048
	s_waitcnt lgkmcnt(0)
	v_mfma_f32_16x16x32_bf16 v[36:39], v[36:39], v[28:31], v[40:43]
	s_nop 2
	ds_read_b128 v[40:43], v49 offset:4096
	v_mfma_f32_16x16x32_bf16 v[44:47], v[66:69], v[28:31], v[44:47]
	ds_read_b128 v[66:69], v49 offset:6144
	s_waitcnt lgkmcnt(0)
	v_mfma_f32_16x16x32_bf16 v[40:43], v[40:43], v[28:31], v[50:53]
	s_nop 2
	ds_read_b128 v[50:53], v49 offset:8192
	v_mfma_f32_16x16x32_bf16 v[66:69], v[66:69], v[28:31], v[72:75]
	s_nop 2
	ds_read_b128 v[72:75], v49 offset:10240
	s_waitcnt lgkmcnt(0)
	v_mfma_f32_16x16x32_bf16 v[50:53], v[50:53], v[28:31], v[76:79]
	s_nop 2
	ds_read_b128 v[76:79], v49 offset:12288
	ds_read_b128 v[120:123], v49 offset:14336
	v_mfma_f32_16x16x32_bf16 v[72:75], v[72:75], v[28:31], v[80:83]
	s_nop 2
	ds_read_b128 v[80:83], v49 offset:32768
	ds_read_b128 v[124:127], v49 offset:34816
	ds_read_b128 v[128:131], v49 offset:36864
	ds_read_b128 v[132:135], v49 offset:38912
	s_waitcnt lgkmcnt(0)
	v_mfma_f32_16x16x32_bf16 v[76:79], v[76:79], v[28:31], v[104:107]
	s_nop 2
	ds_read_b128 v[104:107], v49 offset:40960
	ds_read_b128 v[136:139], v49 offset:43008
	ds_read_b128 v[140:143], v49 offset:45056
	ds_read_b128 v[144:147], v49 offset:47104
	v_mfma_f32_16x16x32_bf16 v[108:111], v[120:123], v[28:31], v[108:111]
	v_mfma_f32_16x16x32_bf16 v[80:83], v[80:83], v[28:31], v[84:87]
	v_mfma_f32_16x16x32_bf16 v[84:87], v[124:127], v[28:31], v[88:91]
	v_mfma_f32_16x16x32_bf16 v[88:91], v[128:131], v[28:31], v[92:95]
	v_mfma_f32_16x16x32_bf16 v[92:95], v[132:135], v[28:31], v[96:99]
	s_waitcnt lgkmcnt(0)
	v_mfma_f32_16x16x32_bf16 v[96:99], v[104:107], v[28:31], v[100:103]
	v_mfma_f32_16x16x32_bf16 v[100:103], v[136:139], v[28:31], v[112:115]
	ds_read_b128 v[104:107], v49 offset:15360
	s_nop 1
	ds_read_b128 v[112:115], v49 offset:13312
	ds_read_b128 v[120:123], v49 offset:11264
	ds_read_b128 v[124:127], v49 offset:9216
	v_mfma_f32_16x16x32_bf16 v[116:119], v[140:143], v[28:31], v[116:119]
	ds_read_b128 v[128:131], v49 offset:7168
	ds_read_b128 v[132:135], v49 offset:5120
	ds_read_b128 v[136:139], v49 offset:3072
	ds_read_b128 v[140:143], v49 offset:1024
	v_mfma_f32_16x16x32_bf16 v[28:31], v[144:147], v[28:31], v[32:35]
	s_waitcnt lgkmcnt(0)
	v_mfma_f32_16x16x32_bf16 v[32:35], v[140:143], v[24:27], v[36:39]
	v_mfma_f32_16x16x32_bf16 v[36:39], v[136:139], v[24:27], v[44:47]
	v_mfma_f32_16x16x32_bf16 v[40:43], v[132:135], v[24:27], v[40:43]
	v_mfma_f32_16x16x32_bf16 v[44:47], v[128:131], v[24:27], v[66:69]
	v_mfma_f32_16x16x32_bf16 v[50:53], v[124:127], v[24:27], v[50:53]
	v_mfma_f32_16x16x32_bf16 v[66:69], v[120:123], v[24:27], v[72:75]
	s_nop 2
	ds_read_b128 v[72:75], v49 offset:33792
	ds_read_b128 v[120:123], v49 offset:35840
	ds_read_b128 v[124:127], v49 offset:37888
	ds_read_b128 v[128:131], v49 offset:39936
	v_mfma_f32_16x16x32_bf16 v[76:79], v[112:115], v[24:27], v[76:79]
	ds_read_b128 v[112:115], v49 offset:41984
	ds_read_b128 v[132:135], v49 offset:44032
	ds_read_b128 v[136:139], v49 offset:46080
	ds_read_b128 v[140:143], v49 offset:48128
	v_mfma_f32_16x16x32_bf16 v[104:107], v[104:107], v[24:27], v[108:111]
	s_waitcnt lgkmcnt(0)
	v_mfma_f32_16x16x32_bf16 v[72:75], v[72:75], v[24:27], v[80:83]
	v_mfma_f32_16x16x32_bf16 v[80:83], v[120:123], v[24:27], v[84:87]
	v_mfma_f32_16x16x32_bf16 v[84:87], v[124:127], v[24:27], v[88:91]
	v_mfma_f32_16x16x32_bf16 v[88:91], v[128:131], v[24:27], v[92:95]
	v_mfma_f32_16x16x32_bf16 v[92:95], v[112:115], v[24:27], v[96:99]
	v_mfma_f32_16x16x32_bf16 v[96:99], v[132:135], v[24:27], v[100:103]
	s_nop 2
	ds_read_b128 v[100:103], v49 offset:30720
	ds_read_b128 v[108:111], v49 offset:28672
	ds_read_b128 v[112:115], v49 offset:26624
	ds_read_b128 v[120:123], v49 offset:24576
	v_mfma_f32_16x16x32_bf16 v[116:119], v[136:139], v[24:27], v[116:119]
	ds_read_b128 v[124:127], v49 offset:22528
	ds_read_b128 v[128:131], v49 offset:20480
	ds_read_b128 v[132:135], v49 offset:18432
	ds_read_b128 v[136:139], v49 offset:16384
	v_mfma_f32_16x16x32_bf16 v[24:27], v[140:143], v[24:27], v[28:31]
	s_waitcnt lgkmcnt(0)
	v_mfma_f32_16x16x32_bf16 v[28:31], v[136:139], v[20:23], v[32:35]
	v_mfma_f32_16x16x32_bf16 v[32:35], v[132:135], v[20:23], v[36:39]
	v_mfma_f32_16x16x32_bf16 v[36:39], v[128:131], v[20:23], v[40:43]
	v_mfma_f32_16x16x32_bf16 v[40:43], v[124:127], v[20:23], v[44:47]
	v_mfma_f32_16x16x32_bf16 v[44:47], v[120:123], v[20:23], v[50:53]
	v_mfma_f32_16x16x32_bf16 v[50:53], v[112:115], v[20:23], v[66:69]
	s_nop 2
	ds_read_b128 v[66:69], v49 offset:49152
	ds_read_b128 v[112:115], v49 offset:51200
	ds_read_b128 v[120:123], v49 offset:53248
	ds_read_b128 v[124:127], v49 offset:55296
	v_mfma_f32_16x16x32_bf16 v[76:79], v[108:111], v[20:23], v[76:79]
	ds_read_b128 v[108:111], v49 offset:57344
	ds_read_b128 v[128:131], v49 offset:59392
	ds_read_b128 v[132:135], v49 offset:61440
	ds_read_b128 v[136:139], v49 offset:63488
	v_mfma_f32_16x16x32_bf16 v[100:103], v[100:103], v[20:23], v[104:107]
	s_waitcnt lgkmcnt(0)
	v_mfma_f32_16x16x32_bf16 v[66:69], v[66:69], v[20:23], v[72:75]
	v_mfma_f32_16x16x32_bf16 v[72:75], v[112:115], v[20:23], v[80:83]
	v_mfma_f32_16x16x32_bf16 v[80:83], v[120:123], v[20:23], v[84:87]
	v_mfma_f32_16x16x32_bf16 v[84:87], v[124:127], v[20:23], v[88:91]
	v_mfma_f32_16x16x32_bf16 v[88:91], v[108:111], v[20:23], v[92:95]
	v_mfma_f32_16x16x32_bf16 v[92:95], v[128:131], v[20:23], v[96:99]
	s_nop 2
	ds_read_b128 v[96:99], v49 offset:31744
	ds_read_b128 v[104:107], v49 offset:29696
	ds_read_b128 v[108:111], v49 offset:27648
	ds_read_b128 v[112:115], v49 offset:25600
	v_mfma_f32_16x16x32_bf16 v[116:119], v[132:135], v[20:23], v[116:119]
	ds_read_b128 v[120:123], v49 offset:23552
	ds_read_b128 v[124:127], v49 offset:21504
	ds_read_b128 v[128:131], v49 offset:19456
	ds_read_b128 v[132:135], v49 offset:17408
	v_mfma_f32_16x16x32_bf16 v[20:23], v[136:139], v[20:23], v[24:27]
	s_waitcnt lgkmcnt(0)
	v_mfma_f32_16x16x32_bf16 v[24:27], v[132:135], v[16:19], v[28:31]
	v_mfma_f32_16x16x32_bf16 v[28:31], v[128:131], v[16:19], v[32:35]
	v_mfma_f32_16x16x32_bf16 v[32:35], v[124:127], v[16:19], v[36:39]
	v_mfma_f32_16x16x32_bf16 v[36:39], v[120:123], v[16:19], v[40:43]
	v_mfma_f32_16x16x32_bf16 v[40:43], v[112:115], v[16:19], v[44:47]
	v_mfma_f32_16x16x32_bf16 v[50:53], v[108:111], v[16:19], v[50:53]
	s_nop 1
	ds_read_b128 v[44:47], v49 offset:50176
	ds_read_b128 v[108:111], v49 offset:52224
	ds_read_b128 v[112:115], v49 offset:54272
	ds_read_b128 v[120:123], v49 offset:56320
	v_mfma_f32_16x16x32_bf16 v[76:79], v[104:107], v[16:19], v[76:79]
	ds_read_b128 v[104:107], v49 offset:58368
	ds_read_b128 v[124:127], v49 offset:60416
	ds_read_b128 v[128:131], v49 offset:62464
	ds_read_b128 v[132:135], v49 offset:64512
	v_mfma_f32_16x16x32_bf16 v[96:99], v[96:99], v[16:19], v[100:103]
	s_waitcnt lgkmcnt(0)
	v_mfma_f32_16x16x32_bf16 v[66:69], v[44:47], v[16:19], v[66:69]
	v_mfma_f32_16x16x32_bf16 v[72:75], v[108:111], v[16:19], v[72:75]
	v_mfma_f32_16x16x32_bf16 v[80:83], v[112:115], v[16:19], v[80:83]
	v_mfma_f32_16x16x32_bf16 v[84:87], v[120:123], v[16:19], v[84:87]
	v_mfma_f32_16x16x32_bf16 v[88:91], v[104:107], v[16:19], v[88:91]
	v_mfma_f32_16x16x32_bf16 v[92:95], v[124:127], v[16:19], v[92:95]
	v_mfma_f32_16x16x32_bf16 v[100:103], v[128:131], v[16:19], v[116:119]
	v_mfma_f32_16x16x32_bf16 v[16:19], v[132:135], v[16:19], v[20:23]
	s_mov_b32 m0, s22
	v_mov_b32_e32 v57, v63
	s_waitcnt vmcnt(0)
	s_waitcnt vmcnt(0)
	s_barrier
	v_lshl_add_u64 v[44:45], s[8:9], 0, v[56:57]
	global_load_lds_dwordx4 v56, s[8:9]
	v_mov_b32_e32 v59, v63
	s_mov_b32 m0, s21
	v_lshl_add_u64 v[46:47], s[8:9], 0, v[58:59]
	global_load_lds_dwordx4 v58, s[8:9]
	v_lshl_add_u64 v[20:21], v[44:45], 0, s[6:7]
	s_mov_b32 m0, s20
	v_mov_b32_e32 v49, v48
	global_load_lds_dwordx4 v[20:21], off
	v_lshl_add_u64 v[20:21], v[46:47], 0, s[6:7]
	s_mov_b32 m0, s23
	s_add_u32 s6, s10, 0x11c10000
	global_load_lds_dwordx4 v[20:21], off
	s_addc_u32 s7, s11, 0
	s_mov_b32 m0, s24
	s_nop 0
	global_load_lds_dwordx4 v56, s[6:7]
	s_mov_b32 m0, s25
	s_nop 0
	global_load_lds_dwordx4 v58, s[6:7]
	s_add_u32 s6, s10, 0x11c10080
	s_addc_u32 s7, s11, 0
	s_mov_b32 m0, s26
	s_nop 0
	global_load_lds_dwordx4 v56, s[6:7]
	s_mov_b32 m0, s27
	s_nop 0
	global_load_lds_dwordx4 v58, s[6:7]
	ds_read_b128 v[20:23], v49
	ds_read_b128 v[104:107], v49 offset:2048
	s_waitcnt lgkmcnt(0)
	v_mfma_f32_16x16x32_bf16 v[20:23], v[20:23], v[12:15], v[24:27]
	s_nop 2
	ds_read_b128 v[24:27], v49 offset:4096
	v_mfma_f32_16x16x32_bf16 v[28:31], v[104:107], v[12:15], v[28:31]
	ds_read_b128 v[104:107], v49 offset:6144
	s_waitcnt lgkmcnt(0)
	v_mfma_f32_16x16x32_bf16 v[24:27], v[24:27], v[12:15], v[32:35]
	s_nop 2
	ds_read_b128 v[32:35], v49 offset:8192
	v_mfma_f32_16x16x32_bf16 v[36:39], v[104:107], v[12:15], v[36:39]
	ds_read_b128 v[104:107], v49 offset:10240
	s_waitcnt lgkmcnt(0)
	v_mfma_f32_16x16x32_bf16 v[32:35], v[32:35], v[12:15], v[40:43]
	s_nop 2
	ds_read_b128 v[40:43], v49 offset:12288
	ds_read_b128 v[108:111], v49 offset:14336
	v_mfma_f32_16x16x32_bf16 v[50:53], v[104:107], v[12:15], v[50:53]
	ds_read_b128 v[104:107], v49 offset:32768
	ds_read_b128 v[112:115], v49 offset:34816
	ds_read_b128 v[116:119], v49 offset:36864
	ds_read_b128 v[120:123], v49 offset:38912
	s_waitcnt lgkmcnt(0)
	v_mfma_f32_16x16x32_bf16 v[40:43], v[40:43], v[12:15], v[76:79]
	s_nop 2
	ds_read_b128 v[76:79], v49 offset:40960
	ds_read_b128 v[124:127], v49 offset:43008
	ds_read_b128 v[128:131], v49 offset:45056
	ds_read_b128 v[132:135], v49 offset:47104
	v_mfma_f32_16x16x32_bf16 v[96:99], v[108:111], v[12:15], v[96:99]
	v_mfma_f32_16x16x32_bf16 v[66:69], v[104:107], v[12:15], v[66:69]
	v_mfma_f32_16x16x32_bf16 v[72:75], v[112:115], v[12:15], v[72:75]
	v_mfma_f32_16x16x32_bf16 v[80:83], v[116:119], v[12:15], v[80:83]
	v_mfma_f32_16x16x32_bf16 v[84:87], v[120:123], v[12:15], v[84:87]
	s_waitcnt lgkmcnt(0)
	v_mfma_f32_16x16x32_bf16 v[76:79], v[76:79], v[12:15], v[88:91]
	v_mfma_f32_16x16x32_bf16 v[88:91], v[124:127], v[12:15], v[92:95]
	s_nop 2
	ds_read_b128 v[92:95], v49 offset:15360
	ds_read_b128 v[104:107], v49 offset:13312
	ds_read_b128 v[108:111], v49 offset:11264
	ds_read_b128 v[112:115], v49 offset:9216
	v_mfma_f32_16x16x32_bf16 v[100:103], v[128:131], v[12:15], v[100:103]
	ds_read_b128 v[116:119], v49 offset:7168
	ds_read_b128 v[120:123], v49 offset:5120
	ds_read_b128 v[124:127], v49 offset:3072
	ds_read_b128 v[128:131], v49 offset:1024
	v_mfma_f32_16x16x32_bf16 v[12:15], v[132:135], v[12:15], v[16:19]
	s_waitcnt lgkmcnt(0)
	v_mfma_f32_16x16x32_bf16 v[16:19], v[128:131], v[8:11], v[20:23]
	v_mfma_f32_16x16x32_bf16 v[20:23], v[124:127], v[8:11], v[28:31]
	v_mfma_f32_16x16x32_bf16 v[24:27], v[120:123], v[8:11], v[24:27]
	v_mfma_f32_16x16x32_bf16 v[28:31], v[116:119], v[8:11], v[36:39]
	v_mfma_f32_16x16x32_bf16 v[32:35], v[112:115], v[8:11], v[32:35]
	v_mfma_f32_16x16x32_bf16 v[36:39], v[108:111], v[8:11], v[50:53]
	s_nop 2
	ds_read_b128 v[50:53], v49 offset:33792
	ds_read_b128 v[108:111], v49 offset:35840
	ds_read_b128 v[112:115], v49 offset:37888
	ds_read_b128 v[116:119], v49 offset:39936
	v_mfma_f32_16x16x32_bf16 v[40:43], v[104:107], v[8:11], v[40:43]
	ds_read_b128 v[104:107], v49 offset:41984
	ds_read_b128 v[120:123], v49 offset:44032
	ds_read_b128 v[124:127], v49 offset:46080
	ds_read_b128 v[128:131], v49 offset:48128
	v_mfma_f32_16x16x32_bf16 v[92:95], v[92:95], v[8:11], v[96:99]
	s_waitcnt lgkmcnt(0)
	v_mfma_f32_16x16x32_bf16 v[50:53], v[50:53], v[8:11], v[66:69]
	v_mfma_f32_16x16x32_bf16 v[66:69], v[108:111], v[8:11], v[72:75]
	v_mfma_f32_16x16x32_bf16 v[72:75], v[112:115], v[8:11], v[80:83]
	v_mfma_f32_16x16x32_bf16 v[80:83], v[116:119], v[8:11], v[84:87]
	v_mfma_f32_16x16x32_bf16 v[76:79], v[104:107], v[8:11], v[76:79]
	v_mfma_f32_16x16x32_bf16 v[84:87], v[120:123], v[8:11], v[88:91]
	s_nop 2
	ds_read_b128 v[88:91], v49 offset:30720
	ds_read_b128 v[96:99], v49 offset:28672
	ds_read_b128 v[104:107], v49 offset:26624
	ds_read_b128 v[108:111], v49 offset:24576
	v_mfma_f32_16x16x32_bf16 v[100:103], v[124:127], v[8:11], v[100:103]
	ds_read_b128 v[112:115], v49 offset:22528
	ds_read_b128 v[116:119], v49 offset:20480
	ds_read_b128 v[120:123], v49 offset:18432
	ds_read_b128 v[124:127], v49 offset:16384
	v_mfma_f32_16x16x32_bf16 v[8:11], v[128:131], v[8:11], v[12:15]
	s_waitcnt lgkmcnt(0)
	v_mfma_f32_16x16x32_bf16 v[12:15], v[124:127], v[4:7], v[16:19]
	v_mfma_f32_16x16x32_bf16 v[16:19], v[120:123], v[4:7], v[20:23]
	v_mfma_f32_16x16x32_bf16 v[20:23], v[116:119], v[4:7], v[24:27]
	v_mfma_f32_16x16x32_bf16 v[24:27], v[112:115], v[4:7], v[28:31]
	v_mfma_f32_16x16x32_bf16 v[28:31], v[108:111], v[4:7], v[32:35]
	v_mfma_f32_16x16x32_bf16 v[32:35], v[104:107], v[4:7], v[36:39]
	s_nop 2
	ds_read_b128 v[36:39], v49 offset:49152
	ds_read_b128 v[104:107], v49 offset:51200
	ds_read_b128 v[108:111], v49 offset:53248
	ds_read_b128 v[112:115], v49 offset:55296
	v_mfma_f32_16x16x32_bf16 v[96:99], v[96:99], v[4:7], v[40:43]
	s_nop 2
	ds_read_b128 v[40:43], v49 offset:57344
	ds_read_b128 v[116:119], v49 offset:59392
	ds_read_b128 v[120:123], v49 offset:61440
	ds_read_b128 v[124:127], v49 offset:63488
	v_mfma_f32_16x16x32_bf16 v[88:91], v[88:91], v[4:7], v[92:95]
	s_waitcnt lgkmcnt(0)
	v_mfma_f32_16x16x32_bf16 v[50:53], v[36:39], v[4:7], v[50:53]
	v_mfma_f32_16x16x32_bf16 v[66:69], v[104:107], v[4:7], v[66:69]
	v_mfma_f32_16x16x32_bf16 v[72:75], v[108:111], v[4:7], v[72:75]
	v_mfma_f32_16x16x32_bf16 v[80:83], v[112:115], v[4:7], v[80:83]
	v_mfma_f32_16x16x32_bf16 v[76:79], v[40:43], v[4:7], v[76:79]
	ds_read_b128 v[92:95], v49 offset:31744
	ds_read_b128 v[36:39], v49 offset:29696
	ds_read_b128 v[40:43], v49 offset:27648
	ds_read_b128 v[104:107], v49 offset:25600
	v_mfma_f32_16x16x32_bf16 v[84:87], v[116:119], v[4:7], v[84:87]
	v_mfma_f32_16x16x32_bf16 v[100:103], v[120:123], v[4:7], v[100:103]
	ds_read_b128 v[108:111], v49 offset:23552
	ds_read_b128 v[112:115], v49 offset:21504
	ds_read_b128 v[116:119], v49 offset:19456
	ds_read_b128 v[120:123], v49 offset:17408
	v_mfma_f32_16x16x32_bf16 v[124:127], v[124:127], v[4:7], v[8:11]
	s_waitcnt lgkmcnt(0)
	v_mfma_f32_16x16x32_bf16 v[120:123], v[120:123], v[0:3], v[12:15]
	v_mfma_f32_16x16x32_bf16 v[116:119], v[116:119], v[0:3], v[16:19]
	ds_read_b128 v[4:7], v49 offset:50176
	ds_read_b128 v[8:11], v49 offset:52224
	ds_read_b128 v[12:15], v49 offset:54272
	ds_read_b128 v[16:19], v49 offset:56320
	v_mfma_f32_16x16x32_bf16 v[36:39], v[36:39], v[0:3], v[96:99]
	s_nop 2
	ds_read_b128 v[96:99], v49 offset:58368
	ds_read_b128 v[128:131], v49 offset:60416
	ds_read_b128 v[132:135], v49 offset:62464
	ds_read_b128 v[136:139], v49 offset:64512
	v_mfma_f32_16x16x32_bf16 v[112:115], v[112:115], v[0:3], v[20:23]
	v_mfma_f32_16x16x32_bf16 v[108:111], v[108:111], v[0:3], v[24:27]
	v_mfma_f32_16x16x32_bf16 v[104:107], v[104:107], v[0:3], v[28:31]
	v_mfma_f32_16x16x32_bf16 v[40:43], v[40:43], v[0:3], v[32:35]
	v_mfma_f32_16x16x32_bf16 v[32:35], v[92:95], v[0:3], v[88:91]
	s_waitcnt lgkmcnt(0)
	v_mfma_f32_16x16x32_bf16 v[28:31], v[4:7], v[0:3], v[50:53]
	v_mfma_f32_16x16x32_bf16 v[24:27], v[8:11], v[0:3], v[66:69]
	v_mfma_f32_16x16x32_bf16 v[20:23], v[12:15], v[0:3], v[72:75]
	v_mfma_f32_16x16x32_bf16 v[16:19], v[16:19], v[0:3], v[80:83]
	v_mfma_f32_16x16x32_bf16 v[12:15], v[96:99], v[0:3], v[76:79]
	v_mfma_f32_16x16x32_bf16 v[8:11], v[128:131], v[0:3], v[84:87]
	v_mfma_f32_16x16x32_bf16 v[4:7], v[132:135], v[0:3], v[100:103]
	v_mfma_f32_16x16x32_bf16 v[0:3], v[136:139], v[0:3], v[124:127]
	v_max_f32_e32 v49, v123, v123
	v_max_f32_e32 v50, v122, v122
	v_max_f32_e32 v49, v50, v49
	v_max_f32_e32 v50, v117, v117
	v_max_f32_e32 v51, v116, v116
	v_max_f32_e32 v50, v51, v50
	v_max_f32_e32 v51, v119, v119
	v_max_f32_e32 v52, v118, v118
	v_max3_f32 v49, v120, v121, v49
	v_max_f32_e32 v51, v52, v51
	v_max3_f32 v49, v49, v50, v51
	v_max_f32_e32 v50, v113, v113
	v_max_f32_e32 v51, v112, v112
	v_max_f32_e32 v50, v51, v50
	v_max_f32_e32 v51, v115, v115
	v_max_f32_e32 v52, v114, v114
	v_max_f32_e32 v51, v52, v51
	v_max3_f32 v49, v49, v50, v51
	v_max_f32_e32 v50, v109, v109
	v_max_f32_e32 v51, v108, v108
	v_max_f32_e32 v50, v51, v50
	v_max_f32_e32 v51, v111, v111
	v_max_f32_e32 v52, v110, v110
	v_max_f32_e32 v51, v52, v51
	v_max3_f32 v49, v49, v50, v51
	v_max_f32_e32 v50, v105, v105
	v_max_f32_e32 v51, v104, v104
	v_max_f32_e32 v50, v51, v50
	v_max_f32_e32 v51, v107, v107
	v_max_f32_e32 v52, v106, v106
	v_max_f32_e32 v51, v52, v51
	v_max3_f32 v49, v49, v50, v51
	v_max_f32_e32 v50, v41, v41
	v_max_f32_e32 v51, v40, v40
	v_max_f32_e32 v50, v51, v50
	v_max_f32_e32 v51, v43, v43
	v_max_f32_e32 v52, v42, v42
	v_max_f32_e32 v51, v52, v51
	v_max3_f32 v49, v49, v50, v51
	v_max_f32_e32 v50, v37, v37
	v_max_f32_e32 v51, v36, v36
	v_max_f32_e32 v50, v51, v50
	v_max_f32_e32 v51, v39, v39
	v_max_f32_e32 v52, v38, v38
	v_max_f32_e32 v51, v52, v51
	v_max3_f32 v49, v49, v50, v51
	v_max_f32_e32 v50, v33, v33
	v_max_f32_e32 v51, v32, v32
	v_max_f32_e32 v50, v51, v50
	v_max_f32_e32 v51, v35, v35
	v_max_f32_e32 v52, v34, v34
	v_max_f32_e32 v51, v52, v51
	v_max3_f32 v49, v49, v50, v51
	v_max_f32_e32 v50, v29, v29
	v_max_f32_e32 v51, v28, v28
	v_max_f32_e32 v50, v51, v50
	v_max_f32_e32 v51, v31, v31
	v_max_f32_e32 v52, v30, v30
	v_max_f32_e32 v51, v52, v51
	v_max3_f32 v49, v49, v50, v51
	v_max_f32_e32 v50, v25, v25
	v_max_f32_e32 v51, v24, v24
	v_max_f32_e32 v50, v51, v50
	v_max_f32_e32 v51, v27, v27
	v_max_f32_e32 v52, v26, v26
	v_max_f32_e32 v51, v52, v51
	v_max3_f32 v49, v49, v50, v51
	v_max_f32_e32 v50, v21, v21
	v_max_f32_e32 v51, v20, v20
	v_max_f32_e32 v50, v51, v50
	v_max_f32_e32 v51, v23, v23
	v_max_f32_e32 v52, v22, v22
	v_max_f32_e32 v51, v52, v51
	v_max3_f32 v49, v49, v50, v51
	v_max_f32_e32 v50, v17, v17
	v_max_f32_e32 v51, v16, v16
	v_max_f32_e32 v50, v51, v50
	v_max_f32_e32 v51, v19, v19
	v_max_f32_e32 v52, v18, v18
	v_max_f32_e32 v51, v52, v51
	v_max3_f32 v49, v49, v50, v51
	v_max_f32_e32 v50, v13, v13
	v_max_f32_e32 v51, v12, v12
	v_max_f32_e32 v50, v51, v50
	v_max_f32_e32 v51, v15, v15
	v_max_f32_e32 v52, v14, v14
	v_max_f32_e32 v51, v52, v51
	v_max3_f32 v49, v49, v50, v51
	v_max_f32_e32 v50, v9, v9
	v_max_f32_e32 v51, v8, v8
	v_max_f32_e32 v50, v51, v50
	v_max_f32_e32 v51, v11, v11
	v_max_f32_e32 v52, v10, v10
	v_max_f32_e32 v51, v52, v51
	v_max3_f32 v49, v49, v50, v51
	v_max_f32_e32 v50, v5, v5
	v_max_f32_e32 v51, v4, v4
	v_max_f32_e32 v50, v51, v50
	v_max_f32_e32 v51, v7, v7
	v_max_f32_e32 v52, v6, v6
	v_max_f32_e32 v51, v52, v51
	v_max3_f32 v49, v49, v50, v51
	v_max_f32_e32 v50, v1, v1
	v_max_f32_e32 v51, v0, v0
	v_max_f32_e32 v50, v51, v50
	v_max_f32_e32 v51, v3, v3
	v_max_f32_e32 v52, v2, v2
	v_max_f32_e32 v51, v52, v51
	v_max3_f32 v49, v49, v50, v51
	v_mbcnt_lo_u32_b32 v50, -1, 0
	v_mbcnt_hi_u32_b32 v50, -1, v50
	v_and_b32_e32 v52, 64, v50
	v_xor_b32_e32 v51, 16, v50
	v_add_u32_e32 v52, 64, v52
	v_cmp_lt_i32_e32 vcc, v51, v52
	s_nop 1
	v_cndmask_b32_e32 v51, v50, v51, vcc
	v_lshlrev_b32_e32 v51, 2, v51
	ds_bpermute_b32 v53, v51, v49
	s_waitcnt lgkmcnt(0)
	v_max_f32_e32 v53, v53, v53
	v_max_f32_e32 v49, v49, v53
	v_xor_b32_e32 v53, 32, v50
	v_cmp_lt_i32_e32 vcc, v53, v52
	s_nop 1
	v_cndmask_b32_e32 v50, v50, v53, vcc
	v_lshlrev_b32_e32 v50, 2, v50
	ds_bpermute_b32 v52, v50, v49
	s_waitcnt lgkmcnt(0)
	v_max_f32_e32 v52, v52, v52
	v_max_f32_e32 v49, v49, v52
	v_sub_f32_e32 v52, v120, v49
	v_exp_f32_e32 v52, v52
	v_sub_f32_e32 v53, v121, v49
	v_exp_f32_e32 v53, v53
	v_sub_f32_e32 v54, v122, v49
	v_exp_f32_e32 v54, v54
	v_sub_f32_e32 v55, v123, v49
	v_exp_f32_e32 v55, v55
	v_sub_f32_e32 v59, v116, v49
	v_add_f32_e32 v57, 0, v52
	v_exp_f32_e32 v59, v59
	v_sub_f32_e32 v62, v117, v49
	v_add_f32_e32 v57, v53, v57
	v_exp_f32_e32 v62, v62
	v_sub_f32_e32 v63, v118, v49
	v_add_f32_e32 v57, v54, v57
	v_exp_f32_e32 v63, v63
	v_sub_f32_e32 v64, v119, v49
	v_add_f32_e32 v57, v55, v57
	v_exp_f32_e32 v64, v64
	v_sub_f32_e32 v66, v112, v49
	v_add_f32_e32 v57, v59, v57
	v_exp_f32_e32 v66, v66
	v_sub_f32_e32 v67, v113, v49
	v_add_f32_e32 v57, v62, v57
	v_exp_f32_e32 v67, v67
	v_sub_f32_e32 v68, v114, v49
	v_add_f32_e32 v57, v63, v57
	v_exp_f32_e32 v68, v68
	v_sub_f32_e32 v69, v115, v49
	v_add_f32_e32 v57, v64, v57
	v_exp_f32_e32 v69, v69
	v_sub_f32_e32 v71, v108, v49
	v_add_f32_e32 v57, v66, v57
	v_exp_f32_e32 v71, v71
	v_sub_f32_e32 v72, v109, v49
	v_add_f32_e32 v57, v67, v57
	v_exp_f32_e32 v72, v72
	v_sub_f32_e32 v73, v110, v49
	v_add_f32_e32 v57, v68, v57
	v_exp_f32_e32 v73, v73
	v_sub_f32_e32 v74, v111, v49
	v_add_f32_e32 v57, v69, v57
	v_exp_f32_e32 v74, v74
	v_sub_f32_e32 v75, v104, v49
	v_add_f32_e32 v57, v71, v57
	v_exp_f32_e32 v75, v75
	v_sub_f32_e32 v76, v105, v49
	v_add_f32_e32 v57, v72, v57
	v_exp_f32_e32 v76, v76
	v_sub_f32_e32 v77, v106, v49
	v_add_f32_e32 v57, v73, v57
	v_exp_f32_e32 v77, v77
	v_sub_f32_e32 v78, v107, v49
	v_add_f32_e32 v57, v74, v57
	v_exp_f32_e32 v78, v78
	v_sub_f32_e32 v40, v40, v49
	v_add_f32_e32 v57, v75, v57
	v_exp_f32_e32 v40, v40
	v_sub_f32_e32 v41, v41, v49
	v_add_f32_e32 v57, v76, v57
	v_exp_f32_e32 v41, v41
	v_sub_f32_e32 v42, v42, v49
	v_add_f32_e32 v57, v77, v57
	v_exp_f32_e32 v42, v42
	v_sub_f32_e32 v43, v43, v49
	v_add_f32_e32 v57, v78, v57
	v_exp_f32_e32 v43, v43
	v_sub_f32_e32 v36, v36, v49
	v_add_f32_e32 v57, v40, v57
	v_exp_f32_e32 v36, v36
	v_sub_f32_e32 v37, v37, v49
	v_add_f32_e32 v57, v41, v57
	v_exp_f32_e32 v37, v37
	v_sub_f32_e32 v38, v38, v49
	v_add_f32_e32 v57, v42, v57
	v_exp_f32_e32 v38, v38
	v_sub_f32_e32 v39, v39, v49
	v_add_f32_e32 v57, v43, v57
	v_exp_f32_e32 v39, v39
	v_sub_f32_e32 v32, v32, v49
	v_add_f32_e32 v57, v36, v57
	v_exp_f32_e32 v32, v32
	v_sub_f32_e32 v33, v33, v49
	v_add_f32_e32 v57, v37, v57
	v_exp_f32_e32 v33, v33
	v_sub_f32_e32 v34, v34, v49
	v_add_f32_e32 v57, v38, v57
	v_exp_f32_e32 v34, v34
	v_sub_f32_e32 v35, v35, v49
	v_add_f32_e32 v57, v39, v57
	v_exp_f32_e32 v35, v35
	v_sub_f32_e32 v28, v28, v49
	v_add_f32_e32 v57, v32, v57
	v_exp_f32_e32 v79, v28
	v_sub_f32_e32 v28, v29, v49
	v_add_f32_e32 v57, v33, v57
	v_exp_f32_e32 v80, v28
	v_sub_f32_e32 v28, v30, v49
	v_add_f32_e32 v57, v34, v57
	v_exp_f32_e32 v81, v28
	v_sub_f32_e32 v28, v31, v49
	v_add_f32_e32 v57, v35, v57
	v_exp_f32_e32 v82, v28
	v_sub_f32_e32 v24, v24, v49
	v_add_f32_e32 v28, v79, v57
	v_exp_f32_e32 v57, v24
	v_sub_f32_e32 v24, v25, v49
	v_add_f32_e32 v28, v80, v28
	v_exp_f32_e32 v83, v24
	v_sub_f32_e32 v24, v26, v49
	v_add_f32_e32 v28, v81, v28
	v_exp_f32_e32 v84, v24
	v_sub_f32_e32 v24, v27, v49
	v_add_f32_e32 v28, v82, v28
	v_exp_f32_e32 v85, v24
	v_sub_f32_e32 v20, v20, v49
	v_add_f32_e32 v24, v57, v28
	v_exp_f32_e32 v86, v20
	v_sub_f32_e32 v20, v21, v49
	v_add_f32_e32 v24, v83, v24
	v_exp_f32_e32 v87, v20
	v_sub_f32_e32 v20, v22, v49
	v_add_f32_e32 v24, v84, v24
	v_exp_f32_e32 v88, v20
	v_sub_f32_e32 v20, v23, v49
	v_add_f32_e32 v24, v85, v24
	v_exp_f32_e32 v89, v20
	v_sub_f32_e32 v16, v16, v49
	v_add_f32_e32 v20, v86, v24
	v_exp_f32_e32 v90, v16
	v_sub_f32_e32 v16, v17, v49
	v_add_f32_e32 v20, v87, v20
	v_exp_f32_e32 v91, v16
	v_sub_f32_e32 v16, v18, v49
	v_add_f32_e32 v20, v88, v20
	v_exp_f32_e32 v92, v16
	v_sub_f32_e32 v16, v19, v49
	v_add_f32_e32 v20, v89, v20
	v_exp_f32_e32 v93, v16
	v_sub_f32_e32 v12, v12, v49
	v_add_f32_e32 v16, v90, v20
	v_exp_f32_e32 v94, v12
	v_sub_f32_e32 v12, v13, v49
	v_add_f32_e32 v16, v91, v16
	v_exp_f32_e32 v95, v12
	v_sub_f32_e32 v12, v14, v49
	v_add_f32_e32 v16, v92, v16
	v_exp_f32_e32 v96, v12
	v_sub_f32_e32 v12, v15, v49
	v_add_f32_e32 v16, v93, v16
	v_exp_f32_e32 v97, v12
	v_sub_f32_e32 v8, v8, v49
	v_add_f32_e32 v12, v94, v16
	v_exp_f32_e32 v98, v8
	v_sub_f32_e32 v8, v9, v49
	v_add_f32_e32 v12, v95, v12
	v_exp_f32_e32 v99, v8
	v_sub_f32_e32 v8, v10, v49
	v_add_f32_e32 v12, v96, v12
	v_exp_f32_e32 v100, v8
	v_sub_f32_e32 v8, v11, v49
	v_add_f32_e32 v12, v97, v12
	v_exp_f32_e32 v11, v8
	v_sub_f32_e32 v4, v4, v49
	v_add_f32_e32 v8, v98, v12
	v_exp_f32_e32 v101, v4
	v_sub_f32_e32 v4, v5, v49
	v_add_f32_e32 v8, v99, v8
	v_exp_f32_e32 v102, v4
	v_sub_f32_e32 v4, v6, v49
	v_add_f32_e32 v8, v100, v8
	v_exp_f32_e32 v103, v4
	v_sub_f32_e32 v4, v7, v49
	v_add_f32_e32 v8, v11, v8
	v_exp_f32_e32 v104, v4
	v_sub_f32_e32 v0, v0, v49
	v_add_f32_e32 v4, v101, v8
	v_exp_f32_e32 v105, v0
	v_sub_f32_e32 v0, v1, v49
	v_add_f32_e32 v4, v102, v4
	v_exp_f32_e32 v106, v0
	v_sub_f32_e32 v0, v2, v49
	v_add_f32_e32 v4, v103, v4
	v_exp_f32_e32 v107, v0
	v_sub_f32_e32 v0, v3, v49
	v_add_f32_e32 v4, v104, v4
	v_exp_f32_e32 v3, v0
	v_add_f32_e32 v0, v105, v4
	v_add_f32_e32 v0, v106, v0
	v_add_f32_e32 v0, v107, v0
	v_add_f32_e32 v0, v3, v0
	ds_bpermute_b32 v1, v51, v0
	v_cvt_pk_bf16_f32 v28, v52, v53
	v_cvt_pk_bf16_f32 v29, v54, v55
	v_cvt_pk_bf16_f32 v30, v59, v62
	v_cvt_pk_bf16_f32 v31, v63, v64
	s_waitcnt lgkmcnt(0)
	v_add_f32_e32 v0, v0, v1
	ds_bpermute_b32 v1, v50, v0
	v_cvt_pk_bf16_f32 v20, v66, v67
	v_cvt_pk_bf16_f32 v21, v68, v69
	v_cvt_pk_bf16_f32 v22, v71, v72
	v_cvt_pk_bf16_f32 v23, v73, v74
	s_waitcnt lgkmcnt(0)
	v_add_f32_e32 v49, v0, v1
	v_cvt_pk_bf16_f32 v24, v75, v76
	v_cvt_pk_bf16_f32 v25, v77, v78
	v_cvt_pk_bf16_f32 v26, v40, v41
	v_cvt_pk_bf16_f32 v27, v42, v43
	v_cvt_pk_bf16_f32 v16, v36, v37
	v_cvt_pk_bf16_f32 v17, v38, v39
	v_cvt_pk_bf16_f32 v18, v32, v33
	v_cvt_pk_bf16_f32 v19, v34, v35
	v_cvt_pk_bf16_f32 v12, v79, v80
	v_cvt_pk_bf16_f32 v13, v81, v82
	v_cvt_pk_bf16_f32 v14, v57, v83
	v_cvt_pk_bf16_f32 v15, v84, v85
	v_cvt_pk_bf16_f32 v4, v86, v87
	v_cvt_pk_bf16_f32 v5, v88, v89
	v_cvt_pk_bf16_f32 v6, v90, v91
	v_cvt_pk_bf16_f32 v7, v92, v93
	v_cvt_pk_bf16_f32 v8, v94, v95
	v_cvt_pk_bf16_f32 v9, v96, v97
	v_cvt_pk_bf16_f32 v10, v98, v99
	v_cvt_pk_bf16_f32 v11, v100, v11
	v_cvt_pk_bf16_f32 v0, v101, v102
	v_cvt_pk_bf16_f32 v1, v103, v104
	v_cvt_pk_bf16_f32 v2, v105, v106
	v_cvt_pk_bf16_f32 v3, v107, v3
	s_mov_b32 m0, s19
	v_lshl_add_u64 v[32:33], v[44:45], 0, s[0:1]
	s_waitcnt vmcnt(0)
	s_waitcnt vmcnt(0)
	s_barrier
	global_load_lds_dwordx4 v[32:33], off
	v_lshl_add_u64 v[32:33], v[46:47], 0, s[0:1]
	s_mov_b32 m0, s13
	s_add_u32 s0, s10, 0x11c10100
	global_load_lds_dwordx4 v[32:33], off
	v_lshl_add_u64 v[32:33], v[44:45], 0, s[4:5]
	s_mov_b32 m0, s12
	s_addc_u32 s1, s11, 0
	global_load_lds_dwordx4 v[32:33], off
	v_lshl_add_u64 v[32:33], v[46:47], 0, s[4:5]
	s_mov_b32 m0, s14
	v_mov_b32_e32 v64, v65
	global_load_lds_dwordx4 v[32:33], off
	s_mov_b32 m0, s15
	v_div_scale_f32 v62, vcc, 1.0, v49, 1.0
	global_load_lds_dwordx4 v56, s[0:1]
	s_mov_b32 m0, s16
	v_lshlrev_b32_e32 v54, 2, v70
	global_load_lds_dwordx4 v58, s[0:1]
	s_add_u32 s0, s10, 0x11c10180
	s_addc_u32 s1, s11, 0
	s_mov_b32 m0, s17
	v_ashrrev_i32_e32 v55, 31, v54
	global_load_lds_dwordx4 v56, s[0:1]
	s_mov_b32 m0, s18
	s_nop 0
	global_load_lds_dwordx4 v58, s[0:1]
	ds_read_b128 v[32:35], v64
	ds_read_b128 v[36:39], v64 offset:2048
	v_div_scale_f32 v57, s[0:1], v49, v49, 1.0
	v_rcp_f32_e32 v59, v57
	s_waitcnt lgkmcnt(0)
	v_mfma_f32_16x16x32_bf16 v[44:47], v[32:35], v[28:31], 0
	v_fma_f32 v40, -v57, v59, 1.0
	v_fmac_f32_e32 v59, v40, v59
	ds_read_b128 v[40:43], v64 offset:4096
	ds_read_b128 v[32:35], v64 offset:6144
	v_mul_f32_e32 v63, v62, v59
	v_fma_f32 v66, -v57, v63, v62
	v_fmac_f32_e32 v63, v66, v59
	v_mfma_f32_16x16x32_bf16 v[50:53], v[36:39], v[28:31], 0
	v_fma_f32 v36, -v57, v63, v62
	ds_read_b128 v[66:69], v64 offset:8192
	ds_read_b128 v[70:73], v64 offset:10240
	v_div_fmas_f32 v36, v36, v59, v63
	s_waitcnt lgkmcnt(0)
	v_mfma_f32_16x16x32_bf16 v[74:77], v[32:35], v[28:31], 0
	v_lshl_add_u64 v[34:35], v[54:55], 1, v[60:61]
	ds_read_b128 v[60:63], v64 offset:12288
	ds_read_b128 v[78:81], v64 offset:14336
	ds_read_b128 v[82:85], v64 offset:32768
	ds_read_b128 v[86:89], v64 offset:34816
	ds_read_b128 v[90:93], v64 offset:36864
	ds_read_b128 v[94:97], v64 offset:38912
	ds_read_b128 v[98:101], v64 offset:40960
	ds_read_b128 v[102:105], v64 offset:43008
	ds_read_b128 v[106:109], v64 offset:45056
	ds_read_b128 v[110:113], v64 offset:47104
	s_mov_b64 s[0:1], 0x1000000
	v_mfma_f32_16x16x32_bf16 v[38:41], v[40:43], v[28:31], 0
	v_div_fixup_f32 v36, v36, v49, 1.0
	v_lshl_add_u64 v[32:33], v[34:35], 0, s[0:1]
	v_mfma_f32_16x16x32_bf16 v[66:69], v[66:69], v[28:31], 0
	v_mfma_f32_16x16x32_bf16 v[70:73], v[70:73], v[28:31], 0
	s_waitcnt lgkmcnt(0)
	v_mfma_f32_16x16x32_bf16 v[60:63], v[60:63], v[28:31], 0
	v_mfma_f32_16x16x32_bf16 v[78:81], v[78:81], v[28:31], 0
	ds_read_b128 v[114:117], v64 offset:30720
	ds_read_b128 v[118:121], v64 offset:28672
	ds_read_b128 v[122:125], v64 offset:26624
	ds_read_b128 v[126:129], v64 offset:24576
	ds_read_b128 v[130:133], v64 offset:22528
	ds_read_b128 v[134:137], v64 offset:20480
	ds_read_b128 v[138:141], v64 offset:18432
	ds_read_b128 v[142:145], v64 offset:16384
	v_mfma_f32_16x16x32_bf16 v[82:85], v[82:85], v[28:31], 0
	v_mfma_f32_16x16x32_bf16 v[86:89], v[86:89], v[28:31], 0
	v_mfma_f32_16x16x32_bf16 v[90:93], v[90:93], v[28:31], 0
	v_mfma_f32_16x16x32_bf16 v[94:97], v[94:97], v[28:31], 0
	v_mfma_f32_16x16x32_bf16 v[98:101], v[98:101], v[28:31], 0
	v_mfma_f32_16x16x32_bf16 v[102:105], v[102:105], v[28:31], 0
	v_mfma_f32_16x16x32_bf16 v[106:109], v[106:109], v[28:31], 0
	v_mfma_f32_16x16x32_bf16 v[110:113], v[110:113], v[28:31], 0
	s_waitcnt lgkmcnt(0)
	v_mfma_f32_16x16x32_bf16 v[42:45], v[142:145], v[24:27], v[44:47]
	v_mfma_f32_16x16x32_bf16 v[50:53], v[138:141], v[24:27], v[50:53]
	v_mfma_f32_16x16x32_bf16 v[38:41], v[134:137], v[24:27], v[38:41]
	v_mfma_f32_16x16x32_bf16 v[74:77], v[130:133], v[24:27], v[74:77]
	v_mfma_f32_16x16x32_bf16 v[66:69], v[126:129], v[24:27], v[66:69]
	v_mfma_f32_16x16x32_bf16 v[70:73], v[122:125], v[24:27], v[70:73]
	ds_read_b128 v[122:125], v64 offset:49152
	ds_read_b128 v[126:129], v64 offset:51200
	ds_read_b128 v[130:133], v64 offset:53248
	ds_read_b128 v[134:137], v64 offset:55296
	v_mfma_f32_16x16x32_bf16 v[60:63], v[118:121], v[24:27], v[60:63]
	ds_read_b128 v[118:121], v64 offset:57344
	ds_read_b128 v[138:141], v64 offset:59392
	ds_read_b128 v[142:145], v64 offset:61440
	ds_read_b128 v[146:149], v64 offset:63488
	v_mfma_f32_16x16x32_bf16 v[78:81], v[114:117], v[24:27], v[78:81]
	s_waitcnt lgkmcnt(0)
	v_mfma_f32_16x16x32_bf16 v[82:85], v[122:125], v[24:27], v[82:85]
	v_mfma_f32_16x16x32_bf16 v[86:89], v[126:129], v[24:27], v[86:89]
	v_mfma_f32_16x16x32_bf16 v[90:93], v[130:133], v[24:27], v[90:93]
	v_mfma_f32_16x16x32_bf16 v[94:97], v[134:137], v[24:27], v[94:97]
	v_mfma_f32_16x16x32_bf16 v[98:101], v[118:121], v[24:27], v[98:101]
	ds_read_b128 v[114:117], v64 offset:15360
	ds_read_b128 v[118:121], v64 offset:13312
	ds_read_b128 v[122:125], v64 offset:11264
	ds_read_b128 v[126:129], v64 offset:9216
	v_mfma_f32_16x16x32_bf16 v[102:105], v[138:141], v[24:27], v[102:105]
	v_mfma_f32_16x16x32_bf16 v[106:109], v[142:145], v[24:27], v[106:109]
	ds_read_b128 v[130:133], v64 offset:7168
	ds_read_b128 v[134:137], v64 offset:5120
	ds_read_b128 v[138:141], v64 offset:3072
	ds_read_b128 v[142:145], v64 offset:1024
	v_mfma_f32_16x16x32_bf16 v[110:113], v[146:149], v[24:27], v[110:113]
	s_waitcnt lgkmcnt(0)
	v_mfma_f32_16x16x32_bf16 v[42:45], v[142:145], v[20:23], v[42:45]
	v_mfma_f32_16x16x32_bf16 v[50:53], v[138:141], v[20:23], v[50:53]
	v_mfma_f32_16x16x32_bf16 v[38:41], v[134:137], v[20:23], v[38:41]
	v_mfma_f32_16x16x32_bf16 v[74:77], v[130:133], v[20:23], v[74:77]
	v_mfma_f32_16x16x32_bf16 v[66:69], v[126:129], v[20:23], v[66:69]
	v_mfma_f32_16x16x32_bf16 v[70:73], v[122:125], v[20:23], v[70:73]
	ds_read_b128 v[122:125], v64 offset:33792
	ds_read_b128 v[126:129], v64 offset:35840
	ds_read_b128 v[130:133], v64 offset:37888
	ds_read_b128 v[134:137], v64 offset:39936
	v_mfma_f32_16x16x32_bf16 v[60:63], v[118:121], v[20:23], v[60:63]
	ds_read_b128 v[118:121], v64 offset:41984
	ds_read_b128 v[138:141], v64 offset:44032
	ds_read_b128 v[142:145], v64 offset:46080
	ds_read_b128 v[146:149], v64 offset:48128
	v_mfma_f32_16x16x32_bf16 v[78:81], v[114:117], v[20:23], v[78:81]
	s_waitcnt lgkmcnt(0)
	v_mfma_f32_16x16x32_bf16 v[82:85], v[122:125], v[20:23], v[82:85]
	v_mfma_f32_16x16x32_bf16 v[86:89], v[126:129], v[20:23], v[86:89]
	v_mfma_f32_16x16x32_bf16 v[90:93], v[130:133], v[20:23], v[90:93]
	v_mfma_f32_16x16x32_bf16 v[94:97], v[134:137], v[20:23], v[94:97]
	v_mfma_f32_16x16x32_bf16 v[98:101], v[118:121], v[20:23], v[98:101]
	ds_read_b128 v[114:117], v64 offset:31744
	ds_read_b128 v[118:121], v64 offset:29696
	ds_read_b128 v[122:125], v64 offset:27648
	ds_read_b128 v[126:129], v64 offset:25600
	v_mfma_f32_16x16x32_bf16 v[102:105], v[138:141], v[20:23], v[102:105]
	v_mfma_f32_16x16x32_bf16 v[106:109], v[142:145], v[20:23], v[106:109]
	ds_read_b128 v[130:133], v64 offset:23552
	ds_read_b128 v[134:137], v64 offset:21504
	ds_read_b128 v[138:141], v64 offset:19456
	ds_read_b128 v[142:145], v64 offset:17408
	v_mfma_f32_16x16x32_bf16 v[110:113], v[146:149], v[20:23], v[110:113]
	s_waitcnt lgkmcnt(0)
	v_mfma_f32_16x16x32_bf16 v[42:45], v[142:145], v[16:19], v[42:45]
	v_mfma_f32_16x16x32_bf16 v[50:53], v[138:141], v[16:19], v[50:53]
	v_mfma_f32_16x16x32_bf16 v[38:41], v[134:137], v[16:19], v[38:41]
	v_mfma_f32_16x16x32_bf16 v[74:77], v[130:133], v[16:19], v[74:77]
	v_mfma_f32_16x16x32_bf16 v[66:69], v[126:129], v[16:19], v[66:69]
	v_mfma_f32_16x16x32_bf16 v[70:73], v[122:125], v[16:19], v[70:73]
	ds_read_b128 v[122:125], v64 offset:50176
	ds_read_b128 v[126:129], v64 offset:52224
	ds_read_b128 v[130:133], v64 offset:54272
	ds_read_b128 v[134:137], v64 offset:56320
	v_mfma_f32_16x16x32_bf16 v[60:63], v[118:121], v[16:19], v[60:63]
	ds_read_b128 v[118:121], v64 offset:58368
	ds_read_b128 v[138:141], v64 offset:60416
	ds_read_b128 v[142:145], v64 offset:62464
	ds_read_b128 v[146:149], v64 offset:64512
	v_mfma_f32_16x16x32_bf16 v[78:81], v[114:117], v[16:19], v[78:81]
	s_waitcnt lgkmcnt(0)
	v_mfma_f32_16x16x32_bf16 v[82:85], v[122:125], v[16:19], v[82:85]
	v_mfma_f32_16x16x32_bf16 v[86:89], v[126:129], v[16:19], v[86:89]
	v_mfma_f32_16x16x32_bf16 v[90:93], v[130:133], v[16:19], v[90:93]
	v_mfma_f32_16x16x32_bf16 v[94:97], v[134:137], v[16:19], v[94:97]
	v_mfma_f32_16x16x32_bf16 v[98:101], v[118:121], v[16:19], v[98:101]
	v_mfma_f32_16x16x32_bf16 v[102:105], v[138:141], v[16:19], v[102:105]
	v_mfma_f32_16x16x32_bf16 v[106:109], v[142:145], v[16:19], v[106:109]
	v_mfma_f32_16x16x32_bf16 v[110:113], v[146:149], v[16:19], v[110:113]
	s_add_u32 s0, s10, 0x11c20000
	s_mov_b32 m0, s22
	s_addc_u32 s1, s11, 0
	s_waitcnt vmcnt(0)
	s_waitcnt vmcnt(0)
	s_barrier
	global_load_lds_dwordx4 v56, s[0:1]
	s_mov_b32 m0, s21
	v_mov_b32_e32 v37, v48
	global_load_lds_dwordx4 v58, s[0:1]
	s_add_u32 s0, s10, 0x11c20080
	s_addc_u32 s1, s11, 0
	s_mov_b32 m0, s20
	s_nop 0
	global_load_lds_dwordx4 v56, s[0:1]
	s_mov_b32 m0, s23
	s_nop 0
	global_load_lds_dwordx4 v58, s[0:1]
	s_add_u32 s0, s10, 0x11c30000
	s_addc_u32 s1, s11, 0
	s_mov_b32 m0, s24
	s_nop 0
	global_load_lds_dwordx4 v56, s[0:1]
	s_mov_b32 m0, s25
	s_nop 0
	global_load_lds_dwordx4 v58, s[0:1]
	s_add_u32 s0, s10, 0x11c30080
	s_addc_u32 s1, s11, 0
	s_mov_b32 m0, s26
	s_nop 0
	global_load_lds_dwordx4 v56, s[0:1]
	s_mov_b32 m0, s27
	s_nop 0
	global_load_lds_dwordx4 v58, s[0:1]
	ds_read_b128 v[114:117], v37
	ds_read_b128 v[118:121], v37 offset:2048
	s_waitcnt lgkmcnt(0)
	v_mfma_f32_16x16x32_bf16 v[42:45], v[114:117], v[12:15], v[42:45]
	ds_read_b128 v[114:117], v37 offset:4096
	v_mfma_f32_16x16x32_bf16 v[50:53], v[118:121], v[12:15], v[50:53]
	ds_read_b128 v[118:121], v37 offset:6144
	s_waitcnt lgkmcnt(0)
	v_mfma_f32_16x16x32_bf16 v[38:41], v[114:117], v[12:15], v[38:41]
	ds_read_b128 v[114:117], v37 offset:8192
	v_mfma_f32_16x16x32_bf16 v[74:77], v[118:121], v[12:15], v[74:77]
	ds_read_b128 v[118:121], v37 offset:10240
	s_waitcnt lgkmcnt(0)
	v_mfma_f32_16x16x32_bf16 v[66:69], v[114:117], v[12:15], v[66:69]
	ds_read_b128 v[114:117], v37 offset:12288
	ds_read_b128 v[122:125], v37 offset:14336
	v_mfma_f32_16x16x32_bf16 v[70:73], v[118:121], v[12:15], v[70:73]
	ds_read_b128 v[118:121], v37 offset:32768
	ds_read_b128 v[126:129], v37 offset:34816
	ds_read_b128 v[130:133], v37 offset:36864
	ds_read_b128 v[134:137], v37 offset:38912
	s_waitcnt lgkmcnt(0)
	v_mfma_f32_16x16x32_bf16 v[60:63], v[114:117], v[12:15], v[60:63]
	ds_read_b128 v[114:117], v37 offset:40960
	ds_read_b128 v[138:141], v37 offset:43008
	ds_read_b128 v[142:145], v37 offset:45056
	ds_read_b128 v[146:149], v37 offset:47104
	v_mfma_f32_16x16x32_bf16 v[78:81], v[122:125], v[12:15], v[78:81]
	v_mfma_f32_16x16x32_bf16 v[82:85], v[118:121], v[12:15], v[82:85]
	v_mfma_f32_16x16x32_bf16 v[86:89], v[126:129], v[12:15], v[86:89]
	v_mfma_f32_16x16x32_bf16 v[90:93], v[130:133], v[12:15], v[90:93]
	v_mfma_f32_16x16x32_bf16 v[94:97], v[134:137], v[12:15], v[94:97]
	s_waitcnt lgkmcnt(0)
	v_mfma_f32_16x16x32_bf16 v[98:101], v[114:117], v[12:15], v[98:101]
	ds_read_b128 v[114:117], v37 offset:30720
	ds_read_b128 v[118:121], v37 offset:28672
	ds_read_b128 v[122:125], v37 offset:26624
	ds_read_b128 v[126:129], v37 offset:24576
	v_mfma_f32_16x16x32_bf16 v[102:105], v[138:141], v[12:15], v[102:105]
	v_mfma_f32_16x16x32_bf16 v[106:109], v[142:145], v[12:15], v[106:109]
	ds_read_b128 v[130:133], v37 offset:22528
	ds_read_b128 v[134:137], v37 offset:20480
	ds_read_b128 v[138:141], v37 offset:18432
	ds_read_b128 v[142:145], v37 offset:16384
	v_mfma_f32_16x16x32_bf16 v[110:113], v[146:149], v[12:15], v[110:113]
	s_waitcnt lgkmcnt(0)
	v_mfma_f32_16x16x32_bf16 v[42:45], v[142:145], v[8:11], v[42:45]
	v_mfma_f32_16x16x32_bf16 v[50:53], v[138:141], v[8:11], v[50:53]
	v_mfma_f32_16x16x32_bf16 v[38:41], v[134:137], v[8:11], v[38:41]
	v_mfma_f32_16x16x32_bf16 v[74:77], v[130:133], v[8:11], v[74:77]
	v_mfma_f32_16x16x32_bf16 v[66:69], v[126:129], v[8:11], v[66:69]
	v_mfma_f32_16x16x32_bf16 v[70:73], v[122:125], v[8:11], v[70:73]
	ds_read_b128 v[122:125], v37 offset:49152
	ds_read_b128 v[126:129], v37 offset:51200
	ds_read_b128 v[130:133], v37 offset:53248
	ds_read_b128 v[134:137], v37 offset:55296
	v_mfma_f32_16x16x32_bf16 v[60:63], v[118:121], v[8:11], v[60:63]
	ds_read_b128 v[118:121], v37 offset:57344
	ds_read_b128 v[138:141], v37 offset:59392
	ds_read_b128 v[142:145], v37 offset:61440
	ds_read_b128 v[146:149], v37 offset:63488
	v_mfma_f32_16x16x32_bf16 v[78:81], v[114:117], v[8:11], v[78:81]
	s_waitcnt lgkmcnt(0)
	v_mfma_f32_16x16x32_bf16 v[82:85], v[122:125], v[8:11], v[82:85]
	v_mfma_f32_16x16x32_bf16 v[86:89], v[126:129], v[8:11], v[86:89]
	v_mfma_f32_16x16x32_bf16 v[90:93], v[130:133], v[8:11], v[90:93]
	v_mfma_f32_16x16x32_bf16 v[94:97], v[134:137], v[8:11], v[94:97]
	v_mfma_f32_16x16x32_bf16 v[98:101], v[118:121], v[8:11], v[98:101]
	ds_read_b128 v[114:117], v37 offset:15360
	ds_read_b128 v[118:121], v37 offset:13312
	ds_read_b128 v[122:125], v37 offset:11264
	ds_read_b128 v[126:129], v37 offset:9216
	v_mfma_f32_16x16x32_bf16 v[102:105], v[138:141], v[8:11], v[102:105]
	v_mfma_f32_16x16x32_bf16 v[106:109], v[142:145], v[8:11], v[106:109]
	ds_read_b128 v[130:133], v37 offset:7168
	ds_read_b128 v[134:137], v37 offset:5120
	ds_read_b128 v[138:141], v37 offset:3072
	ds_read_b128 v[142:145], v37 offset:1024
	v_mfma_f32_16x16x32_bf16 v[110:113], v[146:149], v[8:11], v[110:113]
	s_waitcnt lgkmcnt(0)
	v_mfma_f32_16x16x32_bf16 v[42:45], v[142:145], v[4:7], v[42:45]
	v_mfma_f32_16x16x32_bf16 v[50:53], v[138:141], v[4:7], v[50:53]
	v_mfma_f32_16x16x32_bf16 v[38:41], v[134:137], v[4:7], v[38:41]
	v_mfma_f32_16x16x32_bf16 v[74:77], v[130:133], v[4:7], v[74:77]
	v_mfma_f32_16x16x32_bf16 v[66:69], v[126:129], v[4:7], v[66:69]
	v_mfma_f32_16x16x32_bf16 v[70:73], v[122:125], v[4:7], v[70:73]
	ds_read_b128 v[122:125], v37 offset:33792
	ds_read_b128 v[126:129], v37 offset:35840
	ds_read_b128 v[130:133], v37 offset:37888
	ds_read_b128 v[134:137], v37 offset:39936
	v_mfma_f32_16x16x32_bf16 v[60:63], v[118:121], v[4:7], v[60:63]
	ds_read_b128 v[118:121], v37 offset:41984
	ds_read_b128 v[138:141], v37 offset:44032
	ds_read_b128 v[142:145], v37 offset:46080
	ds_read_b128 v[146:149], v37 offset:48128
	v_mfma_f32_16x16x32_bf16 v[78:81], v[114:117], v[4:7], v[78:81]
	s_waitcnt lgkmcnt(0)
	v_mfma_f32_16x16x32_bf16 v[82:85], v[122:125], v[4:7], v[82:85]
	v_mfma_f32_16x16x32_bf16 v[86:89], v[126:129], v[4:7], v[86:89]
	v_mfma_f32_16x16x32_bf16 v[90:93], v[130:133], v[4:7], v[90:93]
	v_mfma_f32_16x16x32_bf16 v[94:97], v[134:137], v[4:7], v[94:97]
	v_mfma_f32_16x16x32_bf16 v[98:101], v[118:121], v[4:7], v[98:101]
	ds_read_b128 v[114:117], v37 offset:31744
	ds_read_b128 v[118:121], v37 offset:29696
	ds_read_b128 v[122:125], v37 offset:27648
	ds_read_b128 v[126:129], v37 offset:25600
	v_mfma_f32_16x16x32_bf16 v[102:105], v[138:141], v[4:7], v[102:105]
	v_mfma_f32_16x16x32_bf16 v[106:109], v[142:145], v[4:7], v[106:109]
	ds_read_b128 v[130:133], v37 offset:23552
	ds_read_b128 v[134:137], v37 offset:21504
	ds_read_b128 v[138:141], v37 offset:19456
	ds_read_b128 v[142:145], v37 offset:17408
	v_mfma_f32_16x16x32_bf16 v[110:113], v[146:149], v[4:7], v[110:113]
	s_waitcnt lgkmcnt(0)
	v_mfma_f32_16x16x32_bf16 v[42:45], v[142:145], v[0:3], v[42:45]
	v_mfma_f32_16x16x32_bf16 v[50:53], v[138:141], v[0:3], v[50:53]
	v_mfma_f32_16x16x32_bf16 v[38:41], v[134:137], v[0:3], v[38:41]
	v_mfma_f32_16x16x32_bf16 v[74:77], v[130:133], v[0:3], v[74:77]
	v_mfma_f32_16x16x32_bf16 v[66:69], v[126:129], v[0:3], v[66:69]
	v_mfma_f32_16x16x32_bf16 v[70:73], v[122:125], v[0:3], v[70:73]
	ds_read_b128 v[122:125], v37 offset:50176
	ds_read_b128 v[126:129], v37 offset:52224
	ds_read_b128 v[130:133], v37 offset:54272
	ds_read_b128 v[134:137], v37 offset:56320
	v_mfma_f32_16x16x32_bf16 v[60:63], v[118:121], v[0:3], v[60:63]
	ds_read_b128 v[118:121], v37 offset:58368
	ds_read_b128 v[138:141], v37 offset:60416
	ds_read_b128 v[142:145], v37 offset:62464
	ds_read_b128 v[146:149], v37 offset:64512
	v_mfma_f32_16x16x32_bf16 v[78:81], v[114:117], v[0:3], v[78:81]
	s_waitcnt lgkmcnt(0)
	v_mfma_f32_16x16x32_bf16 v[82:85], v[122:125], v[0:3], v[82:85]
	v_mfma_f32_16x16x32_bf16 v[86:89], v[126:129], v[0:3], v[86:89]
	v_mfma_f32_16x16x32_bf16 v[90:93], v[130:133], v[0:3], v[90:93]
	v_mfma_f32_16x16x32_bf16 v[94:97], v[134:137], v[0:3], v[94:97]
	v_mfma_f32_16x16x32_bf16 v[98:101], v[118:121], v[0:3], v[98:101]
	v_mfma_f32_16x16x32_bf16 v[102:105], v[138:141], v[0:3], v[102:105]
	v_mfma_f32_16x16x32_bf16 v[106:109], v[142:145], v[0:3], v[106:109]
	v_mfma_f32_16x16x32_bf16 v[110:113], v[146:149], v[0:3], v[110:113]
	s_mov_b32 s0, 0x1000000
	v_add_co_u32_e32 v34, vcc, s0, v34
	v_mul_f32_e32 v37, v36, v42
	v_mul_f32_e32 v42, v36, v43
	v_mul_f32_e32 v43, v36, v45
	v_addc_co_u32_e32 v35, vcc, 0, v35, vcc
	v_cvt_pk_bf16_f32 v42, v37, v42
	v_mul_f32_e32 v37, v36, v44
	v_cvt_pk_bf16_f32 v43, v37, v43
	global_store_dwordx2 v[34:35], v[42:43], off
	v_mul_f32_e32 v34, v36, v50
	v_mul_f32_e32 v35, v36, v51
	v_cvt_pk_bf16_f32 v34, v34, v35
	v_mul_f32_e32 v35, v36, v52
	v_mul_f32_e32 v37, v36, v53
	v_cvt_pk_bf16_f32 v35, v35, v37
	global_store_dwordx2 v[32:33], v[34:35], off offset:32
	v_mul_f32_e32 v34, v36, v38
	v_mul_f32_e32 v35, v36, v39
	v_cvt_pk_bf16_f32 v34, v34, v35
	v_mul_f32_e32 v35, v36, v40
	v_mul_f32_e32 v37, v36, v41
	v_cvt_pk_bf16_f32 v35, v35, v37
	global_store_dwordx2 v[32:33], v[34:35], off offset:64
	v_mul_f32_e32 v34, v36, v74
	v_mul_f32_e32 v35, v36, v75
	v_cvt_pk_bf16_f32 v34, v34, v35
	v_mul_f32_e32 v35, v36, v76
	v_mul_f32_e32 v37, v36, v77
	v_cvt_pk_bf16_f32 v35, v35, v37
	global_store_dwordx2 v[32:33], v[34:35], off offset:96
	v_mul_f32_e32 v34, v36, v66
	v_mul_f32_e32 v35, v36, v67
	v_cvt_pk_bf16_f32 v34, v34, v35
	v_mul_f32_e32 v35, v36, v68
	v_mul_f32_e32 v37, v36, v69
	v_cvt_pk_bf16_f32 v35, v35, v37
	global_store_dwordx2 v[32:33], v[34:35], off offset:128
	v_mul_f32_e32 v34, v36, v70
	v_mul_f32_e32 v35, v36, v71
	v_cvt_pk_bf16_f32 v34, v34, v35
	v_mul_f32_e32 v35, v36, v72
	v_mul_f32_e32 v37, v36, v73
	v_cvt_pk_bf16_f32 v35, v35, v37
	global_store_dwordx2 v[32:33], v[34:35], off offset:160
	v_mul_f32_e32 v34, v36, v60
	v_mul_f32_e32 v35, v36, v61
	v_cvt_pk_bf16_f32 v34, v34, v35
	v_mul_f32_e32 v35, v36, v62
	v_mul_f32_e32 v37, v36, v63
	v_cvt_pk_bf16_f32 v35, v35, v37
	global_store_dwordx2 v[32:33], v[34:35], off offset:192
	v_mul_f32_e32 v34, v36, v78
	v_mul_f32_e32 v35, v36, v79
	v_cvt_pk_bf16_f32 v34, v34, v35
	v_mul_f32_e32 v35, v36, v80
	v_mul_f32_e32 v37, v36, v81
	v_cvt_pk_bf16_f32 v35, v35, v37
	global_store_dwordx2 v[32:33], v[34:35], off offset:224
	v_mul_f32_e32 v34, v36, v82
	v_mul_f32_e32 v35, v36, v83
	v_cvt_pk_bf16_f32 v34, v34, v35
	v_mul_f32_e32 v35, v36, v84
	v_mul_f32_e32 v37, v36, v85
	v_cvt_pk_bf16_f32 v35, v35, v37
	global_store_dwordx2 v[32:33], v[34:35], off offset:256
	v_mul_f32_e32 v34, v36, v86
	v_mul_f32_e32 v35, v36, v87
	v_cvt_pk_bf16_f32 v34, v34, v35
	v_mul_f32_e32 v35, v36, v88
	v_mul_f32_e32 v37, v36, v89
	v_cvt_pk_bf16_f32 v35, v35, v37
	global_store_dwordx2 v[32:33], v[34:35], off offset:288
	v_mul_f32_e32 v34, v36, v90
	v_mul_f32_e32 v35, v36, v91
	v_cvt_pk_bf16_f32 v34, v34, v35
	v_mul_f32_e32 v35, v36, v92
	v_mul_f32_e32 v37, v36, v93
	v_cvt_pk_bf16_f32 v35, v35, v37
	global_store_dwordx2 v[32:33], v[34:35], off offset:320
	v_mul_f32_e32 v34, v36, v94
	v_mul_f32_e32 v35, v36, v95
	v_cvt_pk_bf16_f32 v34, v34, v35
	v_mul_f32_e32 v35, v36, v96
	v_mul_f32_e32 v37, v36, v97
	v_cvt_pk_bf16_f32 v35, v35, v37
	global_store_dwordx2 v[32:33], v[34:35], off offset:352
	v_mul_f32_e32 v34, v36, v98
	v_mul_f32_e32 v35, v36, v99
	v_cvt_pk_bf16_f32 v34, v34, v35
	v_mul_f32_e32 v35, v36, v100
	v_mul_f32_e32 v37, v36, v101
	v_cvt_pk_bf16_f32 v35, v35, v37
	global_store_dwordx2 v[32:33], v[34:35], off offset:384
	v_mul_f32_e32 v34, v36, v102
	v_mul_f32_e32 v35, v36, v103
	v_cvt_pk_bf16_f32 v34, v34, v35
	v_mul_f32_e32 v35, v36, v104
	v_mul_f32_e32 v37, v36, v105
	v_cvt_pk_bf16_f32 v35, v35, v37
	global_store_dwordx2 v[32:33], v[34:35], off offset:416
	v_mul_f32_e32 v34, v36, v106
	v_mul_f32_e32 v35, v36, v107
	v_cvt_pk_bf16_f32 v34, v34, v35
	v_mul_f32_e32 v35, v36, v108
	v_mul_f32_e32 v37, v36, v109
	v_cvt_pk_bf16_f32 v35, v35, v37
	global_store_dwordx2 v[32:33], v[34:35], off offset:448
	v_mul_f32_e32 v34, v36, v110
	v_mul_f32_e32 v35, v36, v111
	v_cvt_pk_bf16_f32 v34, v34, v35
	v_mul_f32_e32 v35, v36, v112
	s_add_u32 s0, s10, 0x11c20100
	s_mov_b32 m0, s19
	v_mul_f32_e32 v37, v36, v113
	v_cvt_pk_bf16_f32 v35, v35, v37
	global_store_dwordx2 v[32:33], v[34:35], off offset:480
	s_addc_u32 s1, s11, 0
	s_waitcnt vmcnt(0)
	s_waitcnt vmcnt(0)
	s_barrier
	global_load_lds_dwordx4 v56, s[0:1]
	s_mov_b32 m0, s13
	s_nop 0
	global_load_lds_dwordx4 v58, s[0:1]
	s_add_u32 s0, s10, 0x11c20180
	s_addc_u32 s1, s11, 0
	s_mov_b32 m0, s12
	s_nop 0
	global_load_lds_dwordx4 v56, s[0:1]
	s_mov_b32 m0, s14
	s_nop 0
	global_load_lds_dwordx4 v58, s[0:1]
	s_add_u32 s0, s10, 0x11c30100
	s_addc_u32 s1, s11, 0
	s_mov_b32 m0, s15
	s_nop 0
	global_load_lds_dwordx4 v56, s[0:1]
	s_mov_b32 m0, s16
	s_nop 0
	global_load_lds_dwordx4 v58, s[0:1]
	s_add_u32 s0, s10, 0x11c30180
	s_addc_u32 s1, s11, 0
	s_mov_b32 m0, s17
	s_nop 0
	global_load_lds_dwordx4 v56, s[0:1]
	s_mov_b32 m0, s18
	s_nop 0
	global_load_lds_dwordx4 v58, s[0:1]
	ds_read_b128 v[38:41], v65
	ds_read_b128 v[42:45], v65 offset:2048
	ds_read_b128 v[50:53], v65 offset:4096
	ds_read_b128 v[54:57], v65 offset:6144
	ds_read_b128 v[58:61], v65 offset:8192
	ds_read_b128 v[66:69], v65 offset:10240
	ds_read_b128 v[70:73], v65 offset:12288
	ds_read_b128 v[74:77], v65 offset:14336
	ds_read_b128 v[78:81], v65 offset:32768
	ds_read_b128 v[82:85], v65 offset:34816
	ds_read_b128 v[86:89], v65 offset:36864
	ds_read_b128 v[90:93], v65 offset:38912
	ds_read_b128 v[94:97], v65 offset:40960
	ds_read_b128 v[98:101], v65 offset:43008
	ds_read_b128 v[102:105], v65 offset:45056
	ds_read_b128 v[106:109], v65 offset:47104
	s_waitcnt lgkmcnt(0)
	v_mfma_f32_16x16x32_bf16 v[38:41], v[38:41], v[28:31], 0
	v_mfma_f32_16x16x32_bf16 v[42:45], v[42:45], v[28:31], 0
	v_mfma_f32_16x16x32_bf16 v[50:53], v[50:53], v[28:31], 0
	v_mfma_f32_16x16x32_bf16 v[54:57], v[54:57], v[28:31], 0
	v_mfma_f32_16x16x32_bf16 v[58:61], v[58:61], v[28:31], 0
	v_mfma_f32_16x16x32_bf16 v[66:69], v[66:69], v[28:31], 0
	v_mfma_f32_16x16x32_bf16 v[70:73], v[70:73], v[28:31], 0
	v_mfma_f32_16x16x32_bf16 v[74:77], v[74:77], v[28:31], 0
	ds_read_b128 v[110:113], v65 offset:30720
	ds_read_b128 v[114:117], v65 offset:28672
	ds_read_b128 v[118:121], v65 offset:26624
	ds_read_b128 v[122:125], v65 offset:24576
	ds_read_b128 v[126:129], v65 offset:22528
	ds_read_b128 v[130:133], v65 offset:20480
	ds_read_b128 v[134:137], v65 offset:18432
	ds_read_b128 v[138:141], v65 offset:16384
	v_mfma_f32_16x16x32_bf16 v[78:81], v[78:81], v[28:31], 0
	v_mfma_f32_16x16x32_bf16 v[82:85], v[82:85], v[28:31], 0
	v_mfma_f32_16x16x32_bf16 v[86:89], v[86:89], v[28:31], 0
	v_mfma_f32_16x16x32_bf16 v[90:93], v[90:93], v[28:31], 0
	v_mfma_f32_16x16x32_bf16 v[94:97], v[94:97], v[28:31], 0
	v_mfma_f32_16x16x32_bf16 v[98:101], v[98:101], v[28:31], 0
	v_mfma_f32_16x16x32_bf16 v[102:105], v[102:105], v[28:31], 0
	v_mfma_f32_16x16x32_bf16 v[28:31], v[106:109], v[28:31], 0
	s_waitcnt lgkmcnt(0)
	v_mfma_f32_16x16x32_bf16 v[38:41], v[138:141], v[24:27], v[38:41]
	v_mfma_f32_16x16x32_bf16 v[42:45], v[134:137], v[24:27], v[42:45]
	v_mfma_f32_16x16x32_bf16 v[50:53], v[130:133], v[24:27], v[50:53]
	v_mfma_f32_16x16x32_bf16 v[54:57], v[126:129], v[24:27], v[54:57]
	v_mfma_f32_16x16x32_bf16 v[58:61], v[122:125], v[24:27], v[58:61]
	v_mfma_f32_16x16x32_bf16 v[66:69], v[118:121], v[24:27], v[66:69]
	ds_read_b128 v[106:109], v65 offset:49152
	ds_read_b128 v[118:121], v65 offset:51200
	ds_read_b128 v[122:125], v65 offset:53248
	ds_read_b128 v[126:129], v65 offset:55296
	v_mfma_f32_16x16x32_bf16 v[70:73], v[114:117], v[24:27], v[70:73]
	ds_read_b128 v[114:117], v65 offset:57344
	ds_read_b128 v[130:133], v65 offset:59392
	ds_read_b128 v[134:137], v65 offset:61440
	ds_read_b128 v[138:141], v65 offset:63488
	v_mfma_f32_16x16x32_bf16 v[74:77], v[110:113], v[24:27], v[74:77]
	s_waitcnt lgkmcnt(0)
	v_mfma_f32_16x16x32_bf16 v[78:81], v[106:109], v[24:27], v[78:81]
	v_mfma_f32_16x16x32_bf16 v[82:85], v[118:121], v[24:27], v[82:85]
	v_mfma_f32_16x16x32_bf16 v[86:89], v[122:125], v[24:27], v[86:89]
	v_mfma_f32_16x16x32_bf16 v[90:93], v[126:129], v[24:27], v[90:93]
	v_mfma_f32_16x16x32_bf16 v[94:97], v[114:117], v[24:27], v[94:97]
	ds_read_b128 v[106:109], v65 offset:15360
	ds_read_b128 v[110:113], v65 offset:13312
	ds_read_b128 v[114:117], v65 offset:11264
	ds_read_b128 v[118:121], v65 offset:9216
	v_mfma_f32_16x16x32_bf16 v[98:101], v[130:133], v[24:27], v[98:101]
	v_mfma_f32_16x16x32_bf16 v[102:105], v[134:137], v[24:27], v[102:105]
	ds_read_b128 v[122:125], v65 offset:7168
	ds_read_b128 v[126:129], v65 offset:5120
	ds_read_b128 v[130:133], v65 offset:3072
	ds_read_b128 v[134:137], v65 offset:1024
	v_mfma_f32_16x16x32_bf16 v[24:27], v[138:141], v[24:27], v[28:31]
	s_waitcnt lgkmcnt(0)
	v_mfma_f32_16x16x32_bf16 v[28:31], v[134:137], v[20:23], v[38:41]
	v_mfma_f32_16x16x32_bf16 v[38:41], v[130:133], v[20:23], v[42:45]
	v_mfma_f32_16x16x32_bf16 v[42:45], v[126:129], v[20:23], v[50:53]
	v_mfma_f32_16x16x32_bf16 v[50:53], v[122:125], v[20:23], v[54:57]
	v_mfma_f32_16x16x32_bf16 v[54:57], v[118:121], v[20:23], v[58:61]
	v_mfma_f32_16x16x32_bf16 v[58:61], v[114:117], v[20:23], v[66:69]
	s_nop 2
	ds_read_b128 v[66:69], v65 offset:33792
	ds_read_b128 v[114:117], v65 offset:35840
	ds_read_b128 v[118:121], v65 offset:37888
	ds_read_b128 v[122:125], v65 offset:39936
	v_mfma_f32_16x16x32_bf16 v[70:73], v[110:113], v[20:23], v[70:73]
	ds_read_b128 v[110:113], v65 offset:41984
	ds_read_b128 v[126:129], v65 offset:44032
	ds_read_b128 v[130:133], v65 offset:46080
	ds_read_b128 v[134:137], v65 offset:48128
	v_mfma_f32_16x16x32_bf16 v[74:77], v[106:109], v[20:23], v[74:77]
	s_waitcnt lgkmcnt(0)
	v_mfma_f32_16x16x32_bf16 v[66:69], v[66:69], v[20:23], v[78:81]
	v_mfma_f32_16x16x32_bf16 v[78:81], v[114:117], v[20:23], v[82:85]
	v_mfma_f32_16x16x32_bf16 v[82:85], v[118:121], v[20:23], v[86:89]
	v_mfma_f32_16x16x32_bf16 v[86:89], v[122:125], v[20:23], v[90:93]
	v_mfma_f32_16x16x32_bf16 v[90:93], v[110:113], v[20:23], v[94:97]
	v_mfma_f32_16x16x32_bf16 v[94:97], v[126:129], v[20:23], v[98:101]
	s_nop 2
	ds_read_b128 v[98:101], v65 offset:31744
	ds_read_b128 v[106:109], v65 offset:29696
	ds_read_b128 v[110:113], v65 offset:27648
	ds_read_b128 v[114:117], v65 offset:25600
	v_mfma_f32_16x16x32_bf16 v[102:105], v[130:133], v[20:23], v[102:105]
	ds_read_b128 v[118:121], v65 offset:23552
	ds_read_b128 v[122:125], v65 offset:21504
	ds_read_b128 v[126:129], v65 offset:19456
	ds_read_b128 v[130:133], v65 offset:17408
	v_mfma_f32_16x16x32_bf16 v[20:23], v[134:137], v[20:23], v[24:27]
	s_waitcnt lgkmcnt(0)
	v_mfma_f32_16x16x32_bf16 v[24:27], v[130:133], v[16:19], v[28:31]
	v_mfma_f32_16x16x32_bf16 v[28:31], v[126:129], v[16:19], v[38:41]
	v_mfma_f32_16x16x32_bf16 v[38:41], v[122:125], v[16:19], v[42:45]
	v_mfma_f32_16x16x32_bf16 v[42:45], v[118:121], v[16:19], v[50:53]
	v_mfma_f32_16x16x32_bf16 v[50:53], v[114:117], v[16:19], v[54:57]
	v_mfma_f32_16x16x32_bf16 v[54:57], v[110:113], v[16:19], v[58:61]
	s_nop 2
	ds_read_b128 v[58:61], v65 offset:50176
	ds_read_b128 v[110:113], v65 offset:52224
	ds_read_b128 v[114:117], v65 offset:54272
	ds_read_b128 v[118:121], v65 offset:56320
	v_mfma_f32_16x16x32_bf16 v[70:73], v[106:109], v[16:19], v[70:73]
	ds_read_b128 v[106:109], v65 offset:58368
	ds_read_b128 v[122:125], v65 offset:60416
	ds_read_b128 v[126:129], v65 offset:62464
	ds_read_b128 v[62:65], v65 offset:64512
	v_mfma_f32_16x16x32_bf16 v[74:77], v[98:101], v[16:19], v[74:77]
	s_waitcnt lgkmcnt(0)
	v_mfma_f32_16x16x32_bf16 v[58:61], v[58:61], v[16:19], v[66:69]
	v_mfma_f32_16x16x32_bf16 v[66:69], v[110:113], v[16:19], v[78:81]
	v_mfma_f32_16x16x32_bf16 v[78:81], v[114:117], v[16:19], v[82:85]
	v_mfma_f32_16x16x32_bf16 v[82:85], v[118:121], v[16:19], v[86:89]
	v_mfma_f32_16x16x32_bf16 v[86:89], v[106:109], v[16:19], v[90:93]
	v_mfma_f32_16x16x32_bf16 v[90:93], v[122:125], v[16:19], v[94:97]
	v_mfma_f32_16x16x32_bf16 v[94:97], v[126:129], v[16:19], v[102:105]
	v_mfma_f32_16x16x32_bf16 v[16:19], v[62:65], v[16:19], v[20:23]
	s_waitcnt vmcnt(0)
	s_waitcnt vmcnt(0)
	s_barrier
	s_nop 0
	ds_read_b128 v[20:23], v48
	ds_read_b128 v[62:65], v48 offset:2048
	s_waitcnt lgkmcnt(1)
	v_mfma_f32_16x16x32_bf16 v[20:23], v[20:23], v[12:15], v[24:27]
	s_nop 2
	ds_read_b128 v[24:27], v48 offset:4096
	s_waitcnt lgkmcnt(1)
	v_mfma_f32_16x16x32_bf16 v[28:31], v[62:65], v[12:15], v[28:31]
	ds_read_b128 v[62:65], v48 offset:6144
	s_waitcnt lgkmcnt(1)
	v_mfma_f32_16x16x32_bf16 v[24:27], v[24:27], v[12:15], v[38:41]
	s_nop 2
	ds_read_b128 v[38:41], v48 offset:8192
	s_waitcnt lgkmcnt(1)
	v_mfma_f32_16x16x32_bf16 v[42:45], v[62:65], v[12:15], v[42:45]
	ds_read_b128 v[62:65], v48 offset:10240
	s_waitcnt lgkmcnt(1)
	v_mfma_f32_16x16x32_bf16 v[38:41], v[38:41], v[12:15], v[50:53]
	s_nop 2
	ds_read_b128 v[50:53], v48 offset:12288
	ds_read_b128 v[98:101], v48 offset:14336
	s_waitcnt lgkmcnt(2)
	v_mfma_f32_16x16x32_bf16 v[54:57], v[62:65], v[12:15], v[54:57]
	ds_read_b128 v[62:65], v48 offset:32768
	ds_read_b128 v[102:105], v48 offset:34816
	ds_read_b128 v[106:109], v48 offset:36864
	ds_read_b128 v[110:113], v48 offset:38912
	s_waitcnt lgkmcnt(5)
	v_mfma_f32_16x16x32_bf16 v[50:53], v[50:53], v[12:15], v[70:73]
	s_nop 2
	ds_read_b128 v[70:73], v48 offset:40960
	ds_read_b128 v[114:117], v48 offset:43008
	ds_read_b128 v[118:121], v48 offset:45056
	ds_read_b128 v[122:125], v48 offset:47104
	s_waitcnt lgkmcnt(8)
	v_mfma_f32_16x16x32_bf16 v[74:77], v[98:101], v[12:15], v[74:77]
	s_waitcnt lgkmcnt(7)
	v_mfma_f32_16x16x32_bf16 v[58:61], v[62:65], v[12:15], v[58:61]
	s_waitcnt lgkmcnt(6)
	v_mfma_f32_16x16x32_bf16 v[62:65], v[102:105], v[12:15], v[66:69]
	s_waitcnt lgkmcnt(5)
	v_mfma_f32_16x16x32_bf16 v[66:69], v[106:109], v[12:15], v[78:81]
	s_waitcnt lgkmcnt(4)
	v_mfma_f32_16x16x32_bf16 v[78:81], v[110:113], v[12:15], v[82:85]
	s_waitcnt lgkmcnt(3)
	v_mfma_f32_16x16x32_bf16 v[70:73], v[70:73], v[12:15], v[86:89]
	s_waitcnt lgkmcnt(2)
	v_mfma_f32_16x16x32_bf16 v[82:85], v[114:117], v[12:15], v[90:93]
	s_nop 0
	ds_read_b128 v[86:89], v48 offset:30720
	s_nop 0
	ds_read_b128 v[90:93], v48 offset:28672
	ds_read_b128 v[98:101], v48 offset:26624
	ds_read_b128 v[102:105], v48 offset:24576
	s_waitcnt lgkmcnt(5)
	v_mfma_f32_16x16x32_bf16 v[94:97], v[118:121], v[12:15], v[94:97]
	ds_read_b128 v[106:109], v48 offset:22528
	ds_read_b128 v[110:113], v48 offset:20480
	ds_read_b128 v[114:117], v48 offset:18432
	ds_read_b128 v[118:121], v48 offset:16384
	s_waitcnt lgkmcnt(8)
	v_mfma_f32_16x16x32_bf16 v[12:15], v[122:125], v[12:15], v[16:19]
	s_waitcnt lgkmcnt(0)
	v_mfma_f32_16x16x32_bf16 v[16:19], v[118:121], v[8:11], v[20:23]
	v_mfma_f32_16x16x32_bf16 v[20:23], v[114:117], v[8:11], v[28:31]
	v_mfma_f32_16x16x32_bf16 v[24:27], v[110:113], v[8:11], v[24:27]
	v_mfma_f32_16x16x32_bf16 v[28:31], v[106:109], v[8:11], v[42:45]
	v_mfma_f32_16x16x32_bf16 v[38:41], v[102:105], v[8:11], v[38:41]
	v_mfma_f32_16x16x32_bf16 v[42:45], v[98:101], v[8:11], v[54:57]
	s_nop 2
	ds_read_b128 v[54:57], v48 offset:49152
	ds_read_b128 v[98:101], v48 offset:51200
	ds_read_b128 v[102:105], v48 offset:53248
	ds_read_b128 v[106:109], v48 offset:55296
	v_mfma_f32_16x16x32_bf16 v[50:53], v[90:93], v[8:11], v[50:53]
	ds_read_b128 v[90:93], v48 offset:57344
	ds_read_b128 v[110:113], v48 offset:59392
	ds_read_b128 v[114:117], v48 offset:61440
	ds_read_b128 v[118:121], v48 offset:63488
	v_mfma_f32_16x16x32_bf16 v[74:77], v[86:89], v[8:11], v[74:77]
	s_waitcnt lgkmcnt(7)
	v_mfma_f32_16x16x32_bf16 v[54:57], v[54:57], v[8:11], v[58:61]
	s_waitcnt lgkmcnt(6)
	v_mfma_f32_16x16x32_bf16 v[58:61], v[98:101], v[8:11], v[62:65]
	s_waitcnt lgkmcnt(5)
	v_mfma_f32_16x16x32_bf16 v[62:65], v[102:105], v[8:11], v[66:69]
	s_waitcnt lgkmcnt(4)
	v_mfma_f32_16x16x32_bf16 v[66:69], v[106:109], v[8:11], v[78:81]
	s_waitcnt lgkmcnt(3)
	v_mfma_f32_16x16x32_bf16 v[70:73], v[90:93], v[8:11], v[70:73]
	s_waitcnt lgkmcnt(2)
	v_mfma_f32_16x16x32_bf16 v[78:81], v[110:113], v[8:11], v[82:85]
	s_nop 2
	ds_read_b128 v[82:85], v48 offset:15360
	ds_read_b128 v[86:89], v48 offset:13312
	ds_read_b128 v[90:93], v48 offset:11264
	ds_read_b128 v[98:101], v48 offset:9216
	s_waitcnt lgkmcnt(5)
	v_mfma_f32_16x16x32_bf16 v[94:97], v[114:117], v[8:11], v[94:97]
	ds_read_b128 v[102:105], v48 offset:7168
	ds_read_b128 v[106:109], v48 offset:5120
	ds_read_b128 v[110:113], v48 offset:3072
	ds_read_b128 v[114:117], v48 offset:1024
	s_waitcnt lgkmcnt(8)
	v_mfma_f32_16x16x32_bf16 v[8:11], v[118:121], v[8:11], v[12:15]
	s_waitcnt lgkmcnt(0)
	v_mfma_f32_16x16x32_bf16 v[12:15], v[114:117], v[4:7], v[16:19]
	v_mfma_f32_16x16x32_bf16 v[16:19], v[110:113], v[4:7], v[20:23]
	v_mfma_f32_16x16x32_bf16 v[20:23], v[106:109], v[4:7], v[24:27]
	v_mfma_f32_16x16x32_bf16 v[24:27], v[102:105], v[4:7], v[28:31]
	v_mfma_f32_16x16x32_bf16 v[28:31], v[98:101], v[4:7], v[38:41]
	v_mfma_f32_16x16x32_bf16 v[38:41], v[90:93], v[4:7], v[42:45]
	s_nop 2
	ds_read_b128 v[42:45], v48 offset:33792
	ds_read_b128 v[90:93], v48 offset:35840
	ds_read_b128 v[98:101], v48 offset:37888
	ds_read_b128 v[102:105], v48 offset:39936
	v_mfma_f32_16x16x32_bf16 v[50:53], v[86:89], v[4:7], v[50:53]
	ds_read_b128 v[86:89], v48 offset:41984
	ds_read_b128 v[106:109], v48 offset:44032
	ds_read_b128 v[110:113], v48 offset:46080
	ds_read_b128 v[114:117], v48 offset:48128
	v_mfma_f32_16x16x32_bf16 v[74:77], v[82:85], v[4:7], v[74:77]
	s_waitcnt lgkmcnt(7)
	v_mfma_f32_16x16x32_bf16 v[42:45], v[42:45], v[4:7], v[54:57]
	s_waitcnt lgkmcnt(6)
	v_mfma_f32_16x16x32_bf16 v[54:57], v[90:93], v[4:7], v[58:61]
	s_waitcnt lgkmcnt(5)
	v_mfma_f32_16x16x32_bf16 v[58:61], v[98:101], v[4:7], v[62:65]
	s_waitcnt lgkmcnt(4)
	v_mfma_f32_16x16x32_bf16 v[62:65], v[102:105], v[4:7], v[66:69]
	s_waitcnt lgkmcnt(3)
	v_mfma_f32_16x16x32_bf16 v[66:69], v[86:89], v[4:7], v[70:73]
	s_waitcnt lgkmcnt(2)
	v_mfma_f32_16x16x32_bf16 v[70:73], v[106:109], v[4:7], v[78:81]
	s_nop 2
	ds_read_b128 v[78:81], v48 offset:31744
	ds_read_b128 v[82:85], v48 offset:29696
	ds_read_b128 v[86:89], v48 offset:27648
	ds_read_b128 v[90:93], v48 offset:25600
	s_waitcnt lgkmcnt(5)
	v_mfma_f32_16x16x32_bf16 v[94:97], v[110:113], v[4:7], v[94:97]
	ds_read_b128 v[98:101], v48 offset:23552
	ds_read_b128 v[102:105], v48 offset:21504
	ds_read_b128 v[106:109], v48 offset:19456
	ds_read_b128 v[110:113], v48 offset:17408
	s_waitcnt lgkmcnt(8)
	v_mfma_f32_16x16x32_bf16 v[4:7], v[114:117], v[4:7], v[8:11]
	s_waitcnt lgkmcnt(0)
	v_mfma_f32_16x16x32_bf16 v[8:11], v[110:113], v[0:3], v[12:15]
	v_mfma_f32_16x16x32_bf16 v[12:15], v[106:109], v[0:3], v[16:19]
	v_mfma_f32_16x16x32_bf16 v[16:19], v[102:105], v[0:3], v[20:23]
	v_mfma_f32_16x16x32_bf16 v[20:23], v[98:101], v[0:3], v[24:27]
	v_mfma_f32_16x16x32_bf16 v[24:27], v[90:93], v[0:3], v[28:31]
	v_mfma_f32_16x16x32_bf16 v[28:31], v[86:89], v[0:3], v[38:41]
	s_nop 2
	ds_read_b128 v[38:41], v48 offset:50176
	ds_read_b128 v[86:89], v48 offset:52224
	ds_read_b128 v[90:93], v48 offset:54272
	ds_read_b128 v[98:101], v48 offset:56320
	v_mfma_f32_16x16x32_bf16 v[50:53], v[82:85], v[0:3], v[50:53]
	ds_read_b128 v[82:85], v48 offset:58368
	ds_read_b128 v[102:105], v48 offset:60416
	ds_read_b128 v[106:109], v48 offset:62464
	ds_read_b128 v[46:49], v48 offset:64512
	v_mfma_f32_16x16x32_bf16 v[74:77], v[78:81], v[0:3], v[74:77]
	s_waitcnt lgkmcnt(7)
	v_mfma_f32_16x16x32_bf16 v[38:41], v[38:41], v[0:3], v[42:45]
	s_waitcnt lgkmcnt(6)
	v_mfma_f32_16x16x32_bf16 v[42:45], v[86:89], v[0:3], v[54:57]
	s_waitcnt lgkmcnt(5)
	v_mfma_f32_16x16x32_bf16 v[54:57], v[90:93], v[0:3], v[58:61]
	s_waitcnt lgkmcnt(4)
	v_mfma_f32_16x16x32_bf16 v[58:61], v[98:101], v[0:3], v[62:65]
	s_waitcnt lgkmcnt(3)
	v_mfma_f32_16x16x32_bf16 v[62:65], v[82:85], v[0:3], v[66:69]
	s_waitcnt lgkmcnt(2)
	v_mfma_f32_16x16x32_bf16 v[66:69], v[102:105], v[0:3], v[70:73]
	s_waitcnt lgkmcnt(1)
	v_mfma_f32_16x16x32_bf16 v[70:73], v[106:109], v[0:3], v[94:97]
	s_waitcnt lgkmcnt(0)
	v_mfma_f32_16x16x32_bf16 v[0:3], v[46:49], v[0:3], v[4:7]
	s_nop 2
	v_mul_f32_e32 v4, v36, v8
	v_mul_f32_e32 v5, v36, v9
	v_cvt_pk_bf16_f32 v4, v4, v5
	v_mul_f32_e32 v5, v36, v10
	v_mul_f32_e32 v6, v36, v11
	v_cvt_pk_bf16_f32 v5, v5, v6
	global_store_dwordx2 v[32:33], v[4:5], off offset:512
	v_mul_f32_e32 v4, v36, v12
	v_mul_f32_e32 v5, v36, v13
	v_cvt_pk_bf16_f32 v4, v4, v5
	v_mul_f32_e32 v5, v36, v14
	v_mul_f32_e32 v6, v36, v15
	v_cvt_pk_bf16_f32 v5, v5, v6
	global_store_dwordx2 v[32:33], v[4:5], off offset:544
	v_mul_f32_e32 v4, v36, v16
	v_mul_f32_e32 v5, v36, v17
	v_cvt_pk_bf16_f32 v4, v4, v5
	v_mul_f32_e32 v5, v36, v18
	v_mul_f32_e32 v6, v36, v19
	v_cvt_pk_bf16_f32 v5, v5, v6
	global_store_dwordx2 v[32:33], v[4:5], off offset:576
	v_mul_f32_e32 v4, v36, v20
	v_mul_f32_e32 v5, v36, v21
	v_cvt_pk_bf16_f32 v4, v4, v5
	v_mul_f32_e32 v5, v36, v22
	v_mul_f32_e32 v6, v36, v23
	v_cvt_pk_bf16_f32 v5, v5, v6
	global_store_dwordx2 v[32:33], v[4:5], off offset:608
	v_mul_f32_e32 v4, v36, v24
	v_mul_f32_e32 v5, v36, v25
	v_cvt_pk_bf16_f32 v4, v4, v5
	v_mul_f32_e32 v5, v36, v26
	v_mul_f32_e32 v6, v36, v27
	v_cvt_pk_bf16_f32 v5, v5, v6
	global_store_dwordx2 v[32:33], v[4:5], off offset:640
	v_mul_f32_e32 v4, v36, v28
	v_mul_f32_e32 v5, v36, v29
	v_cvt_pk_bf16_f32 v4, v4, v5
	v_mul_f32_e32 v5, v36, v30
	v_mul_f32_e32 v6, v36, v31
	v_cvt_pk_bf16_f32 v5, v5, v6
	global_store_dwordx2 v[32:33], v[4:5], off offset:672
	v_mul_f32_e32 v4, v36, v50
	v_mul_f32_e32 v5, v36, v51
	v_cvt_pk_bf16_f32 v4, v4, v5
	v_mul_f32_e32 v5, v36, v52
	v_mul_f32_e32 v6, v36, v53
	v_cvt_pk_bf16_f32 v5, v5, v6
	global_store_dwordx2 v[32:33], v[4:5], off offset:704
	v_mul_f32_e32 v4, v36, v74
	v_mul_f32_e32 v5, v36, v75
	v_cvt_pk_bf16_f32 v4, v4, v5
	v_mul_f32_e32 v5, v36, v76
	v_mul_f32_e32 v6, v36, v77
	v_cvt_pk_bf16_f32 v5, v5, v6
	global_store_dwordx2 v[32:33], v[4:5], off offset:736
	v_mul_f32_e32 v4, v36, v38
	v_mul_f32_e32 v5, v36, v39
	v_cvt_pk_bf16_f32 v4, v4, v5
	v_mul_f32_e32 v5, v36, v40
	v_mul_f32_e32 v6, v36, v41
	v_cvt_pk_bf16_f32 v5, v5, v6
	global_store_dwordx2 v[32:33], v[4:5], off offset:768
	v_mul_f32_e32 v4, v36, v42
	v_mul_f32_e32 v5, v36, v43
	v_cvt_pk_bf16_f32 v4, v4, v5
	v_mul_f32_e32 v5, v36, v44
	v_mul_f32_e32 v6, v36, v45
	v_cvt_pk_bf16_f32 v5, v5, v6
	global_store_dwordx2 v[32:33], v[4:5], off offset:800
	v_mul_f32_e32 v4, v36, v54
	v_mul_f32_e32 v5, v36, v55
	v_cvt_pk_bf16_f32 v4, v4, v5
	v_mul_f32_e32 v5, v36, v56
	v_mul_f32_e32 v6, v36, v57
	v_cvt_pk_bf16_f32 v5, v5, v6
	global_store_dwordx2 v[32:33], v[4:5], off offset:832
	v_mul_f32_e32 v4, v36, v58
	v_mul_f32_e32 v5, v36, v59
	v_cvt_pk_bf16_f32 v4, v4, v5
	v_mul_f32_e32 v5, v36, v60
	v_mul_f32_e32 v6, v36, v61
	v_cvt_pk_bf16_f32 v5, v5, v6
	global_store_dwordx2 v[32:33], v[4:5], off offset:864
	v_mul_f32_e32 v4, v36, v62
	v_mul_f32_e32 v5, v36, v63
	v_cvt_pk_bf16_f32 v4, v4, v5
	v_mul_f32_e32 v5, v36, v64
	v_mul_f32_e32 v6, v36, v65
	v_cvt_pk_bf16_f32 v5, v5, v6
	global_store_dwordx2 v[32:33], v[4:5], off offset:896
	v_mul_f32_e32 v4, v36, v66
	v_mul_f32_e32 v5, v36, v67
	v_cvt_pk_bf16_f32 v4, v4, v5
	v_mul_f32_e32 v5, v36, v68
	v_mul_f32_e32 v6, v36, v69
	v_cvt_pk_bf16_f32 v5, v5, v6
	global_store_dwordx2 v[32:33], v[4:5], off offset:928
	v_mul_f32_e32 v4, v36, v70
	v_mul_f32_e32 v5, v36, v71
	v_cvt_pk_bf16_f32 v4, v4, v5
	v_mul_f32_e32 v5, v36, v72
	v_mul_f32_e32 v0, v36, v0
	v_mul_f32_e32 v1, v36, v1
	v_mul_f32_e32 v6, v36, v73
	v_cvt_pk_bf16_f32 v5, v5, v6
	global_store_dwordx2 v[32:33], v[4:5], off offset:960
	v_cvt_pk_bf16_f32 v0, v0, v1
	v_mul_f32_e32 v1, v36, v2
	v_mul_f32_e32 v2, v36, v3
	v_cvt_pk_bf16_f32 v1, v1, v2
	global_store_dwordx2 v[32:33], v[0:1], off offset:992
	s_waitcnt vmcnt(0)
	s_barrier

.LBB0_1078:
	s_mov_b64 s[14:15], 0x80
	s_add_i32 m0, s46, 0x18000
	v_lshl_add_u64 v[22:23], v[22:23], 0, s[14:15]
	s_waitcnt vmcnt(2)
	s_barrier
	global_load_lds_dwordx4 v[22:23], off
	v_lshl_add_u64 v[20:21], v[20:21], 0, s[14:15]
	s_add_i32 m0, s46, 0x1a000
	s_add_i32 s50, s46, 0x8000
	s_add_i32 s51, s46, 0xa000
	global_load_lds_dwordx4 v[20:21], off
	v_lshl_add_u64 v[16:17], v[16:17], 0, s[14:15]
	s_mov_b32 m0, s50
	s_add_u32 s0, s10, 0x80080
	global_load_lds_dwordx4 v[16:17], off
	v_lshl_add_u64 v[16:17], v[18:19], 0, s[14:15]
	s_mov_b32 m0, s51
	s_addc_u32 s1, s11, 0
	global_load_lds_dwordx4 v[16:17], off
	s_add_i32 m0, s46, 0x1c000
	v_lshl_add_u64 v[16:17], s[0:1], 0, v[130:131]
	global_load_lds_dwordx4 v[16:17], off
	v_lshl_add_u64 v[16:17], s[0:1], 0, v[134:135]
	s_add_i32 m0, s46, 0x1e000
	s_nop 0
	global_load_lds_dwordx4 v[16:17], off
	s_waitcnt vmcnt(6)
	s_barrier
	s_and_saveexec_b64 s[0:1], s[2:3]
	s_cbranch_execz .LBB0_1080
	v_pk_add_f32 v[10:11], v[10:11], v[14:15]
	v_pk_add_f32 v[8:9], v[8:9], v[12:13]
	v_pk_add_f32 v[4:5], v[6:7], v[4:5]
	v_pk_add_f32 v[0:1], v[2:3], v[0:1]
	v_pk_add_f32 v[2:3], v[4:5], v[10:11]
	v_pk_add_f32 v[0:1], v[0:1], v[8:9]
	s_nop 0
	v_pk_mov_b32 v[4:5], v[2:3], v[0:1] op_sel:[1,0]
	v_mov_b32_e32 v3, v1
	v_pk_add_f32 v[0:1], v[4:5], v[2:3]
	s_nop 0
	v_add_f32_e32 v0, v0, v1
	v_mov_b32_e32 v1, 0x358637bd
	v_fmac_f32_e32 v1, 0x3a000000, v0
	v_rsq_f32_e32 v0, v1
	v_lshl_add_u32 v1, v25, 2, 0
	v_add_u32_e32 v1, 0x20000, v1
	ds_write_b32 v1, v0
.LBB0_1080:
	s_or_b64 exec, exec, s[0:1]
	s_mul_i32 s0, s16, 0x1400000
	s_add_u32 s0, s94, s0
	s_addc_u32 s1, s95, 0
	s_lshl_b32 s2, s16, 24
	s_sub_u32 s2, 0, s2
	s_subb_u32 s3, 0, 0
	s_add_u32 s0, s0, s2
	s_addc_u32 s1, s1, s3
	s_add_u32 s2, s0, 0x13000000
	s_addc_u32 s3, s1, 0
	v_ashrrev_i32_e32 v0, 6, v24
	s_lshl_b32 s0, s18, 13
	v_lshl_add_u32 v2, v0, 10, s0
	s_lshl_b32 s0, s88, 5
	s_and_b32 s54, s0, 0x60
	v_and_b32_e32 v148, 15, v24
	v_and_b32_e32 v1, 48, v24
	v_lshlrev_b32_e32 v3, 2, v24
	s_lshr_b32 s0, s54, 3
	v_lshl_or_b32 v1, v148, 6, v1
	v_and_b32_e32 v3, 32, v3
	v_add_lshl_u32 v0, v0, s0, 10
	v_bitop3_b32 v2, v1, v2, v3 bitop3:0xde
	v_bitop3_b32 v0, v1, v0, v3 bitop3:0xde
	v_lshlrev_b32_e32 v1, 15, v26
	v_and_b32_e32 v1, 0xffff0000, v1
	v_lshl_add_u32 v1, v27, 12, v1
	v_and_b32_e32 v3, 1, v26
	v_lshl_or_b32 v1, v3, 6, v1
	s_lshl_b32 s53, s18, 6
	v_lshl_add_u32 v136, v28, 1, v1
	v_lshlrev_b32_e32 v1, 15, v29
	s_cmpk_lt_u32 s33, 0x100
	v_and_b32_e32 v1, 0xffff0000, v1
	s_cselect_b64 s[16:17], -1, 0
	s_lshl_b32 s0, s18, 8
	v_lshl_add_u32 v1, v30, 12, v1
	v_and_b32_e32 v3, 1, v29
	s_add_i32 s55, s0, 0
	v_mov_b32_e32 v137, 0
	v_lshl_or_b32 v1, v3, 6, v1
	s_add_i32 s56, 0, 0x10000
	s_add_i32 s57, 0, 0x14000
	s_add_i32 s58, 0, 0x18000
	s_add_i32 s59, 0, 0x1c000
	s_mov_b32 s52, 0
	v_ashrrev_i32_e32 v149, 4, v24
	s_add_i32 s55, s55, 0x20000
	v_lshl_add_u32 v138, v31, 1, v1
	v_mov_b32_e32 v139, v137
	v_add_u32_e32 v150, s56, v0
	v_add_u32_e32 v151, s57, v0
	v_add_u32_e32 v152, 0, v2
	s_mov_b64 s[18:19], 0x80000
	v_add_u32_e32 v153, s58, v0
	v_add_u32_e32 v154, s59, v0
	s_mov_b64 s[20:21], 0x40000
	s_lshr_b32 s84, s88, 2
	s_mul_i32 s85, s84, 0x3000
	s_add_i32 s85, s85, s46
	s_mul_i32 s86, s84, 0x60000
	v_add_u32_e32 v222, s86, v128
	s_mov_b32 s60, 0x40000
	s_mov_b32 s61, 0x80000
	s_mov_b64 s[22:23], 0xc0000
	s_mov_b32 s62, 0xc0000
	s_mov_b64 s[24:25], 0x200000
	s_mov_b32 s63, 0x200000
	s_mov_b64 s[26:27], 0x240000
	s_mov_b32 s64, 0x240000
	s_mov_b64 s[28:29], 0x280000
	s_mov_b32 s65, 0x280000
	s_mov_b64 s[30:31], 0x2c0000
	s_mov_b32 s66, 0x2c0000
	s_branch .LBB0_1083

.LBB0_1084:
	ds_read_b128 v[140:143], v150
	ds_read_b128 v[144:147], v150 offset:1024
	ds_read_b128 v[156:159], v150 offset:2048
	ds_read_b128 v[160:163], v150 offset:3072
	ds_read_b128 v[164:167], v151
	ds_read_b128 v[168:171], v151 offset:1024
	ds_read_b128 v[172:175], v151 offset:2048
	ds_read_b128 v[176:179], v151 offset:3072
	s_add_u32 s36, s0, 0xfff80080
	s_addc_u32 s37, s1, -1
	s_cmp_eq_u32 s74, 28
	s_cselect_b32 s39, s68, s37
	s_cselect_b32 s38, s69, s36
	s_cselect_b32 s37, s70, s73
	s_cselect_b32 s36, s71, s72
	s_sub_u32 s98, s0, 0x80000
	s_subb_u32 s99, s1, 0
	s_add_i32 m0, s85, 0x8000
	ds_read_b128 v[180:183], v152
	ds_read_b128 v[184:187], v152 offset:1024
	ds_read_b128 v[188:191], v152 offset:2048
	ds_read_b128 v[192:195], v152 offset:3072
	ds_read_b128 v[196:199], v152 offset:4096
	ds_read_b128 v[200:203], v152 offset:5120
	ds_read_b128 v[204:207], v152 offset:6144
	ds_read_b128 v[208:211], v152 offset:7168
	global_load_lds_dwordx4 v222, s[98:99]
	s_add_u32 s98, s98, 0x20000
	s_addc_u32 s99, s99, 0
	s_add_i32 m0, s85, 0x9000
	s_nop 0
	global_load_lds_dwordx4 v222, s[98:99]
	s_add_u32 s98, s98, 0x20000
	s_addc_u32 s99, s99, 0
	s_add_i32 m0, s85, 0xa000
	s_nop 0
	global_load_lds_dwordx4 v222, s[98:99]
	s_add_u32 s98, s98, 0x20000
	s_addc_u32 s99, s99, 0
	s_add_i32 m0, s85, 0xb000
	s_nop 0
	global_load_lds_dwordx4 v222, s[98:99]
	s_waitcnt vmcnt(8)
	s_waitcnt lgkmcnt(0)
	s_barrier
	s_setprio 1
	s_waitcnt lgkmcnt(0)
	v_mfma_f32_16x16x32_bf16 v[124:127], v[140:143], v[180:183], v[124:127]
	v_mfma_f32_16x16x32_bf16 v[120:123], v[156:159], v[180:183], v[120:123]
	v_mfma_f32_16x16x32_bf16 v[108:111], v[140:143], v[188:191], v[108:111]
	v_mfma_f32_16x16x32_bf16 v[104:107], v[156:159], v[188:191], v[104:107]
	v_mfma_f32_16x16x32_bf16 v[92:95], v[140:143], v[196:199], v[92:95]
	v_mfma_f32_16x16x32_bf16 v[88:91], v[156:159], v[196:199], v[88:91]
	v_mfma_f32_16x16x32_bf16 v[76:79], v[140:143], v[204:207], v[76:79]
	v_mfma_f32_16x16x32_bf16 v[72:75], v[156:159], v[204:207], v[72:75]
	v_mfma_f32_16x16x32_bf16 v[124:127], v[144:147], v[184:187], v[124:127]
	v_mfma_f32_16x16x32_bf16 v[120:123], v[160:163], v[184:187], v[120:123]
	v_mfma_f32_16x16x32_bf16 v[108:111], v[144:147], v[192:195], v[108:111]
	v_mfma_f32_16x16x32_bf16 v[104:107], v[160:163], v[192:195], v[104:107]
	v_mfma_f32_16x16x32_bf16 v[92:95], v[144:147], v[200:203], v[92:95]
	v_mfma_f32_16x16x32_bf16 v[88:91], v[160:163], v[200:203], v[88:91]
	v_mfma_f32_16x16x32_bf16 v[76:79], v[144:147], v[208:211], v[76:79]
	v_mfma_f32_16x16x32_bf16 v[72:75], v[160:163], v[208:211], v[72:75]
	s_setprio 0
	s_setprio 1
	v_mfma_f32_16x16x32_bf16 v[116:119], v[164:167], v[180:183], v[116:119]
	v_mfma_f32_16x16x32_bf16 v[112:115], v[172:175], v[180:183], v[112:115]
	v_mfma_f32_16x16x32_bf16 v[100:103], v[164:167], v[188:191], v[100:103]
	v_mfma_f32_16x16x32_bf16 v[96:99], v[172:175], v[188:191], v[96:99]
	v_mfma_f32_16x16x32_bf16 v[84:87], v[164:167], v[196:199], v[84:87]
	v_mfma_f32_16x16x32_bf16 v[80:83], v[172:175], v[196:199], v[80:83]
	v_mfma_f32_16x16x32_bf16 v[68:71], v[164:167], v[204:207], v[68:71]
	v_mfma_f32_16x16x32_bf16 v[64:67], v[172:175], v[204:207], v[64:67]
	v_mfma_f32_16x16x32_bf16 v[116:119], v[168:171], v[184:187], v[116:119]
	v_mfma_f32_16x16x32_bf16 v[112:115], v[176:179], v[184:187], v[112:115]
	v_mfma_f32_16x16x32_bf16 v[100:103], v[168:171], v[192:195], v[100:103]
	v_mfma_f32_16x16x32_bf16 v[96:99], v[176:179], v[192:195], v[96:99]
	v_mfma_f32_16x16x32_bf16 v[84:87], v[168:171], v[200:203], v[84:87]
	v_mfma_f32_16x16x32_bf16 v[80:83], v[176:179], v[200:203], v[80:83]
	v_mfma_f32_16x16x32_bf16 v[68:71], v[168:171], v[208:211], v[68:71]
	v_mfma_f32_16x16x32_bf16 v[64:67], v[176:179], v[208:211], v[64:67]
	s_setprio 0
	s_barrier
	s_add_i32 s75, s56, s5
	v_lshl_add_u64 v[212:213], s[36:37], 0, v[130:131]
	s_mov_b32 m0, s75
	ds_read_b128 v[180:183], v152 offset:16384
	ds_read_b128 v[184:187], v152 offset:17408
	ds_read_b128 v[188:191], v152 offset:18432
	ds_read_b128 v[192:195], v152 offset:19456
	ds_read_b128 v[196:199], v152 offset:20480
	ds_read_b128 v[200:203], v152 offset:21504
	ds_read_b128 v[204:207], v152 offset:22528
	ds_read_b128 v[208:211], v152 offset:23552
	global_load_lds_dwordx4 v[212:213], off
	s_add_i32 m0, s75, 0x2000
	s_add_u32 s76, s36, 0x80000
	v_lshl_add_u64 v[214:215], s[36:37], 0, v[134:135]
	s_addc_u32 s77, s37, 0
	s_add_i32 s75, s57, s5
	global_load_lds_dwordx4 v[214:215], off
	v_lshl_add_u64 v[216:217], s[76:77], 0, v[130:131]
	s_mov_b32 m0, s75
	global_load_lds_dwordx4 v[216:217], off
	v_lshl_add_u64 v[216:217], s[76:77], 0, v[134:135]
	s_add_i32 m0, s75, 0x2000
	s_nop 0
	global_load_lds_dwordx4 v[216:217], off
	s_waitcnt vmcnt(8)
	s_waitcnt lgkmcnt(0)
	s_barrier
	s_setprio 1
	s_waitcnt lgkmcnt(0)
	v_mfma_f32_16x16x32_bf16 v[60:63], v[140:143], v[180:183], v[60:63]
	v_mfma_f32_16x16x32_bf16 v[56:59], v[156:159], v[180:183], v[56:59]
	v_mfma_f32_16x16x32_bf16 v[44:47], v[140:143], v[188:191], v[44:47]
	v_mfma_f32_16x16x32_bf16 v[40:43], v[156:159], v[188:191], v[40:43]
	v_mfma_f32_16x16x32_bf16 v[28:31], v[140:143], v[196:199], v[28:31]
	v_mfma_f32_16x16x32_bf16 v[24:27], v[156:159], v[196:199], v[24:27]
	v_mfma_f32_16x16x32_bf16 v[12:15], v[140:143], v[204:207], v[12:15]
	v_mfma_f32_16x16x32_bf16 v[8:11], v[156:159], v[204:207], v[8:11]
	v_mfma_f32_16x16x32_bf16 v[60:63], v[144:147], v[184:187], v[60:63]
	v_mfma_f32_16x16x32_bf16 v[56:59], v[160:163], v[184:187], v[56:59]
	v_mfma_f32_16x16x32_bf16 v[44:47], v[144:147], v[192:195], v[44:47]
	v_mfma_f32_16x16x32_bf16 v[40:43], v[160:163], v[192:195], v[40:43]
	v_mfma_f32_16x16x32_bf16 v[28:31], v[144:147], v[200:203], v[28:31]
	v_mfma_f32_16x16x32_bf16 v[24:27], v[160:163], v[200:203], v[24:27]
	v_mfma_f32_16x16x32_bf16 v[12:15], v[144:147], v[208:211], v[12:15]
	v_mfma_f32_16x16x32_bf16 v[8:11], v[160:163], v[208:211], v[8:11]
	s_setprio 0
	s_setprio 1
	v_mfma_f32_16x16x32_bf16 v[52:55], v[164:167], v[180:183], v[52:55]
	v_mfma_f32_16x16x32_bf16 v[48:51], v[172:175], v[180:183], v[48:51]
	v_mfma_f32_16x16x32_bf16 v[36:39], v[164:167], v[188:191], v[36:39]
	v_mfma_f32_16x16x32_bf16 v[32:35], v[172:175], v[188:191], v[32:35]
	v_mfma_f32_16x16x32_bf16 v[20:23], v[164:167], v[196:199], v[20:23]
	v_mfma_f32_16x16x32_bf16 v[16:19], v[172:175], v[196:199], v[16:19]
	v_mfma_f32_16x16x32_bf16 v[4:7], v[164:167], v[204:207], v[4:7]
	v_mfma_f32_16x16x32_bf16 v[0:3], v[172:175], v[204:207], v[0:3]
	v_mfma_f32_16x16x32_bf16 v[52:55], v[168:171], v[184:187], v[52:55]
	v_mfma_f32_16x16x32_bf16 v[48:51], v[176:179], v[184:187], v[48:51]
	v_mfma_f32_16x16x32_bf16 v[36:39], v[168:171], v[192:195], v[36:39]
	v_mfma_f32_16x16x32_bf16 v[32:35], v[176:179], v[192:195], v[32:35]
	v_mfma_f32_16x16x32_bf16 v[20:23], v[168:171], v[200:203], v[20:23]
	v_mfma_f32_16x16x32_bf16 v[16:19], v[176:179], v[200:203], v[16:19]
	v_mfma_f32_16x16x32_bf16 v[4:7], v[168:171], v[208:211], v[4:7]
	v_mfma_f32_16x16x32_bf16 v[0:3], v[176:179], v[208:211], v[0:3]
	s_setprio 0
	s_waitcnt vmcnt(4)
	s_barrier
	ds_read_b128 v[140:143], v153
	ds_read_b128 v[144:147], v153 offset:1024
	ds_read_b128 v[156:159], v153 offset:2048
	ds_read_b128 v[160:163], v153 offset:3072
	ds_read_b128 v[164:167], v154
	ds_read_b128 v[168:171], v154 offset:1024
	ds_read_b128 v[172:175], v154 offset:2048
	ds_read_b128 v[176:179], v154 offset:3072
	s_mov_b32 s98, s38
	s_mov_b32 s99, s39
	s_add_i32 m0, s85, 0
	ds_read_b128 v[180:183], v152 offset:32768
	ds_read_b128 v[184:187], v152 offset:33792
	ds_read_b128 v[188:191], v152 offset:34816
	ds_read_b128 v[192:195], v152 offset:35840
	ds_read_b128 v[196:199], v152 offset:36864
	ds_read_b128 v[200:203], v152 offset:37888
	ds_read_b128 v[204:207], v152 offset:38912
	ds_read_b128 v[208:211], v152 offset:39936
	global_load_lds_dwordx4 v222, s[98:99]
	s_add_u32 s98, s98, 0x20000
	s_addc_u32 s99, s99, 0
	s_add_i32 m0, s85, 0x1000
	s_nop 0
	global_load_lds_dwordx4 v222, s[98:99]
	s_add_u32 s98, s98, 0x20000
	s_addc_u32 s99, s99, 0
	s_add_i32 m0, s85, 0x2000
	s_nop 0
	global_load_lds_dwordx4 v222, s[98:99]
	s_add_u32 s98, s98, 0x20000
	s_addc_u32 s99, s99, 0
	s_add_i32 m0, s85, 0x3000
	s_nop 0
	global_load_lds_dwordx4 v222, s[98:99]
	s_waitcnt vmcnt(8)
	s_waitcnt lgkmcnt(0)
	s_barrier
	s_setprio 1
	s_waitcnt lgkmcnt(0)
	v_mfma_f32_16x16x32_bf16 v[124:127], v[140:143], v[180:183], v[124:127]
	v_mfma_f32_16x16x32_bf16 v[120:123], v[156:159], v[180:183], v[120:123]
	v_mfma_f32_16x16x32_bf16 v[108:111], v[140:143], v[188:191], v[108:111]
	v_mfma_f32_16x16x32_bf16 v[104:107], v[156:159], v[188:191], v[104:107]
	v_mfma_f32_16x16x32_bf16 v[92:95], v[140:143], v[196:199], v[92:95]
	v_mfma_f32_16x16x32_bf16 v[88:91], v[156:159], v[196:199], v[88:91]
	v_mfma_f32_16x16x32_bf16 v[76:79], v[140:143], v[204:207], v[76:79]
	v_mfma_f32_16x16x32_bf16 v[72:75], v[156:159], v[204:207], v[72:75]
	v_mfma_f32_16x16x32_bf16 v[124:127], v[144:147], v[184:187], v[124:127]
	v_mfma_f32_16x16x32_bf16 v[120:123], v[160:163], v[184:187], v[120:123]
	v_mfma_f32_16x16x32_bf16 v[108:111], v[144:147], v[192:195], v[108:111]
	v_mfma_f32_16x16x32_bf16 v[104:107], v[160:163], v[192:195], v[104:107]
	v_mfma_f32_16x16x32_bf16 v[92:95], v[144:147], v[200:203], v[92:95]
	v_mfma_f32_16x16x32_bf16 v[88:91], v[160:163], v[200:203], v[88:91]
	v_mfma_f32_16x16x32_bf16 v[76:79], v[144:147], v[208:211], v[76:79]
	v_mfma_f32_16x16x32_bf16 v[72:75], v[160:163], v[208:211], v[72:75]
	s_setprio 0
	s_setprio 1
	v_mfma_f32_16x16x32_bf16 v[116:119], v[164:167], v[180:183], v[116:119]
	v_mfma_f32_16x16x32_bf16 v[112:115], v[172:175], v[180:183], v[112:115]
	v_mfma_f32_16x16x32_bf16 v[100:103], v[164:167], v[188:191], v[100:103]
	v_mfma_f32_16x16x32_bf16 v[96:99], v[172:175], v[188:191], v[96:99]
	v_mfma_f32_16x16x32_bf16 v[84:87], v[164:167], v[196:199], v[84:87]
	v_mfma_f32_16x16x32_bf16 v[80:83], v[172:175], v[196:199], v[80:83]
	v_mfma_f32_16x16x32_bf16 v[68:71], v[164:167], v[204:207], v[68:71]
	v_mfma_f32_16x16x32_bf16 v[64:67], v[172:175], v[204:207], v[64:67]
	v_mfma_f32_16x16x32_bf16 v[116:119], v[168:171], v[184:187], v[116:119]
	v_mfma_f32_16x16x32_bf16 v[112:115], v[176:179], v[184:187], v[112:115]
	v_mfma_f32_16x16x32_bf16 v[100:103], v[168:171], v[192:195], v[100:103]
	v_mfma_f32_16x16x32_bf16 v[96:99], v[176:179], v[192:195], v[96:99]
	v_mfma_f32_16x16x32_bf16 v[84:87], v[168:171], v[200:203], v[84:87]
	v_mfma_f32_16x16x32_bf16 v[80:83], v[176:179], v[200:203], v[80:83]
	v_mfma_f32_16x16x32_bf16 v[68:71], v[168:171], v[208:211], v[68:71]
	v_mfma_f32_16x16x32_bf16 v[64:67], v[176:179], v[208:211], v[64:67]
	s_setprio 0
	s_barrier
	s_add_i32 s38, s58, s5
	v_lshl_add_u64 v[212:213], v[212:213], 0, s[14:15]
	s_mov_b32 m0, s38
	ds_read_b128 v[180:183], v152 offset:49152
	ds_read_b128 v[184:187], v152 offset:50176
	ds_read_b128 v[188:191], v152 offset:51200
	ds_read_b128 v[192:195], v152 offset:52224
	ds_read_b128 v[196:199], v152 offset:53248
	ds_read_b128 v[200:203], v152 offset:54272
	ds_read_b128 v[204:207], v152 offset:55296
	ds_read_b128 v[208:211], v152 offset:56320
	global_load_lds_dwordx4 v[212:213], off
	s_add_i32 m0, s38, 0x2000
	s_add_u32 s36, s36, 0x80080
	v_lshl_add_u64 v[212:213], v[214:215], 0, s[14:15]
	s_addc_u32 s37, s37, 0
	s_add_i32 s38, s59, s5
	global_load_lds_dwordx4 v[212:213], off
	v_lshl_add_u64 v[212:213], s[36:37], 0, v[130:131]
	s_mov_b32 m0, s38
	s_nop 0
	global_load_lds_dwordx4 v[212:213], off
	v_lshl_add_u64 v[212:213], s[36:37], 0, v[134:135]
	s_add_i32 m0, s38, 0x2000
	s_nop 0
	global_load_lds_dwordx4 v[212:213], off
	s_waitcnt vmcnt(8)
	s_waitcnt lgkmcnt(0)
	s_barrier
	s_setprio 1
	s_waitcnt lgkmcnt(0)
	v_mfma_f32_16x16x32_bf16 v[60:63], v[140:143], v[180:183], v[60:63]
	v_mfma_f32_16x16x32_bf16 v[56:59], v[156:159], v[180:183], v[56:59]
	v_mfma_f32_16x16x32_bf16 v[44:47], v[140:143], v[188:191], v[44:47]
	v_mfma_f32_16x16x32_bf16 v[40:43], v[156:159], v[188:191], v[40:43]
	v_mfma_f32_16x16x32_bf16 v[28:31], v[140:143], v[196:199], v[28:31]
	v_mfma_f32_16x16x32_bf16 v[24:27], v[156:159], v[196:199], v[24:27]
	v_mfma_f32_16x16x32_bf16 v[12:15], v[140:143], v[204:207], v[12:15]
	v_mfma_f32_16x16x32_bf16 v[8:11], v[156:159], v[204:207], v[8:11]
	v_mfma_f32_16x16x32_bf16 v[60:63], v[144:147], v[184:187], v[60:63]
	v_mfma_f32_16x16x32_bf16 v[56:59], v[160:163], v[184:187], v[56:59]
	v_mfma_f32_16x16x32_bf16 v[44:47], v[144:147], v[192:195], v[44:47]
	v_mfma_f32_16x16x32_bf16 v[40:43], v[160:163], v[192:195], v[40:43]
	v_mfma_f32_16x16x32_bf16 v[28:31], v[144:147], v[200:203], v[28:31]
	v_mfma_f32_16x16x32_bf16 v[24:27], v[160:163], v[200:203], v[24:27]
	v_mfma_f32_16x16x32_bf16 v[12:15], v[144:147], v[208:211], v[12:15]
	v_mfma_f32_16x16x32_bf16 v[8:11], v[160:163], v[208:211], v[8:11]
	s_setprio 0
	s_setprio 1
	v_mfma_f32_16x16x32_bf16 v[52:55], v[164:167], v[180:183], v[52:55]
	v_mfma_f32_16x16x32_bf16 v[48:51], v[172:175], v[180:183], v[48:51]
	v_mfma_f32_16x16x32_bf16 v[36:39], v[164:167], v[188:191], v[36:39]
	v_mfma_f32_16x16x32_bf16 v[32:35], v[172:175], v[188:191], v[32:35]
	v_mfma_f32_16x16x32_bf16 v[20:23], v[164:167], v[196:199], v[20:23]
	v_mfma_f32_16x16x32_bf16 v[16:19], v[172:175], v[196:199], v[16:19]
	v_mfma_f32_16x16x32_bf16 v[4:7], v[164:167], v[204:207], v[4:7]
	v_mfma_f32_16x16x32_bf16 v[0:3], v[172:175], v[204:207], v[0:3]
	v_mfma_f32_16x16x32_bf16 v[52:55], v[168:171], v[184:187], v[52:55]
	v_mfma_f32_16x16x32_bf16 v[48:51], v[176:179], v[184:187], v[48:51]
	v_mfma_f32_16x16x32_bf16 v[36:39], v[168:171], v[192:195], v[36:39]
	v_mfma_f32_16x16x32_bf16 v[32:35], v[176:179], v[192:195], v[32:35]
	v_mfma_f32_16x16x32_bf16 v[20:23], v[168:171], v[200:203], v[20:23]
	v_mfma_f32_16x16x32_bf16 v[16:19], v[176:179], v[200:203], v[16:19]
	v_mfma_f32_16x16x32_bf16 v[4:7], v[168:171], v[208:211], v[4:7]
	v_mfma_f32_16x16x32_bf16 v[0:3], v[176:179], v[208:211], v[0:3]
	s_setprio 0
	s_waitcnt vmcnt(4)
	s_barrier
	s_add_i32 s74, s74, 2
	s_add_u32 s0, s0, 0x100
	s_addc_u32 s1, s1, 0
	s_add_u32 s72, s72, 0x100
	s_addc_u32 s73, s73, 0
	s_cmp_gt_u32 s74, 29
	s_cbranch_scc0 .LBB0_1084
	s_and_b64 vcc, exec, s[16:17]
	s_cbranch_vccz .LBB0_1087
	s_barrier

.LBB0_1318:
	s_mov_b64 s[10:11], 0x80
	s_add_i32 m0, s44, 0x18000
	v_lshl_add_u64 v[22:23], v[22:23], 0, s[10:11]
	s_waitcnt vmcnt(2)
	s_barrier
	global_load_lds_dwordx4 v[22:23], off
	v_lshl_add_u64 v[20:21], v[20:21], 0, s[10:11]
	s_add_i32 m0, s44, 0x1a000
	s_add_i32 s48, s44, 0x8000
	s_add_i32 s49, s44, 0xa000
	global_load_lds_dwordx4 v[20:21], off
	v_lshl_add_u64 v[16:17], v[16:17], 0, s[10:11]
	s_mov_b32 m0, s48
	s_add_u32 s12, s0, 0x80080
	global_load_lds_dwordx4 v[16:17], off
	v_lshl_add_u64 v[16:17], v[18:19], 0, s[10:11]
	s_mov_b32 m0, s49
	s_addc_u32 s13, s1, 0
	global_load_lds_dwordx4 v[16:17], off
	s_add_i32 m0, s44, 0x1c000
	v_lshl_add_u64 v[16:17], s[12:13], 0, v[130:131]
	global_load_lds_dwordx4 v[16:17], off
	v_lshl_add_u64 v[16:17], s[12:13], 0, v[134:135]
	s_add_i32 m0, s44, 0x1e000
	s_nop 0
	global_load_lds_dwordx4 v[16:17], off
	s_waitcnt vmcnt(6)
	s_barrier
	s_and_saveexec_b64 s[12:13], s[2:3]
	s_cbranch_execz .LBB0_1320
	v_pk_add_f32 v[10:11], v[10:11], v[14:15]
	v_pk_add_f32 v[8:9], v[8:9], v[12:13]
	v_pk_add_f32 v[4:5], v[6:7], v[4:5]
	v_pk_add_f32 v[0:1], v[2:3], v[0:1]
	v_pk_add_f32 v[2:3], v[4:5], v[10:11]
	v_pk_add_f32 v[0:1], v[0:1], v[8:9]
	s_nop 0
	v_pk_mov_b32 v[4:5], v[2:3], v[0:1] op_sel:[1,0]
	v_mov_b32_e32 v3, v1
	v_pk_add_f32 v[0:1], v[4:5], v[2:3]
	s_nop 0
	v_add_f32_e32 v0, v0, v1
	v_mov_b32_e32 v1, 0x358637bd
	v_fmac_f32_e32 v1, 0x3a000000, v0
	v_rsq_f32_e32 v0, v1
	v_lshl_add_u32 v1, v25, 2, 0
	v_add_u32_e32 v1, 0x20000, v1
	ds_write_b32 v1, v0

.LBB0_1324:
	ds_read_b128 v[140:143], v148
	ds_read_b128 v[154:157], v148 offset:1024
	ds_read_b128 v[158:161], v148 offset:2048
	ds_read_b128 v[162:165], v148 offset:3072
	ds_read_b128 v[166:169], v149
	ds_read_b128 v[170:173], v149 offset:1024
	ds_read_b128 v[174:177], v149 offset:2048
	ds_read_b128 v[178:181], v149 offset:3072
	s_add_u32 s34, s30, 0xfff80080
	s_addc_u32 s35, s31, -1
	s_cmp_eq_u32 s72, 28
	s_cselect_b32 s37, s66, s35
	s_cselect_b32 s36, s67, s34
	s_cselect_b32 s35, s68, s71
	s_cselect_b32 s34, s69, s70
	v_lshl_add_u64 v[144:145], s[30:31], 0, v[136:137]
	s_add_i32 m0, s44, 0xc000
	ds_read_b128 v[182:185], v150
	ds_read_b128 v[186:189], v150 offset:1024
	ds_read_b128 v[190:193], v150 offset:2048
	ds_read_b128 v[194:197], v150 offset:3072
	ds_read_b128 v[198:201], v150 offset:4096
	ds_read_b128 v[202:205], v150 offset:5120
	ds_read_b128 v[206:209], v150 offset:6144
	ds_read_b128 v[210:213], v150 offset:7168
	global_load_lds_dwordx4 v[144:145], off
	v_lshl_add_u64 v[144:145], s[30:31], 0, v[138:139]
	s_add_i32 m0, s44, 0xe000
	s_nop 0
	global_load_lds_dwordx4 v[144:145], off
	s_waitcnt vmcnt(8)
	s_waitcnt lgkmcnt(0)
	s_barrier
	s_setprio 1
	s_waitcnt lgkmcnt(0)
	v_mfma_f32_16x16x32_bf16 v[124:127], v[140:143], v[182:185], v[124:127]
	v_mfma_f32_16x16x32_bf16 v[120:123], v[158:161], v[182:185], v[120:123]
	v_mfma_f32_16x16x32_bf16 v[112:115], v[140:143], v[190:193], v[112:115]
	v_mfma_f32_16x16x32_bf16 v[104:107], v[158:161], v[190:193], v[104:107]
	v_mfma_f32_16x16x32_bf16 v[96:99], v[140:143], v[198:201], v[96:99]
	v_mfma_f32_16x16x32_bf16 v[88:91], v[158:161], v[198:201], v[88:91]
	v_mfma_f32_16x16x32_bf16 v[80:83], v[140:143], v[206:209], v[80:83]
	v_mfma_f32_16x16x32_bf16 v[72:75], v[158:161], v[206:209], v[72:75]
	v_mfma_f32_16x16x32_bf16 v[124:127], v[154:157], v[186:189], v[124:127]
	v_mfma_f32_16x16x32_bf16 v[120:123], v[162:165], v[186:189], v[120:123]
	v_mfma_f32_16x16x32_bf16 v[112:115], v[154:157], v[194:197], v[112:115]
	v_mfma_f32_16x16x32_bf16 v[104:107], v[162:165], v[194:197], v[104:107]
	v_mfma_f32_16x16x32_bf16 v[96:99], v[154:157], v[202:205], v[96:99]
	v_mfma_f32_16x16x32_bf16 v[88:91], v[162:165], v[202:205], v[88:91]
	v_mfma_f32_16x16x32_bf16 v[80:83], v[154:157], v[210:213], v[80:83]
	v_mfma_f32_16x16x32_bf16 v[72:75], v[162:165], v[210:213], v[72:75]
	s_setprio 0
	s_setprio 1
	v_mfma_f32_16x16x32_bf16 v[116:119], v[166:169], v[182:185], v[116:119]
	v_mfma_f32_16x16x32_bf16 v[108:111], v[174:177], v[182:185], v[108:111]
	v_mfma_f32_16x16x32_bf16 v[100:103], v[166:169], v[190:193], v[100:103]
	v_mfma_f32_16x16x32_bf16 v[92:95], v[174:177], v[190:193], v[92:95]
	v_mfma_f32_16x16x32_bf16 v[84:87], v[166:169], v[198:201], v[84:87]
	v_mfma_f32_16x16x32_bf16 v[76:79], v[174:177], v[198:201], v[76:79]
	v_mfma_f32_16x16x32_bf16 v[68:71], v[166:169], v[206:209], v[68:71]
	v_mfma_f32_16x16x32_bf16 v[64:67], v[174:177], v[206:209], v[64:67]
	v_mfma_f32_16x16x32_bf16 v[116:119], v[170:173], v[186:189], v[116:119]
	v_mfma_f32_16x16x32_bf16 v[108:111], v[178:181], v[186:189], v[108:111]
	v_mfma_f32_16x16x32_bf16 v[100:103], v[170:173], v[194:197], v[100:103]
	v_mfma_f32_16x16x32_bf16 v[92:95], v[178:181], v[194:197], v[92:95]
	v_mfma_f32_16x16x32_bf16 v[84:87], v[170:173], v[202:205], v[84:87]
	v_mfma_f32_16x16x32_bf16 v[76:79], v[178:181], v[202:205], v[76:79]
	v_mfma_f32_16x16x32_bf16 v[68:71], v[170:173], v[210:213], v[68:71]
	v_mfma_f32_16x16x32_bf16 v[64:67], v[178:181], v[210:213], v[64:67]
	s_setprio 0
	s_barrier
	s_add_i32 s73, s56, s5
	v_lshl_add_u64 v[144:145], s[34:35], 0, v[130:131]
	s_mov_b32 m0, s73
	ds_read_b128 v[182:185], v150 offset:16384
	ds_read_b128 v[186:189], v150 offset:17408
	ds_read_b128 v[190:193], v150 offset:18432
	ds_read_b128 v[194:197], v150 offset:19456
	ds_read_b128 v[198:201], v150 offset:20480
	ds_read_b128 v[202:205], v150 offset:21504
	ds_read_b128 v[206:209], v150 offset:22528
	ds_read_b128 v[210:213], v150 offset:23552
	global_load_lds_dwordx4 v[144:145], off
	s_add_i32 m0, s73, 0x2000
	s_add_u32 s74, s34, 0x80000
	v_lshl_add_u64 v[214:215], s[34:35], 0, v[134:135]
	s_addc_u32 s75, s35, 0
	s_add_i32 s73, s57, s5
	global_load_lds_dwordx4 v[214:215], off
	v_lshl_add_u64 v[216:217], s[74:75], 0, v[130:131]
	s_mov_b32 m0, s73
	v_lshl_add_u64 v[218:219], s[36:37], 0, v[132:133]
	global_load_lds_dwordx4 v[216:217], off
	v_lshl_add_u64 v[216:217], s[74:75], 0, v[134:135]
	s_add_i32 m0, s73, 0x2000
	s_nop 0
	global_load_lds_dwordx4 v[216:217], off
	v_lshl_add_u64 v[216:217], s[36:37], 0, v[128:129]
	s_mov_b32 m0, s44
	s_nop 0
	global_load_lds_dwordx4 v[216:217], off
	s_mov_b32 m0, s45
	s_nop 0
	global_load_lds_dwordx4 v[218:219], off
	s_waitcnt vmcnt(8)
	s_waitcnt lgkmcnt(0)
	s_barrier
	s_setprio 1
	s_waitcnt lgkmcnt(0)
	v_mfma_f32_16x16x32_bf16 v[60:63], v[140:143], v[182:185], v[60:63]
	v_mfma_f32_16x16x32_bf16 v[56:59], v[158:161], v[182:185], v[56:59]
	v_mfma_f32_16x16x32_bf16 v[48:51], v[140:143], v[190:193], v[48:51]
	v_mfma_f32_16x16x32_bf16 v[40:43], v[158:161], v[190:193], v[40:43]
	v_mfma_f32_16x16x32_bf16 v[32:35], v[140:143], v[198:201], v[32:35]
	v_mfma_f32_16x16x32_bf16 v[24:27], v[158:161], v[198:201], v[24:27]
	v_mfma_f32_16x16x32_bf16 v[16:19], v[140:143], v[206:209], v[16:19]
	v_mfma_f32_16x16x32_bf16 v[8:11], v[158:161], v[206:209], v[8:11]
	v_mfma_f32_16x16x32_bf16 v[60:63], v[154:157], v[186:189], v[60:63]
	v_mfma_f32_16x16x32_bf16 v[56:59], v[162:165], v[186:189], v[56:59]
	v_mfma_f32_16x16x32_bf16 v[48:51], v[154:157], v[194:197], v[48:51]
	v_mfma_f32_16x16x32_bf16 v[40:43], v[162:165], v[194:197], v[40:43]
	v_mfma_f32_16x16x32_bf16 v[32:35], v[154:157], v[202:205], v[32:35]
	v_mfma_f32_16x16x32_bf16 v[24:27], v[162:165], v[202:205], v[24:27]
	v_mfma_f32_16x16x32_bf16 v[16:19], v[154:157], v[210:213], v[16:19]
	v_mfma_f32_16x16x32_bf16 v[8:11], v[162:165], v[210:213], v[8:11]
	s_setprio 0
	s_setprio 1
	v_mfma_f32_16x16x32_bf16 v[52:55], v[166:169], v[182:185], v[52:55]
	v_mfma_f32_16x16x32_bf16 v[44:47], v[174:177], v[182:185], v[44:47]
	v_mfma_f32_16x16x32_bf16 v[36:39], v[166:169], v[190:193], v[36:39]
	v_mfma_f32_16x16x32_bf16 v[28:31], v[174:177], v[190:193], v[28:31]
	v_mfma_f32_16x16x32_bf16 v[20:23], v[166:169], v[198:201], v[20:23]
	v_mfma_f32_16x16x32_bf16 v[12:15], v[174:177], v[198:201], v[12:15]
	v_mfma_f32_16x16x32_bf16 v[4:7], v[166:169], v[206:209], v[4:7]
	v_mfma_f32_16x16x32_bf16 v[0:3], v[174:177], v[206:209], v[0:3]
	v_mfma_f32_16x16x32_bf16 v[52:55], v[170:173], v[186:189], v[52:55]
	v_mfma_f32_16x16x32_bf16 v[44:47], v[178:181], v[186:189], v[44:47]
	v_mfma_f32_16x16x32_bf16 v[36:39], v[170:173], v[194:197], v[36:39]
	v_mfma_f32_16x16x32_bf16 v[28:31], v[178:181], v[194:197], v[28:31]
	v_mfma_f32_16x16x32_bf16 v[20:23], v[170:173], v[202:205], v[20:23]
	v_mfma_f32_16x16x32_bf16 v[12:15], v[178:181], v[202:205], v[12:15]
	v_mfma_f32_16x16x32_bf16 v[4:7], v[170:173], v[210:213], v[4:7]
	v_mfma_f32_16x16x32_bf16 v[0:3], v[178:181], v[210:213], v[0:3]
	s_setprio 0
	s_barrier
	ds_read_b128 v[140:143], v151
	ds_read_b128 v[154:157], v151 offset:1024
	ds_read_b128 v[158:161], v151 offset:2048
	ds_read_b128 v[162:165], v151 offset:3072
	ds_read_b128 v[166:169], v152
	ds_read_b128 v[170:173], v152 offset:1024
	ds_read_b128 v[174:177], v152 offset:2048
	ds_read_b128 v[178:181], v152 offset:3072
	s_add_u32 s36, s36, 0x80000
	s_addc_u32 s37, s37, 0
	s_mov_b32 m0, s46
	v_lshl_add_u64 v[220:221], s[36:37], 0, v[128:129]
	ds_read_b128 v[182:185], v150 offset:32768
	ds_read_b128 v[186:189], v150 offset:33792
	ds_read_b128 v[190:193], v150 offset:34816
	ds_read_b128 v[194:197], v150 offset:35840
	ds_read_b128 v[198:201], v150 offset:36864
	ds_read_b128 v[202:205], v150 offset:37888
	ds_read_b128 v[206:209], v150 offset:38912
	ds_read_b128 v[210:213], v150 offset:39936
	global_load_lds_dwordx4 v[220:221], off
	v_lshl_add_u64 v[220:221], s[36:37], 0, v[132:133]
	s_mov_b32 m0, s47
	s_nop 0
	global_load_lds_dwordx4 v[220:221], off
	s_waitcnt vmcnt(8)
	s_waitcnt lgkmcnt(0)
	s_barrier
	s_setprio 1
	s_waitcnt lgkmcnt(0)
	v_mfma_f32_16x16x32_bf16 v[124:127], v[140:143], v[182:185], v[124:127]
	v_mfma_f32_16x16x32_bf16 v[120:123], v[158:161], v[182:185], v[120:123]
	v_mfma_f32_16x16x32_bf16 v[112:115], v[140:143], v[190:193], v[112:115]
	v_mfma_f32_16x16x32_bf16 v[104:107], v[158:161], v[190:193], v[104:107]
	v_mfma_f32_16x16x32_bf16 v[96:99], v[140:143], v[198:201], v[96:99]
	v_mfma_f32_16x16x32_bf16 v[88:91], v[158:161], v[198:201], v[88:91]
	v_mfma_f32_16x16x32_bf16 v[80:83], v[140:143], v[206:209], v[80:83]
	v_mfma_f32_16x16x32_bf16 v[72:75], v[158:161], v[206:209], v[72:75]
	v_mfma_f32_16x16x32_bf16 v[124:127], v[154:157], v[186:189], v[124:127]
	v_mfma_f32_16x16x32_bf16 v[120:123], v[162:165], v[186:189], v[120:123]
	v_mfma_f32_16x16x32_bf16 v[112:115], v[154:157], v[194:197], v[112:115]
	v_mfma_f32_16x16x32_bf16 v[104:107], v[162:165], v[194:197], v[104:107]
	v_mfma_f32_16x16x32_bf16 v[96:99], v[154:157], v[202:205], v[96:99]
	v_mfma_f32_16x16x32_bf16 v[88:91], v[162:165], v[202:205], v[88:91]
	v_mfma_f32_16x16x32_bf16 v[80:83], v[154:157], v[210:213], v[80:83]
	v_mfma_f32_16x16x32_bf16 v[72:75], v[162:165], v[210:213], v[72:75]
	s_setprio 0
	s_setprio 1
	v_mfma_f32_16x16x32_bf16 v[116:119], v[166:169], v[182:185], v[116:119]
	v_mfma_f32_16x16x32_bf16 v[108:111], v[174:177], v[182:185], v[108:111]
	v_mfma_f32_16x16x32_bf16 v[100:103], v[166:169], v[190:193], v[100:103]
	v_mfma_f32_16x16x32_bf16 v[92:95], v[174:177], v[190:193], v[92:95]
	v_mfma_f32_16x16x32_bf16 v[84:87], v[166:169], v[198:201], v[84:87]
	v_mfma_f32_16x16x32_bf16 v[76:79], v[174:177], v[198:201], v[76:79]
	v_mfma_f32_16x16x32_bf16 v[68:71], v[166:169], v[206:209], v[68:71]
	v_mfma_f32_16x16x32_bf16 v[64:67], v[174:177], v[206:209], v[64:67]
	v_mfma_f32_16x16x32_bf16 v[116:119], v[170:173], v[186:189], v[116:119]
	v_mfma_f32_16x16x32_bf16 v[108:111], v[178:181], v[186:189], v[108:111]
	v_mfma_f32_16x16x32_bf16 v[100:103], v[170:173], v[194:197], v[100:103]
	v_mfma_f32_16x16x32_bf16 v[92:95], v[178:181], v[194:197], v[92:95]
	v_mfma_f32_16x16x32_bf16 v[84:87], v[170:173], v[202:205], v[84:87]
	v_mfma_f32_16x16x32_bf16 v[76:79], v[178:181], v[202:205], v[76:79]
	v_mfma_f32_16x16x32_bf16 v[68:71], v[170:173], v[210:213], v[68:71]
	v_mfma_f32_16x16x32_bf16 v[64:67], v[178:181], v[210:213], v[64:67]
	s_setprio 0
	s_barrier
	s_add_i32 s36, s58, s5
	v_lshl_add_u64 v[144:145], v[144:145], 0, s[10:11]
	s_mov_b32 m0, s36
	ds_read_b128 v[182:185], v150 offset:49152
	ds_read_b128 v[186:189], v150 offset:50176
	ds_read_b128 v[190:193], v150 offset:51200
	ds_read_b128 v[194:197], v150 offset:52224
	ds_read_b128 v[198:201], v150 offset:53248
	ds_read_b128 v[202:205], v150 offset:54272
	ds_read_b128 v[206:209], v150 offset:55296
	ds_read_b128 v[210:213], v150 offset:56320
	global_load_lds_dwordx4 v[144:145], off
	s_add_i32 m0, s36, 0x2000
	s_add_u32 s34, s34, 0x80080
	v_lshl_add_u64 v[144:145], v[214:215], 0, s[10:11]
	s_addc_u32 s35, s35, 0
	s_add_i32 s36, s59, s5
	global_load_lds_dwordx4 v[144:145], off
	v_lshl_add_u64 v[144:145], s[34:35], 0, v[130:131]
	s_mov_b32 m0, s36
	s_nop 0
	global_load_lds_dwordx4 v[144:145], off
	v_lshl_add_u64 v[144:145], s[34:35], 0, v[134:135]
	s_add_i32 m0, s36, 0x2000
	s_nop 0
	global_load_lds_dwordx4 v[144:145], off
	v_lshl_add_u64 v[144:145], v[216:217], 0, s[10:11]
	s_mov_b32 m0, s48
	s_nop 0
	global_load_lds_dwordx4 v[144:145], off
	v_lshl_add_u64 v[144:145], v[218:219], 0, s[10:11]
	s_mov_b32 m0, s49
	s_nop 0
	global_load_lds_dwordx4 v[144:145], off
	s_waitcnt vmcnt(8)
	s_waitcnt lgkmcnt(0)
	s_barrier
	s_setprio 1
	s_waitcnt lgkmcnt(0)
	v_mfma_f32_16x16x32_bf16 v[60:63], v[140:143], v[182:185], v[60:63]
	v_mfma_f32_16x16x32_bf16 v[56:59], v[158:161], v[182:185], v[56:59]
	v_mfma_f32_16x16x32_bf16 v[48:51], v[140:143], v[190:193], v[48:51]
	v_mfma_f32_16x16x32_bf16 v[40:43], v[158:161], v[190:193], v[40:43]
	v_mfma_f32_16x16x32_bf16 v[32:35], v[140:143], v[198:201], v[32:35]
	v_mfma_f32_16x16x32_bf16 v[24:27], v[158:161], v[198:201], v[24:27]
	v_mfma_f32_16x16x32_bf16 v[16:19], v[140:143], v[206:209], v[16:19]
	v_mfma_f32_16x16x32_bf16 v[8:11], v[158:161], v[206:209], v[8:11]
	v_mfma_f32_16x16x32_bf16 v[60:63], v[154:157], v[186:189], v[60:63]
	v_mfma_f32_16x16x32_bf16 v[56:59], v[162:165], v[186:189], v[56:59]
	v_mfma_f32_16x16x32_bf16 v[48:51], v[154:157], v[194:197], v[48:51]
	v_mfma_f32_16x16x32_bf16 v[40:43], v[162:165], v[194:197], v[40:43]
	v_mfma_f32_16x16x32_bf16 v[32:35], v[154:157], v[202:205], v[32:35]
	v_mfma_f32_16x16x32_bf16 v[24:27], v[162:165], v[202:205], v[24:27]
	v_mfma_f32_16x16x32_bf16 v[16:19], v[154:157], v[210:213], v[16:19]
	v_mfma_f32_16x16x32_bf16 v[8:11], v[162:165], v[210:213], v[8:11]
	s_setprio 0
	s_setprio 1
	v_mfma_f32_16x16x32_bf16 v[52:55], v[166:169], v[182:185], v[52:55]
	v_mfma_f32_16x16x32_bf16 v[44:47], v[174:177], v[182:185], v[44:47]
	v_mfma_f32_16x16x32_bf16 v[36:39], v[166:169], v[190:193], v[36:39]
	v_mfma_f32_16x16x32_bf16 v[28:31], v[174:177], v[190:193], v[28:31]
	v_mfma_f32_16x16x32_bf16 v[20:23], v[166:169], v[198:201], v[20:23]
	v_mfma_f32_16x16x32_bf16 v[12:15], v[174:177], v[198:201], v[12:15]
	v_mfma_f32_16x16x32_bf16 v[4:7], v[166:169], v[206:209], v[4:7]
	v_mfma_f32_16x16x32_bf16 v[0:3], v[174:177], v[206:209], v[0:3]
	v_mfma_f32_16x16x32_bf16 v[52:55], v[170:173], v[186:189], v[52:55]
	v_mfma_f32_16x16x32_bf16 v[44:47], v[178:181], v[186:189], v[44:47]
	v_mfma_f32_16x16x32_bf16 v[36:39], v[170:173], v[194:197], v[36:39]
	v_mfma_f32_16x16x32_bf16 v[28:31], v[178:181], v[194:197], v[28:31]
	v_mfma_f32_16x16x32_bf16 v[20:23], v[170:173], v[202:205], v[20:23]
	v_mfma_f32_16x16x32_bf16 v[12:15], v[178:181], v[202:205], v[12:15]
	v_mfma_f32_16x16x32_bf16 v[4:7], v[170:173], v[210:213], v[4:7]
	v_mfma_f32_16x16x32_bf16 v[0:3], v[178:181], v[210:213], v[0:3]
	s_setprio 0
	s_barrier
	s_add_i32 s72, s72, 2
	s_add_u32 s30, s30, 0x100
	s_addc_u32 s31, s31, 0
	s_add_u32 s70, s70, 0x100
	s_addc_u32 s71, s71, 0
	s_cmp_gt_u32 s72, 29
	s_cbranch_scc0 .LBB0_1324
	s_and_b64 vcc, exec, s[12:13]
	s_cbranch_vccz .LBB0_1327
	s_barrier

.LBB0_1522:
	s_add_u32 s16, s94, 0xf200000
	s_addc_u32 s17, s95, 0
	s_add_u32 s18, s94, 0x12000000
	s_mov_b64 s[20:21], 0x80
	s_addc_u32 s19, s95, 0
	s_add_i32 m0, s7, 0x18000
	v_lshl_add_u64 v[6:7], v[6:7], 0, s[20:21]
	s_bfe_u32 s44, s33, 0x20006
	s_lshl_b32 s45, s2, 6
	s_waitcnt vmcnt(2)
	s_barrier
	global_load_lds_dwordx4 v[6:7], off
	v_lshl_add_u64 v[4:5], v[4:5], 0, s[20:21]
	s_add_i32 m0, s7, 0x1a000
	s_add_i32 s46, s7, 0x8000
	s_add_i32 s47, s7, 0xa000
	global_load_lds_dwordx4 v[4:5], off
	v_lshl_add_u64 v[0:1], v[0:1], 0, s[20:21]
	s_mov_b32 m0, s46
	s_add_u32 s0, s8, 0x80080
	global_load_lds_dwordx4 v[0:1], off
	v_lshl_add_u64 v[0:1], v[2:3], 0, s[20:21]
	s_mov_b32 m0, s47
	s_addc_u32 s1, s9, 0
	global_load_lds_dwordx4 v[0:1], off
	s_add_i32 m0, s7, 0x1c000
	v_lshl_add_u64 v[0:1], s[0:1], 0, v[146:147]
	global_load_lds_dwordx4 v[0:1], off
	v_lshl_add_u64 v[0:1], s[0:1], 0, v[144:145]
	s_add_i32 m0, s7, 0x1e000
	v_and_b32_e32 v182, 15, v8
	global_load_lds_dwordx4 v[0:1], off
	v_and_b32_e32 v0, 48, v8
	v_and_b32_e32 v1, 0xfffffc00, v12
	v_lshlrev_b32_e32 v3, 2, v8
	v_lshl_add_u32 v2, s2, 13, v1
	v_lshl_or_b32 v0, v182, 6, v0
	v_and_b32_e32 v3, 32, v3
	v_lshl_add_u32 v1, s44, 12, v1
	v_bitop3_b32 v2, v0, v2, v3 bitop3:0xde
	v_bitop3_b32 v184, v0, v1, v3 bitop3:0xde
	v_lshlrev_b32_e32 v0, 15, v13
	v_and_b32_e32 v0, 0xffff0000, v0
	v_lshl_add_u32 v0, v14, 12, v0
	v_and_b32_e32 v1, 1, v13
	v_lshl_or_b32 v0, v1, 6, v0
	v_lshl_add_u32 v148, v15, 1, v0
	v_lshlrev_b32_e32 v0, 15, v9
	s_cmpk_lt_u32 s33, 0x100
	v_and_b32_e32 v0, 0xffff0000, v0
	s_cselect_b64 s[24:25], -1, 0
	s_lshl_b32 s48, s44, 4
	v_lshl_add_u32 v0, v10, 12, v0
	v_and_b32_e32 v1, 1, v9
	s_waitcnt vmcnt(6)
	s_waitcnt lgkmcnt(0)
	s_add_u32 s26, s12, 0x2000
	v_lshl_or_b32 v0, v1, 6, v0
	s_addc_u32 s27, s13, 0
	v_lshl_add_u32 v150, v11, 1, v0
	s_add_i32 s49, 0, 0x10000
	s_add_i32 s50, 0, 0x14000
	v_mbcnt_lo_u32_b32 v0, -1, 0
	v_ashrrev_i32_e32 v183, 4, v8
	s_mov_b32 s23, 0
	v_mov_b32_e32 v149, v147
	v_mov_b32_e32 v151, v147
	v_add_u32_e32 v185, s49, v184
	v_add_u32_e32 v186, s50, v184
	v_add_u32_e32 v187, 0, v2
	v_mbcnt_hi_u32_b32 v188, -1, v0
	s_mov_b32 s51, 0
	s_barrier
	s_branch .LBB0_1525

.LBB0_1526:
	ds_read_b128 v[80:83], v185
	ds_read_b128 v[84:87], v185 offset:1024
	ds_read_b128 v[92:95], v185 offset:2048
	ds_read_b128 v[100:103], v185 offset:3072
	ds_read_b128 v[152:155], v186
	ds_read_b128 v[156:159], v186 offset:1024
	ds_read_b128 v[160:163], v186 offset:2048
	ds_read_b128 v[164:167], v186 offset:3072
	s_add_u32 s2, s0, 0xfff80080
	s_addc_u32 s3, s1, -1
	s_cmp_eq_u32 s58, 28
	s_cselect_b32 s31, s52, s3
	s_cselect_b32 s30, s53, s2
	s_cselect_b32 s3, s54, s57
	s_cselect_b32 s2, s55, s56
	v_lshl_add_u64 v[180:181], s[0:1], 0, v[148:149]
	s_add_i32 m0, s7, 0xc000
	ds_read_b128 v[168:171], v187
	ds_read_b128 v[172:175], v187 offset:1024
	ds_read_b128 v[176:179], v187 offset:2048
	ds_read_b128 v[190:193], v187 offset:3072
	ds_read_b128 v[194:197], v187 offset:4096
	ds_read_b128 v[198:201], v187 offset:5120
	ds_read_b128 v[202:205], v187 offset:6144
	ds_read_b128 v[206:209], v187 offset:7168
	global_load_lds_dwordx4 v[180:181], off
	v_lshl_add_u64 v[180:181], s[0:1], 0, v[150:151]
	s_add_i32 m0, s7, 0xe000
	s_nop 0
	global_load_lds_dwordx4 v[180:181], off
	s_waitcnt vmcnt(8)
	s_waitcnt lgkmcnt(0)
	s_barrier
	s_setprio 1
	s_waitcnt lgkmcnt(0)
	v_mfma_f32_16x16x32_bf16 v[136:139], v[80:83], v[168:171], v[136:139]
	v_mfma_f32_16x16x32_bf16 v[140:143], v[92:95], v[168:171], v[140:143]
	v_mfma_f32_16x16x32_bf16 v[120:123], v[80:83], v[176:179], v[120:123]
	v_mfma_f32_16x16x32_bf16 v[124:127], v[92:95], v[176:179], v[124:127]
	v_mfma_f32_16x16x32_bf16 v[104:107], v[80:83], v[194:197], v[104:107]
	v_mfma_f32_16x16x32_bf16 v[108:111], v[92:95], v[194:197], v[108:111]
	v_mfma_f32_16x16x32_bf16 v[72:75], v[80:83], v[202:205], v[72:75]
	v_mfma_f32_16x16x32_bf16 v[76:79], v[92:95], v[202:205], v[76:79]
	v_mfma_f32_16x16x32_bf16 v[136:139], v[84:87], v[172:175], v[136:139]
	v_mfma_f32_16x16x32_bf16 v[140:143], v[100:103], v[172:175], v[140:143]
	v_mfma_f32_16x16x32_bf16 v[120:123], v[84:87], v[190:193], v[120:123]
	v_mfma_f32_16x16x32_bf16 v[124:127], v[100:103], v[190:193], v[124:127]
	v_mfma_f32_16x16x32_bf16 v[104:107], v[84:87], v[198:201], v[104:107]
	v_mfma_f32_16x16x32_bf16 v[108:111], v[100:103], v[198:201], v[108:111]
	v_mfma_f32_16x16x32_bf16 v[72:75], v[84:87], v[206:209], v[72:75]
	v_mfma_f32_16x16x32_bf16 v[76:79], v[100:103], v[206:209], v[76:79]
	s_setprio 0
	s_setprio 1
	v_mfma_f32_16x16x32_bf16 v[128:131], v[152:155], v[168:171], v[128:131]
	v_mfma_f32_16x16x32_bf16 v[132:135], v[160:163], v[168:171], v[132:135]
	v_mfma_f32_16x16x32_bf16 v[112:115], v[152:155], v[176:179], v[112:115]
	v_mfma_f32_16x16x32_bf16 v[116:119], v[160:163], v[176:179], v[116:119]
	v_mfma_f32_16x16x32_bf16 v[88:91], v[152:155], v[194:197], v[88:91]
	v_mfma_f32_16x16x32_bf16 v[96:99], v[160:163], v[194:197], v[96:99]
	v_mfma_f32_16x16x32_bf16 v[64:67], v[152:155], v[202:205], v[64:67]
	v_mfma_f32_16x16x32_bf16 v[68:71], v[160:163], v[202:205], v[68:71]
	v_mfma_f32_16x16x32_bf16 v[128:131], v[156:159], v[172:175], v[128:131]
	v_mfma_f32_16x16x32_bf16 v[132:135], v[164:167], v[172:175], v[132:135]
	v_mfma_f32_16x16x32_bf16 v[112:115], v[156:159], v[190:193], v[112:115]
	v_mfma_f32_16x16x32_bf16 v[116:119], v[164:167], v[190:193], v[116:119]
	v_mfma_f32_16x16x32_bf16 v[88:91], v[156:159], v[198:201], v[88:91]
	v_mfma_f32_16x16x32_bf16 v[96:99], v[164:167], v[198:201], v[96:99]
	v_mfma_f32_16x16x32_bf16 v[64:67], v[156:159], v[206:209], v[64:67]
	v_mfma_f32_16x16x32_bf16 v[68:71], v[164:167], v[206:209], v[68:71]
	s_setprio 0
	s_barrier
	s_add_i32 s59, s49, s39
	v_lshl_add_u64 v[180:181], s[2:3], 0, v[146:147]
	s_mov_b32 m0, s59
	ds_read_b128 v[168:171], v187 offset:16384
	ds_read_b128 v[172:175], v187 offset:17408
	ds_read_b128 v[176:179], v187 offset:18432
	ds_read_b128 v[190:193], v187 offset:19456
	ds_read_b128 v[194:197], v187 offset:20480
	ds_read_b128 v[198:201], v187 offset:21504
	ds_read_b128 v[202:205], v187 offset:22528
	ds_read_b128 v[206:209], v187 offset:23552
	global_load_lds_dwordx4 v[180:181], off
	s_add_i32 m0, s59, 0x2000
	s_add_u32 s60, s2, 0x80000
	v_lshl_add_u64 v[210:211], s[2:3], 0, v[144:145]
	s_addc_u32 s61, s3, 0
	s_add_i32 s59, s50, s39
	global_load_lds_dwordx4 v[210:211], off
	v_lshl_add_u64 v[212:213], s[60:61], 0, v[146:147]
	s_mov_b32 m0, s59
	v_lshl_add_u64 v[214:215], s[30:31], 0, v[144:145]
	global_load_lds_dwordx4 v[212:213], off
	v_lshl_add_u64 v[212:213], s[60:61], 0, v[144:145]
	s_add_i32 m0, s59, 0x2000
	s_nop 0
	global_load_lds_dwordx4 v[212:213], off
	v_lshl_add_u64 v[212:213], s[30:31], 0, v[146:147]
	s_mov_b32 m0, s7
	s_nop 0
	global_load_lds_dwordx4 v[212:213], off
	s_mov_b32 m0, s41
	s_nop 0
	global_load_lds_dwordx4 v[214:215], off
	s_waitcnt vmcnt(8)
	s_waitcnt lgkmcnt(0)
	s_barrier
	s_setprio 1
	s_waitcnt lgkmcnt(0)
	v_mfma_f32_16x16x32_bf16 v[56:59], v[80:83], v[168:171], v[56:59]
	v_mfma_f32_16x16x32_bf16 v[60:63], v[92:95], v[168:171], v[60:63]
	v_mfma_f32_16x16x32_bf16 v[40:43], v[80:83], v[176:179], v[40:43]
	v_mfma_f32_16x16x32_bf16 v[44:47], v[92:95], v[176:179], v[44:47]
	v_mfma_f32_16x16x32_bf16 v[24:27], v[80:83], v[194:197], v[24:27]
	v_mfma_f32_16x16x32_bf16 v[28:31], v[92:95], v[194:197], v[28:31]
	v_mfma_f32_16x16x32_bf16 v[8:11], v[80:83], v[202:205], v[8:11]
	v_mfma_f32_16x16x32_bf16 v[12:15], v[92:95], v[202:205], v[12:15]
	v_mfma_f32_16x16x32_bf16 v[56:59], v[84:87], v[172:175], v[56:59]
	v_mfma_f32_16x16x32_bf16 v[60:63], v[100:103], v[172:175], v[60:63]
	v_mfma_f32_16x16x32_bf16 v[40:43], v[84:87], v[190:193], v[40:43]
	v_mfma_f32_16x16x32_bf16 v[44:47], v[100:103], v[190:193], v[44:47]
	v_mfma_f32_16x16x32_bf16 v[24:27], v[84:87], v[198:201], v[24:27]
	v_mfma_f32_16x16x32_bf16 v[28:31], v[100:103], v[198:201], v[28:31]
	v_mfma_f32_16x16x32_bf16 v[8:11], v[84:87], v[206:209], v[8:11]
	v_mfma_f32_16x16x32_bf16 v[12:15], v[100:103], v[206:209], v[12:15]
	s_setprio 0
	s_setprio 1
	v_mfma_f32_16x16x32_bf16 v[48:51], v[152:155], v[168:171], v[48:51]
	v_mfma_f32_16x16x32_bf16 v[52:55], v[160:163], v[168:171], v[52:55]
	v_mfma_f32_16x16x32_bf16 v[32:35], v[152:155], v[176:179], v[32:35]
	v_mfma_f32_16x16x32_bf16 v[36:39], v[160:163], v[176:179], v[36:39]
	v_mfma_f32_16x16x32_bf16 v[16:19], v[152:155], v[194:197], v[16:19]
	v_mfma_f32_16x16x32_bf16 v[20:23], v[160:163], v[194:197], v[20:23]
	v_mfma_f32_16x16x32_bf16 v[0:3], v[152:155], v[202:205], v[0:3]
	v_mfma_f32_16x16x32_bf16 v[4:7], v[160:163], v[202:205], v[4:7]
	v_mfma_f32_16x16x32_bf16 v[48:51], v[156:159], v[172:175], v[48:51]
	v_mfma_f32_16x16x32_bf16 v[52:55], v[164:167], v[172:175], v[52:55]
	v_mfma_f32_16x16x32_bf16 v[32:35], v[156:159], v[190:193], v[32:35]
	v_mfma_f32_16x16x32_bf16 v[36:39], v[164:167], v[190:193], v[36:39]
	v_mfma_f32_16x16x32_bf16 v[16:19], v[156:159], v[198:201], v[16:19]
	v_mfma_f32_16x16x32_bf16 v[20:23], v[164:167], v[198:201], v[20:23]
	v_mfma_f32_16x16x32_bf16 v[0:3], v[156:159], v[206:209], v[0:3]
	v_mfma_f32_16x16x32_bf16 v[4:7], v[164:167], v[206:209], v[4:7]
	s_setprio 0
	s_barrier
	s_add_i32 s59, 0, 0x18000
	s_add_i32 s60, 0, 0x1c000
	v_add_u32_e32 v100, s59, v184
	v_add_u32_e32 v164, s60, v184
	ds_read_b128 v[80:83], v100
	ds_read_b128 v[84:87], v100 offset:1024
	ds_read_b128 v[92:95], v100 offset:2048
	ds_read_b128 v[100:103], v100 offset:3072
	ds_read_b128 v[152:155], v164
	ds_read_b128 v[156:159], v164 offset:1024
	ds_read_b128 v[160:163], v164 offset:2048
	ds_read_b128 v[164:167], v164 offset:3072
	s_add_u32 s30, s30, 0x80000
	s_addc_u32 s31, s31, 0
	s_mov_b32 m0, s42
	v_lshl_add_u64 v[216:217], s[30:31], 0, v[146:147]
	ds_read_b128 v[168:171], v187 offset:32768
	ds_read_b128 v[172:175], v187 offset:33792
	ds_read_b128 v[176:179], v187 offset:34816
	ds_read_b128 v[190:193], v187 offset:35840
	ds_read_b128 v[194:197], v187 offset:36864
	ds_read_b128 v[198:201], v187 offset:37888
	ds_read_b128 v[202:205], v187 offset:38912
	ds_read_b128 v[206:209], v187 offset:39936
	global_load_lds_dwordx4 v[216:217], off
	v_lshl_add_u64 v[216:217], s[30:31], 0, v[144:145]
	s_mov_b32 m0, s43
	s_nop 0
	global_load_lds_dwordx4 v[216:217], off
	s_waitcnt vmcnt(8)
	s_waitcnt lgkmcnt(0)
	s_barrier
	s_setprio 1
	s_waitcnt lgkmcnt(0)
	v_mfma_f32_16x16x32_bf16 v[136:139], v[80:83], v[168:171], v[136:139]
	v_mfma_f32_16x16x32_bf16 v[140:143], v[92:95], v[168:171], v[140:143]
	v_mfma_f32_16x16x32_bf16 v[120:123], v[80:83], v[176:179], v[120:123]
	v_mfma_f32_16x16x32_bf16 v[124:127], v[92:95], v[176:179], v[124:127]
	v_mfma_f32_16x16x32_bf16 v[104:107], v[80:83], v[194:197], v[104:107]
	v_mfma_f32_16x16x32_bf16 v[108:111], v[92:95], v[194:197], v[108:111]
	v_mfma_f32_16x16x32_bf16 v[72:75], v[80:83], v[202:205], v[72:75]
	v_mfma_f32_16x16x32_bf16 v[76:79], v[92:95], v[202:205], v[76:79]
	v_mfma_f32_16x16x32_bf16 v[136:139], v[84:87], v[172:175], v[136:139]
	v_mfma_f32_16x16x32_bf16 v[140:143], v[100:103], v[172:175], v[140:143]
	v_mfma_f32_16x16x32_bf16 v[120:123], v[84:87], v[190:193], v[120:123]
	v_mfma_f32_16x16x32_bf16 v[124:127], v[100:103], v[190:193], v[124:127]
	v_mfma_f32_16x16x32_bf16 v[104:107], v[84:87], v[198:201], v[104:107]
	v_mfma_f32_16x16x32_bf16 v[108:111], v[100:103], v[198:201], v[108:111]
	v_mfma_f32_16x16x32_bf16 v[72:75], v[84:87], v[206:209], v[72:75]
	v_mfma_f32_16x16x32_bf16 v[76:79], v[100:103], v[206:209], v[76:79]
	s_setprio 0
	s_setprio 1
	v_mfma_f32_16x16x32_bf16 v[128:131], v[152:155], v[168:171], v[128:131]
	v_mfma_f32_16x16x32_bf16 v[132:135], v[160:163], v[168:171], v[132:135]
	v_mfma_f32_16x16x32_bf16 v[112:115], v[152:155], v[176:179], v[112:115]
	v_mfma_f32_16x16x32_bf16 v[116:119], v[160:163], v[176:179], v[116:119]
	v_mfma_f32_16x16x32_bf16 v[88:91], v[152:155], v[194:197], v[88:91]
	v_mfma_f32_16x16x32_bf16 v[96:99], v[160:163], v[194:197], v[96:99]
	v_mfma_f32_16x16x32_bf16 v[64:67], v[152:155], v[202:205], v[64:67]
	v_mfma_f32_16x16x32_bf16 v[68:71], v[160:163], v[202:205], v[68:71]
	v_mfma_f32_16x16x32_bf16 v[128:131], v[156:159], v[172:175], v[128:131]
	v_mfma_f32_16x16x32_bf16 v[132:135], v[164:167], v[172:175], v[132:135]
	v_mfma_f32_16x16x32_bf16 v[112:115], v[156:159], v[190:193], v[112:115]
	v_mfma_f32_16x16x32_bf16 v[116:119], v[164:167], v[190:193], v[116:119]
	v_mfma_f32_16x16x32_bf16 v[88:91], v[156:159], v[198:201], v[88:91]
	v_mfma_f32_16x16x32_bf16 v[96:99], v[164:167], v[198:201], v[96:99]
	v_mfma_f32_16x16x32_bf16 v[64:67], v[156:159], v[206:209], v[64:67]
	v_mfma_f32_16x16x32_bf16 v[68:71], v[164:167], v[206:209], v[68:71]
	s_setprio 0
	s_barrier
	s_add_i32 s30, s59, s39
	v_lshl_add_u64 v[180:181], v[180:181], 0, s[20:21]
	s_mov_b32 m0, s30
	ds_read_b128 v[168:171], v187 offset:49152
	ds_read_b128 v[172:175], v187 offset:50176
	ds_read_b128 v[176:179], v187 offset:51200
	ds_read_b128 v[190:193], v187 offset:52224
	ds_read_b128 v[194:197], v187 offset:53248
	ds_read_b128 v[198:201], v187 offset:54272
	ds_read_b128 v[202:205], v187 offset:55296
	ds_read_b128 v[206:209], v187 offset:56320
	global_load_lds_dwordx4 v[180:181], off
	s_add_i32 m0, s30, 0x2000
	s_add_u32 s2, s2, 0x80080
	v_lshl_add_u64 v[180:181], v[210:211], 0, s[20:21]
	s_addc_u32 s3, s3, 0
	s_add_i32 s30, s60, s39
	global_load_lds_dwordx4 v[180:181], off
	v_lshl_add_u64 v[180:181], s[2:3], 0, v[146:147]
	s_mov_b32 m0, s30
	s_nop 0
	global_load_lds_dwordx4 v[180:181], off
	v_lshl_add_u64 v[180:181], s[2:3], 0, v[144:145]
	s_add_i32 m0, s30, 0x2000
	s_nop 0
	global_load_lds_dwordx4 v[180:181], off
	v_lshl_add_u64 v[180:181], v[212:213], 0, s[20:21]
	s_mov_b32 m0, s46
	s_nop 0
	global_load_lds_dwordx4 v[180:181], off
	v_lshl_add_u64 v[180:181], v[214:215], 0, s[20:21]
	s_mov_b32 m0, s47
	s_nop 0
	global_load_lds_dwordx4 v[180:181], off
	s_waitcnt vmcnt(8)
	s_waitcnt lgkmcnt(0)
	s_barrier
	s_setprio 1
	s_waitcnt lgkmcnt(0)
	v_mfma_f32_16x16x32_bf16 v[56:59], v[80:83], v[168:171], v[56:59]
	v_mfma_f32_16x16x32_bf16 v[60:63], v[92:95], v[168:171], v[60:63]
	v_mfma_f32_16x16x32_bf16 v[40:43], v[80:83], v[176:179], v[40:43]
	v_mfma_f32_16x16x32_bf16 v[44:47], v[92:95], v[176:179], v[44:47]
	v_mfma_f32_16x16x32_bf16 v[24:27], v[80:83], v[194:197], v[24:27]
	v_mfma_f32_16x16x32_bf16 v[28:31], v[92:95], v[194:197], v[28:31]
	v_mfma_f32_16x16x32_bf16 v[8:11], v[80:83], v[202:205], v[8:11]
	v_mfma_f32_16x16x32_bf16 v[12:15], v[92:95], v[202:205], v[12:15]
	v_mfma_f32_16x16x32_bf16 v[56:59], v[84:87], v[172:175], v[56:59]
	v_mfma_f32_16x16x32_bf16 v[60:63], v[100:103], v[172:175], v[60:63]
	v_mfma_f32_16x16x32_bf16 v[40:43], v[84:87], v[190:193], v[40:43]
	v_mfma_f32_16x16x32_bf16 v[44:47], v[100:103], v[190:193], v[44:47]
	v_mfma_f32_16x16x32_bf16 v[24:27], v[84:87], v[198:201], v[24:27]
	v_mfma_f32_16x16x32_bf16 v[28:31], v[100:103], v[198:201], v[28:31]
	v_mfma_f32_16x16x32_bf16 v[8:11], v[84:87], v[206:209], v[8:11]
	v_mfma_f32_16x16x32_bf16 v[12:15], v[100:103], v[206:209], v[12:15]
	s_setprio 0
	s_setprio 1
	v_mfma_f32_16x16x32_bf16 v[48:51], v[152:155], v[168:171], v[48:51]
	v_mfma_f32_16x16x32_bf16 v[52:55], v[160:163], v[168:171], v[52:55]
	v_mfma_f32_16x16x32_bf16 v[32:35], v[152:155], v[176:179], v[32:35]
	v_mfma_f32_16x16x32_bf16 v[36:39], v[160:163], v[176:179], v[36:39]
	v_mfma_f32_16x16x32_bf16 v[16:19], v[152:155], v[194:197], v[16:19]
	v_mfma_f32_16x16x32_bf16 v[20:23], v[160:163], v[194:197], v[20:23]
	v_mfma_f32_16x16x32_bf16 v[0:3], v[152:155], v[202:205], v[0:3]
	v_mfma_f32_16x16x32_bf16 v[4:7], v[160:163], v[202:205], v[4:7]
	v_mfma_f32_16x16x32_bf16 v[48:51], v[156:159], v[172:175], v[48:51]
	v_mfma_f32_16x16x32_bf16 v[52:55], v[164:167], v[172:175], v[52:55]
	v_mfma_f32_16x16x32_bf16 v[32:35], v[156:159], v[190:193], v[32:35]
	v_mfma_f32_16x16x32_bf16 v[36:39], v[164:167], v[190:193], v[36:39]
	v_mfma_f32_16x16x32_bf16 v[16:19], v[156:159], v[198:201], v[16:19]
	v_mfma_f32_16x16x32_bf16 v[20:23], v[164:167], v[198:201], v[20:23]
	v_mfma_f32_16x16x32_bf16 v[0:3], v[156:159], v[206:209], v[0:3]
	v_mfma_f32_16x16x32_bf16 v[4:7], v[164:167], v[206:209], v[4:7]
	s_setprio 0
	s_barrier
	s_add_i32 s58, s58, 2
	s_add_u32 s0, s0, 0x100
	s_addc_u32 s1, s1, 0
	s_add_u32 s56, s56, 0x100
	s_addc_u32 s57, s57, 0
	s_cmp_gt_u32 s58, 29
	s_cbranch_scc0 .LBB0_1526
	s_and_b64 vcc, exec, s[24:25]
	s_cbranch_vccz .LBB0_1529
	s_barrier

.LBB0_1650:
	s_mov_b64 s[12:13], 0x80
	s_add_i32 m0, s47, 0x18000
	v_lshl_add_u64 v[22:23], v[22:23], 0, s[12:13]
	s_waitcnt vmcnt(2)
	s_barrier
	global_load_lds_dwordx4 v[22:23], off
	v_lshl_add_u64 v[20:21], v[20:21], 0, s[12:13]
	s_add_i32 m0, s47, 0x1a000
	s_add_i32 s51, s47, 0x8000
	s_add_i32 s52, s47, 0xa000
	global_load_lds_dwordx4 v[20:21], off
	v_lshl_add_u64 v[16:17], v[16:17], 0, s[12:13]
	s_mov_b32 m0, s51
	s_add_u32 s14, s10, 0x80080
	global_load_lds_dwordx4 v[16:17], off
	v_lshl_add_u64 v[16:17], v[18:19], 0, s[12:13]
	s_mov_b32 m0, s52
	s_addc_u32 s15, s11, 0
	global_load_lds_dwordx4 v[16:17], off
	s_add_i32 m0, s47, 0x1c000
	v_lshl_add_u64 v[16:17], s[14:15], 0, v[130:131]
	global_load_lds_dwordx4 v[16:17], off
	v_lshl_add_u64 v[16:17], s[14:15], 0, v[134:135]
	s_add_i32 m0, s47, 0x1e000
	s_nop 0
	global_load_lds_dwordx4 v[16:17], off
	s_waitcnt vmcnt(6)
	s_barrier
	s_and_saveexec_b64 s[14:15], s[2:3]
	s_cbranch_execz .LBB0_1652
	v_pk_add_f32 v[10:11], v[10:11], v[14:15]
	v_pk_add_f32 v[8:9], v[8:9], v[12:13]
	v_pk_add_f32 v[2:3], v[6:7], v[2:3]
	v_pk_add_f32 v[0:1], v[4:5], v[0:1]
	v_pk_add_f32 v[2:3], v[2:3], v[10:11]
	v_pk_add_f32 v[0:1], v[0:1], v[8:9]
	s_nop 0
	v_pk_mov_b32 v[4:5], v[2:3], v[0:1] op_sel:[1,0]
	v_mov_b32_e32 v3, v1
	v_pk_add_f32 v[0:1], v[4:5], v[2:3]
	s_nop 0
	v_add_f32_e32 v0, v0, v1
	v_mov_b32_e32 v1, 0x358637bd
	v_fmac_f32_e32 v1, 0x3a000000, v0
	v_rsq_f32_e32 v0, v1
	v_lshl_add_u32 v1, v25, 2, 0
	v_add_u32_e32 v1, 0x20000, v1
	ds_write_b32 v1, v0

.LBB0_1739:
.LBB0_1740:
	s_add_i32 s0, 0, 0x23f94
	s_waitcnt vmcnt(0)
	v_mov_b32_e32 v0, s0
	v_mbcnt_lo_u32_b32 v58, -1, 0
	v_mbcnt_hi_u32_b32 v58, -1, v58
	ds_read_b32 v0, v0
	v_lshlrev_b32_e32 v71, 4, v58
	v_and_b32_e32 v59, 15, v58
	s_mov_b32 s1, 0
	v_ashrrev_i32_e32 v70, 4, v58
	s_waitcnt lgkmcnt(0)
	v_readfirstlane_b32 s0, v0
	s_and_b32 s4, s0, 7
	s_mul_i32 s5, s4, 0x1400000
	s_add_u32 s5, s94, s5
	s_addc_u32 s6, s95, 0
	s_lshl_b32 s4, s4, 22
	s_sub_u32 s4, 0, s4
	s_subb_u32 s7, 0, 0
	s_add_u32 s4, s5, s4
	s_addc_u32 s5, s6, s7
	s_lshl_b32 s8, s88, 10
	v_add_u32_e32 v0, s8, v71
	v_ashrrev_i32_e32 v1, 31, v0
	v_lshrrev_b32_e32 v1, 22, v1
	v_add_u32_e32 v1, v0, v1
	v_ashrrev_i32_e32 v1, 10, v1
	v_mul_i32_i24_e32 v2, 0x400, v1
	v_sub_u32_e32 v2, v0, v2
	v_lshrrev_b32_e32 v3, 4, v2
	v_bitop3_b32 v2, v3, v2, 32 bitop3:0x6c
	v_ashrrev_i32_e32 v4, 31, v2
	v_lshrrev_b32_e32 v4, 26, v4
	v_lshlrev_b32_e32 v3, 3, v1
	v_add_u32_e32 v4, v2, v4
	v_and_b32_e32 v3, -16, v3
	v_ashrrev_i32_e32 v5, 6, v4
	v_add_u32_e32 v104, v5, v3
	v_and_b32_e32 v3, 0xc0, v4
	v_lshlrev_b32_e32 v1, 5, v1
	v_sub_u32_e32 v2, v2, v3
	v_mov_b32_e32 v3, 1
	v_and_b32_e32 v1, 32, v1
	v_ashrrev_i16_sdwa v2, v3, sext(v2) dst_sel:DWORD dst_unused:UNUSED_PAD src0_sel:DWORD src1_sel:BYTE_0
	v_add_u32_sdwa v1, v1, sext(v2) dst_sel:DWORD dst_unused:UNUSED_PAD src0_sel:DWORD src1_sel:WORD_0
	v_lshlrev_b32_e32 v2, 10, v104
	v_add_u32_e32 v0, 0x2000, v0
	v_lshl_add_u32 v62, v1, 1, v2
	v_ashrrev_i32_e32 v1, 31, v0
	v_lshrrev_b32_e32 v1, 22, v1
	v_add_u32_e32 v1, v0, v1
	v_ashrrev_i32_e32 v1, 10, v1
	v_mul_i32_i24_e32 v2, 0x400, v1
	v_sub_u32_e32 v0, v0, v2
	v_lshrrev_b32_e32 v2, 4, v0
	s_lshl_b32 s6, s0, 3
	v_bitop3_b32 v0, v2, v0, 32 bitop3:0x6c
	s_and_b32 s6, s6, 56
	s_ashr_i32 s7, s0, 5
	v_ashrrev_i32_e32 v4, 31, v0
	s_add_i32 s9, s6, s7
	v_lshrrev_b32_e32 v4, 26, v4
	s_ashr_i32 s12, s9, 5
	v_lshlrev_b32_e32 v2, 3, v1
	v_add_u32_e32 v4, v0, v4
	s_bfe_u32 s0, s0, 0x20003
	s_lshl_b32 s6, s12, 2
	v_and_b32_e32 v2, -16, v2
	v_ashrrev_i32_e32 v5, 6, v4
	s_or_b32 s6, s6, s0
	v_add_u32_e32 v108, v5, v2
	v_and_b32_e32 v2, 0xffc0, v4
	s_ashr_i32 s7, s6, 31
	v_sub_u32_e32 v0, v0, v2
	s_lshl_b64 s[6:7], s[6:7], 18
	v_lshrrev_b16_e32 v2, 7, v0
	s_add_u32 s10, s94, s6
	v_and_b32_e32 v2, 1, v2
	s_addc_u32 s11, s95, s7
	v_lshlrev_b32_e32 v1, 5, v1
	v_add_u16_e32 v0, v0, v2
	s_add_u32 s6, s10, 0x11600000
	v_and_b32_e32 v1, 32, v1
	v_ashrrev_i16_sdwa v0, v3, sext(v0) dst_sel:DWORD dst_unused:UNUSED_PAD src0_sel:DWORD src1_sel:BYTE_0
	s_addc_u32 s7, s11, 0
	s_lshl_b32 s9, s9, 7
	v_add_u32_sdwa v0, v1, sext(v0) dst_sel:DWORD dst_unused:UNUSED_PAD src0_sel:DWORD src1_sel:WORD_0
	v_lshlrev_b32_e32 v1, 10, v108
	s_lshl_b32 s12, s12, 12
	s_and_b32 s9, s9, 0xf80
	v_lshl_add_u32 v64, v0, 1, v1
	v_lshl_or_b32 v1, s88, 4, v59
	s_or_b32 s9, s12, s9
	v_add_u32_e32 v2, s9, v1
	v_ashrrev_i32_e32 v3, 31, v2
	v_lshlrev_b64 v[2:3], 12, v[2:3]
	s_lshl_b32 s0, s0, 10
	v_lshl_add_u64 v[2:3], s[4:5], 0, v[2:3]
	v_lshlrev_b32_e32 v0, 3, v70
	v_lshl_add_u64 v[2:3], v[2:3], 0, s[0:1]
	s_mov_b64 s[0:1], 0x13000000
	v_ashrrev_i32_e32 v1, 31, v0
	v_lshl_add_u64 v[60:61], v[2:3], 0, s[0:1]
	v_lshl_add_u64 v[0:1], v[0:1], 1, v[60:61]
	s_mov_b64 s[0:1], 0xc00000
	v_lshl_add_u64 v[2:3], v[0:1], 0, s[0:1]
	s_mov_b32 s0, 0xc00000
	v_add_co_u32_e32 v0, vcc, s0, v0
	s_add_i32 s22, s8, 0
	s_nop 0
	v_addc_co_u32_e32 v1, vcc, 0, v1, vcc
	v_mov_b32_e32 v63, 0
	s_mov_b32 m0, s22
	s_add_i32 s21, s22, 0x2000
	global_load_dwordx4 v[72:75], v[2:3], off offset:64
	global_load_dwordx4 v[52:55], v[2:3], off offset:128
	global_load_dwordx4 v[48:51], v[2:3], off offset:192
	global_load_dwordx4 v[44:47], v[2:3], off offset:256
	global_load_dwordx4 v[40:43], v[2:3], off offset:320
	global_load_dwordx4 v[36:39], v[2:3], off offset:384
	global_load_dwordx4 v[32:35], v[2:3], off offset:448
	global_load_dwordx4 v[28:31], v[2:3], off offset:512
	global_load_dwordx4 v[24:27], v[2:3], off offset:576
	global_load_dwordx4 v[20:23], v[2:3], off offset:640
	global_load_dwordx4 v[16:19], v[2:3], off offset:704
	global_load_dwordx4 v[12:15], v[2:3], off offset:768
	global_load_dwordx4 v[8:11], v[2:3], off offset:832
	global_load_dwordx4 v[4:7], v[2:3], off offset:896
	global_load_dwordx4 v[76:79], v[0:1], off
	s_nop 0
	global_load_dwordx4 v[0:3], v[2:3], off offset:960
	v_mov_b32_e32 v65, v63
	global_load_lds_dwordx4 v62, s[6:7]
	s_mov_b32 m0, s21
	v_lshl_add_u64 v[66:67], s[6:7], 0, v[62:63]
	v_lshl_add_u64 v[68:69], s[6:7], 0, v[64:65]
	global_load_lds_dwordx4 v64, s[6:7]
	s_add_i32 s20, s22, 0x4000
	s_mov_b64 s[6:7], 0x80
	s_add_i32 s23, s22, 0x6000
	v_lshl_add_u64 v[56:57], v[66:67], 0, s[6:7]
	s_mov_b32 m0, s20
	s_add_u32 s0, s10, 0x11620000
	global_load_lds_dwordx4 v[56:57], off
	v_lshl_add_u64 v[56:57], v[68:69], 0, s[6:7]
	s_mov_b32 m0, s23
	s_addc_u32 s1, s11, 0
	s_add_i32 s24, s22, 0x8000
	global_load_lds_dwordx4 v[56:57], off
	s_mov_b32 m0, s24
	s_add_i32 s25, s22, 0xa000
	global_load_lds_dwordx4 v62, s[0:1]
	s_mov_b32 m0, s25
	s_mov_b64 s[4:5], 0x180
	global_load_lds_dwordx4 v64, s[0:1]
	s_add_u32 s0, s10, 0x11620080
	s_addc_u32 s1, s11, 0
	s_add_i32 s26, s22, 0xc000
	s_mov_b32 m0, s26
	s_add_i32 s27, s22, 0xe000
	global_load_lds_dwordx4 v62, s[0:1]
	s_mov_b32 m0, s27
	s_add_u32 s8, s10, 0x11e00000
	global_load_lds_dwordx4 v64, s[0:1]
	s_addc_u32 s9, s11, 0
	s_add_i32 s19, s22, 0x10000
	s_mov_b64 s[0:1], 0x100
	v_lshl_add_u64 v[56:57], v[66:67], 0, s[0:1]
	s_mov_b32 m0, s19
	s_add_i32 s13, s22, 0x12000
	s_waitcnt vmcnt(0)
	s_waitcnt vmcnt(0) lgkmcnt(0)
	s_barrier
	global_load_lds_dwordx4 v[56:57], off
	v_lshl_add_u64 v[56:57], v[68:69], 0, s[0:1]
	s_mov_b32 m0, s13
	s_add_i32 s12, s22, 0x14000
	s_add_i32 s14, s22, 0x16000
	global_load_lds_dwordx4 v[56:57], off
	v_lshl_add_u64 v[56:57], v[66:67], 0, s[4:5]
	s_mov_b32 m0, s12
	s_add_u32 s28, s10, 0x11620100
	global_load_lds_dwordx4 v[56:57], off
	v_lshl_add_u64 v[56:57], v[68:69], 0, s[4:5]
	s_mov_b32 m0, s14
	s_addc_u32 s29, s11, 0
	s_add_i32 s15, s22, 0x18000
	global_load_lds_dwordx4 v[56:57], off
	s_mov_b32 m0, s15
	s_add_i32 s16, s22, 0x1a000
	global_load_lds_dwordx4 v62, s[28:29]
	s_mov_b32 m0, s16
	v_and_b32_e32 v57, 48, v58
	global_load_lds_dwordx4 v64, s[28:29]
	s_add_u32 s28, s10, 0x11620180
	s_addc_u32 s29, s11, 0
	s_add_i32 s17, s22, 0x1c000
	s_mov_b32 m0, s17
	s_add_i32 s18, s22, 0x1e000
	global_load_lds_dwordx4 v62, s[28:29]
	s_mov_b32 m0, s18
	v_lshlrev_b32_e32 v58, 2, v58
	global_load_lds_dwordx4 v64, s[28:29]
	v_lshlrev_b32_e32 v56, 6, v59
	v_and_b32_e32 v58, 32, v58
	v_bitop3_b32 v56, v56, v58, v57 bitop3:0x36
	v_and_b32_e32 v57, 0xfffffc00, v71
	v_add3_u32 v65, 0, v56, v57
	v_mov_b32_e32 v71, v65
	ds_read_b128 v[56:59], v71
	ds_read_b128 v[80:83], v71 offset:2048
	s_waitcnt lgkmcnt(0)
	v_mfma_f32_16x16x32_bf16 v[84:87], v[56:59], v[76:79], 0
	ds_read_b128 v[56:59], v71 offset:4096
	ds_read_b128 v[88:91], v71 offset:6144
	ds_read_b128 v[96:99], v71 offset:8192
	ds_read_b128 v[100:103], v71 offset:10240
	s_waitcnt lgkmcnt(0)
	v_mfma_f32_16x16x32_bf16 v[92:95], v[56:59], v[76:79], 0
	v_lshlrev_b32_e32 v56, 9, v104
	ds_read_b128 v[104:107], v71 offset:12288
	v_lshlrev_b32_e32 v57, 9, v108
	ds_read_b128 v[108:111], v71 offset:14336
	ds_read_b128 v[112:115], v71 offset:32768
	ds_read_b128 v[116:119], v71 offset:34816
	ds_read_b128 v[120:123], v71 offset:36864
	ds_read_b128 v[124:127], v71 offset:38912
	ds_read_b128 v[128:131], v71 offset:40960
	ds_read_b128 v[132:135], v71 offset:43008
	ds_read_b128 v[136:139], v71 offset:45056
	ds_read_b128 v[140:143], v71 offset:47104
	v_mfma_f32_16x16x32_bf16 v[80:83], v[80:83], v[76:79], 0
	v_sub_u32_e32 v56, v62, v56
	v_sub_u32_e32 v58, v64, v57
	v_mfma_f32_16x16x32_bf16 v[88:91], v[88:91], v[76:79], 0
	v_mfma_f32_16x16x32_bf16 v[96:99], v[96:99], v[76:79], 0
	v_mfma_f32_16x16x32_bf16 v[100:103], v[100:103], v[76:79], 0
	s_waitcnt lgkmcnt(0)
	v_mfma_f32_16x16x32_bf16 v[104:107], v[104:107], v[76:79], 0
	v_mfma_f32_16x16x32_bf16 v[108:111], v[108:111], v[76:79], 0
	ds_read_b128 v[144:147], v71 offset:15360
	ds_read_b128 v[148:151], v71 offset:13312
	ds_read_b128 v[152:155], v71 offset:11264
	ds_read_b128 v[156:159], v71 offset:9216
	ds_read_b128 v[160:163], v71 offset:7168
	ds_read_b128 v[164:167], v71 offset:5120
	ds_read_b128 v[168:171], v71 offset:3072
	ds_read_b128 v[172:175], v71 offset:1024
	v_mfma_f32_16x16x32_bf16 v[112:115], v[112:115], v[76:79], 0
	v_mfma_f32_16x16x32_bf16 v[116:119], v[116:119], v[76:79], 0
	v_mfma_f32_16x16x32_bf16 v[120:123], v[120:123], v[76:79], 0
	v_mfma_f32_16x16x32_bf16 v[124:127], v[124:127], v[76:79], 0
	v_mfma_f32_16x16x32_bf16 v[128:131], v[128:131], v[76:79], 0
	v_mfma_f32_16x16x32_bf16 v[132:135], v[132:135], v[76:79], 0
	v_mfma_f32_16x16x32_bf16 v[136:139], v[136:139], v[76:79], 0
	v_mfma_f32_16x16x32_bf16 v[76:79], v[140:143], v[76:79], 0
	s_waitcnt lgkmcnt(0)
	v_mfma_f32_16x16x32_bf16 v[84:87], v[172:175], v[72:75], v[84:87]
	v_mfma_f32_16x16x32_bf16 v[80:83], v[168:171], v[72:75], v[80:83]
	v_mfma_f32_16x16x32_bf16 v[92:95], v[164:167], v[72:75], v[92:95]
	v_mfma_f32_16x16x32_bf16 v[88:91], v[160:163], v[72:75], v[88:91]
	v_mfma_f32_16x16x32_bf16 v[96:99], v[156:159], v[72:75], v[96:99]
	v_mfma_f32_16x16x32_bf16 v[100:103], v[152:155], v[72:75], v[100:103]
	ds_read_b128 v[140:143], v71 offset:33792
	ds_read_b128 v[152:155], v71 offset:35840
	ds_read_b128 v[156:159], v71 offset:37888
	ds_read_b128 v[160:163], v71 offset:39936
	v_mfma_f32_16x16x32_bf16 v[104:107], v[148:151], v[72:75], v[104:107]
	ds_read_b128 v[148:151], v71 offset:41984
	ds_read_b128 v[164:167], v71 offset:44032
	ds_read_b128 v[168:171], v71 offset:46080
	ds_read_b128 v[172:175], v71 offset:48128
	v_mfma_f32_16x16x32_bf16 v[108:111], v[144:147], v[72:75], v[108:111]
	s_waitcnt lgkmcnt(0)
	v_mfma_f32_16x16x32_bf16 v[112:115], v[140:143], v[72:75], v[112:115]
	v_mfma_f32_16x16x32_bf16 v[116:119], v[152:155], v[72:75], v[116:119]
	v_mfma_f32_16x16x32_bf16 v[120:123], v[156:159], v[72:75], v[120:123]
	v_mfma_f32_16x16x32_bf16 v[124:127], v[160:163], v[72:75], v[124:127]
	v_mfma_f32_16x16x32_bf16 v[128:131], v[148:151], v[72:75], v[128:131]
	ds_read_b128 v[140:143], v71 offset:30720
	ds_read_b128 v[144:147], v71 offset:28672
	ds_read_b128 v[148:151], v71 offset:26624
	ds_read_b128 v[152:155], v71 offset:24576
	v_mfma_f32_16x16x32_bf16 v[132:135], v[164:167], v[72:75], v[132:135]
	v_mfma_f32_16x16x32_bf16 v[136:139], v[168:171], v[72:75], v[136:139]
	ds_read_b128 v[156:159], v71 offset:22528
	ds_read_b128 v[160:163], v71 offset:20480
	ds_read_b128 v[164:167], v71 offset:18432
	ds_read_b128 v[168:171], v71 offset:16384
	v_mfma_f32_16x16x32_bf16 v[72:75], v[172:175], v[72:75], v[76:79]
	s_waitcnt lgkmcnt(0)
	v_mfma_f32_16x16x32_bf16 v[76:79], v[168:171], v[52:55], v[84:87]
	v_mfma_f32_16x16x32_bf16 v[80:83], v[164:167], v[52:55], v[80:83]
	v_mfma_f32_16x16x32_bf16 v[84:87], v[160:163], v[52:55], v[92:95]
	v_mfma_f32_16x16x32_bf16 v[88:91], v[156:159], v[52:55], v[88:91]
	v_mfma_f32_16x16x32_bf16 v[92:95], v[152:155], v[52:55], v[96:99]
	v_mfma_f32_16x16x32_bf16 v[96:99], v[148:151], v[52:55], v[100:103]
	s_nop 2
	ds_read_b128 v[100:103], v71 offset:49152
	ds_read_b128 v[148:151], v71 offset:51200
	ds_read_b128 v[152:155], v71 offset:53248
	ds_read_b128 v[156:159], v71 offset:55296
	v_mfma_f32_16x16x32_bf16 v[104:107], v[144:147], v[52:55], v[104:107]
	ds_read_b128 v[144:147], v71 offset:57344
	ds_read_b128 v[160:163], v71 offset:59392
	ds_read_b128 v[164:167], v71 offset:61440
	ds_read_b128 v[168:171], v71 offset:63488
	v_mfma_f32_16x16x32_bf16 v[108:111], v[140:143], v[52:55], v[108:111]
	s_waitcnt lgkmcnt(0)
	v_mfma_f32_16x16x32_bf16 v[100:103], v[100:103], v[52:55], v[112:115]
	v_mfma_f32_16x16x32_bf16 v[112:115], v[148:151], v[52:55], v[116:119]
	v_mfma_f32_16x16x32_bf16 v[116:119], v[152:155], v[52:55], v[120:123]
	v_mfma_f32_16x16x32_bf16 v[120:123], v[156:159], v[52:55], v[124:127]
	v_mfma_f32_16x16x32_bf16 v[124:127], v[144:147], v[52:55], v[128:131]
	v_mfma_f32_16x16x32_bf16 v[128:131], v[160:163], v[52:55], v[132:135]
	s_nop 2
	ds_read_b128 v[132:135], v71 offset:31744
	ds_read_b128 v[140:143], v71 offset:29696
	ds_read_b128 v[144:147], v71 offset:27648
	ds_read_b128 v[148:151], v71 offset:25600
	v_mfma_f32_16x16x32_bf16 v[136:139], v[164:167], v[52:55], v[136:139]
	ds_read_b128 v[152:155], v71 offset:23552
	ds_read_b128 v[156:159], v71 offset:21504
	ds_read_b128 v[160:163], v71 offset:19456
	ds_read_b128 v[164:167], v71 offset:17408
	v_mfma_f32_16x16x32_bf16 v[52:55], v[168:171], v[52:55], v[72:75]
	s_waitcnt lgkmcnt(0)
	v_mfma_f32_16x16x32_bf16 v[72:75], v[164:167], v[48:51], v[76:79]
	v_mfma_f32_16x16x32_bf16 v[76:79], v[160:163], v[48:51], v[80:83]
	v_mfma_f32_16x16x32_bf16 v[80:83], v[156:159], v[48:51], v[84:87]
	v_mfma_f32_16x16x32_bf16 v[84:87], v[152:155], v[48:51], v[88:91]
	v_mfma_f32_16x16x32_bf16 v[88:91], v[148:151], v[48:51], v[92:95]
	v_mfma_f32_16x16x32_bf16 v[92:95], v[144:147], v[48:51], v[96:99]
	s_nop 2
	ds_read_b128 v[96:99], v71 offset:50176
	ds_read_b128 v[144:147], v71 offset:52224
	ds_read_b128 v[148:151], v71 offset:54272
	ds_read_b128 v[152:155], v71 offset:56320
	v_mfma_f32_16x16x32_bf16 v[104:107], v[140:143], v[48:51], v[104:107]
	ds_read_b128 v[140:143], v71 offset:58368
	ds_read_b128 v[156:159], v71 offset:60416
	ds_read_b128 v[160:163], v71 offset:62464
	ds_read_b128 v[164:167], v71 offset:64512
	v_mfma_f32_16x16x32_bf16 v[108:111], v[132:135], v[48:51], v[108:111]
	s_waitcnt lgkmcnt(0)
	v_mfma_f32_16x16x32_bf16 v[96:99], v[96:99], v[48:51], v[100:103]
	v_mfma_f32_16x16x32_bf16 v[100:103], v[144:147], v[48:51], v[112:115]
	v_mfma_f32_16x16x32_bf16 v[112:115], v[148:151], v[48:51], v[116:119]
	v_mfma_f32_16x16x32_bf16 v[116:119], v[152:155], v[48:51], v[120:123]
	v_mfma_f32_16x16x32_bf16 v[120:123], v[140:143], v[48:51], v[124:127]
	v_mfma_f32_16x16x32_bf16 v[124:127], v[156:159], v[48:51], v[128:131]
	v_mfma_f32_16x16x32_bf16 v[128:131], v[160:163], v[48:51], v[136:139]
	v_mfma_f32_16x16x32_bf16 v[50:53], v[164:167], v[48:51], v[52:55]
	s_mov_b64 s[28:29], 0x200
	s_mov_b32 m0, s22
	v_lshl_add_u64 v[48:49], v[66:67], 0, s[28:29]
	s_waitcnt vmcnt(0)
	s_waitcnt vmcnt(0)
	s_barrier
	global_load_lds_dwordx4 v[48:49], off
	v_lshl_add_u64 v[48:49], v[68:69], 0, s[28:29]
	s_mov_b32 m0, s21
	s_mov_b64 s[28:29], 0x280
	global_load_lds_dwordx4 v[48:49], off
	v_lshl_add_u64 v[48:49], v[66:67], 0, s[28:29]
	s_mov_b32 m0, s20
	s_nop 0
	global_load_lds_dwordx4 v[48:49], off
	v_lshl_add_u64 v[48:49], v[68:69], 0, s[28:29]
	s_mov_b32 m0, s23
	s_add_u32 s28, s10, 0x11620200
	global_load_lds_dwordx4 v[48:49], off
	s_addc_u32 s29, s11, 0
	s_mov_b32 m0, s24
	v_add_u32_e32 v48, 0x10000, v65
	global_load_lds_dwordx4 v62, s[28:29]
	s_mov_b32 m0, s25
	v_mov_b32_e32 v49, v48
	global_load_lds_dwordx4 v64, s[28:29]
	s_add_u32 s28, s10, 0x11620280
	s_addc_u32 s29, s11, 0
	s_mov_b32 m0, s26
	s_nop 0
	global_load_lds_dwordx4 v62, s[28:29]
	s_mov_b32 m0, s27
	s_nop 0
	global_load_lds_dwordx4 v64, s[28:29]
	ds_read_b128 v[132:135], v49
	ds_read_b128 v[136:139], v49 offset:2048
	s_waitcnt lgkmcnt(0)
	v_mfma_f32_16x16x32_bf16 v[72:75], v[132:135], v[44:47], v[72:75]
	ds_read_b128 v[132:135], v49 offset:4096
	v_mfma_f32_16x16x32_bf16 v[76:79], v[136:139], v[44:47], v[76:79]
	ds_read_b128 v[136:139], v49 offset:6144
	s_waitcnt lgkmcnt(0)
	v_mfma_f32_16x16x32_bf16 v[80:83], v[132:135], v[44:47], v[80:83]
	ds_read_b128 v[132:135], v49 offset:8192
	v_mfma_f32_16x16x32_bf16 v[84:87], v[136:139], v[44:47], v[84:87]
	ds_read_b128 v[136:139], v49 offset:10240
	s_waitcnt lgkmcnt(0)
	v_mfma_f32_16x16x32_bf16 v[88:91], v[132:135], v[44:47], v[88:91]
	ds_read_b128 v[132:135], v49 offset:12288
	ds_read_b128 v[140:143], v49 offset:14336
	v_mfma_f32_16x16x32_bf16 v[92:95], v[136:139], v[44:47], v[92:95]
	ds_read_b128 v[136:139], v49 offset:32768
	ds_read_b128 v[144:147], v49 offset:34816
	ds_read_b128 v[148:151], v49 offset:36864
	ds_read_b128 v[152:155], v49 offset:38912
	s_waitcnt lgkmcnt(0)
	v_mfma_f32_16x16x32_bf16 v[104:107], v[132:135], v[44:47], v[104:107]
	ds_read_b128 v[132:135], v49 offset:40960
	ds_read_b128 v[156:159], v49 offset:43008
	ds_read_b128 v[160:163], v49 offset:45056
	ds_read_b128 v[164:167], v49 offset:47104
	v_mfma_f32_16x16x32_bf16 v[108:111], v[140:143], v[44:47], v[108:111]
	v_mfma_f32_16x16x32_bf16 v[96:99], v[136:139], v[44:47], v[96:99]
	v_mfma_f32_16x16x32_bf16 v[100:103], v[144:147], v[44:47], v[100:103]
	v_mfma_f32_16x16x32_bf16 v[112:115], v[148:151], v[44:47], v[112:115]
	v_mfma_f32_16x16x32_bf16 v[116:119], v[152:155], v[44:47], v[116:119]
	s_waitcnt lgkmcnt(0)
	v_mfma_f32_16x16x32_bf16 v[120:123], v[132:135], v[44:47], v[120:123]
	ds_read_b128 v[132:135], v49 offset:15360
	ds_read_b128 v[136:139], v49 offset:13312
	ds_read_b128 v[140:143], v49 offset:11264
	ds_read_b128 v[144:147], v49 offset:9216
	v_mfma_f32_16x16x32_bf16 v[124:127], v[156:159], v[44:47], v[124:127]
	v_mfma_f32_16x16x32_bf16 v[128:131], v[160:163], v[44:47], v[128:131]
	ds_read_b128 v[148:151], v49 offset:7168
	ds_read_b128 v[152:155], v49 offset:5120
	ds_read_b128 v[156:159], v49 offset:3072
	ds_read_b128 v[160:163], v49 offset:1024
	v_mfma_f32_16x16x32_bf16 v[44:47], v[164:167], v[44:47], v[50:53]
	s_waitcnt lgkmcnt(0)
	v_mfma_f32_16x16x32_bf16 v[50:53], v[160:163], v[40:43], v[72:75]
	v_mfma_f32_16x16x32_bf16 v[72:75], v[156:159], v[40:43], v[76:79]
	v_mfma_f32_16x16x32_bf16 v[76:79], v[152:155], v[40:43], v[80:83]
	v_mfma_f32_16x16x32_bf16 v[80:83], v[148:151], v[40:43], v[84:87]
	v_mfma_f32_16x16x32_bf16 v[84:87], v[144:147], v[40:43], v[88:91]
	v_mfma_f32_16x16x32_bf16 v[88:91], v[140:143], v[40:43], v[92:95]
	s_nop 2
	ds_read_b128 v[92:95], v49 offset:33792
	ds_read_b128 v[140:143], v49 offset:35840
	ds_read_b128 v[144:147], v49 offset:37888
	ds_read_b128 v[148:151], v49 offset:39936
	v_mfma_f32_16x16x32_bf16 v[104:107], v[136:139], v[40:43], v[104:107]
	ds_read_b128 v[136:139], v49 offset:41984
	ds_read_b128 v[152:155], v49 offset:44032
	ds_read_b128 v[156:159], v49 offset:46080
	ds_read_b128 v[160:163], v49 offset:48128
	v_mfma_f32_16x16x32_bf16 v[108:111], v[132:135], v[40:43], v[108:111]
	s_waitcnt lgkmcnt(0)
	v_mfma_f32_16x16x32_bf16 v[92:95], v[92:95], v[40:43], v[96:99]
	v_mfma_f32_16x16x32_bf16 v[96:99], v[140:143], v[40:43], v[100:103]
	v_mfma_f32_16x16x32_bf16 v[100:103], v[144:147], v[40:43], v[112:115]
	v_mfma_f32_16x16x32_bf16 v[112:115], v[148:151], v[40:43], v[116:119]
	v_mfma_f32_16x16x32_bf16 v[116:119], v[136:139], v[40:43], v[120:123]
	v_mfma_f32_16x16x32_bf16 v[120:123], v[152:155], v[40:43], v[124:127]
	s_nop 2
	ds_read_b128 v[124:127], v49 offset:30720
	ds_read_b128 v[132:135], v49 offset:28672
	ds_read_b128 v[136:139], v49 offset:26624
	ds_read_b128 v[140:143], v49 offset:24576
	v_mfma_f32_16x16x32_bf16 v[128:131], v[156:159], v[40:43], v[128:131]
	ds_read_b128 v[144:147], v49 offset:22528
	ds_read_b128 v[148:151], v49 offset:20480
	ds_read_b128 v[152:155], v49 offset:18432
	ds_read_b128 v[156:159], v49 offset:16384
	v_mfma_f32_16x16x32_bf16 v[40:43], v[160:163], v[40:43], v[44:47]
	s_waitcnt lgkmcnt(0)
	v_mfma_f32_16x16x32_bf16 v[44:47], v[156:159], v[36:39], v[50:53]
	v_mfma_f32_16x16x32_bf16 v[50:53], v[152:155], v[36:39], v[72:75]
	v_mfma_f32_16x16x32_bf16 v[72:75], v[148:151], v[36:39], v[76:79]
	v_mfma_f32_16x16x32_bf16 v[76:79], v[144:147], v[36:39], v[80:83]
	v_mfma_f32_16x16x32_bf16 v[80:83], v[140:143], v[36:39], v[84:87]
	v_mfma_f32_16x16x32_bf16 v[84:87], v[136:139], v[36:39], v[88:91]
	s_nop 2
	ds_read_b128 v[88:91], v49 offset:49152
	ds_read_b128 v[136:139], v49 offset:51200
	ds_read_b128 v[140:143], v49 offset:53248
	ds_read_b128 v[144:147], v49 offset:55296
	v_mfma_f32_16x16x32_bf16 v[104:107], v[132:135], v[36:39], v[104:107]
	ds_read_b128 v[132:135], v49 offset:57344
	ds_read_b128 v[148:151], v49 offset:59392
	ds_read_b128 v[152:155], v49 offset:61440
	ds_read_b128 v[156:159], v49 offset:63488
	v_mfma_f32_16x16x32_bf16 v[108:111], v[124:127], v[36:39], v[108:111]
	s_waitcnt lgkmcnt(0)
	v_mfma_f32_16x16x32_bf16 v[88:91], v[88:91], v[36:39], v[92:95]
	v_mfma_f32_16x16x32_bf16 v[92:95], v[136:139], v[36:39], v[96:99]
	v_mfma_f32_16x16x32_bf16 v[96:99], v[140:143], v[36:39], v[100:103]
	v_mfma_f32_16x16x32_bf16 v[100:103], v[144:147], v[36:39], v[112:115]
	v_mfma_f32_16x16x32_bf16 v[112:115], v[132:135], v[36:39], v[116:119]
	v_mfma_f32_16x16x32_bf16 v[116:119], v[148:151], v[36:39], v[120:123]
	s_nop 2
	ds_read_b128 v[120:123], v49 offset:31744
	ds_read_b128 v[124:127], v49 offset:29696
	ds_read_b128 v[132:135], v49 offset:27648
	ds_read_b128 v[136:139], v49 offset:25600
	v_mfma_f32_16x16x32_bf16 v[128:131], v[152:155], v[36:39], v[128:131]
	ds_read_b128 v[140:143], v49 offset:23552
	ds_read_b128 v[144:147], v49 offset:21504
	ds_read_b128 v[148:151], v49 offset:19456
	ds_read_b128 v[152:155], v49 offset:17408
	v_mfma_f32_16x16x32_bf16 v[36:39], v[156:159], v[36:39], v[40:43]
	s_waitcnt lgkmcnt(0)
	v_mfma_f32_16x16x32_bf16 v[40:43], v[152:155], v[32:35], v[44:47]
	v_mfma_f32_16x16x32_bf16 v[44:47], v[148:151], v[32:35], v[50:53]
	v_mfma_f32_16x16x32_bf16 v[50:53], v[144:147], v[32:35], v[72:75]
	v_mfma_f32_16x16x32_bf16 v[72:75], v[140:143], v[32:35], v[76:79]
	v_mfma_f32_16x16x32_bf16 v[76:79], v[136:139], v[32:35], v[80:83]
	v_mfma_f32_16x16x32_bf16 v[80:83], v[132:135], v[32:35], v[84:87]
	s_nop 2
	ds_read_b128 v[84:87], v49 offset:50176
	ds_read_b128 v[132:135], v49 offset:52224
	ds_read_b128 v[136:139], v49 offset:54272
	ds_read_b128 v[140:143], v49 offset:56320
	v_mfma_f32_16x16x32_bf16 v[104:107], v[124:127], v[32:35], v[104:107]
	ds_read_b128 v[124:127], v49 offset:58368
	ds_read_b128 v[144:147], v49 offset:60416
	ds_read_b128 v[148:151], v49 offset:62464
	ds_read_b128 v[152:155], v49 offset:64512
	v_mfma_f32_16x16x32_bf16 v[108:111], v[120:123], v[32:35], v[108:111]
	s_waitcnt lgkmcnt(0)
	v_mfma_f32_16x16x32_bf16 v[84:87], v[84:87], v[32:35], v[88:91]
	v_mfma_f32_16x16x32_bf16 v[88:91], v[132:135], v[32:35], v[92:95]
	v_mfma_f32_16x16x32_bf16 v[92:95], v[136:139], v[32:35], v[96:99]
	v_mfma_f32_16x16x32_bf16 v[96:99], v[140:143], v[32:35], v[100:103]
	v_mfma_f32_16x16x32_bf16 v[100:103], v[124:127], v[32:35], v[112:115]
	v_mfma_f32_16x16x32_bf16 v[112:115], v[144:147], v[32:35], v[116:119]
	v_mfma_f32_16x16x32_bf16 v[116:119], v[148:151], v[32:35], v[128:131]
	v_mfma_f32_16x16x32_bf16 v[32:35], v[152:155], v[32:35], v[36:39]
	s_mov_b64 s[28:29], 0x300
	s_mov_b32 m0, s19
	s_nop 0
	v_lshl_add_u64 v[36:37], v[66:67], 0, s[28:29]
	s_waitcnt vmcnt(0)
	s_waitcnt vmcnt(0)
	s_barrier
	global_load_lds_dwordx4 v[36:37], off
	v_lshl_add_u64 v[36:37], v[68:69], 0, s[28:29]
	s_mov_b32 m0, s13
	s_mov_b64 s[28:29], 0x380
	global_load_lds_dwordx4 v[36:37], off
	v_lshl_add_u64 v[36:37], v[66:67], 0, s[28:29]
	s_mov_b32 m0, s12
	v_mov_b32_e32 v49, v65
	global_load_lds_dwordx4 v[36:37], off
	v_lshl_add_u64 v[36:37], v[68:69], 0, s[28:29]
	s_mov_b32 m0, s14
	s_add_u32 s28, s10, 0x11620300
	global_load_lds_dwordx4 v[36:37], off
	s_addc_u32 s29, s11, 0
	s_mov_b32 m0, s15
	s_nop 0
	global_load_lds_dwordx4 v62, s[28:29]
	s_mov_b32 m0, s16
	s_nop 0
	global_load_lds_dwordx4 v64, s[28:29]
	s_add_u32 s28, s10, 0x11620380
	s_addc_u32 s29, s11, 0
	s_mov_b32 m0, s17
	s_nop 0
	global_load_lds_dwordx4 v62, s[28:29]
	s_mov_b32 m0, s18
	s_nop 0
	global_load_lds_dwordx4 v64, s[28:29]
	ds_read_b128 v[36:39], v49
	ds_read_b128 v[66:69], v49 offset:2048
	s_waitcnt lgkmcnt(0)
	v_mfma_f32_16x16x32_bf16 v[36:39], v[36:39], v[28:31], v[40:43]
	s_nop 2
	ds_read_b128 v[40:43], v49 offset:4096
	v_mfma_f32_16x16x32_bf16 v[44:47], v[66:69], v[28:31], v[44:47]
	ds_read_b128 v[66:69], v49 offset:6144
	s_waitcnt lgkmcnt(0)
	v_mfma_f32_16x16x32_bf16 v[40:43], v[40:43], v[28:31], v[50:53]
	s_nop 2
	ds_read_b128 v[50:53], v49 offset:8192
	v_mfma_f32_16x16x32_bf16 v[66:69], v[66:69], v[28:31], v[72:75]
	s_nop 2
	ds_read_b128 v[72:75], v49 offset:10240
	s_waitcnt lgkmcnt(0)
	v_mfma_f32_16x16x32_bf16 v[50:53], v[50:53], v[28:31], v[76:79]
	s_nop 2
	ds_read_b128 v[76:79], v49 offset:12288
	ds_read_b128 v[120:123], v49 offset:14336
	v_mfma_f32_16x16x32_bf16 v[72:75], v[72:75], v[28:31], v[80:83]
	s_nop 2
	ds_read_b128 v[80:83], v49 offset:32768
	ds_read_b128 v[124:127], v49 offset:34816
	ds_read_b128 v[128:131], v49 offset:36864
	ds_read_b128 v[132:135], v49 offset:38912
	s_waitcnt lgkmcnt(0)
	v_mfma_f32_16x16x32_bf16 v[76:79], v[76:79], v[28:31], v[104:107]
	s_nop 2
	ds_read_b128 v[104:107], v49 offset:40960
	ds_read_b128 v[136:139], v49 offset:43008
	ds_read_b128 v[140:143], v49 offset:45056
	ds_read_b128 v[144:147], v49 offset:47104
	v_mfma_f32_16x16x32_bf16 v[108:111], v[120:123], v[28:31], v[108:111]
	v_mfma_f32_16x16x32_bf16 v[80:83], v[80:83], v[28:31], v[84:87]
	v_mfma_f32_16x16x32_bf16 v[84:87], v[124:127], v[28:31], v[88:91]
	v_mfma_f32_16x16x32_bf16 v[88:91], v[128:131], v[28:31], v[92:95]
	v_mfma_f32_16x16x32_bf16 v[92:95], v[132:135], v[28:31], v[96:99]
	s_waitcnt lgkmcnt(0)
	v_mfma_f32_16x16x32_bf16 v[96:99], v[104:107], v[28:31], v[100:103]
	v_mfma_f32_16x16x32_bf16 v[100:103], v[136:139], v[28:31], v[112:115]
	ds_read_b128 v[104:107], v49 offset:15360
	s_nop 1
	ds_read_b128 v[112:115], v49 offset:13312
	ds_read_b128 v[120:123], v49 offset:11264
	ds_read_b128 v[124:127], v49 offset:9216
	v_mfma_f32_16x16x32_bf16 v[116:119], v[140:143], v[28:31], v[116:119]
	ds_read_b128 v[128:131], v49 offset:7168
	ds_read_b128 v[132:135], v49 offset:5120
	ds_read_b128 v[136:139], v49 offset:3072
	ds_read_b128 v[140:143], v49 offset:1024
	v_mfma_f32_16x16x32_bf16 v[28:31], v[144:147], v[28:31], v[32:35]
	s_waitcnt lgkmcnt(0)
	v_mfma_f32_16x16x32_bf16 v[32:35], v[140:143], v[24:27], v[36:39]
	v_mfma_f32_16x16x32_bf16 v[36:39], v[136:139], v[24:27], v[44:47]
	v_mfma_f32_16x16x32_bf16 v[40:43], v[132:135], v[24:27], v[40:43]
	v_mfma_f32_16x16x32_bf16 v[44:47], v[128:131], v[24:27], v[66:69]
	v_mfma_f32_16x16x32_bf16 v[50:53], v[124:127], v[24:27], v[50:53]
	v_mfma_f32_16x16x32_bf16 v[66:69], v[120:123], v[24:27], v[72:75]
	s_nop 2
	ds_read_b128 v[72:75], v49 offset:33792
	ds_read_b128 v[120:123], v49 offset:35840
	ds_read_b128 v[124:127], v49 offset:37888
	ds_read_b128 v[128:131], v49 offset:39936
	v_mfma_f32_16x16x32_bf16 v[76:79], v[112:115], v[24:27], v[76:79]
	ds_read_b128 v[112:115], v49 offset:41984
	ds_read_b128 v[132:135], v49 offset:44032
	ds_read_b128 v[136:139], v49 offset:46080
	ds_read_b128 v[140:143], v49 offset:48128
	v_mfma_f32_16x16x32_bf16 v[104:107], v[104:107], v[24:27], v[108:111]
	s_waitcnt lgkmcnt(0)
	v_mfma_f32_16x16x32_bf16 v[72:75], v[72:75], v[24:27], v[80:83]
	v_mfma_f32_16x16x32_bf16 v[80:83], v[120:123], v[24:27], v[84:87]
	v_mfma_f32_16x16x32_bf16 v[84:87], v[124:127], v[24:27], v[88:91]
	v_mfma_f32_16x16x32_bf16 v[88:91], v[128:131], v[24:27], v[92:95]
	v_mfma_f32_16x16x32_bf16 v[92:95], v[112:115], v[24:27], v[96:99]
	v_mfma_f32_16x16x32_bf16 v[96:99], v[132:135], v[24:27], v[100:103]
	s_nop 2
	ds_read_b128 v[100:103], v49 offset:30720
	ds_read_b128 v[108:111], v49 offset:28672
	ds_read_b128 v[112:115], v49 offset:26624
	ds_read_b128 v[120:123], v49 offset:24576
	v_mfma_f32_16x16x32_bf16 v[116:119], v[136:139], v[24:27], v[116:119]
	ds_read_b128 v[124:127], v49 offset:22528
	ds_read_b128 v[128:131], v49 offset:20480
	ds_read_b128 v[132:135], v49 offset:18432
	ds_read_b128 v[136:139], v49 offset:16384
	v_mfma_f32_16x16x32_bf16 v[24:27], v[140:143], v[24:27], v[28:31]
	s_waitcnt lgkmcnt(0)
	v_mfma_f32_16x16x32_bf16 v[28:31], v[136:139], v[20:23], v[32:35]
	v_mfma_f32_16x16x32_bf16 v[32:35], v[132:135], v[20:23], v[36:39]
	v_mfma_f32_16x16x32_bf16 v[36:39], v[128:131], v[20:23], v[40:43]
	v_mfma_f32_16x16x32_bf16 v[40:43], v[124:127], v[20:23], v[44:47]
	v_mfma_f32_16x16x32_bf16 v[44:47], v[120:123], v[20:23], v[50:53]
	v_mfma_f32_16x16x32_bf16 v[50:53], v[112:115], v[20:23], v[66:69]
	s_nop 2
	ds_read_b128 v[66:69], v49 offset:49152
	ds_read_b128 v[112:115], v49 offset:51200
	ds_read_b128 v[120:123], v49 offset:53248
	ds_read_b128 v[124:127], v49 offset:55296
	v_mfma_f32_16x16x32_bf16 v[76:79], v[108:111], v[20:23], v[76:79]
	ds_read_b128 v[108:111], v49 offset:57344
	ds_read_b128 v[128:131], v49 offset:59392
	ds_read_b128 v[132:135], v49 offset:61440
	ds_read_b128 v[136:139], v49 offset:63488
	v_mfma_f32_16x16x32_bf16 v[100:103], v[100:103], v[20:23], v[104:107]
	s_waitcnt lgkmcnt(0)
	v_mfma_f32_16x16x32_bf16 v[66:69], v[66:69], v[20:23], v[72:75]
	v_mfma_f32_16x16x32_bf16 v[72:75], v[112:115], v[20:23], v[80:83]
	v_mfma_f32_16x16x32_bf16 v[80:83], v[120:123], v[20:23], v[84:87]
	v_mfma_f32_16x16x32_bf16 v[84:87], v[124:127], v[20:23], v[88:91]
	v_mfma_f32_16x16x32_bf16 v[88:91], v[108:111], v[20:23], v[92:95]
	v_mfma_f32_16x16x32_bf16 v[92:95], v[128:131], v[20:23], v[96:99]
	s_nop 2
	ds_read_b128 v[96:99], v49 offset:31744
	ds_read_b128 v[104:107], v49 offset:29696
	ds_read_b128 v[108:111], v49 offset:27648
	ds_read_b128 v[112:115], v49 offset:25600
	v_mfma_f32_16x16x32_bf16 v[116:119], v[132:135], v[20:23], v[116:119]
	ds_read_b128 v[120:123], v49 offset:23552
	ds_read_b128 v[124:127], v49 offset:21504
	ds_read_b128 v[128:131], v49 offset:19456
	ds_read_b128 v[132:135], v49 offset:17408
	v_mfma_f32_16x16x32_bf16 v[20:23], v[136:139], v[20:23], v[24:27]
	s_waitcnt lgkmcnt(0)
	v_mfma_f32_16x16x32_bf16 v[24:27], v[132:135], v[16:19], v[28:31]
	v_mfma_f32_16x16x32_bf16 v[28:31], v[128:131], v[16:19], v[32:35]
	v_mfma_f32_16x16x32_bf16 v[32:35], v[124:127], v[16:19], v[36:39]
	v_mfma_f32_16x16x32_bf16 v[36:39], v[120:123], v[16:19], v[40:43]
	v_mfma_f32_16x16x32_bf16 v[40:43], v[112:115], v[16:19], v[44:47]
	v_mfma_f32_16x16x32_bf16 v[50:53], v[108:111], v[16:19], v[50:53]
	s_nop 1
	ds_read_b128 v[44:47], v49 offset:50176
	ds_read_b128 v[108:111], v49 offset:52224
	ds_read_b128 v[112:115], v49 offset:54272
	ds_read_b128 v[120:123], v49 offset:56320
	v_mfma_f32_16x16x32_bf16 v[76:79], v[104:107], v[16:19], v[76:79]
	ds_read_b128 v[104:107], v49 offset:58368
	ds_read_b128 v[124:127], v49 offset:60416
	ds_read_b128 v[128:131], v49 offset:62464
	ds_read_b128 v[132:135], v49 offset:64512
	v_mfma_f32_16x16x32_bf16 v[96:99], v[96:99], v[16:19], v[100:103]
	s_waitcnt lgkmcnt(0)
	v_mfma_f32_16x16x32_bf16 v[66:69], v[44:47], v[16:19], v[66:69]
	v_mfma_f32_16x16x32_bf16 v[72:75], v[108:111], v[16:19], v[72:75]
	v_mfma_f32_16x16x32_bf16 v[80:83], v[112:115], v[16:19], v[80:83]
	v_mfma_f32_16x16x32_bf16 v[84:87], v[120:123], v[16:19], v[84:87]
	v_mfma_f32_16x16x32_bf16 v[88:91], v[104:107], v[16:19], v[88:91]
	v_mfma_f32_16x16x32_bf16 v[92:95], v[124:127], v[16:19], v[92:95]
	v_mfma_f32_16x16x32_bf16 v[100:103], v[128:131], v[16:19], v[116:119]
	v_mfma_f32_16x16x32_bf16 v[16:19], v[132:135], v[16:19], v[20:23]
	s_mov_b32 m0, s22
	v_mov_b32_e32 v57, v63
	s_waitcnt vmcnt(0)
	s_waitcnt vmcnt(0)
	s_barrier
	v_lshl_add_u64 v[44:45], s[8:9], 0, v[56:57]
	global_load_lds_dwordx4 v56, s[8:9]
	v_mov_b32_e32 v59, v63
	s_mov_b32 m0, s21
	v_lshl_add_u64 v[46:47], s[8:9], 0, v[58:59]
	global_load_lds_dwordx4 v58, s[8:9]
	v_lshl_add_u64 v[20:21], v[44:45], 0, s[6:7]
	s_mov_b32 m0, s20
	v_mov_b32_e32 v49, v48
	global_load_lds_dwordx4 v[20:21], off
	v_lshl_add_u64 v[20:21], v[46:47], 0, s[6:7]
	s_mov_b32 m0, s23
	s_add_u32 s6, s10, 0x11e10000
	global_load_lds_dwordx4 v[20:21], off
	s_addc_u32 s7, s11, 0
	s_mov_b32 m0, s24
	s_nop 0
	global_load_lds_dwordx4 v56, s[6:7]
	s_mov_b32 m0, s25
	s_nop 0
	global_load_lds_dwordx4 v58, s[6:7]
	s_add_u32 s6, s10, 0x11e10080
	s_addc_u32 s7, s11, 0
	s_mov_b32 m0, s26
	s_nop 0
	global_load_lds_dwordx4 v56, s[6:7]
	s_mov_b32 m0, s27
	s_nop 0
	global_load_lds_dwordx4 v58, s[6:7]
	ds_read_b128 v[20:23], v49
	ds_read_b128 v[104:107], v49 offset:2048
	s_waitcnt lgkmcnt(0)
	v_mfma_f32_16x16x32_bf16 v[20:23], v[20:23], v[12:15], v[24:27]
	s_nop 2
	ds_read_b128 v[24:27], v49 offset:4096
	v_mfma_f32_16x16x32_bf16 v[28:31], v[104:107], v[12:15], v[28:31]
	ds_read_b128 v[104:107], v49 offset:6144
	s_waitcnt lgkmcnt(0)
	v_mfma_f32_16x16x32_bf16 v[24:27], v[24:27], v[12:15], v[32:35]
	s_nop 2
	ds_read_b128 v[32:35], v49 offset:8192
	v_mfma_f32_16x16x32_bf16 v[36:39], v[104:107], v[12:15], v[36:39]
	ds_read_b128 v[104:107], v49 offset:10240
	s_waitcnt lgkmcnt(0)
	v_mfma_f32_16x16x32_bf16 v[32:35], v[32:35], v[12:15], v[40:43]
	s_nop 2
	ds_read_b128 v[40:43], v49 offset:12288
	ds_read_b128 v[108:111], v49 offset:14336
	v_mfma_f32_16x16x32_bf16 v[50:53], v[104:107], v[12:15], v[50:53]
	ds_read_b128 v[104:107], v49 offset:32768
	ds_read_b128 v[112:115], v49 offset:34816
	ds_read_b128 v[116:119], v49 offset:36864
	ds_read_b128 v[120:123], v49 offset:38912
	s_waitcnt lgkmcnt(0)
	v_mfma_f32_16x16x32_bf16 v[40:43], v[40:43], v[12:15], v[76:79]
	s_nop 2
	ds_read_b128 v[76:79], v49 offset:40960
	ds_read_b128 v[124:127], v49 offset:43008
	ds_read_b128 v[128:131], v49 offset:45056
	ds_read_b128 v[132:135], v49 offset:47104
	v_mfma_f32_16x16x32_bf16 v[96:99], v[108:111], v[12:15], v[96:99]
	v_mfma_f32_16x16x32_bf16 v[66:69], v[104:107], v[12:15], v[66:69]
	v_mfma_f32_16x16x32_bf16 v[72:75], v[112:115], v[12:15], v[72:75]
	v_mfma_f32_16x16x32_bf16 v[80:83], v[116:119], v[12:15], v[80:83]
	v_mfma_f32_16x16x32_bf16 v[84:87], v[120:123], v[12:15], v[84:87]
	s_waitcnt lgkmcnt(0)
	v_mfma_f32_16x16x32_bf16 v[76:79], v[76:79], v[12:15], v[88:91]
	v_mfma_f32_16x16x32_bf16 v[88:91], v[124:127], v[12:15], v[92:95]
	s_nop 2
	ds_read_b128 v[92:95], v49 offset:15360
	ds_read_b128 v[104:107], v49 offset:13312
	ds_read_b128 v[108:111], v49 offset:11264
	ds_read_b128 v[112:115], v49 offset:9216
	v_mfma_f32_16x16x32_bf16 v[100:103], v[128:131], v[12:15], v[100:103]
	ds_read_b128 v[116:119], v49 offset:7168
	ds_read_b128 v[120:123], v49 offset:5120
	ds_read_b128 v[124:127], v49 offset:3072
	ds_read_b128 v[128:131], v49 offset:1024
	v_mfma_f32_16x16x32_bf16 v[12:15], v[132:135], v[12:15], v[16:19]
	s_waitcnt lgkmcnt(0)
	v_mfma_f32_16x16x32_bf16 v[16:19], v[128:131], v[8:11], v[20:23]
	v_mfma_f32_16x16x32_bf16 v[20:23], v[124:127], v[8:11], v[28:31]
	v_mfma_f32_16x16x32_bf16 v[24:27], v[120:123], v[8:11], v[24:27]
	v_mfma_f32_16x16x32_bf16 v[28:31], v[116:119], v[8:11], v[36:39]
	v_mfma_f32_16x16x32_bf16 v[32:35], v[112:115], v[8:11], v[32:35]
	v_mfma_f32_16x16x32_bf16 v[36:39], v[108:111], v[8:11], v[50:53]
	s_nop 2
	ds_read_b128 v[50:53], v49 offset:33792
	ds_read_b128 v[108:111], v49 offset:35840
	ds_read_b128 v[112:115], v49 offset:37888
	ds_read_b128 v[116:119], v49 offset:39936
	v_mfma_f32_16x16x32_bf16 v[40:43], v[104:107], v[8:11], v[40:43]
	ds_read_b128 v[104:107], v49 offset:41984
	ds_read_b128 v[120:123], v49 offset:44032
	ds_read_b128 v[124:127], v49 offset:46080
	ds_read_b128 v[128:131], v49 offset:48128
	v_mfma_f32_16x16x32_bf16 v[92:95], v[92:95], v[8:11], v[96:99]
	s_waitcnt lgkmcnt(0)
	v_mfma_f32_16x16x32_bf16 v[50:53], v[50:53], v[8:11], v[66:69]
	v_mfma_f32_16x16x32_bf16 v[66:69], v[108:111], v[8:11], v[72:75]
	v_mfma_f32_16x16x32_bf16 v[72:75], v[112:115], v[8:11], v[80:83]
	v_mfma_f32_16x16x32_bf16 v[80:83], v[116:119], v[8:11], v[84:87]
	v_mfma_f32_16x16x32_bf16 v[76:79], v[104:107], v[8:11], v[76:79]
	v_mfma_f32_16x16x32_bf16 v[84:87], v[120:123], v[8:11], v[88:91]
	s_nop 2
	ds_read_b128 v[88:91], v49 offset:30720
	ds_read_b128 v[96:99], v49 offset:28672
	ds_read_b128 v[104:107], v49 offset:26624
	ds_read_b128 v[108:111], v49 offset:24576
	v_mfma_f32_16x16x32_bf16 v[100:103], v[124:127], v[8:11], v[100:103]
	ds_read_b128 v[112:115], v49 offset:22528
	ds_read_b128 v[116:119], v49 offset:20480
	ds_read_b128 v[120:123], v49 offset:18432
	ds_read_b128 v[124:127], v49 offset:16384
	v_mfma_f32_16x16x32_bf16 v[8:11], v[128:131], v[8:11], v[12:15]
	s_waitcnt lgkmcnt(0)
	v_mfma_f32_16x16x32_bf16 v[12:15], v[124:127], v[4:7], v[16:19]
	v_mfma_f32_16x16x32_bf16 v[16:19], v[120:123], v[4:7], v[20:23]
	v_mfma_f32_16x16x32_bf16 v[20:23], v[116:119], v[4:7], v[24:27]
	v_mfma_f32_16x16x32_bf16 v[24:27], v[112:115], v[4:7], v[28:31]
	v_mfma_f32_16x16x32_bf16 v[28:31], v[108:111], v[4:7], v[32:35]
	v_mfma_f32_16x16x32_bf16 v[32:35], v[104:107], v[4:7], v[36:39]
	s_nop 2
	ds_read_b128 v[36:39], v49 offset:49152
	ds_read_b128 v[104:107], v49 offset:51200
	ds_read_b128 v[108:111], v49 offset:53248
	ds_read_b128 v[112:115], v49 offset:55296
	v_mfma_f32_16x16x32_bf16 v[96:99], v[96:99], v[4:7], v[40:43]
	s_nop 2
	ds_read_b128 v[40:43], v49 offset:57344
	ds_read_b128 v[116:119], v49 offset:59392
	ds_read_b128 v[120:123], v49 offset:61440
	ds_read_b128 v[124:127], v49 offset:63488
	v_mfma_f32_16x16x32_bf16 v[88:91], v[88:91], v[4:7], v[92:95]
	s_waitcnt lgkmcnt(0)
	v_mfma_f32_16x16x32_bf16 v[50:53], v[36:39], v[4:7], v[50:53]
	v_mfma_f32_16x16x32_bf16 v[66:69], v[104:107], v[4:7], v[66:69]
	v_mfma_f32_16x16x32_bf16 v[72:75], v[108:111], v[4:7], v[72:75]
	v_mfma_f32_16x16x32_bf16 v[80:83], v[112:115], v[4:7], v[80:83]
	v_mfma_f32_16x16x32_bf16 v[76:79], v[40:43], v[4:7], v[76:79]
	ds_read_b128 v[92:95], v49 offset:31744
	ds_read_b128 v[36:39], v49 offset:29696
	ds_read_b128 v[40:43], v49 offset:27648
	ds_read_b128 v[104:107], v49 offset:25600
	v_mfma_f32_16x16x32_bf16 v[84:87], v[116:119], v[4:7], v[84:87]
	v_mfma_f32_16x16x32_bf16 v[100:103], v[120:123], v[4:7], v[100:103]
	ds_read_b128 v[108:111], v49 offset:23552
	ds_read_b128 v[112:115], v49 offset:21504
	ds_read_b128 v[116:119], v49 offset:19456
	ds_read_b128 v[120:123], v49 offset:17408
	v_mfma_f32_16x16x32_bf16 v[124:127], v[124:127], v[4:7], v[8:11]
	s_waitcnt lgkmcnt(0)
	v_mfma_f32_16x16x32_bf16 v[120:123], v[120:123], v[0:3], v[12:15]
	v_mfma_f32_16x16x32_bf16 v[116:119], v[116:119], v[0:3], v[16:19]
	ds_read_b128 v[4:7], v49 offset:50176
	ds_read_b128 v[8:11], v49 offset:52224
	ds_read_b128 v[12:15], v49 offset:54272
	ds_read_b128 v[16:19], v49 offset:56320
	v_mfma_f32_16x16x32_bf16 v[36:39], v[36:39], v[0:3], v[96:99]
	s_nop 2
	ds_read_b128 v[96:99], v49 offset:58368
	ds_read_b128 v[128:131], v49 offset:60416
	ds_read_b128 v[132:135], v49 offset:62464
	ds_read_b128 v[136:139], v49 offset:64512
	v_mfma_f32_16x16x32_bf16 v[112:115], v[112:115], v[0:3], v[20:23]
	v_mfma_f32_16x16x32_bf16 v[108:111], v[108:111], v[0:3], v[24:27]
	v_mfma_f32_16x16x32_bf16 v[104:107], v[104:107], v[0:3], v[28:31]
	v_mfma_f32_16x16x32_bf16 v[40:43], v[40:43], v[0:3], v[32:35]
	v_mfma_f32_16x16x32_bf16 v[32:35], v[92:95], v[0:3], v[88:91]
	s_waitcnt lgkmcnt(0)
	v_mfma_f32_16x16x32_bf16 v[28:31], v[4:7], v[0:3], v[50:53]
	v_mfma_f32_16x16x32_bf16 v[24:27], v[8:11], v[0:3], v[66:69]
	v_mfma_f32_16x16x32_bf16 v[20:23], v[12:15], v[0:3], v[72:75]
	v_mfma_f32_16x16x32_bf16 v[16:19], v[16:19], v[0:3], v[80:83]
	v_mfma_f32_16x16x32_bf16 v[12:15], v[96:99], v[0:3], v[76:79]
	v_mfma_f32_16x16x32_bf16 v[8:11], v[128:131], v[0:3], v[84:87]
	v_mfma_f32_16x16x32_bf16 v[4:7], v[132:135], v[0:3], v[100:103]
	v_mfma_f32_16x16x32_bf16 v[0:3], v[136:139], v[0:3], v[124:127]
	v_max_f32_e32 v49, v123, v123
	v_max_f32_e32 v50, v122, v122
	v_max_f32_e32 v49, v50, v49
	v_max_f32_e32 v50, v117, v117
	v_max_f32_e32 v51, v116, v116
	v_max_f32_e32 v50, v51, v50
	v_max_f32_e32 v51, v119, v119
	v_max_f32_e32 v52, v118, v118
	v_max3_f32 v49, v120, v121, v49
	v_max_f32_e32 v51, v52, v51
	v_max3_f32 v49, v49, v50, v51
	v_max_f32_e32 v50, v113, v113
	v_max_f32_e32 v51, v112, v112
	v_max_f32_e32 v50, v51, v50
	v_max_f32_e32 v51, v115, v115
	v_max_f32_e32 v52, v114, v114
	v_max_f32_e32 v51, v52, v51
	v_max3_f32 v49, v49, v50, v51
	v_max_f32_e32 v50, v109, v109
	v_max_f32_e32 v51, v108, v108
	v_max_f32_e32 v50, v51, v50
	v_max_f32_e32 v51, v111, v111
	v_max_f32_e32 v52, v110, v110
	v_max_f32_e32 v51, v52, v51
	v_max3_f32 v49, v49, v50, v51
	v_max_f32_e32 v50, v105, v105
	v_max_f32_e32 v51, v104, v104
	v_max_f32_e32 v50, v51, v50
	v_max_f32_e32 v51, v107, v107
	v_max_f32_e32 v52, v106, v106
	v_max_f32_e32 v51, v52, v51
	v_max3_f32 v49, v49, v50, v51
	v_max_f32_e32 v50, v41, v41
	v_max_f32_e32 v51, v40, v40
	v_max_f32_e32 v50, v51, v50
	v_max_f32_e32 v51, v43, v43
	v_max_f32_e32 v52, v42, v42
	v_max_f32_e32 v51, v52, v51
	v_max3_f32 v49, v49, v50, v51
	v_max_f32_e32 v50, v37, v37
	v_max_f32_e32 v51, v36, v36
	v_max_f32_e32 v50, v51, v50
	v_max_f32_e32 v51, v39, v39
	v_max_f32_e32 v52, v38, v38
	v_max_f32_e32 v51, v52, v51
	v_max3_f32 v49, v49, v50, v51
	v_max_f32_e32 v50, v33, v33
	v_max_f32_e32 v51, v32, v32
	v_max_f32_e32 v50, v51, v50
	v_max_f32_e32 v51, v35, v35
	v_max_f32_e32 v52, v34, v34
	v_max_f32_e32 v51, v52, v51
	v_max3_f32 v49, v49, v50, v51
	v_max_f32_e32 v50, v29, v29
	v_max_f32_e32 v51, v28, v28
	v_max_f32_e32 v50, v51, v50
	v_max_f32_e32 v51, v31, v31
	v_max_f32_e32 v52, v30, v30
	v_max_f32_e32 v51, v52, v51
	v_max3_f32 v49, v49, v50, v51
	v_max_f32_e32 v50, v25, v25
	v_max_f32_e32 v51, v24, v24
	v_max_f32_e32 v50, v51, v50
	v_max_f32_e32 v51, v27, v27
	v_max_f32_e32 v52, v26, v26
	v_max_f32_e32 v51, v52, v51
	v_max3_f32 v49, v49, v50, v51
	v_max_f32_e32 v50, v21, v21
	v_max_f32_e32 v51, v20, v20
	v_max_f32_e32 v50, v51, v50
	v_max_f32_e32 v51, v23, v23
	v_max_f32_e32 v52, v22, v22
	v_max_f32_e32 v51, v52, v51
	v_max3_f32 v49, v49, v50, v51
	v_max_f32_e32 v50, v17, v17
	v_max_f32_e32 v51, v16, v16
	v_max_f32_e32 v50, v51, v50
	v_max_f32_e32 v51, v19, v19
	v_max_f32_e32 v52, v18, v18
	v_max_f32_e32 v51, v52, v51
	v_max3_f32 v49, v49, v50, v51
	v_max_f32_e32 v50, v13, v13
	v_max_f32_e32 v51, v12, v12
	v_max_f32_e32 v50, v51, v50
	v_max_f32_e32 v51, v15, v15
	v_max_f32_e32 v52, v14, v14
	v_max_f32_e32 v51, v52, v51
	v_max3_f32 v49, v49, v50, v51
	v_max_f32_e32 v50, v9, v9
	v_max_f32_e32 v51, v8, v8
	v_max_f32_e32 v50, v51, v50
	v_max_f32_e32 v51, v11, v11
	v_max_f32_e32 v52, v10, v10
	v_max_f32_e32 v51, v52, v51
	v_max3_f32 v49, v49, v50, v51
	v_max_f32_e32 v50, v5, v5
	v_max_f32_e32 v51, v4, v4
	v_max_f32_e32 v50, v51, v50
	v_max_f32_e32 v51, v7, v7
	v_max_f32_e32 v52, v6, v6
	v_max_f32_e32 v51, v52, v51
	v_max3_f32 v49, v49, v50, v51
	v_max_f32_e32 v50, v1, v1
	v_max_f32_e32 v51, v0, v0
	v_max_f32_e32 v50, v51, v50
	v_max_f32_e32 v51, v3, v3
	v_max_f32_e32 v52, v2, v2
	v_max_f32_e32 v51, v52, v51
	v_max3_f32 v49, v49, v50, v51
	v_mbcnt_lo_u32_b32 v50, -1, 0
	v_mbcnt_hi_u32_b32 v50, -1, v50
	v_and_b32_e32 v52, 64, v50
	v_xor_b32_e32 v51, 16, v50
	v_add_u32_e32 v52, 64, v52
	v_cmp_lt_i32_e32 vcc, v51, v52
	s_nop 1
	v_cndmask_b32_e32 v51, v50, v51, vcc
	v_lshlrev_b32_e32 v51, 2, v51
	ds_bpermute_b32 v53, v51, v49
	s_waitcnt lgkmcnt(0)
	v_max_f32_e32 v53, v53, v53
	v_max_f32_e32 v49, v49, v53
	v_xor_b32_e32 v53, 32, v50
	v_cmp_lt_i32_e32 vcc, v53, v52
	s_nop 1
	v_cndmask_b32_e32 v50, v50, v53, vcc
	v_lshlrev_b32_e32 v50, 2, v50
	ds_bpermute_b32 v52, v50, v49
	s_waitcnt lgkmcnt(0)
	v_max_f32_e32 v52, v52, v52
	v_max_f32_e32 v49, v49, v52
	v_sub_f32_e32 v52, v120, v49
	v_exp_f32_e32 v52, v52
	v_sub_f32_e32 v53, v121, v49
	v_exp_f32_e32 v53, v53
	v_sub_f32_e32 v54, v122, v49
	v_exp_f32_e32 v54, v54
	v_sub_f32_e32 v55, v123, v49
	v_exp_f32_e32 v55, v55
	v_sub_f32_e32 v59, v116, v49
	v_add_f32_e32 v57, 0, v52
	v_exp_f32_e32 v59, v59
	v_sub_f32_e32 v62, v117, v49
	v_add_f32_e32 v57, v53, v57
	v_exp_f32_e32 v62, v62
	v_sub_f32_e32 v63, v118, v49
	v_add_f32_e32 v57, v54, v57
	v_exp_f32_e32 v63, v63
	v_sub_f32_e32 v64, v119, v49
	v_add_f32_e32 v57, v55, v57
	v_exp_f32_e32 v64, v64
	v_sub_f32_e32 v66, v112, v49
	v_add_f32_e32 v57, v59, v57
	v_exp_f32_e32 v66, v66
	v_sub_f32_e32 v67, v113, v49
	v_add_f32_e32 v57, v62, v57
	v_exp_f32_e32 v67, v67
	v_sub_f32_e32 v68, v114, v49
	v_add_f32_e32 v57, v63, v57
	v_exp_f32_e32 v68, v68
	v_sub_f32_e32 v69, v115, v49
	v_add_f32_e32 v57, v64, v57
	v_exp_f32_e32 v69, v69
	v_sub_f32_e32 v71, v108, v49
	v_add_f32_e32 v57, v66, v57
	v_exp_f32_e32 v71, v71
	v_sub_f32_e32 v72, v109, v49
	v_add_f32_e32 v57, v67, v57
	v_exp_f32_e32 v72, v72
	v_sub_f32_e32 v73, v110, v49
	v_add_f32_e32 v57, v68, v57
	v_exp_f32_e32 v73, v73
	v_sub_f32_e32 v74, v111, v49
	v_add_f32_e32 v57, v69, v57
	v_exp_f32_e32 v74, v74
	v_sub_f32_e32 v75, v104, v49
	v_add_f32_e32 v57, v71, v57
	v_exp_f32_e32 v75, v75
	v_sub_f32_e32 v76, v105, v49
	v_add_f32_e32 v57, v72, v57
	v_exp_f32_e32 v76, v76
	v_sub_f32_e32 v77, v106, v49
	v_add_f32_e32 v57, v73, v57
	v_exp_f32_e32 v77, v77
	v_sub_f32_e32 v78, v107, v49
	v_add_f32_e32 v57, v74, v57
	v_exp_f32_e32 v78, v78
	v_sub_f32_e32 v40, v40, v49
	v_add_f32_e32 v57, v75, v57
	v_exp_f32_e32 v40, v40
	v_sub_f32_e32 v41, v41, v49
	v_add_f32_e32 v57, v76, v57
	v_exp_f32_e32 v41, v41
	v_sub_f32_e32 v42, v42, v49
	v_add_f32_e32 v57, v77, v57
	v_exp_f32_e32 v42, v42
	v_sub_f32_e32 v43, v43, v49
	v_add_f32_e32 v57, v78, v57
	v_exp_f32_e32 v43, v43
	v_sub_f32_e32 v36, v36, v49
	v_add_f32_e32 v57, v40, v57
	v_exp_f32_e32 v36, v36
	v_sub_f32_e32 v37, v37, v49
	v_add_f32_e32 v57, v41, v57
	v_exp_f32_e32 v37, v37
	v_sub_f32_e32 v38, v38, v49
	v_add_f32_e32 v57, v42, v57
	v_exp_f32_e32 v38, v38
	v_sub_f32_e32 v39, v39, v49
	v_add_f32_e32 v57, v43, v57
	v_exp_f32_e32 v39, v39
	v_sub_f32_e32 v32, v32, v49
	v_add_f32_e32 v57, v36, v57
	v_exp_f32_e32 v32, v32
	v_sub_f32_e32 v33, v33, v49
	v_add_f32_e32 v57, v37, v57
	v_exp_f32_e32 v33, v33
	v_sub_f32_e32 v34, v34, v49
	v_add_f32_e32 v57, v38, v57
	v_exp_f32_e32 v34, v34
	v_sub_f32_e32 v35, v35, v49
	v_add_f32_e32 v57, v39, v57
	v_exp_f32_e32 v35, v35
	v_sub_f32_e32 v28, v28, v49
	v_add_f32_e32 v57, v32, v57
	v_exp_f32_e32 v79, v28
	v_sub_f32_e32 v28, v29, v49
	v_add_f32_e32 v57, v33, v57
	v_exp_f32_e32 v80, v28
	v_sub_f32_e32 v28, v30, v49
	v_add_f32_e32 v57, v34, v57
	v_exp_f32_e32 v81, v28
	v_sub_f32_e32 v28, v31, v49
	v_add_f32_e32 v57, v35, v57
	v_exp_f32_e32 v82, v28
	v_sub_f32_e32 v24, v24, v49
	v_add_f32_e32 v28, v79, v57
	v_exp_f32_e32 v57, v24
	v_sub_f32_e32 v24, v25, v49
	v_add_f32_e32 v28, v80, v28
	v_exp_f32_e32 v83, v24
	v_sub_f32_e32 v24, v26, v49
	v_add_f32_e32 v28, v81, v28
	v_exp_f32_e32 v84, v24
	v_sub_f32_e32 v24, v27, v49
	v_add_f32_e32 v28, v82, v28
	v_exp_f32_e32 v85, v24
	v_sub_f32_e32 v20, v20, v49
	v_add_f32_e32 v24, v57, v28
	v_exp_f32_e32 v86, v20
	v_sub_f32_e32 v20, v21, v49
	v_add_f32_e32 v24, v83, v24
	v_exp_f32_e32 v87, v20
	v_sub_f32_e32 v20, v22, v49
	v_add_f32_e32 v24, v84, v24
	v_exp_f32_e32 v88, v20
	v_sub_f32_e32 v20, v23, v49
	v_add_f32_e32 v24, v85, v24
	v_exp_f32_e32 v89, v20
	v_sub_f32_e32 v16, v16, v49
	v_add_f32_e32 v20, v86, v24
	v_exp_f32_e32 v90, v16
	v_sub_f32_e32 v16, v17, v49
	v_add_f32_e32 v20, v87, v20
	v_exp_f32_e32 v91, v16
	v_sub_f32_e32 v16, v18, v49
	v_add_f32_e32 v20, v88, v20
	v_exp_f32_e32 v92, v16
	v_sub_f32_e32 v16, v19, v49
	v_add_f32_e32 v20, v89, v20
	v_exp_f32_e32 v93, v16
	v_sub_f32_e32 v12, v12, v49
	v_add_f32_e32 v16, v90, v20
	v_exp_f32_e32 v94, v12
	v_sub_f32_e32 v12, v13, v49
	v_add_f32_e32 v16, v91, v16
	v_exp_f32_e32 v95, v12
	v_sub_f32_e32 v12, v14, v49
	v_add_f32_e32 v16, v92, v16
	v_exp_f32_e32 v96, v12
	v_sub_f32_e32 v12, v15, v49
	v_add_f32_e32 v16, v93, v16
	v_exp_f32_e32 v97, v12
	v_sub_f32_e32 v8, v8, v49
	v_add_f32_e32 v12, v94, v16
	v_exp_f32_e32 v98, v8
	v_sub_f32_e32 v8, v9, v49
	v_add_f32_e32 v12, v95, v12
	v_exp_f32_e32 v99, v8
	v_sub_f32_e32 v8, v10, v49
	v_add_f32_e32 v12, v96, v12
	v_exp_f32_e32 v100, v8
	v_sub_f32_e32 v8, v11, v49
	v_add_f32_e32 v12, v97, v12
	v_exp_f32_e32 v11, v8
	v_sub_f32_e32 v4, v4, v49
	v_add_f32_e32 v8, v98, v12
	v_exp_f32_e32 v101, v4
	v_sub_f32_e32 v4, v5, v49
	v_add_f32_e32 v8, v99, v8
	v_exp_f32_e32 v102, v4
	v_sub_f32_e32 v4, v6, v49
	v_add_f32_e32 v8, v100, v8
	v_exp_f32_e32 v103, v4
	v_sub_f32_e32 v4, v7, v49
	v_add_f32_e32 v8, v11, v8
	v_exp_f32_e32 v104, v4
	v_sub_f32_e32 v0, v0, v49
	v_add_f32_e32 v4, v101, v8
	v_exp_f32_e32 v105, v0
	v_sub_f32_e32 v0, v1, v49
	v_add_f32_e32 v4, v102, v4
	v_exp_f32_e32 v106, v0
	v_sub_f32_e32 v0, v2, v49
	v_add_f32_e32 v4, v103, v4
	v_exp_f32_e32 v107, v0
	v_sub_f32_e32 v0, v3, v49
	v_add_f32_e32 v4, v104, v4
	v_exp_f32_e32 v3, v0
	v_add_f32_e32 v0, v105, v4
	v_add_f32_e32 v0, v106, v0
	v_add_f32_e32 v0, v107, v0
	v_add_f32_e32 v0, v3, v0
	ds_bpermute_b32 v1, v51, v0
	v_cvt_pk_bf16_f32 v28, v52, v53
	v_cvt_pk_bf16_f32 v29, v54, v55
	v_cvt_pk_bf16_f32 v30, v59, v62
	v_cvt_pk_bf16_f32 v31, v63, v64
	s_waitcnt lgkmcnt(0)
	v_add_f32_e32 v0, v0, v1
	ds_bpermute_b32 v1, v50, v0
	v_cvt_pk_bf16_f32 v20, v66, v67
	v_cvt_pk_bf16_f32 v21, v68, v69
	v_cvt_pk_bf16_f32 v22, v71, v72
	v_cvt_pk_bf16_f32 v23, v73, v74
	s_waitcnt lgkmcnt(0)
	v_add_f32_e32 v49, v0, v1
	v_cvt_pk_bf16_f32 v24, v75, v76
	v_cvt_pk_bf16_f32 v25, v77, v78
	v_cvt_pk_bf16_f32 v26, v40, v41
	v_cvt_pk_bf16_f32 v27, v42, v43
	v_cvt_pk_bf16_f32 v16, v36, v37
	v_cvt_pk_bf16_f32 v17, v38, v39
	v_cvt_pk_bf16_f32 v18, v32, v33
	v_cvt_pk_bf16_f32 v19, v34, v35
	v_cvt_pk_bf16_f32 v12, v79, v80
	v_cvt_pk_bf16_f32 v13, v81, v82
	v_cvt_pk_bf16_f32 v14, v57, v83
	v_cvt_pk_bf16_f32 v15, v84, v85
	v_cvt_pk_bf16_f32 v4, v86, v87
	v_cvt_pk_bf16_f32 v5, v88, v89
	v_cvt_pk_bf16_f32 v6, v90, v91
	v_cvt_pk_bf16_f32 v7, v92, v93
	v_cvt_pk_bf16_f32 v8, v94, v95
	v_cvt_pk_bf16_f32 v9, v96, v97
	v_cvt_pk_bf16_f32 v10, v98, v99
	v_cvt_pk_bf16_f32 v11, v100, v11
	v_cvt_pk_bf16_f32 v0, v101, v102
	v_cvt_pk_bf16_f32 v1, v103, v104
	v_cvt_pk_bf16_f32 v2, v105, v106
	v_cvt_pk_bf16_f32 v3, v107, v3
	s_mov_b32 m0, s19
	v_lshl_add_u64 v[32:33], v[44:45], 0, s[0:1]
	s_waitcnt vmcnt(0)
	s_waitcnt vmcnt(0)
	s_barrier
	global_load_lds_dwordx4 v[32:33], off
	v_lshl_add_u64 v[32:33], v[46:47], 0, s[0:1]
	s_mov_b32 m0, s13
	s_add_u32 s0, s10, 0x11e10100
	global_load_lds_dwordx4 v[32:33], off
	v_lshl_add_u64 v[32:33], v[44:45], 0, s[4:5]
	s_mov_b32 m0, s12
	s_addc_u32 s1, s11, 0
	global_load_lds_dwordx4 v[32:33], off
	v_lshl_add_u64 v[32:33], v[46:47], 0, s[4:5]
	s_mov_b32 m0, s14
	v_mov_b32_e32 v64, v65
	global_load_lds_dwordx4 v[32:33], off
	s_mov_b32 m0, s15
	v_div_scale_f32 v62, vcc, 1.0, v49, 1.0
	global_load_lds_dwordx4 v56, s[0:1]
	s_mov_b32 m0, s16
	v_lshlrev_b32_e32 v54, 2, v70
	global_load_lds_dwordx4 v58, s[0:1]
	s_add_u32 s0, s10, 0x11e10180
	s_addc_u32 s1, s11, 0
	s_mov_b32 m0, s17
	v_ashrrev_i32_e32 v55, 31, v54
	global_load_lds_dwordx4 v56, s[0:1]
	s_mov_b32 m0, s18
	s_nop 0
	global_load_lds_dwordx4 v58, s[0:1]
	ds_read_b128 v[32:35], v64
	ds_read_b128 v[36:39], v64 offset:2048
	v_div_scale_f32 v57, s[0:1], v49, v49, 1.0
	v_rcp_f32_e32 v59, v57
	s_waitcnt lgkmcnt(0)
	v_mfma_f32_16x16x32_bf16 v[44:47], v[32:35], v[28:31], 0
	v_fma_f32 v40, -v57, v59, 1.0
	v_fmac_f32_e32 v59, v40, v59
	ds_read_b128 v[40:43], v64 offset:4096
	ds_read_b128 v[32:35], v64 offset:6144
	v_mul_f32_e32 v63, v62, v59
	v_fma_f32 v66, -v57, v63, v62
	v_fmac_f32_e32 v63, v66, v59
	v_mfma_f32_16x16x32_bf16 v[50:53], v[36:39], v[28:31], 0
	v_fma_f32 v36, -v57, v63, v62
	ds_read_b128 v[66:69], v64 offset:8192
	ds_read_b128 v[70:73], v64 offset:10240
	v_div_fmas_f32 v36, v36, v59, v63
	s_waitcnt lgkmcnt(0)
	v_mfma_f32_16x16x32_bf16 v[74:77], v[32:35], v[28:31], 0
	v_lshl_add_u64 v[34:35], v[54:55], 1, v[60:61]
	ds_read_b128 v[60:63], v64 offset:12288
	ds_read_b128 v[78:81], v64 offset:14336
	ds_read_b128 v[82:85], v64 offset:32768
	ds_read_b128 v[86:89], v64 offset:34816
	ds_read_b128 v[90:93], v64 offset:36864
	ds_read_b128 v[94:97], v64 offset:38912
	ds_read_b128 v[98:101], v64 offset:40960
	ds_read_b128 v[102:105], v64 offset:43008
	ds_read_b128 v[106:109], v64 offset:45056
	ds_read_b128 v[110:113], v64 offset:47104
	s_mov_b64 s[0:1], 0x1000000
	v_mfma_f32_16x16x32_bf16 v[38:41], v[40:43], v[28:31], 0
	v_div_fixup_f32 v36, v36, v49, 1.0
	v_lshl_add_u64 v[32:33], v[34:35], 0, s[0:1]
	v_mfma_f32_16x16x32_bf16 v[66:69], v[66:69], v[28:31], 0
	v_mfma_f32_16x16x32_bf16 v[70:73], v[70:73], v[28:31], 0
	s_waitcnt lgkmcnt(0)
	v_mfma_f32_16x16x32_bf16 v[60:63], v[60:63], v[28:31], 0
	v_mfma_f32_16x16x32_bf16 v[78:81], v[78:81], v[28:31], 0
	ds_read_b128 v[114:117], v64 offset:30720
	ds_read_b128 v[118:121], v64 offset:28672
	ds_read_b128 v[122:125], v64 offset:26624
	ds_read_b128 v[126:129], v64 offset:24576
	ds_read_b128 v[130:133], v64 offset:22528
	ds_read_b128 v[134:137], v64 offset:20480
	ds_read_b128 v[138:141], v64 offset:18432
	ds_read_b128 v[142:145], v64 offset:16384
	v_mfma_f32_16x16x32_bf16 v[82:85], v[82:85], v[28:31], 0
	v_mfma_f32_16x16x32_bf16 v[86:89], v[86:89], v[28:31], 0
	v_mfma_f32_16x16x32_bf16 v[90:93], v[90:93], v[28:31], 0
	v_mfma_f32_16x16x32_bf16 v[94:97], v[94:97], v[28:31], 0
	v_mfma_f32_16x16x32_bf16 v[98:101], v[98:101], v[28:31], 0
	v_mfma_f32_16x16x32_bf16 v[102:105], v[102:105], v[28:31], 0
	v_mfma_f32_16x16x32_bf16 v[106:109], v[106:109], v[28:31], 0
	v_mfma_f32_16x16x32_bf16 v[110:113], v[110:113], v[28:31], 0
	s_waitcnt lgkmcnt(0)
	v_mfma_f32_16x16x32_bf16 v[42:45], v[142:145], v[24:27], v[44:47]
	v_mfma_f32_16x16x32_bf16 v[50:53], v[138:141], v[24:27], v[50:53]
	v_mfma_f32_16x16x32_bf16 v[38:41], v[134:137], v[24:27], v[38:41]
	v_mfma_f32_16x16x32_bf16 v[74:77], v[130:133], v[24:27], v[74:77]
	v_mfma_f32_16x16x32_bf16 v[66:69], v[126:129], v[24:27], v[66:69]
	v_mfma_f32_16x16x32_bf16 v[70:73], v[122:125], v[24:27], v[70:73]
	ds_read_b128 v[122:125], v64 offset:49152
	ds_read_b128 v[126:129], v64 offset:51200
	ds_read_b128 v[130:133], v64 offset:53248
	ds_read_b128 v[134:137], v64 offset:55296
	v_mfma_f32_16x16x32_bf16 v[60:63], v[118:121], v[24:27], v[60:63]
	ds_read_b128 v[118:121], v64 offset:57344
	ds_read_b128 v[138:141], v64 offset:59392
	ds_read_b128 v[142:145], v64 offset:61440
	ds_read_b128 v[146:149], v64 offset:63488
	v_mfma_f32_16x16x32_bf16 v[78:81], v[114:117], v[24:27], v[78:81]
	s_waitcnt lgkmcnt(0)
	v_mfma_f32_16x16x32_bf16 v[82:85], v[122:125], v[24:27], v[82:85]
	v_mfma_f32_16x16x32_bf16 v[86:89], v[126:129], v[24:27], v[86:89]
	v_mfma_f32_16x16x32_bf16 v[90:93], v[130:133], v[24:27], v[90:93]
	v_mfma_f32_16x16x32_bf16 v[94:97], v[134:137], v[24:27], v[94:97]
	v_mfma_f32_16x16x32_bf16 v[98:101], v[118:121], v[24:27], v[98:101]
	ds_read_b128 v[114:117], v64 offset:15360
	ds_read_b128 v[118:121], v64 offset:13312
	ds_read_b128 v[122:125], v64 offset:11264
	ds_read_b128 v[126:129], v64 offset:9216
	v_mfma_f32_16x16x32_bf16 v[102:105], v[138:141], v[24:27], v[102:105]
	v_mfma_f32_16x16x32_bf16 v[106:109], v[142:145], v[24:27], v[106:109]
	ds_read_b128 v[130:133], v64 offset:7168
	ds_read_b128 v[134:137], v64 offset:5120
	ds_read_b128 v[138:141], v64 offset:3072
	ds_read_b128 v[142:145], v64 offset:1024
	v_mfma_f32_16x16x32_bf16 v[110:113], v[146:149], v[24:27], v[110:113]
	s_waitcnt lgkmcnt(0)
	v_mfma_f32_16x16x32_bf16 v[42:45], v[142:145], v[20:23], v[42:45]
	v_mfma_f32_16x16x32_bf16 v[50:53], v[138:141], v[20:23], v[50:53]
	v_mfma_f32_16x16x32_bf16 v[38:41], v[134:137], v[20:23], v[38:41]
	v_mfma_f32_16x16x32_bf16 v[74:77], v[130:133], v[20:23], v[74:77]
	v_mfma_f32_16x16x32_bf16 v[66:69], v[126:129], v[20:23], v[66:69]
	v_mfma_f32_16x16x32_bf16 v[70:73], v[122:125], v[20:23], v[70:73]
	ds_read_b128 v[122:125], v64 offset:33792
	ds_read_b128 v[126:129], v64 offset:35840
	ds_read_b128 v[130:133], v64 offset:37888
	ds_read_b128 v[134:137], v64 offset:39936
	v_mfma_f32_16x16x32_bf16 v[60:63], v[118:121], v[20:23], v[60:63]
	ds_read_b128 v[118:121], v64 offset:41984
	ds_read_b128 v[138:141], v64 offset:44032
	ds_read_b128 v[142:145], v64 offset:46080
	ds_read_b128 v[146:149], v64 offset:48128
	v_mfma_f32_16x16x32_bf16 v[78:81], v[114:117], v[20:23], v[78:81]
	s_waitcnt lgkmcnt(0)
	v_mfma_f32_16x16x32_bf16 v[82:85], v[122:125], v[20:23], v[82:85]
	v_mfma_f32_16x16x32_bf16 v[86:89], v[126:129], v[20:23], v[86:89]
	v_mfma_f32_16x16x32_bf16 v[90:93], v[130:133], v[20:23], v[90:93]
	v_mfma_f32_16x16x32_bf16 v[94:97], v[134:137], v[20:23], v[94:97]
	v_mfma_f32_16x16x32_bf16 v[98:101], v[118:121], v[20:23], v[98:101]
	ds_read_b128 v[114:117], v64 offset:31744
	ds_read_b128 v[118:121], v64 offset:29696
	ds_read_b128 v[122:125], v64 offset:27648
	ds_read_b128 v[126:129], v64 offset:25600
	v_mfma_f32_16x16x32_bf16 v[102:105], v[138:141], v[20:23], v[102:105]
	v_mfma_f32_16x16x32_bf16 v[106:109], v[142:145], v[20:23], v[106:109]
	ds_read_b128 v[130:133], v64 offset:23552
	ds_read_b128 v[134:137], v64 offset:21504
	ds_read_b128 v[138:141], v64 offset:19456
	ds_read_b128 v[142:145], v64 offset:17408
	v_mfma_f32_16x16x32_bf16 v[110:113], v[146:149], v[20:23], v[110:113]
	s_waitcnt lgkmcnt(0)
	v_mfma_f32_16x16x32_bf16 v[42:45], v[142:145], v[16:19], v[42:45]
	v_mfma_f32_16x16x32_bf16 v[50:53], v[138:141], v[16:19], v[50:53]
	v_mfma_f32_16x16x32_bf16 v[38:41], v[134:137], v[16:19], v[38:41]
	v_mfma_f32_16x16x32_bf16 v[74:77], v[130:133], v[16:19], v[74:77]
	v_mfma_f32_16x16x32_bf16 v[66:69], v[126:129], v[16:19], v[66:69]
	v_mfma_f32_16x16x32_bf16 v[70:73], v[122:125], v[16:19], v[70:73]
	ds_read_b128 v[122:125], v64 offset:50176
	ds_read_b128 v[126:129], v64 offset:52224
	ds_read_b128 v[130:133], v64 offset:54272
	ds_read_b128 v[134:137], v64 offset:56320
	v_mfma_f32_16x16x32_bf16 v[60:63], v[118:121], v[16:19], v[60:63]
	ds_read_b128 v[118:121], v64 offset:58368
	ds_read_b128 v[138:141], v64 offset:60416
	ds_read_b128 v[142:145], v64 offset:62464
	ds_read_b128 v[146:149], v64 offset:64512
	v_mfma_f32_16x16x32_bf16 v[78:81], v[114:117], v[16:19], v[78:81]
	s_waitcnt lgkmcnt(0)
	v_mfma_f32_16x16x32_bf16 v[82:85], v[122:125], v[16:19], v[82:85]
	v_mfma_f32_16x16x32_bf16 v[86:89], v[126:129], v[16:19], v[86:89]
	v_mfma_f32_16x16x32_bf16 v[90:93], v[130:133], v[16:19], v[90:93]
	v_mfma_f32_16x16x32_bf16 v[94:97], v[134:137], v[16:19], v[94:97]
	v_mfma_f32_16x16x32_bf16 v[98:101], v[118:121], v[16:19], v[98:101]
	v_mfma_f32_16x16x32_bf16 v[102:105], v[138:141], v[16:19], v[102:105]
	v_mfma_f32_16x16x32_bf16 v[106:109], v[142:145], v[16:19], v[106:109]
	v_mfma_f32_16x16x32_bf16 v[110:113], v[146:149], v[16:19], v[110:113]
	s_add_u32 s0, s10, 0x11e20000
	s_mov_b32 m0, s22
	s_addc_u32 s1, s11, 0
	s_waitcnt vmcnt(0)
	s_waitcnt vmcnt(0)
	s_barrier
	global_load_lds_dwordx4 v56, s[0:1]
	s_mov_b32 m0, s21
	v_mov_b32_e32 v37, v48
	global_load_lds_dwordx4 v58, s[0:1]
	s_add_u32 s0, s10, 0x11e20080
	s_addc_u32 s1, s11, 0
	s_mov_b32 m0, s20
	s_nop 0
	global_load_lds_dwordx4 v56, s[0:1]
	s_mov_b32 m0, s23
	s_nop 0
	global_load_lds_dwordx4 v58, s[0:1]
	s_add_u32 s0, s10, 0x11e30000
	s_addc_u32 s1, s11, 0
	s_mov_b32 m0, s24
	s_nop 0
	global_load_lds_dwordx4 v56, s[0:1]
	s_mov_b32 m0, s25
	s_nop 0
	global_load_lds_dwordx4 v58, s[0:1]
	s_add_u32 s0, s10, 0x11e30080
	s_addc_u32 s1, s11, 0
	s_mov_b32 m0, s26
	s_nop 0
	global_load_lds_dwordx4 v56, s[0:1]
	s_mov_b32 m0, s27
	s_nop 0
	global_load_lds_dwordx4 v58, s[0:1]
	ds_read_b128 v[114:117], v37
	ds_read_b128 v[118:121], v37 offset:2048
	s_waitcnt lgkmcnt(0)
	v_mfma_f32_16x16x32_bf16 v[42:45], v[114:117], v[12:15], v[42:45]
	ds_read_b128 v[114:117], v37 offset:4096
	v_mfma_f32_16x16x32_bf16 v[50:53], v[118:121], v[12:15], v[50:53]
	ds_read_b128 v[118:121], v37 offset:6144
	s_waitcnt lgkmcnt(0)
	v_mfma_f32_16x16x32_bf16 v[38:41], v[114:117], v[12:15], v[38:41]
	ds_read_b128 v[114:117], v37 offset:8192
	v_mfma_f32_16x16x32_bf16 v[74:77], v[118:121], v[12:15], v[74:77]
	ds_read_b128 v[118:121], v37 offset:10240
	s_waitcnt lgkmcnt(0)
	v_mfma_f32_16x16x32_bf16 v[66:69], v[114:117], v[12:15], v[66:69]
	ds_read_b128 v[114:117], v37 offset:12288
	ds_read_b128 v[122:125], v37 offset:14336
	v_mfma_f32_16x16x32_bf16 v[70:73], v[118:121], v[12:15], v[70:73]
	ds_read_b128 v[118:121], v37 offset:32768
	ds_read_b128 v[126:129], v37 offset:34816
	ds_read_b128 v[130:133], v37 offset:36864
	ds_read_b128 v[134:137], v37 offset:38912
	s_waitcnt lgkmcnt(0)
	v_mfma_f32_16x16x32_bf16 v[60:63], v[114:117], v[12:15], v[60:63]
	ds_read_b128 v[114:117], v37 offset:40960
	ds_read_b128 v[138:141], v37 offset:43008
	ds_read_b128 v[142:145], v37 offset:45056
	ds_read_b128 v[146:149], v37 offset:47104
	v_mfma_f32_16x16x32_bf16 v[78:81], v[122:125], v[12:15], v[78:81]
	v_mfma_f32_16x16x32_bf16 v[82:85], v[118:121], v[12:15], v[82:85]
	v_mfma_f32_16x16x32_bf16 v[86:89], v[126:129], v[12:15], v[86:89]
	v_mfma_f32_16x16x32_bf16 v[90:93], v[130:133], v[12:15], v[90:93]
	v_mfma_f32_16x16x32_bf16 v[94:97], v[134:137], v[12:15], v[94:97]
	s_waitcnt lgkmcnt(0)
	v_mfma_f32_16x16x32_bf16 v[98:101], v[114:117], v[12:15], v[98:101]
	ds_read_b128 v[114:117], v37 offset:30720
	ds_read_b128 v[118:121], v37 offset:28672
	ds_read_b128 v[122:125], v37 offset:26624
	ds_read_b128 v[126:129], v37 offset:24576
	v_mfma_f32_16x16x32_bf16 v[102:105], v[138:141], v[12:15], v[102:105]
	v_mfma_f32_16x16x32_bf16 v[106:109], v[142:145], v[12:15], v[106:109]
	ds_read_b128 v[130:133], v37 offset:22528
	ds_read_b128 v[134:137], v37 offset:20480
	ds_read_b128 v[138:141], v37 offset:18432
	ds_read_b128 v[142:145], v37 offset:16384
	v_mfma_f32_16x16x32_bf16 v[110:113], v[146:149], v[12:15], v[110:113]
	s_waitcnt lgkmcnt(0)
	v_mfma_f32_16x16x32_bf16 v[42:45], v[142:145], v[8:11], v[42:45]
	v_mfma_f32_16x16x32_bf16 v[50:53], v[138:141], v[8:11], v[50:53]
	v_mfma_f32_16x16x32_bf16 v[38:41], v[134:137], v[8:11], v[38:41]
	v_mfma_f32_16x16x32_bf16 v[74:77], v[130:133], v[8:11], v[74:77]
	v_mfma_f32_16x16x32_bf16 v[66:69], v[126:129], v[8:11], v[66:69]
	v_mfma_f32_16x16x32_bf16 v[70:73], v[122:125], v[8:11], v[70:73]
	ds_read_b128 v[122:125], v37 offset:49152
	ds_read_b128 v[126:129], v37 offset:51200
	ds_read_b128 v[130:133], v37 offset:53248
	ds_read_b128 v[134:137], v37 offset:55296
	v_mfma_f32_16x16x32_bf16 v[60:63], v[118:121], v[8:11], v[60:63]
	ds_read_b128 v[118:121], v37 offset:57344
	ds_read_b128 v[138:141], v37 offset:59392
	ds_read_b128 v[142:145], v37 offset:61440
	ds_read_b128 v[146:149], v37 offset:63488
	v_mfma_f32_16x16x32_bf16 v[78:81], v[114:117], v[8:11], v[78:81]
	s_waitcnt lgkmcnt(0)
	v_mfma_f32_16x16x32_bf16 v[82:85], v[122:125], v[8:11], v[82:85]
	v_mfma_f32_16x16x32_bf16 v[86:89], v[126:129], v[8:11], v[86:89]
	v_mfma_f32_16x16x32_bf16 v[90:93], v[130:133], v[8:11], v[90:93]
	v_mfma_f32_16x16x32_bf16 v[94:97], v[134:137], v[8:11], v[94:97]
	v_mfma_f32_16x16x32_bf16 v[98:101], v[118:121], v[8:11], v[98:101]
	ds_read_b128 v[114:117], v37 offset:15360
	ds_read_b128 v[118:121], v37 offset:13312
	ds_read_b128 v[122:125], v37 offset:11264
	ds_read_b128 v[126:129], v37 offset:9216
	v_mfma_f32_16x16x32_bf16 v[102:105], v[138:141], v[8:11], v[102:105]
	v_mfma_f32_16x16x32_bf16 v[106:109], v[142:145], v[8:11], v[106:109]
	ds_read_b128 v[130:133], v37 offset:7168
	ds_read_b128 v[134:137], v37 offset:5120
	ds_read_b128 v[138:141], v37 offset:3072
	ds_read_b128 v[142:145], v37 offset:1024
	v_mfma_f32_16x16x32_bf16 v[110:113], v[146:149], v[8:11], v[110:113]
	s_waitcnt lgkmcnt(0)
	v_mfma_f32_16x16x32_bf16 v[42:45], v[142:145], v[4:7], v[42:45]
	v_mfma_f32_16x16x32_bf16 v[50:53], v[138:141], v[4:7], v[50:53]
	v_mfma_f32_16x16x32_bf16 v[38:41], v[134:137], v[4:7], v[38:41]
	v_mfma_f32_16x16x32_bf16 v[74:77], v[130:133], v[4:7], v[74:77]
	v_mfma_f32_16x16x32_bf16 v[66:69], v[126:129], v[4:7], v[66:69]
	v_mfma_f32_16x16x32_bf16 v[70:73], v[122:125], v[4:7], v[70:73]
	ds_read_b128 v[122:125], v37 offset:33792
	ds_read_b128 v[126:129], v37 offset:35840
	ds_read_b128 v[130:133], v37 offset:37888
	ds_read_b128 v[134:137], v37 offset:39936
	v_mfma_f32_16x16x32_bf16 v[60:63], v[118:121], v[4:7], v[60:63]
	ds_read_b128 v[118:121], v37 offset:41984
	ds_read_b128 v[138:141], v37 offset:44032
	ds_read_b128 v[142:145], v37 offset:46080
	ds_read_b128 v[146:149], v37 offset:48128
	v_mfma_f32_16x16x32_bf16 v[78:81], v[114:117], v[4:7], v[78:81]
	s_waitcnt lgkmcnt(0)
	v_mfma_f32_16x16x32_bf16 v[82:85], v[122:125], v[4:7], v[82:85]
	v_mfma_f32_16x16x32_bf16 v[86:89], v[126:129], v[4:7], v[86:89]
	v_mfma_f32_16x16x32_bf16 v[90:93], v[130:133], v[4:7], v[90:93]
	v_mfma_f32_16x16x32_bf16 v[94:97], v[134:137], v[4:7], v[94:97]
	v_mfma_f32_16x16x32_bf16 v[98:101], v[118:121], v[4:7], v[98:101]
	ds_read_b128 v[114:117], v37 offset:31744
	ds_read_b128 v[118:121], v37 offset:29696
	ds_read_b128 v[122:125], v37 offset:27648
	ds_read_b128 v[126:129], v37 offset:25600
	v_mfma_f32_16x16x32_bf16 v[102:105], v[138:141], v[4:7], v[102:105]
	v_mfma_f32_16x16x32_bf16 v[106:109], v[142:145], v[4:7], v[106:109]
	ds_read_b128 v[130:133], v37 offset:23552
	ds_read_b128 v[134:137], v37 offset:21504
	ds_read_b128 v[138:141], v37 offset:19456
	ds_read_b128 v[142:145], v37 offset:17408
	v_mfma_f32_16x16x32_bf16 v[110:113], v[146:149], v[4:7], v[110:113]
	s_waitcnt lgkmcnt(0)
	v_mfma_f32_16x16x32_bf16 v[42:45], v[142:145], v[0:3], v[42:45]
	v_mfma_f32_16x16x32_bf16 v[50:53], v[138:141], v[0:3], v[50:53]
	v_mfma_f32_16x16x32_bf16 v[38:41], v[134:137], v[0:3], v[38:41]
	v_mfma_f32_16x16x32_bf16 v[74:77], v[130:133], v[0:3], v[74:77]
	v_mfma_f32_16x16x32_bf16 v[66:69], v[126:129], v[0:3], v[66:69]
	v_mfma_f32_16x16x32_bf16 v[70:73], v[122:125], v[0:3], v[70:73]
	ds_read_b128 v[122:125], v37 offset:50176
	ds_read_b128 v[126:129], v37 offset:52224
	ds_read_b128 v[130:133], v37 offset:54272
	ds_read_b128 v[134:137], v37 offset:56320
	v_mfma_f32_16x16x32_bf16 v[60:63], v[118:121], v[0:3], v[60:63]
	ds_read_b128 v[118:121], v37 offset:58368
	ds_read_b128 v[138:141], v37 offset:60416
	ds_read_b128 v[142:145], v37 offset:62464
	ds_read_b128 v[146:149], v37 offset:64512
	v_mfma_f32_16x16x32_bf16 v[78:81], v[114:117], v[0:3], v[78:81]
	s_waitcnt lgkmcnt(0)
	v_mfma_f32_16x16x32_bf16 v[82:85], v[122:125], v[0:3], v[82:85]
	v_mfma_f32_16x16x32_bf16 v[86:89], v[126:129], v[0:3], v[86:89]
	v_mfma_f32_16x16x32_bf16 v[90:93], v[130:133], v[0:3], v[90:93]
	v_mfma_f32_16x16x32_bf16 v[94:97], v[134:137], v[0:3], v[94:97]
	v_mfma_f32_16x16x32_bf16 v[98:101], v[118:121], v[0:3], v[98:101]
	v_mfma_f32_16x16x32_bf16 v[102:105], v[138:141], v[0:3], v[102:105]
	v_mfma_f32_16x16x32_bf16 v[106:109], v[142:145], v[0:3], v[106:109]
	v_mfma_f32_16x16x32_bf16 v[110:113], v[146:149], v[0:3], v[110:113]
	s_mov_b32 s0, 0x1000000
	v_add_co_u32_e32 v34, vcc, s0, v34
	v_mul_f32_e32 v37, v36, v42
	v_mul_f32_e32 v42, v36, v43
	v_mul_f32_e32 v43, v36, v45
	v_addc_co_u32_e32 v35, vcc, 0, v35, vcc
	v_cvt_pk_bf16_f32 v42, v37, v42
	v_mul_f32_e32 v37, v36, v44
	v_cvt_pk_bf16_f32 v43, v37, v43
	global_store_dwordx2 v[34:35], v[42:43], off
	v_mul_f32_e32 v34, v36, v50
	v_mul_f32_e32 v35, v36, v51
	v_cvt_pk_bf16_f32 v34, v34, v35
	v_mul_f32_e32 v35, v36, v52
	v_mul_f32_e32 v37, v36, v53
	v_cvt_pk_bf16_f32 v35, v35, v37
	global_store_dwordx2 v[32:33], v[34:35], off offset:32
	v_mul_f32_e32 v34, v36, v38
	v_mul_f32_e32 v35, v36, v39
	v_cvt_pk_bf16_f32 v34, v34, v35
	v_mul_f32_e32 v35, v36, v40
	v_mul_f32_e32 v37, v36, v41
	v_cvt_pk_bf16_f32 v35, v35, v37
	global_store_dwordx2 v[32:33], v[34:35], off offset:64
	v_mul_f32_e32 v34, v36, v74
	v_mul_f32_e32 v35, v36, v75
	v_cvt_pk_bf16_f32 v34, v34, v35
	v_mul_f32_e32 v35, v36, v76
	v_mul_f32_e32 v37, v36, v77
	v_cvt_pk_bf16_f32 v35, v35, v37
	global_store_dwordx2 v[32:33], v[34:35], off offset:96
	v_mul_f32_e32 v34, v36, v66
	v_mul_f32_e32 v35, v36, v67
	v_cvt_pk_bf16_f32 v34, v34, v35
	v_mul_f32_e32 v35, v36, v68
	v_mul_f32_e32 v37, v36, v69
	v_cvt_pk_bf16_f32 v35, v35, v37
	global_store_dwordx2 v[32:33], v[34:35], off offset:128
	v_mul_f32_e32 v34, v36, v70
	v_mul_f32_e32 v35, v36, v71
	v_cvt_pk_bf16_f32 v34, v34, v35
	v_mul_f32_e32 v35, v36, v72
	v_mul_f32_e32 v37, v36, v73
	v_cvt_pk_bf16_f32 v35, v35, v37
	global_store_dwordx2 v[32:33], v[34:35], off offset:160
	v_mul_f32_e32 v34, v36, v60
	v_mul_f32_e32 v35, v36, v61
	v_cvt_pk_bf16_f32 v34, v34, v35
	v_mul_f32_e32 v35, v36, v62
	v_mul_f32_e32 v37, v36, v63
	v_cvt_pk_bf16_f32 v35, v35, v37
	global_store_dwordx2 v[32:33], v[34:35], off offset:192
	v_mul_f32_e32 v34, v36, v78
	v_mul_f32_e32 v35, v36, v79
	v_cvt_pk_bf16_f32 v34, v34, v35
	v_mul_f32_e32 v35, v36, v80
	v_mul_f32_e32 v37, v36, v81
	v_cvt_pk_bf16_f32 v35, v35, v37
	global_store_dwordx2 v[32:33], v[34:35], off offset:224
	v_mul_f32_e32 v34, v36, v82
	v_mul_f32_e32 v35, v36, v83
	v_cvt_pk_bf16_f32 v34, v34, v35
	v_mul_f32_e32 v35, v36, v84
	v_mul_f32_e32 v37, v36, v85
	v_cvt_pk_bf16_f32 v35, v35, v37
	global_store_dwordx2 v[32:33], v[34:35], off offset:256
	v_mul_f32_e32 v34, v36, v86
	v_mul_f32_e32 v35, v36, v87
	v_cvt_pk_bf16_f32 v34, v34, v35
	v_mul_f32_e32 v35, v36, v88
	v_mul_f32_e32 v37, v36, v89
	v_cvt_pk_bf16_f32 v35, v35, v37
	global_store_dwordx2 v[32:33], v[34:35], off offset:288
	v_mul_f32_e32 v34, v36, v90
	v_mul_f32_e32 v35, v36, v91
	v_cvt_pk_bf16_f32 v34, v34, v35
	v_mul_f32_e32 v35, v36, v92
	v_mul_f32_e32 v37, v36, v93
	v_cvt_pk_bf16_f32 v35, v35, v37
	global_store_dwordx2 v[32:33], v[34:35], off offset:320
	v_mul_f32_e32 v34, v36, v94
	v_mul_f32_e32 v35, v36, v95
	v_cvt_pk_bf16_f32 v34, v34, v35
	v_mul_f32_e32 v35, v36, v96
	v_mul_f32_e32 v37, v36, v97
	v_cvt_pk_bf16_f32 v35, v35, v37
	global_store_dwordx2 v[32:33], v[34:35], off offset:352
	v_mul_f32_e32 v34, v36, v98
	v_mul_f32_e32 v35, v36, v99
	v_cvt_pk_bf16_f32 v34, v34, v35
	v_mul_f32_e32 v35, v36, v100
	v_mul_f32_e32 v37, v36, v101
	v_cvt_pk_bf16_f32 v35, v35, v37
	global_store_dwordx2 v[32:33], v[34:35], off offset:384
	v_mul_f32_e32 v34, v36, v102
	v_mul_f32_e32 v35, v36, v103
	v_cvt_pk_bf16_f32 v34, v34, v35
	v_mul_f32_e32 v35, v36, v104
	v_mul_f32_e32 v37, v36, v105
	v_cvt_pk_bf16_f32 v35, v35, v37
	global_store_dwordx2 v[32:33], v[34:35], off offset:416
	v_mul_f32_e32 v34, v36, v106
	v_mul_f32_e32 v35, v36, v107
	v_cvt_pk_bf16_f32 v34, v34, v35
	v_mul_f32_e32 v35, v36, v108
	v_mul_f32_e32 v37, v36, v109
	v_cvt_pk_bf16_f32 v35, v35, v37
	global_store_dwordx2 v[32:33], v[34:35], off offset:448
	v_mul_f32_e32 v34, v36, v110
	v_mul_f32_e32 v35, v36, v111
	v_cvt_pk_bf16_f32 v34, v34, v35
	v_mul_f32_e32 v35, v36, v112
	s_add_u32 s0, s10, 0x11e20100
	s_mov_b32 m0, s19
	v_mul_f32_e32 v37, v36, v113
	v_cvt_pk_bf16_f32 v35, v35, v37
	global_store_dwordx2 v[32:33], v[34:35], off offset:480
	s_addc_u32 s1, s11, 0
	s_waitcnt vmcnt(0)
	s_waitcnt vmcnt(0)
	s_barrier
	global_load_lds_dwordx4 v56, s[0:1]
	s_mov_b32 m0, s13
	s_nop 0
	global_load_lds_dwordx4 v58, s[0:1]
	s_add_u32 s0, s10, 0x11e20180
	s_addc_u32 s1, s11, 0
	s_mov_b32 m0, s12
	s_nop 0
	global_load_lds_dwordx4 v56, s[0:1]
	s_mov_b32 m0, s14
	s_nop 0
	global_load_lds_dwordx4 v58, s[0:1]
	s_add_u32 s0, s10, 0x11e30100
	s_addc_u32 s1, s11, 0
	s_mov_b32 m0, s15
	s_nop 0
	global_load_lds_dwordx4 v56, s[0:1]
	s_mov_b32 m0, s16
	s_nop 0
	global_load_lds_dwordx4 v58, s[0:1]
	s_add_u32 s0, s10, 0x11e30180
	s_addc_u32 s1, s11, 0
	s_mov_b32 m0, s17
	s_nop 0
	global_load_lds_dwordx4 v56, s[0:1]
	s_mov_b32 m0, s18
	s_nop 0
	global_load_lds_dwordx4 v58, s[0:1]
	ds_read_b128 v[38:41], v65
	ds_read_b128 v[42:45], v65 offset:2048
	ds_read_b128 v[50:53], v65 offset:4096
	ds_read_b128 v[54:57], v65 offset:6144
	ds_read_b128 v[58:61], v65 offset:8192
	ds_read_b128 v[66:69], v65 offset:10240
	ds_read_b128 v[70:73], v65 offset:12288
	ds_read_b128 v[74:77], v65 offset:14336
	ds_read_b128 v[78:81], v65 offset:32768
	ds_read_b128 v[82:85], v65 offset:34816
	ds_read_b128 v[86:89], v65 offset:36864
	ds_read_b128 v[90:93], v65 offset:38912
	ds_read_b128 v[94:97], v65 offset:40960
	ds_read_b128 v[98:101], v65 offset:43008
	ds_read_b128 v[102:105], v65 offset:45056
	ds_read_b128 v[106:109], v65 offset:47104
	s_waitcnt lgkmcnt(0)
	v_mfma_f32_16x16x32_bf16 v[38:41], v[38:41], v[28:31], 0
	v_mfma_f32_16x16x32_bf16 v[42:45], v[42:45], v[28:31], 0
	v_mfma_f32_16x16x32_bf16 v[50:53], v[50:53], v[28:31], 0
	v_mfma_f32_16x16x32_bf16 v[54:57], v[54:57], v[28:31], 0
	v_mfma_f32_16x16x32_bf16 v[58:61], v[58:61], v[28:31], 0
	v_mfma_f32_16x16x32_bf16 v[66:69], v[66:69], v[28:31], 0
	v_mfma_f32_16x16x32_bf16 v[70:73], v[70:73], v[28:31], 0
	v_mfma_f32_16x16x32_bf16 v[74:77], v[74:77], v[28:31], 0
	ds_read_b128 v[110:113], v65 offset:30720
	ds_read_b128 v[114:117], v65 offset:28672
	ds_read_b128 v[118:121], v65 offset:26624
	ds_read_b128 v[122:125], v65 offset:24576
	ds_read_b128 v[126:129], v65 offset:22528
	ds_read_b128 v[130:133], v65 offset:20480
	ds_read_b128 v[134:137], v65 offset:18432
	ds_read_b128 v[138:141], v65 offset:16384
	v_mfma_f32_16x16x32_bf16 v[78:81], v[78:81], v[28:31], 0
	v_mfma_f32_16x16x32_bf16 v[82:85], v[82:85], v[28:31], 0
	v_mfma_f32_16x16x32_bf16 v[86:89], v[86:89], v[28:31], 0
	v_mfma_f32_16x16x32_bf16 v[90:93], v[90:93], v[28:31], 0
	v_mfma_f32_16x16x32_bf16 v[94:97], v[94:97], v[28:31], 0
	v_mfma_f32_16x16x32_bf16 v[98:101], v[98:101], v[28:31], 0
	v_mfma_f32_16x16x32_bf16 v[102:105], v[102:105], v[28:31], 0
	v_mfma_f32_16x16x32_bf16 v[28:31], v[106:109], v[28:31], 0
	s_waitcnt lgkmcnt(0)
	v_mfma_f32_16x16x32_bf16 v[38:41], v[138:141], v[24:27], v[38:41]
	v_mfma_f32_16x16x32_bf16 v[42:45], v[134:137], v[24:27], v[42:45]
	v_mfma_f32_16x16x32_bf16 v[50:53], v[130:133], v[24:27], v[50:53]
	v_mfma_f32_16x16x32_bf16 v[54:57], v[126:129], v[24:27], v[54:57]
	v_mfma_f32_16x16x32_bf16 v[58:61], v[122:125], v[24:27], v[58:61]
	v_mfma_f32_16x16x32_bf16 v[66:69], v[118:121], v[24:27], v[66:69]
	ds_read_b128 v[106:109], v65 offset:49152
	ds_read_b128 v[118:121], v65 offset:51200
	ds_read_b128 v[122:125], v65 offset:53248
	ds_read_b128 v[126:129], v65 offset:55296
	v_mfma_f32_16x16x32_bf16 v[70:73], v[114:117], v[24:27], v[70:73]
	ds_read_b128 v[114:117], v65 offset:57344
	ds_read_b128 v[130:133], v65 offset:59392
	ds_read_b128 v[134:137], v65 offset:61440
	ds_read_b128 v[138:141], v65 offset:63488
	v_mfma_f32_16x16x32_bf16 v[74:77], v[110:113], v[24:27], v[74:77]
	s_waitcnt lgkmcnt(0)
	v_mfma_f32_16x16x32_bf16 v[78:81], v[106:109], v[24:27], v[78:81]
	v_mfma_f32_16x16x32_bf16 v[82:85], v[118:121], v[24:27], v[82:85]
	v_mfma_f32_16x16x32_bf16 v[86:89], v[122:125], v[24:27], v[86:89]
	v_mfma_f32_16x16x32_bf16 v[90:93], v[126:129], v[24:27], v[90:93]
	v_mfma_f32_16x16x32_bf16 v[94:97], v[114:117], v[24:27], v[94:97]
	ds_read_b128 v[106:109], v65 offset:15360
	ds_read_b128 v[110:113], v65 offset:13312
	ds_read_b128 v[114:117], v65 offset:11264
	ds_read_b128 v[118:121], v65 offset:9216
	v_mfma_f32_16x16x32_bf16 v[98:101], v[130:133], v[24:27], v[98:101]
	v_mfma_f32_16x16x32_bf16 v[102:105], v[134:137], v[24:27], v[102:105]
	ds_read_b128 v[122:125], v65 offset:7168
	ds_read_b128 v[126:129], v65 offset:5120
	ds_read_b128 v[130:133], v65 offset:3072
	ds_read_b128 v[134:137], v65 offset:1024
	v_mfma_f32_16x16x32_bf16 v[24:27], v[138:141], v[24:27], v[28:31]
	s_waitcnt lgkmcnt(0)
	v_mfma_f32_16x16x32_bf16 v[28:31], v[134:137], v[20:23], v[38:41]
	v_mfma_f32_16x16x32_bf16 v[38:41], v[130:133], v[20:23], v[42:45]
	v_mfma_f32_16x16x32_bf16 v[42:45], v[126:129], v[20:23], v[50:53]
	v_mfma_f32_16x16x32_bf16 v[50:53], v[122:125], v[20:23], v[54:57]
	v_mfma_f32_16x16x32_bf16 v[54:57], v[118:121], v[20:23], v[58:61]
	v_mfma_f32_16x16x32_bf16 v[58:61], v[114:117], v[20:23], v[66:69]
	s_nop 2
	ds_read_b128 v[66:69], v65 offset:33792
	ds_read_b128 v[114:117], v65 offset:35840
	ds_read_b128 v[118:121], v65 offset:37888
	ds_read_b128 v[122:125], v65 offset:39936
	v_mfma_f32_16x16x32_bf16 v[70:73], v[110:113], v[20:23], v[70:73]
	ds_read_b128 v[110:113], v65 offset:41984
	ds_read_b128 v[126:129], v65 offset:44032
	ds_read_b128 v[130:133], v65 offset:46080
	ds_read_b128 v[134:137], v65 offset:48128
	v_mfma_f32_16x16x32_bf16 v[74:77], v[106:109], v[20:23], v[74:77]
	s_waitcnt lgkmcnt(0)
	v_mfma_f32_16x16x32_bf16 v[66:69], v[66:69], v[20:23], v[78:81]
	v_mfma_f32_16x16x32_bf16 v[78:81], v[114:117], v[20:23], v[82:85]
	v_mfma_f32_16x16x32_bf16 v[82:85], v[118:121], v[20:23], v[86:89]
	v_mfma_f32_16x16x32_bf16 v[86:89], v[122:125], v[20:23], v[90:93]
	v_mfma_f32_16x16x32_bf16 v[90:93], v[110:113], v[20:23], v[94:97]
	v_mfma_f32_16x16x32_bf16 v[94:97], v[126:129], v[20:23], v[98:101]
	s_nop 2
	ds_read_b128 v[98:101], v65 offset:31744
	ds_read_b128 v[106:109], v65 offset:29696
	ds_read_b128 v[110:113], v65 offset:27648
	ds_read_b128 v[114:117], v65 offset:25600
	v_mfma_f32_16x16x32_bf16 v[102:105], v[130:133], v[20:23], v[102:105]
	ds_read_b128 v[118:121], v65 offset:23552
	ds_read_b128 v[122:125], v65 offset:21504
	ds_read_b128 v[126:129], v65 offset:19456
	ds_read_b128 v[130:133], v65 offset:17408
	v_mfma_f32_16x16x32_bf16 v[20:23], v[134:137], v[20:23], v[24:27]
	s_waitcnt lgkmcnt(0)
	v_mfma_f32_16x16x32_bf16 v[24:27], v[130:133], v[16:19], v[28:31]
	v_mfma_f32_16x16x32_bf16 v[28:31], v[126:129], v[16:19], v[38:41]
	v_mfma_f32_16x16x32_bf16 v[38:41], v[122:125], v[16:19], v[42:45]
	v_mfma_f32_16x16x32_bf16 v[42:45], v[118:121], v[16:19], v[50:53]
	v_mfma_f32_16x16x32_bf16 v[50:53], v[114:117], v[16:19], v[54:57]
	v_mfma_f32_16x16x32_bf16 v[54:57], v[110:113], v[16:19], v[58:61]
	s_nop 2
	ds_read_b128 v[58:61], v65 offset:50176
	ds_read_b128 v[110:113], v65 offset:52224
	ds_read_b128 v[114:117], v65 offset:54272
	ds_read_b128 v[118:121], v65 offset:56320
	v_mfma_f32_16x16x32_bf16 v[70:73], v[106:109], v[16:19], v[70:73]
	ds_read_b128 v[106:109], v65 offset:58368
	ds_read_b128 v[122:125], v65 offset:60416
	ds_read_b128 v[126:129], v65 offset:62464
	ds_read_b128 v[62:65], v65 offset:64512
	v_mfma_f32_16x16x32_bf16 v[74:77], v[98:101], v[16:19], v[74:77]
	s_waitcnt lgkmcnt(0)
	v_mfma_f32_16x16x32_bf16 v[58:61], v[58:61], v[16:19], v[66:69]
	v_mfma_f32_16x16x32_bf16 v[66:69], v[110:113], v[16:19], v[78:81]
	v_mfma_f32_16x16x32_bf16 v[78:81], v[114:117], v[16:19], v[82:85]
	v_mfma_f32_16x16x32_bf16 v[82:85], v[118:121], v[16:19], v[86:89]
	v_mfma_f32_16x16x32_bf16 v[86:89], v[106:109], v[16:19], v[90:93]
	v_mfma_f32_16x16x32_bf16 v[90:93], v[122:125], v[16:19], v[94:97]
	v_mfma_f32_16x16x32_bf16 v[94:97], v[126:129], v[16:19], v[102:105]
	v_mfma_f32_16x16x32_bf16 v[16:19], v[62:65], v[16:19], v[20:23]
	s_waitcnt vmcnt(0)
	s_waitcnt vmcnt(0)
	s_barrier
	s_nop 0
	ds_read_b128 v[20:23], v48
	ds_read_b128 v[62:65], v48 offset:2048
	s_waitcnt lgkmcnt(1)
	v_mfma_f32_16x16x32_bf16 v[20:23], v[20:23], v[12:15], v[24:27]
	s_nop 2
	ds_read_b128 v[24:27], v48 offset:4096
	s_waitcnt lgkmcnt(1)
	v_mfma_f32_16x16x32_bf16 v[28:31], v[62:65], v[12:15], v[28:31]
	ds_read_b128 v[62:65], v48 offset:6144
	s_waitcnt lgkmcnt(1)
	v_mfma_f32_16x16x32_bf16 v[24:27], v[24:27], v[12:15], v[38:41]
	s_nop 2
	ds_read_b128 v[38:41], v48 offset:8192
	s_waitcnt lgkmcnt(1)
	v_mfma_f32_16x16x32_bf16 v[42:45], v[62:65], v[12:15], v[42:45]
	ds_read_b128 v[62:65], v48 offset:10240
	s_waitcnt lgkmcnt(1)
	v_mfma_f32_16x16x32_bf16 v[38:41], v[38:41], v[12:15], v[50:53]
	s_nop 2
	ds_read_b128 v[50:53], v48 offset:12288
	ds_read_b128 v[98:101], v48 offset:14336
	s_waitcnt lgkmcnt(2)
	v_mfma_f32_16x16x32_bf16 v[54:57], v[62:65], v[12:15], v[54:57]
	ds_read_b128 v[62:65], v48 offset:32768
	ds_read_b128 v[102:105], v48 offset:34816
	ds_read_b128 v[106:109], v48 offset:36864
	ds_read_b128 v[110:113], v48 offset:38912
	s_waitcnt lgkmcnt(5)
	v_mfma_f32_16x16x32_bf16 v[50:53], v[50:53], v[12:15], v[70:73]
	s_nop 2
	ds_read_b128 v[70:73], v48 offset:40960
	ds_read_b128 v[114:117], v48 offset:43008
	ds_read_b128 v[118:121], v48 offset:45056
	ds_read_b128 v[122:125], v48 offset:47104
	s_waitcnt lgkmcnt(8)
	v_mfma_f32_16x16x32_bf16 v[74:77], v[98:101], v[12:15], v[74:77]
	s_waitcnt lgkmcnt(7)
	v_mfma_f32_16x16x32_bf16 v[58:61], v[62:65], v[12:15], v[58:61]
	s_waitcnt lgkmcnt(6)
	v_mfma_f32_16x16x32_bf16 v[62:65], v[102:105], v[12:15], v[66:69]
	s_waitcnt lgkmcnt(5)
	v_mfma_f32_16x16x32_bf16 v[66:69], v[106:109], v[12:15], v[78:81]
	s_waitcnt lgkmcnt(4)
	v_mfma_f32_16x16x32_bf16 v[78:81], v[110:113], v[12:15], v[82:85]
	s_waitcnt lgkmcnt(3)
	v_mfma_f32_16x16x32_bf16 v[70:73], v[70:73], v[12:15], v[86:89]
	s_waitcnt lgkmcnt(2)
	v_mfma_f32_16x16x32_bf16 v[82:85], v[114:117], v[12:15], v[90:93]
	s_nop 0
	ds_read_b128 v[86:89], v48 offset:30720
	s_nop 0
	ds_read_b128 v[90:93], v48 offset:28672
	ds_read_b128 v[98:101], v48 offset:26624
	ds_read_b128 v[102:105], v48 offset:24576
	s_waitcnt lgkmcnt(5)
	v_mfma_f32_16x16x32_bf16 v[94:97], v[118:121], v[12:15], v[94:97]
	ds_read_b128 v[106:109], v48 offset:22528
	ds_read_b128 v[110:113], v48 offset:20480
	ds_read_b128 v[114:117], v48 offset:18432
	ds_read_b128 v[118:121], v48 offset:16384
	s_waitcnt lgkmcnt(8)
	v_mfma_f32_16x16x32_bf16 v[12:15], v[122:125], v[12:15], v[16:19]
	s_waitcnt lgkmcnt(0)
	v_mfma_f32_16x16x32_bf16 v[16:19], v[118:121], v[8:11], v[20:23]
	v_mfma_f32_16x16x32_bf16 v[20:23], v[114:117], v[8:11], v[28:31]
	v_mfma_f32_16x16x32_bf16 v[24:27], v[110:113], v[8:11], v[24:27]
	v_mfma_f32_16x16x32_bf16 v[28:31], v[106:109], v[8:11], v[42:45]
	v_mfma_f32_16x16x32_bf16 v[38:41], v[102:105], v[8:11], v[38:41]
	v_mfma_f32_16x16x32_bf16 v[42:45], v[98:101], v[8:11], v[54:57]
	s_nop 2
	ds_read_b128 v[54:57], v48 offset:49152
	ds_read_b128 v[98:101], v48 offset:51200
	ds_read_b128 v[102:105], v48 offset:53248
	ds_read_b128 v[106:109], v48 offset:55296
	v_mfma_f32_16x16x32_bf16 v[50:53], v[90:93], v[8:11], v[50:53]
	ds_read_b128 v[90:93], v48 offset:57344
	ds_read_b128 v[110:113], v48 offset:59392
	ds_read_b128 v[114:117], v48 offset:61440
	ds_read_b128 v[118:121], v48 offset:63488
	v_mfma_f32_16x16x32_bf16 v[74:77], v[86:89], v[8:11], v[74:77]
	s_waitcnt lgkmcnt(7)
	v_mfma_f32_16x16x32_bf16 v[54:57], v[54:57], v[8:11], v[58:61]
	s_waitcnt lgkmcnt(6)
	v_mfma_f32_16x16x32_bf16 v[58:61], v[98:101], v[8:11], v[62:65]
	s_waitcnt lgkmcnt(5)
	v_mfma_f32_16x16x32_bf16 v[62:65], v[102:105], v[8:11], v[66:69]
	s_waitcnt lgkmcnt(4)
	v_mfma_f32_16x16x32_bf16 v[66:69], v[106:109], v[8:11], v[78:81]
	s_waitcnt lgkmcnt(3)
	v_mfma_f32_16x16x32_bf16 v[70:73], v[90:93], v[8:11], v[70:73]
	s_waitcnt lgkmcnt(2)
	v_mfma_f32_16x16x32_bf16 v[78:81], v[110:113], v[8:11], v[82:85]
	s_nop 2
	ds_read_b128 v[82:85], v48 offset:15360
	ds_read_b128 v[86:89], v48 offset:13312
	ds_read_b128 v[90:93], v48 offset:11264
	ds_read_b128 v[98:101], v48 offset:9216
	s_waitcnt lgkmcnt(5)
	v_mfma_f32_16x16x32_bf16 v[94:97], v[114:117], v[8:11], v[94:97]
	ds_read_b128 v[102:105], v48 offset:7168
	ds_read_b128 v[106:109], v48 offset:5120
	ds_read_b128 v[110:113], v48 offset:3072
	ds_read_b128 v[114:117], v48 offset:1024
	s_waitcnt lgkmcnt(8)
	v_mfma_f32_16x16x32_bf16 v[8:11], v[118:121], v[8:11], v[12:15]
	s_waitcnt lgkmcnt(0)
	v_mfma_f32_16x16x32_bf16 v[12:15], v[114:117], v[4:7], v[16:19]
	v_mfma_f32_16x16x32_bf16 v[16:19], v[110:113], v[4:7], v[20:23]
	v_mfma_f32_16x16x32_bf16 v[20:23], v[106:109], v[4:7], v[24:27]
	v_mfma_f32_16x16x32_bf16 v[24:27], v[102:105], v[4:7], v[28:31]
	v_mfma_f32_16x16x32_bf16 v[28:31], v[98:101], v[4:7], v[38:41]
	v_mfma_f32_16x16x32_bf16 v[38:41], v[90:93], v[4:7], v[42:45]
	s_nop 2
	ds_read_b128 v[42:45], v48 offset:33792
	ds_read_b128 v[90:93], v48 offset:35840
	ds_read_b128 v[98:101], v48 offset:37888
	ds_read_b128 v[102:105], v48 offset:39936
	v_mfma_f32_16x16x32_bf16 v[50:53], v[86:89], v[4:7], v[50:53]
	ds_read_b128 v[86:89], v48 offset:41984
	ds_read_b128 v[106:109], v48 offset:44032
	ds_read_b128 v[110:113], v48 offset:46080
	ds_read_b128 v[114:117], v48 offset:48128
	v_mfma_f32_16x16x32_bf16 v[74:77], v[82:85], v[4:7], v[74:77]
	s_waitcnt lgkmcnt(7)
	v_mfma_f32_16x16x32_bf16 v[42:45], v[42:45], v[4:7], v[54:57]
	s_waitcnt lgkmcnt(6)
	v_mfma_f32_16x16x32_bf16 v[54:57], v[90:93], v[4:7], v[58:61]
	s_waitcnt lgkmcnt(5)
	v_mfma_f32_16x16x32_bf16 v[58:61], v[98:101], v[4:7], v[62:65]
	s_waitcnt lgkmcnt(4)
	v_mfma_f32_16x16x32_bf16 v[62:65], v[102:105], v[4:7], v[66:69]
	s_waitcnt lgkmcnt(3)
	v_mfma_f32_16x16x32_bf16 v[66:69], v[86:89], v[4:7], v[70:73]
	s_waitcnt lgkmcnt(2)
	v_mfma_f32_16x16x32_bf16 v[70:73], v[106:109], v[4:7], v[78:81]
	s_nop 2
	ds_read_b128 v[78:81], v48 offset:31744
	ds_read_b128 v[82:85], v48 offset:29696
	ds_read_b128 v[86:89], v48 offset:27648
	ds_read_b128 v[90:93], v48 offset:25600
	s_waitcnt lgkmcnt(5)
	v_mfma_f32_16x16x32_bf16 v[94:97], v[110:113], v[4:7], v[94:97]
	ds_read_b128 v[98:101], v48 offset:23552
	ds_read_b128 v[102:105], v48 offset:21504
	ds_read_b128 v[106:109], v48 offset:19456
	ds_read_b128 v[110:113], v48 offset:17408
	s_waitcnt lgkmcnt(8)
	v_mfma_f32_16x16x32_bf16 v[4:7], v[114:117], v[4:7], v[8:11]
	s_waitcnt lgkmcnt(0)
	v_mfma_f32_16x16x32_bf16 v[8:11], v[110:113], v[0:3], v[12:15]
	v_mfma_f32_16x16x32_bf16 v[12:15], v[106:109], v[0:3], v[16:19]
	v_mfma_f32_16x16x32_bf16 v[16:19], v[102:105], v[0:3], v[20:23]
	v_mfma_f32_16x16x32_bf16 v[20:23], v[98:101], v[0:3], v[24:27]
	v_mfma_f32_16x16x32_bf16 v[24:27], v[90:93], v[0:3], v[28:31]
	v_mfma_f32_16x16x32_bf16 v[28:31], v[86:89], v[0:3], v[38:41]
	s_nop 2
	ds_read_b128 v[38:41], v48 offset:50176
	ds_read_b128 v[86:89], v48 offset:52224
	ds_read_b128 v[90:93], v48 offset:54272
	ds_read_b128 v[98:101], v48 offset:56320
	v_mfma_f32_16x16x32_bf16 v[50:53], v[82:85], v[0:3], v[50:53]
	ds_read_b128 v[82:85], v48 offset:58368
	ds_read_b128 v[102:105], v48 offset:60416
	ds_read_b128 v[106:109], v48 offset:62464
	ds_read_b128 v[46:49], v48 offset:64512
	v_mfma_f32_16x16x32_bf16 v[74:77], v[78:81], v[0:3], v[74:77]
	s_waitcnt lgkmcnt(7)
	v_mfma_f32_16x16x32_bf16 v[38:41], v[38:41], v[0:3], v[42:45]
	s_waitcnt lgkmcnt(6)
	v_mfma_f32_16x16x32_bf16 v[42:45], v[86:89], v[0:3], v[54:57]
	s_waitcnt lgkmcnt(5)
	v_mfma_f32_16x16x32_bf16 v[54:57], v[90:93], v[0:3], v[58:61]
	s_waitcnt lgkmcnt(4)
	v_mfma_f32_16x16x32_bf16 v[58:61], v[98:101], v[0:3], v[62:65]
	s_waitcnt lgkmcnt(3)
	v_mfma_f32_16x16x32_bf16 v[62:65], v[82:85], v[0:3], v[66:69]
	s_waitcnt lgkmcnt(2)
	v_mfma_f32_16x16x32_bf16 v[66:69], v[102:105], v[0:3], v[70:73]
	s_waitcnt lgkmcnt(1)
	v_mfma_f32_16x16x32_bf16 v[70:73], v[106:109], v[0:3], v[94:97]
	s_waitcnt lgkmcnt(0)
	v_mfma_f32_16x16x32_bf16 v[0:3], v[46:49], v[0:3], v[4:7]
	s_nop 2
	v_mul_f32_e32 v4, v36, v8
	v_mul_f32_e32 v5, v36, v9
	v_cvt_pk_bf16_f32 v4, v4, v5
	v_mul_f32_e32 v5, v36, v10
	v_mul_f32_e32 v6, v36, v11
	v_cvt_pk_bf16_f32 v5, v5, v6
	global_store_dwordx2 v[32:33], v[4:5], off offset:512
	v_mul_f32_e32 v4, v36, v12
	v_mul_f32_e32 v5, v36, v13
	v_cvt_pk_bf16_f32 v4, v4, v5
	v_mul_f32_e32 v5, v36, v14
	v_mul_f32_e32 v6, v36, v15
	v_cvt_pk_bf16_f32 v5, v5, v6
	global_store_dwordx2 v[32:33], v[4:5], off offset:544
	v_mul_f32_e32 v4, v36, v16
	v_mul_f32_e32 v5, v36, v17
	v_cvt_pk_bf16_f32 v4, v4, v5
	v_mul_f32_e32 v5, v36, v18
	v_mul_f32_e32 v6, v36, v19
	v_cvt_pk_bf16_f32 v5, v5, v6
	global_store_dwordx2 v[32:33], v[4:5], off offset:576
	v_mul_f32_e32 v4, v36, v20
	v_mul_f32_e32 v5, v36, v21
	v_cvt_pk_bf16_f32 v4, v4, v5
	v_mul_f32_e32 v5, v36, v22
	v_mul_f32_e32 v6, v36, v23
	v_cvt_pk_bf16_f32 v5, v5, v6
	global_store_dwordx2 v[32:33], v[4:5], off offset:608
	v_mul_f32_e32 v4, v36, v24
	v_mul_f32_e32 v5, v36, v25
	v_cvt_pk_bf16_f32 v4, v4, v5
	v_mul_f32_e32 v5, v36, v26
	v_mul_f32_e32 v6, v36, v27
	v_cvt_pk_bf16_f32 v5, v5, v6
	global_store_dwordx2 v[32:33], v[4:5], off offset:640
	v_mul_f32_e32 v4, v36, v28
	v_mul_f32_e32 v5, v36, v29
	v_cvt_pk_bf16_f32 v4, v4, v5
	v_mul_f32_e32 v5, v36, v30
	v_mul_f32_e32 v6, v36, v31
	v_cvt_pk_bf16_f32 v5, v5, v6
	global_store_dwordx2 v[32:33], v[4:5], off offset:672
	v_mul_f32_e32 v4, v36, v50
	v_mul_f32_e32 v5, v36, v51
	v_cvt_pk_bf16_f32 v4, v4, v5
	v_mul_f32_e32 v5, v36, v52
	v_mul_f32_e32 v6, v36, v53
	v_cvt_pk_bf16_f32 v5, v5, v6
	global_store_dwordx2 v[32:33], v[4:5], off offset:704
	v_mul_f32_e32 v4, v36, v74
	v_mul_f32_e32 v5, v36, v75
	v_cvt_pk_bf16_f32 v4, v4, v5
	v_mul_f32_e32 v5, v36, v76
	v_mul_f32_e32 v6, v36, v77
	v_cvt_pk_bf16_f32 v5, v5, v6
	global_store_dwordx2 v[32:33], v[4:5], off offset:736
	v_mul_f32_e32 v4, v36, v38
	v_mul_f32_e32 v5, v36, v39
	v_cvt_pk_bf16_f32 v4, v4, v5
	v_mul_f32_e32 v5, v36, v40
	v_mul_f32_e32 v6, v36, v41
	v_cvt_pk_bf16_f32 v5, v5, v6
	global_store_dwordx2 v[32:33], v[4:5], off offset:768
	v_mul_f32_e32 v4, v36, v42
	v_mul_f32_e32 v5, v36, v43
	v_cvt_pk_bf16_f32 v4, v4, v5
	v_mul_f32_e32 v5, v36, v44
	v_mul_f32_e32 v6, v36, v45
	v_cvt_pk_bf16_f32 v5, v5, v6
	global_store_dwordx2 v[32:33], v[4:5], off offset:800
	v_mul_f32_e32 v4, v36, v54
	v_mul_f32_e32 v5, v36, v55
	v_cvt_pk_bf16_f32 v4, v4, v5
	v_mul_f32_e32 v5, v36, v56
	v_mul_f32_e32 v6, v36, v57
	v_cvt_pk_bf16_f32 v5, v5, v6
	global_store_dwordx2 v[32:33], v[4:5], off offset:832
	v_mul_f32_e32 v4, v36, v58
	v_mul_f32_e32 v5, v36, v59
	v_cvt_pk_bf16_f32 v4, v4, v5
	v_mul_f32_e32 v5, v36, v60
	v_mul_f32_e32 v6, v36, v61
	v_cvt_pk_bf16_f32 v5, v5, v6
	global_store_dwordx2 v[32:33], v[4:5], off offset:864
	v_mul_f32_e32 v4, v36, v62
	v_mul_f32_e32 v5, v36, v63
	v_cvt_pk_bf16_f32 v4, v4, v5
	v_mul_f32_e32 v5, v36, v64
	v_mul_f32_e32 v6, v36, v65
	v_cvt_pk_bf16_f32 v5, v5, v6
	global_store_dwordx2 v[32:33], v[4:5], off offset:896
	v_mul_f32_e32 v4, v36, v66
	v_mul_f32_e32 v5, v36, v67
	v_cvt_pk_bf16_f32 v4, v4, v5
	v_mul_f32_e32 v5, v36, v68
	v_mul_f32_e32 v6, v36, v69
	v_cvt_pk_bf16_f32 v5, v5, v6
	global_store_dwordx2 v[32:33], v[4:5], off offset:928
	v_mul_f32_e32 v4, v36, v70
	v_mul_f32_e32 v5, v36, v71
	v_cvt_pk_bf16_f32 v4, v4, v5
	v_mul_f32_e32 v5, v36, v72
	v_mul_f32_e32 v0, v36, v0
	v_mul_f32_e32 v1, v36, v1
	v_mul_f32_e32 v6, v36, v73
	v_cvt_pk_bf16_f32 v5, v5, v6
	global_store_dwordx2 v[32:33], v[4:5], off offset:960
	v_cvt_pk_bf16_f32 v0, v0, v1
	v_mul_f32_e32 v1, v36, v2
	v_mul_f32_e32 v2, v36, v3
	v_cvt_pk_bf16_f32 v1, v1, v2
	global_store_dwordx2 v[32:33], v[0:1], off offset:992
	s_waitcnt vmcnt(0)
	s_barrier

.LBB0_1955:
	ds_read_b128 v[140:143], v150
	ds_read_b128 v[144:147], v150 offset:1024
	ds_read_b128 v[156:159], v150 offset:2048
	ds_read_b128 v[160:163], v150 offset:3072
	ds_read_b128 v[164:167], v151
	ds_read_b128 v[168:171], v151 offset:1024
	ds_read_b128 v[172:175], v151 offset:2048
	ds_read_b128 v[176:179], v151 offset:3072
	s_add_u32 s36, s0, 0xfff80080
	s_addc_u32 s37, s1, -1
	s_cmp_eq_u32 s74, 28
	s_cselect_b32 s39, s68, s37
	s_cselect_b32 s38, s69, s36
	s_cselect_b32 s37, s70, s73
	s_cselect_b32 s36, s71, s72
	s_sub_u32 s98, s0, 0x80000
	s_subb_u32 s99, s1, 0
	s_add_i32 m0, s85, 0x8000
	ds_read_b128 v[180:183], v152
	ds_read_b128 v[184:187], v152 offset:1024
	ds_read_b128 v[188:191], v152 offset:2048
	ds_read_b128 v[192:195], v152 offset:3072
	ds_read_b128 v[196:199], v152 offset:4096
	ds_read_b128 v[200:203], v152 offset:5120
	ds_read_b128 v[204:207], v152 offset:6144
	ds_read_b128 v[208:211], v152 offset:7168
	global_load_lds_dwordx4 v222, s[98:99]
	s_add_u32 s98, s98, 0x20000
	s_addc_u32 s99, s99, 0
	s_add_i32 m0, s85, 0x9000
	s_nop 0
	global_load_lds_dwordx4 v222, s[98:99]
	s_add_u32 s98, s98, 0x20000
	s_addc_u32 s99, s99, 0
	s_add_i32 m0, s85, 0xa000
	s_nop 0
	global_load_lds_dwordx4 v222, s[98:99]
	s_add_u32 s98, s98, 0x20000
	s_addc_u32 s99, s99, 0
	s_add_i32 m0, s85, 0xb000
	s_nop 0
	global_load_lds_dwordx4 v222, s[98:99]
	s_waitcnt vmcnt(8)
	s_waitcnt lgkmcnt(0)
	s_barrier
	s_setprio 1
	s_waitcnt lgkmcnt(0)
	v_mfma_f32_16x16x32_bf16 v[124:127], v[140:143], v[180:183], v[124:127]
	v_mfma_f32_16x16x32_bf16 v[120:123], v[156:159], v[180:183], v[120:123]
	v_mfma_f32_16x16x32_bf16 v[108:111], v[140:143], v[188:191], v[108:111]
	v_mfma_f32_16x16x32_bf16 v[104:107], v[156:159], v[188:191], v[104:107]
	v_mfma_f32_16x16x32_bf16 v[92:95], v[140:143], v[196:199], v[92:95]
	v_mfma_f32_16x16x32_bf16 v[88:91], v[156:159], v[196:199], v[88:91]
	v_mfma_f32_16x16x32_bf16 v[76:79], v[140:143], v[204:207], v[76:79]
	v_mfma_f32_16x16x32_bf16 v[72:75], v[156:159], v[204:207], v[72:75]
	v_mfma_f32_16x16x32_bf16 v[124:127], v[144:147], v[184:187], v[124:127]
	v_mfma_f32_16x16x32_bf16 v[120:123], v[160:163], v[184:187], v[120:123]
	v_mfma_f32_16x16x32_bf16 v[108:111], v[144:147], v[192:195], v[108:111]
	v_mfma_f32_16x16x32_bf16 v[104:107], v[160:163], v[192:195], v[104:107]
	v_mfma_f32_16x16x32_bf16 v[92:95], v[144:147], v[200:203], v[92:95]
	v_mfma_f32_16x16x32_bf16 v[88:91], v[160:163], v[200:203], v[88:91]
	v_mfma_f32_16x16x32_bf16 v[76:79], v[144:147], v[208:211], v[76:79]
	v_mfma_f32_16x16x32_bf16 v[72:75], v[160:163], v[208:211], v[72:75]
	s_setprio 0
	s_setprio 1
	v_mfma_f32_16x16x32_bf16 v[116:119], v[164:167], v[180:183], v[116:119]
	v_mfma_f32_16x16x32_bf16 v[112:115], v[172:175], v[180:183], v[112:115]
	v_mfma_f32_16x16x32_bf16 v[100:103], v[164:167], v[188:191], v[100:103]
	v_mfma_f32_16x16x32_bf16 v[96:99], v[172:175], v[188:191], v[96:99]
	v_mfma_f32_16x16x32_bf16 v[84:87], v[164:167], v[196:199], v[84:87]
	v_mfma_f32_16x16x32_bf16 v[80:83], v[172:175], v[196:199], v[80:83]
	v_mfma_f32_16x16x32_bf16 v[68:71], v[164:167], v[204:207], v[68:71]
	v_mfma_f32_16x16x32_bf16 v[64:67], v[172:175], v[204:207], v[64:67]
	v_mfma_f32_16x16x32_bf16 v[116:119], v[168:171], v[184:187], v[116:119]
	v_mfma_f32_16x16x32_bf16 v[112:115], v[176:179], v[184:187], v[112:115]
	v_mfma_f32_16x16x32_bf16 v[100:103], v[168:171], v[192:195], v[100:103]
	v_mfma_f32_16x16x32_bf16 v[96:99], v[176:179], v[192:195], v[96:99]
	v_mfma_f32_16x16x32_bf16 v[84:87], v[168:171], v[200:203], v[84:87]
	v_mfma_f32_16x16x32_bf16 v[80:83], v[176:179], v[200:203], v[80:83]
	v_mfma_f32_16x16x32_bf16 v[68:71], v[168:171], v[208:211], v[68:71]
	v_mfma_f32_16x16x32_bf16 v[64:67], v[176:179], v[208:211], v[64:67]
	s_setprio 0
	s_barrier
	s_add_i32 s75, s56, s7
	v_lshl_add_u64 v[212:213], s[36:37], 0, v[130:131]
	s_mov_b32 m0, s75
	ds_read_b128 v[180:183], v152 offset:16384
	ds_read_b128 v[184:187], v152 offset:17408
	ds_read_b128 v[188:191], v152 offset:18432
	ds_read_b128 v[192:195], v152 offset:19456
	ds_read_b128 v[196:199], v152 offset:20480
	ds_read_b128 v[200:203], v152 offset:21504
	ds_read_b128 v[204:207], v152 offset:22528
	ds_read_b128 v[208:211], v152 offset:23552
	global_load_lds_dwordx4 v[212:213], off
	s_add_i32 m0, s75, 0x2000
	s_add_u32 s76, s36, 0x80000
	v_lshl_add_u64 v[214:215], s[36:37], 0, v[134:135]
	s_addc_u32 s77, s37, 0
	s_add_i32 s75, s57, s7
	global_load_lds_dwordx4 v[214:215], off
	v_lshl_add_u64 v[216:217], s[76:77], 0, v[130:131]
	s_mov_b32 m0, s75
	global_load_lds_dwordx4 v[216:217], off
	v_lshl_add_u64 v[216:217], s[76:77], 0, v[134:135]
	s_add_i32 m0, s75, 0x2000
	s_nop 0
	global_load_lds_dwordx4 v[216:217], off
	s_waitcnt vmcnt(8)
	s_waitcnt lgkmcnt(0)
	s_barrier
	s_setprio 1
	s_waitcnt lgkmcnt(0)
	v_mfma_f32_16x16x32_bf16 v[60:63], v[140:143], v[180:183], v[60:63]
	v_mfma_f32_16x16x32_bf16 v[56:59], v[156:159], v[180:183], v[56:59]
	v_mfma_f32_16x16x32_bf16 v[44:47], v[140:143], v[188:191], v[44:47]
	v_mfma_f32_16x16x32_bf16 v[40:43], v[156:159], v[188:191], v[40:43]
	v_mfma_f32_16x16x32_bf16 v[28:31], v[140:143], v[196:199], v[28:31]
	v_mfma_f32_16x16x32_bf16 v[24:27], v[156:159], v[196:199], v[24:27]
	v_mfma_f32_16x16x32_bf16 v[12:15], v[140:143], v[204:207], v[12:15]
	v_mfma_f32_16x16x32_bf16 v[8:11], v[156:159], v[204:207], v[8:11]
	v_mfma_f32_16x16x32_bf16 v[60:63], v[144:147], v[184:187], v[60:63]
	v_mfma_f32_16x16x32_bf16 v[56:59], v[160:163], v[184:187], v[56:59]
	v_mfma_f32_16x16x32_bf16 v[44:47], v[144:147], v[192:195], v[44:47]
	v_mfma_f32_16x16x32_bf16 v[40:43], v[160:163], v[192:195], v[40:43]
	v_mfma_f32_16x16x32_bf16 v[28:31], v[144:147], v[200:203], v[28:31]
	v_mfma_f32_16x16x32_bf16 v[24:27], v[160:163], v[200:203], v[24:27]
	v_mfma_f32_16x16x32_bf16 v[12:15], v[144:147], v[208:211], v[12:15]
	v_mfma_f32_16x16x32_bf16 v[8:11], v[160:163], v[208:211], v[8:11]
	s_setprio 0
	s_setprio 1
	v_mfma_f32_16x16x32_bf16 v[52:55], v[164:167], v[180:183], v[52:55]
	v_mfma_f32_16x16x32_bf16 v[48:51], v[172:175], v[180:183], v[48:51]
	v_mfma_f32_16x16x32_bf16 v[36:39], v[164:167], v[188:191], v[36:39]
	v_mfma_f32_16x16x32_bf16 v[32:35], v[172:175], v[188:191], v[32:35]
	v_mfma_f32_16x16x32_bf16 v[20:23], v[164:167], v[196:199], v[20:23]
	v_mfma_f32_16x16x32_bf16 v[16:19], v[172:175], v[196:199], v[16:19]
	v_mfma_f32_16x16x32_bf16 v[4:7], v[164:167], v[204:207], v[4:7]
	v_mfma_f32_16x16x32_bf16 v[0:3], v[172:175], v[204:207], v[0:3]
	v_mfma_f32_16x16x32_bf16 v[52:55], v[168:171], v[184:187], v[52:55]
	v_mfma_f32_16x16x32_bf16 v[48:51], v[176:179], v[184:187], v[48:51]
	v_mfma_f32_16x16x32_bf16 v[36:39], v[168:171], v[192:195], v[36:39]
	v_mfma_f32_16x16x32_bf16 v[32:35], v[176:179], v[192:195], v[32:35]
	v_mfma_f32_16x16x32_bf16 v[20:23], v[168:171], v[200:203], v[20:23]
	v_mfma_f32_16x16x32_bf16 v[16:19], v[176:179], v[200:203], v[16:19]
	v_mfma_f32_16x16x32_bf16 v[4:7], v[168:171], v[208:211], v[4:7]
	v_mfma_f32_16x16x32_bf16 v[0:3], v[176:179], v[208:211], v[0:3]
	s_setprio 0
	s_waitcnt vmcnt(4)
	s_barrier
	ds_read_b128 v[140:143], v153
	ds_read_b128 v[144:147], v153 offset:1024
	ds_read_b128 v[156:159], v153 offset:2048
	ds_read_b128 v[160:163], v153 offset:3072
	ds_read_b128 v[164:167], v154
	ds_read_b128 v[168:171], v154 offset:1024
	ds_read_b128 v[172:175], v154 offset:2048
	ds_read_b128 v[176:179], v154 offset:3072
	s_mov_b32 s98, s38
	s_mov_b32 s99, s39
	s_add_i32 m0, s85, 0
	ds_read_b128 v[180:183], v152 offset:32768
	ds_read_b128 v[184:187], v152 offset:33792
	ds_read_b128 v[188:191], v152 offset:34816
	ds_read_b128 v[192:195], v152 offset:35840
	ds_read_b128 v[196:199], v152 offset:36864
	ds_read_b128 v[200:203], v152 offset:37888
	ds_read_b128 v[204:207], v152 offset:38912
	ds_read_b128 v[208:211], v152 offset:39936
	global_load_lds_dwordx4 v222, s[98:99]
	s_add_u32 s98, s98, 0x20000
	s_addc_u32 s99, s99, 0
	s_add_i32 m0, s85, 0x1000
	s_nop 0
	global_load_lds_dwordx4 v222, s[98:99]
	s_add_u32 s98, s98, 0x20000
	s_addc_u32 s99, s99, 0
	s_add_i32 m0, s85, 0x2000
	s_nop 0
	global_load_lds_dwordx4 v222, s[98:99]
	s_add_u32 s98, s98, 0x20000
	s_addc_u32 s99, s99, 0
	s_add_i32 m0, s85, 0x3000
	s_nop 0
	global_load_lds_dwordx4 v222, s[98:99]
	s_waitcnt vmcnt(8)
	s_waitcnt lgkmcnt(0)
	s_barrier
	s_setprio 1
	s_waitcnt lgkmcnt(0)
	v_mfma_f32_16x16x32_bf16 v[124:127], v[140:143], v[180:183], v[124:127]
	v_mfma_f32_16x16x32_bf16 v[120:123], v[156:159], v[180:183], v[120:123]
	v_mfma_f32_16x16x32_bf16 v[108:111], v[140:143], v[188:191], v[108:111]
	v_mfma_f32_16x16x32_bf16 v[104:107], v[156:159], v[188:191], v[104:107]
	v_mfma_f32_16x16x32_bf16 v[92:95], v[140:143], v[196:199], v[92:95]
	v_mfma_f32_16x16x32_bf16 v[88:91], v[156:159], v[196:199], v[88:91]
	v_mfma_f32_16x16x32_bf16 v[76:79], v[140:143], v[204:207], v[76:79]
	v_mfma_f32_16x16x32_bf16 v[72:75], v[156:159], v[204:207], v[72:75]
	v_mfma_f32_16x16x32_bf16 v[124:127], v[144:147], v[184:187], v[124:127]
	v_mfma_f32_16x16x32_bf16 v[120:123], v[160:163], v[184:187], v[120:123]
	v_mfma_f32_16x16x32_bf16 v[108:111], v[144:147], v[192:195], v[108:111]
	v_mfma_f32_16x16x32_bf16 v[104:107], v[160:163], v[192:195], v[104:107]
	v_mfma_f32_16x16x32_bf16 v[92:95], v[144:147], v[200:203], v[92:95]
	v_mfma_f32_16x16x32_bf16 v[88:91], v[160:163], v[200:203], v[88:91]
	v_mfma_f32_16x16x32_bf16 v[76:79], v[144:147], v[208:211], v[76:79]
	v_mfma_f32_16x16x32_bf16 v[72:75], v[160:163], v[208:211], v[72:75]
	s_setprio 0
	s_setprio 1
	v_mfma_f32_16x16x32_bf16 v[116:119], v[164:167], v[180:183], v[116:119]
	v_mfma_f32_16x16x32_bf16 v[112:115], v[172:175], v[180:183], v[112:115]
	v_mfma_f32_16x16x32_bf16 v[100:103], v[164:167], v[188:191], v[100:103]
	v_mfma_f32_16x16x32_bf16 v[96:99], v[172:175], v[188:191], v[96:99]
	v_mfma_f32_16x16x32_bf16 v[84:87], v[164:167], v[196:199], v[84:87]
	v_mfma_f32_16x16x32_bf16 v[80:83], v[172:175], v[196:199], v[80:83]
	v_mfma_f32_16x16x32_bf16 v[68:71], v[164:167], v[204:207], v[68:71]
	v_mfma_f32_16x16x32_bf16 v[64:67], v[172:175], v[204:207], v[64:67]
	v_mfma_f32_16x16x32_bf16 v[116:119], v[168:171], v[184:187], v[116:119]
	v_mfma_f32_16x16x32_bf16 v[112:115], v[176:179], v[184:187], v[112:115]
	v_mfma_f32_16x16x32_bf16 v[100:103], v[168:171], v[192:195], v[100:103]
	v_mfma_f32_16x16x32_bf16 v[96:99], v[176:179], v[192:195], v[96:99]
	v_mfma_f32_16x16x32_bf16 v[84:87], v[168:171], v[200:203], v[84:87]
	v_mfma_f32_16x16x32_bf16 v[80:83], v[176:179], v[200:203], v[80:83]
	v_mfma_f32_16x16x32_bf16 v[68:71], v[168:171], v[208:211], v[68:71]
	v_mfma_f32_16x16x32_bf16 v[64:67], v[176:179], v[208:211], v[64:67]
	s_setprio 0
	s_barrier
	s_add_i32 s38, s58, s7
	v_lshl_add_u64 v[212:213], v[212:213], 0, s[14:15]
	s_mov_b32 m0, s38
	ds_read_b128 v[180:183], v152 offset:49152
	ds_read_b128 v[184:187], v152 offset:50176
	ds_read_b128 v[188:191], v152 offset:51200
	ds_read_b128 v[192:195], v152 offset:52224
	ds_read_b128 v[196:199], v152 offset:53248
	ds_read_b128 v[200:203], v152 offset:54272
	ds_read_b128 v[204:207], v152 offset:55296
	ds_read_b128 v[208:211], v152 offset:56320
	global_load_lds_dwordx4 v[212:213], off
	s_add_i32 m0, s38, 0x2000
	s_add_u32 s36, s36, 0x80080
	v_lshl_add_u64 v[212:213], v[214:215], 0, s[14:15]
	s_addc_u32 s37, s37, 0
	s_add_i32 s38, s59, s7
	global_load_lds_dwordx4 v[212:213], off
	v_lshl_add_u64 v[212:213], s[36:37], 0, v[130:131]
	s_mov_b32 m0, s38
	s_nop 0
	global_load_lds_dwordx4 v[212:213], off
	v_lshl_add_u64 v[212:213], s[36:37], 0, v[134:135]
	s_add_i32 m0, s38, 0x2000
	s_nop 0
	global_load_lds_dwordx4 v[212:213], off
	s_waitcnt vmcnt(8)
	s_waitcnt lgkmcnt(0)
	s_barrier
	s_setprio 1
	s_waitcnt lgkmcnt(0)
	v_mfma_f32_16x16x32_bf16 v[60:63], v[140:143], v[180:183], v[60:63]
	v_mfma_f32_16x16x32_bf16 v[56:59], v[156:159], v[180:183], v[56:59]
	v_mfma_f32_16x16x32_bf16 v[44:47], v[140:143], v[188:191], v[44:47]
	v_mfma_f32_16x16x32_bf16 v[40:43], v[156:159], v[188:191], v[40:43]
	v_mfma_f32_16x16x32_bf16 v[28:31], v[140:143], v[196:199], v[28:31]
	v_mfma_f32_16x16x32_bf16 v[24:27], v[156:159], v[196:199], v[24:27]
	v_mfma_f32_16x16x32_bf16 v[12:15], v[140:143], v[204:207], v[12:15]
	v_mfma_f32_16x16x32_bf16 v[8:11], v[156:159], v[204:207], v[8:11]
	v_mfma_f32_16x16x32_bf16 v[60:63], v[144:147], v[184:187], v[60:63]
	v_mfma_f32_16x16x32_bf16 v[56:59], v[160:163], v[184:187], v[56:59]
	v_mfma_f32_16x16x32_bf16 v[44:47], v[144:147], v[192:195], v[44:47]
	v_mfma_f32_16x16x32_bf16 v[40:43], v[160:163], v[192:195], v[40:43]
	v_mfma_f32_16x16x32_bf16 v[28:31], v[144:147], v[200:203], v[28:31]
	v_mfma_f32_16x16x32_bf16 v[24:27], v[160:163], v[200:203], v[24:27]
	v_mfma_f32_16x16x32_bf16 v[12:15], v[144:147], v[208:211], v[12:15]
	v_mfma_f32_16x16x32_bf16 v[8:11], v[160:163], v[208:211], v[8:11]
	s_setprio 0
	s_setprio 1
	v_mfma_f32_16x16x32_bf16 v[52:55], v[164:167], v[180:183], v[52:55]
	v_mfma_f32_16x16x32_bf16 v[48:51], v[172:175], v[180:183], v[48:51]
	v_mfma_f32_16x16x32_bf16 v[36:39], v[164:167], v[188:191], v[36:39]
	v_mfma_f32_16x16x32_bf16 v[32:35], v[172:175], v[188:191], v[32:35]
	v_mfma_f32_16x16x32_bf16 v[20:23], v[164:167], v[196:199], v[20:23]
	v_mfma_f32_16x16x32_bf16 v[16:19], v[172:175], v[196:199], v[16:19]
	v_mfma_f32_16x16x32_bf16 v[4:7], v[164:167], v[204:207], v[4:7]
	v_mfma_f32_16x16x32_bf16 v[0:3], v[172:175], v[204:207], v[0:3]
	v_mfma_f32_16x16x32_bf16 v[52:55], v[168:171], v[184:187], v[52:55]
	v_mfma_f32_16x16x32_bf16 v[48:51], v[176:179], v[184:187], v[48:51]
	v_mfma_f32_16x16x32_bf16 v[36:39], v[168:171], v[192:195], v[36:39]
	v_mfma_f32_16x16x32_bf16 v[32:35], v[176:179], v[192:195], v[32:35]
	v_mfma_f32_16x16x32_bf16 v[20:23], v[168:171], v[200:203], v[20:23]
	v_mfma_f32_16x16x32_bf16 v[16:19], v[176:179], v[200:203], v[16:19]
	v_mfma_f32_16x16x32_bf16 v[4:7], v[168:171], v[208:211], v[4:7]
	v_mfma_f32_16x16x32_bf16 v[0:3], v[176:179], v[208:211], v[0:3]
	s_setprio 0
	s_waitcnt vmcnt(4)
	s_barrier
	s_add_i32 s74, s74, 2
	s_add_u32 s0, s0, 0x100
	s_addc_u32 s1, s1, 0
	s_add_u32 s72, s72, 0x100
	s_addc_u32 s73, s73, 0
	s_cmp_gt_u32 s74, 29
	s_cbranch_scc0 .LBB0_1955
	s_and_b64 vcc, exec, s[16:17]
	s_cbranch_vccz .LBB0_1958
	s_barrier

.LBB0_2061:
	s_mov_b64 s[8:9], 0x80
	s_add_i32 m0, s1, 0x18000
	v_lshl_add_u64 v[6:7], v[6:7], 0, s[8:9]
	s_bfe_u32 s29, s33, 0x20006
	s_lshl_b32 s42, s10, 6
	s_waitcnt vmcnt(2)
	s_barrier
	global_load_lds_dwordx4 v[6:7], off
	v_lshl_add_u64 v[4:5], v[4:5], 0, s[8:9]
	s_add_i32 m0, s1, 0x1a000
	s_add_i32 s43, s1, 0x8000
	s_add_i32 s44, s1, 0xa000
	global_load_lds_dwordx4 v[4:5], off
	v_lshl_add_u64 v[0:1], v[0:1], 0, s[8:9]
	s_mov_b32 m0, s43
	s_add_u32 s14, s12, 0x200080
	global_load_lds_dwordx4 v[0:1], off
	v_lshl_add_u64 v[0:1], v[2:3], 0, s[8:9]
	s_mov_b32 m0, s44
	s_addc_u32 s15, s13, 0
	global_load_lds_dwordx4 v[0:1], off
	s_add_i32 m0, s1, 0x1c000
	v_lshl_add_u64 v[0:1], s[14:15], 0, v[132:133]
	global_load_lds_dwordx4 v[0:1], off
	v_lshl_add_u64 v[0:1], s[14:15], 0, v[128:129]
	s_add_i32 m0, s1, 0x1e000
	v_and_b32_e32 v144, 15, v201
	global_load_lds_dwordx4 v[0:1], off
	v_and_b32_e32 v0, 48, v201
	v_and_b32_e32 v1, 0xfffffc00, v10
	v_lshlrev_b32_e32 v3, 2, v201
	v_lshl_add_u32 v2, s10, 13, v1
	v_lshl_or_b32 v0, v144, 6, v0
	v_and_b32_e32 v3, 32, v3
	v_lshl_add_u32 v1, s29, 12, v1
	v_bitop3_b32 v4, v0, v2, v3 bitop3:0xde
	v_bitop3_b32 v145, v0, v1, v3 bitop3:0xde
	v_lshlrev_b32_e32 v0, 17, v12
	v_and_b32_e32 v0, 0xfffc0000, v0
	v_lshl_add_u32 v0, v13, 14, v0
	v_and_b32_e32 v1, 1, v12
	v_lshl_or_b32 v0, v1, 6, v0
	s_mov_b64 s[14:15], 0x200080
	v_lshl_add_u32 v0, v14, 1, v0
	v_mov_b32_e32 v1, v133
	v_lshl_add_u64 v[136:137], v[0:1], 0, s[14:15]
	v_lshlrev_b32_e32 v0, 17, v8
	v_and_b32_e32 v0, 0xfffc0000, v0
	v_lshl_add_u32 v0, v9, 14, v0
	v_and_b32_e32 v1, 1, v8
	s_cmpk_lt_u32 s33, 0x100
	v_lshl_or_b32 v0, v1, 6, v0
	s_waitcnt vmcnt(6)
	s_cselect_b64 s[10:11], -1, 0
	v_lshl_add_u32 v0, v11, 1, v0
	v_mov_b32_e32 v1, v133
	v_mov_b32_e32 v2, v133
	v_mov_b32_e32 v3, v133
	s_add_i32 s33, 0, 0x10000
	s_add_i32 s45, 0, 0x14000
	v_lshl_add_u64 v[138:139], v[0:1], 0, s[14:15]
	v_mov_b32_e32 v0, v133
	v_add_u32_e32 v146, 0, v4
	s_add_i32 s48, s33, s38
	s_add_i32 s50, s45, s38
	v_mov_b64_e32 v[6:7], v[2:3]
	v_mov_b64_e32 v[18:19], v[2:3]
	v_mov_b64_e32 v[22:23], v[2:3]
	v_mov_b64_e32 v[34:35], v[2:3]
	v_mov_b64_e32 v[38:39], v[2:3]
	v_mov_b64_e32 v[50:51], v[2:3]
	v_mov_b64_e32 v[54:55], v[2:3]
	v_mov_b64_e32 v[10:11], v[2:3]
	v_mov_b64_e32 v[14:15], v[2:3]
	v_mov_b64_e32 v[26:27], v[2:3]
	v_mov_b64_e32 v[30:31], v[2:3]
	v_mov_b64_e32 v[42:43], v[2:3]
	v_mov_b64_e32 v[46:47], v[2:3]
	v_mov_b64_e32 v[58:59], v[2:3]
	v_mov_b64_e32 v[62:63], v[2:3]
	v_mov_b64_e32 v[66:67], v[2:3]
	v_mov_b64_e32 v[70:71], v[2:3]
	v_mov_b64_e32 v[82:83], v[2:3]
	v_mov_b64_e32 v[86:87], v[2:3]
	v_mov_b64_e32 v[98:99], v[2:3]
	v_mov_b64_e32 v[102:103], v[2:3]
	v_mov_b64_e32 v[114:115], v[2:3]
	v_mov_b64_e32 v[118:119], v[2:3]
	v_mov_b64_e32 v[74:75], v[2:3]
	v_mov_b64_e32 v[78:79], v[2:3]
	v_mov_b64_e32 v[90:91], v[2:3]
	v_mov_b64_e32 v[94:95], v[2:3]
	v_mov_b64_e32 v[106:107], v[2:3]
	v_mov_b64_e32 v[110:111], v[2:3]
	v_mov_b64_e32 v[122:123], v[2:3]
	v_mov_b64_e32 v[126:127], v[2:3]
	s_mov_b32 s55, 0
	s_add_i32 s46, s1, 0xc000
	s_add_i32 s47, s1, 0xe000
	s_add_i32 s49, s48, 0x2000
	s_add_i32 s51, s50, 0x2000
	s_add_i32 s52, 0, 0x18000
	v_mov_b64_e32 v[4:5], v[0:1]
	v_mov_b64_e32 v[16:17], v[0:1]
	v_mov_b64_e32 v[20:21], v[0:1]
	v_mov_b64_e32 v[32:33], v[0:1]
	v_mov_b64_e32 v[36:37], v[0:1]
	v_mov_b64_e32 v[48:49], v[0:1]
	v_mov_b64_e32 v[52:53], v[0:1]
	v_mov_b64_e32 v[8:9], v[0:1]
	v_mov_b64_e32 v[12:13], v[0:1]
	v_mov_b64_e32 v[24:25], v[0:1]
	v_mov_b64_e32 v[28:29], v[0:1]
	v_mov_b64_e32 v[40:41], v[0:1]
	v_mov_b64_e32 v[44:45], v[0:1]
	v_mov_b64_e32 v[56:57], v[0:1]
	v_mov_b64_e32 v[60:61], v[0:1]
	v_mov_b64_e32 v[64:65], v[0:1]
	v_mov_b64_e32 v[68:69], v[0:1]
	v_mov_b64_e32 v[80:81], v[0:1]
	v_mov_b64_e32 v[84:85], v[0:1]
	v_mov_b64_e32 v[96:97], v[0:1]
	v_mov_b64_e32 v[100:101], v[0:1]
	v_mov_b64_e32 v[112:113], v[0:1]
	v_mov_b64_e32 v[116:117], v[0:1]
	v_mov_b64_e32 v[72:73], v[0:1]
	v_mov_b64_e32 v[76:77], v[0:1]
	v_mov_b64_e32 v[88:89], v[0:1]
	v_mov_b64_e32 v[92:93], v[0:1]
	v_mov_b64_e32 v[104:105], v[0:1]
	v_mov_b64_e32 v[108:109], v[0:1]
	v_mov_b64_e32 v[120:121], v[0:1]
	v_mov_b64_e32 v[124:125], v[0:1]
	s_barrier

.LBB0_2063:
	v_add_u32_e32 v147, s33, v145
	ds_read_b128 v[148:151], v147
	ds_read_b128 v[152:155], v147 offset:1024
	ds_read_b128 v[156:159], v147 offset:2048
	ds_read_b128 v[160:163], v147 offset:3072
	v_add_u32_e32 v147, s45, v145
	s_add_u32 s24, s18, s22
	ds_read_b128 v[164:167], v147
	ds_read_b128 v[168:171], v147 offset:1024
	ds_read_b128 v[172:175], v147 offset:2048
	ds_read_b128 v[176:179], v147 offset:3072
	s_addc_u32 s25, s19, s23
	s_add_u32 s24, s24, 0x100
	s_addc_u32 s25, s25, 0
	s_add_u32 s63, s56, s22
	s_addc_u32 s64, s57, s23
	s_cmpk_eq_i32 s22, 0x3f00
	s_cselect_b32 s27, s58, s25
	s_cselect_b32 s26, s59, s24
	s_cselect_b32 s25, s60, s64
	s_cselect_b32 s24, s61, s63
	s_mov_b32 m0, s46
	v_lshl_add_u64 v[214:215], v[140:141], 0, s[22:23]
	ds_read_b128 v[180:183], v146
	ds_read_b128 v[184:187], v146 offset:1024
	ds_read_b128 v[188:191], v146 offset:2048
	ds_read_b128 v[192:195], v146 offset:3072
	ds_read_b128 v[196:199], v146 offset:4096
	ds_read_b128 v[202:205], v146 offset:5120
	ds_read_b128 v[206:209], v146 offset:6144
	ds_read_b128 v[210:213], v146 offset:7168
	global_load_lds_dwordx4 v[214:215], off
	v_lshl_add_u64 v[214:215], v[142:143], 0, s[22:23]
	s_mov_b32 m0, s47
	s_nop 0
	global_load_lds_dwordx4 v[214:215], off
	s_waitcnt vmcnt(8)
	s_waitcnt lgkmcnt(0)
	s_barrier
	s_setprio 1
	s_waitcnt lgkmcnt(0)
	v_mfma_f32_16x16x32_bf16 v[124:127], v[148:151], v[180:183], v[124:127]
	v_mfma_f32_16x16x32_bf16 v[120:123], v[156:159], v[180:183], v[120:123]
	v_mfma_f32_16x16x32_bf16 v[108:111], v[148:151], v[188:191], v[108:111]
	v_mfma_f32_16x16x32_bf16 v[104:107], v[156:159], v[188:191], v[104:107]
	v_mfma_f32_16x16x32_bf16 v[92:95], v[148:151], v[196:199], v[92:95]
	v_mfma_f32_16x16x32_bf16 v[88:91], v[156:159], v[196:199], v[88:91]
	v_mfma_f32_16x16x32_bf16 v[76:79], v[148:151], v[206:209], v[76:79]
	v_mfma_f32_16x16x32_bf16 v[72:75], v[156:159], v[206:209], v[72:75]
	v_mfma_f32_16x16x32_bf16 v[124:127], v[152:155], v[184:187], v[124:127]
	v_mfma_f32_16x16x32_bf16 v[120:123], v[160:163], v[184:187], v[120:123]
	v_mfma_f32_16x16x32_bf16 v[108:111], v[152:155], v[192:195], v[108:111]
	v_mfma_f32_16x16x32_bf16 v[104:107], v[160:163], v[192:195], v[104:107]
	v_mfma_f32_16x16x32_bf16 v[92:95], v[152:155], v[202:205], v[92:95]
	v_mfma_f32_16x16x32_bf16 v[88:91], v[160:163], v[202:205], v[88:91]
	v_mfma_f32_16x16x32_bf16 v[76:79], v[152:155], v[210:213], v[76:79]
	v_mfma_f32_16x16x32_bf16 v[72:75], v[160:163], v[210:213], v[72:75]
	s_setprio 0
	s_setprio 1
	v_mfma_f32_16x16x32_bf16 v[116:119], v[164:167], v[180:183], v[116:119]
	v_mfma_f32_16x16x32_bf16 v[112:115], v[172:175], v[180:183], v[112:115]
	v_mfma_f32_16x16x32_bf16 v[100:103], v[164:167], v[188:191], v[100:103]
	v_mfma_f32_16x16x32_bf16 v[96:99], v[172:175], v[188:191], v[96:99]
	v_mfma_f32_16x16x32_bf16 v[84:87], v[164:167], v[196:199], v[84:87]
	v_mfma_f32_16x16x32_bf16 v[80:83], v[172:175], v[196:199], v[80:83]
	v_mfma_f32_16x16x32_bf16 v[68:71], v[164:167], v[206:209], v[68:71]
	v_mfma_f32_16x16x32_bf16 v[64:67], v[172:175], v[206:209], v[64:67]
	v_mfma_f32_16x16x32_bf16 v[116:119], v[168:171], v[184:187], v[116:119]
	v_mfma_f32_16x16x32_bf16 v[112:115], v[176:179], v[184:187], v[112:115]
	v_mfma_f32_16x16x32_bf16 v[100:103], v[168:171], v[192:195], v[100:103]
	v_mfma_f32_16x16x32_bf16 v[96:99], v[176:179], v[192:195], v[96:99]
	v_mfma_f32_16x16x32_bf16 v[84:87], v[168:171], v[202:205], v[84:87]
	v_mfma_f32_16x16x32_bf16 v[80:83], v[176:179], v[202:205], v[80:83]
	v_mfma_f32_16x16x32_bf16 v[68:71], v[168:171], v[210:213], v[68:71]
	v_mfma_f32_16x16x32_bf16 v[64:67], v[176:179], v[210:213], v[64:67]
	s_setprio 0
	s_barrier
	s_mov_b32 m0, s48
	v_lshl_add_u64 v[214:215], s[24:25], 0, v[132:133]
	s_add_u32 s64, s24, 0x200000
	ds_read_b128 v[180:183], v146 offset:16384
	ds_read_b128 v[184:187], v146 offset:17408
	ds_read_b128 v[188:191], v146 offset:18432
	ds_read_b128 v[192:195], v146 offset:19456
	ds_read_b128 v[196:199], v146 offset:20480
	ds_read_b128 v[202:205], v146 offset:21504
	ds_read_b128 v[206:209], v146 offset:22528
	ds_read_b128 v[210:213], v146 offset:23552
	global_load_lds_dwordx4 v[214:215], off
	v_lshl_add_u64 v[216:217], s[24:25], 0, v[128:129]
	s_mov_b32 m0, s49
	s_addc_u32 s65, s25, 0
	global_load_lds_dwordx4 v[216:217], off
	v_lshl_add_u64 v[218:219], s[64:65], 0, v[132:133]
	s_mov_b32 m0, s50
	v_lshl_add_u64 v[220:221], s[26:27], 0, v[130:131]
	global_load_lds_dwordx4 v[218:219], off
	v_lshl_add_u64 v[218:219], s[64:65], 0, v[128:129]
	s_mov_b32 m0, s51
	s_nop 0
	global_load_lds_dwordx4 v[218:219], off
	v_lshl_add_u64 v[218:219], s[26:27], 0, v[134:135]
	s_mov_b32 m0, s1
	s_nop 0
	global_load_lds_dwordx4 v[218:219], off
	s_mov_b32 m0, s39
	s_nop 0
	global_load_lds_dwordx4 v[220:221], off
	s_waitcnt vmcnt(8)
	s_waitcnt lgkmcnt(0)
	s_barrier
	s_setprio 1
	s_waitcnt lgkmcnt(0)
	v_mfma_f32_16x16x32_bf16 v[60:63], v[148:151], v[180:183], v[60:63]
	v_mfma_f32_16x16x32_bf16 v[56:59], v[156:159], v[180:183], v[56:59]
	v_mfma_f32_16x16x32_bf16 v[44:47], v[148:151], v[188:191], v[44:47]
	v_mfma_f32_16x16x32_bf16 v[40:43], v[156:159], v[188:191], v[40:43]
	v_mfma_f32_16x16x32_bf16 v[28:31], v[148:151], v[196:199], v[28:31]
	v_mfma_f32_16x16x32_bf16 v[24:27], v[156:159], v[196:199], v[24:27]
	v_mfma_f32_16x16x32_bf16 v[12:15], v[148:151], v[206:209], v[12:15]
	v_mfma_f32_16x16x32_bf16 v[8:11], v[156:159], v[206:209], v[8:11]
	v_mfma_f32_16x16x32_bf16 v[60:63], v[152:155], v[184:187], v[60:63]
	v_mfma_f32_16x16x32_bf16 v[56:59], v[160:163], v[184:187], v[56:59]
	v_mfma_f32_16x16x32_bf16 v[44:47], v[152:155], v[192:195], v[44:47]
	v_mfma_f32_16x16x32_bf16 v[40:43], v[160:163], v[192:195], v[40:43]
	v_mfma_f32_16x16x32_bf16 v[28:31], v[152:155], v[202:205], v[28:31]
	v_mfma_f32_16x16x32_bf16 v[24:27], v[160:163], v[202:205], v[24:27]
	v_mfma_f32_16x16x32_bf16 v[12:15], v[152:155], v[210:213], v[12:15]
	v_mfma_f32_16x16x32_bf16 v[8:11], v[160:163], v[210:213], v[8:11]
	s_setprio 0
	s_setprio 1
	v_mfma_f32_16x16x32_bf16 v[52:55], v[164:167], v[180:183], v[52:55]
	v_mfma_f32_16x16x32_bf16 v[48:51], v[172:175], v[180:183], v[48:51]
	v_mfma_f32_16x16x32_bf16 v[36:39], v[164:167], v[188:191], v[36:39]
	v_mfma_f32_16x16x32_bf16 v[32:35], v[172:175], v[188:191], v[32:35]
	v_mfma_f32_16x16x32_bf16 v[20:23], v[164:167], v[196:199], v[20:23]
	v_mfma_f32_16x16x32_bf16 v[16:19], v[172:175], v[196:199], v[16:19]
	v_mfma_f32_16x16x32_bf16 v[4:7], v[164:167], v[206:209], v[4:7]
	v_mfma_f32_16x16x32_bf16 v[0:3], v[172:175], v[206:209], v[0:3]
	v_mfma_f32_16x16x32_bf16 v[52:55], v[168:171], v[184:187], v[52:55]
	v_mfma_f32_16x16x32_bf16 v[48:51], v[176:179], v[184:187], v[48:51]
	v_mfma_f32_16x16x32_bf16 v[36:39], v[168:171], v[192:195], v[36:39]
	v_mfma_f32_16x16x32_bf16 v[32:35], v[176:179], v[192:195], v[32:35]
	v_mfma_f32_16x16x32_bf16 v[20:23], v[168:171], v[202:205], v[20:23]
	v_mfma_f32_16x16x32_bf16 v[16:19], v[176:179], v[202:205], v[16:19]
	v_mfma_f32_16x16x32_bf16 v[4:7], v[168:171], v[210:213], v[4:7]
	v_mfma_f32_16x16x32_bf16 v[0:3], v[176:179], v[210:213], v[0:3]
	s_setprio 0
	s_barrier
	v_add_u32_e32 v147, s52, v145
	s_add_i32 s63, 0, 0x1c000
	ds_read_b128 v[148:151], v147
	ds_read_b128 v[152:155], v147 offset:1024
	ds_read_b128 v[156:159], v147 offset:2048
	ds_read_b128 v[160:163], v147 offset:3072
	v_add_u32_e32 v147, s63, v145
	ds_read_b128 v[164:167], v147
	ds_read_b128 v[168:171], v147 offset:1024
	ds_read_b128 v[172:175], v147 offset:2048
	ds_read_b128 v[176:179], v147 offset:3072
	s_add_u32 s26, s26, 0x200000
	s_addc_u32 s27, s27, 0
	s_mov_b32 m0, s40
	v_lshl_add_u64 v[222:223], s[26:27], 0, v[134:135]
	ds_read_b128 v[180:183], v146 offset:32768
	ds_read_b128 v[184:187], v146 offset:33792
	ds_read_b128 v[188:191], v146 offset:34816
	ds_read_b128 v[192:195], v146 offset:35840
	ds_read_b128 v[196:199], v146 offset:36864
	ds_read_b128 v[202:205], v146 offset:37888
	ds_read_b128 v[206:209], v146 offset:38912
	ds_read_b128 v[210:213], v146 offset:39936
	global_load_lds_dwordx4 v[222:223], off
	v_lshl_add_u64 v[222:223], s[26:27], 0, v[130:131]
	s_mov_b32 m0, s41
	s_nop 0
	global_load_lds_dwordx4 v[222:223], off
	s_waitcnt vmcnt(8)
	s_waitcnt lgkmcnt(0)
	s_barrier
	s_setprio 1
	s_waitcnt lgkmcnt(0)
	v_mfma_f32_16x16x32_bf16 v[124:127], v[148:151], v[180:183], v[124:127]
	v_mfma_f32_16x16x32_bf16 v[120:123], v[156:159], v[180:183], v[120:123]
	v_mfma_f32_16x16x32_bf16 v[108:111], v[148:151], v[188:191], v[108:111]
	v_mfma_f32_16x16x32_bf16 v[104:107], v[156:159], v[188:191], v[104:107]
	v_mfma_f32_16x16x32_bf16 v[92:95], v[148:151], v[196:199], v[92:95]
	v_mfma_f32_16x16x32_bf16 v[88:91], v[156:159], v[196:199], v[88:91]
	v_mfma_f32_16x16x32_bf16 v[76:79], v[148:151], v[206:209], v[76:79]
	v_mfma_f32_16x16x32_bf16 v[72:75], v[156:159], v[206:209], v[72:75]
	v_mfma_f32_16x16x32_bf16 v[124:127], v[152:155], v[184:187], v[124:127]
	v_mfma_f32_16x16x32_bf16 v[120:123], v[160:163], v[184:187], v[120:123]
	v_mfma_f32_16x16x32_bf16 v[108:111], v[152:155], v[192:195], v[108:111]
	v_mfma_f32_16x16x32_bf16 v[104:107], v[160:163], v[192:195], v[104:107]
	v_mfma_f32_16x16x32_bf16 v[92:95], v[152:155], v[202:205], v[92:95]
	v_mfma_f32_16x16x32_bf16 v[88:91], v[160:163], v[202:205], v[88:91]
	v_mfma_f32_16x16x32_bf16 v[76:79], v[152:155], v[210:213], v[76:79]
	v_mfma_f32_16x16x32_bf16 v[72:75], v[160:163], v[210:213], v[72:75]
	s_setprio 0
	s_setprio 1
	v_mfma_f32_16x16x32_bf16 v[116:119], v[164:167], v[180:183], v[116:119]
	v_mfma_f32_16x16x32_bf16 v[112:115], v[172:175], v[180:183], v[112:115]
	v_mfma_f32_16x16x32_bf16 v[100:103], v[164:167], v[188:191], v[100:103]
	v_mfma_f32_16x16x32_bf16 v[96:99], v[172:175], v[188:191], v[96:99]
	v_mfma_f32_16x16x32_bf16 v[84:87], v[164:167], v[196:199], v[84:87]
	v_mfma_f32_16x16x32_bf16 v[80:83], v[172:175], v[196:199], v[80:83]
	v_mfma_f32_16x16x32_bf16 v[68:71], v[164:167], v[206:209], v[68:71]
	v_mfma_f32_16x16x32_bf16 v[64:67], v[172:175], v[206:209], v[64:67]
	v_mfma_f32_16x16x32_bf16 v[116:119], v[168:171], v[184:187], v[116:119]
	v_mfma_f32_16x16x32_bf16 v[112:115], v[176:179], v[184:187], v[112:115]
	v_mfma_f32_16x16x32_bf16 v[100:103], v[168:171], v[192:195], v[100:103]
	v_mfma_f32_16x16x32_bf16 v[96:99], v[176:179], v[192:195], v[96:99]
	v_mfma_f32_16x16x32_bf16 v[84:87], v[168:171], v[202:205], v[84:87]
	v_mfma_f32_16x16x32_bf16 v[80:83], v[176:179], v[202:205], v[80:83]
	v_mfma_f32_16x16x32_bf16 v[68:71], v[168:171], v[210:213], v[68:71]
	v_mfma_f32_16x16x32_bf16 v[64:67], v[176:179], v[210:213], v[64:67]
	s_setprio 0
	s_barrier
	s_add_i32 s26, s52, s38
	v_lshl_add_u64 v[214:215], v[214:215], 0, s[8:9]
	s_mov_b32 m0, s26
	ds_read_b128 v[180:183], v146 offset:49152
	ds_read_b128 v[184:187], v146 offset:50176
	ds_read_b128 v[188:191], v146 offset:51200
	ds_read_b128 v[192:195], v146 offset:52224
	ds_read_b128 v[196:199], v146 offset:53248
	ds_read_b128 v[202:205], v146 offset:54272
	ds_read_b128 v[206:209], v146 offset:55296
	ds_read_b128 v[210:213], v146 offset:56320
	global_load_lds_dwordx4 v[214:215], off
	s_add_i32 m0, s26, 0x2000
	s_add_u32 s24, s24, 0x200080
	v_lshl_add_u64 v[214:215], v[216:217], 0, s[8:9]
	s_addc_u32 s25, s25, 0
	s_add_i32 s26, s63, s38
	global_load_lds_dwordx4 v[214:215], off
	v_lshl_add_u64 v[214:215], s[24:25], 0, v[132:133]
	s_mov_b32 m0, s26
	s_nop 0
	global_load_lds_dwordx4 v[214:215], off
	v_lshl_add_u64 v[214:215], s[24:25], 0, v[128:129]
	s_add_i32 m0, s26, 0x2000
	s_nop 0
	global_load_lds_dwordx4 v[214:215], off
	v_lshl_add_u64 v[214:215], v[218:219], 0, s[8:9]
	s_mov_b32 m0, s43
	s_nop 0
	global_load_lds_dwordx4 v[214:215], off
	v_lshl_add_u64 v[214:215], v[220:221], 0, s[8:9]
	s_mov_b32 m0, s44
	s_nop 0
	global_load_lds_dwordx4 v[214:215], off
	s_waitcnt vmcnt(8)
	s_waitcnt lgkmcnt(0)
	s_barrier
	s_setprio 1
	s_waitcnt lgkmcnt(0)
	v_mfma_f32_16x16x32_bf16 v[60:63], v[148:151], v[180:183], v[60:63]
	v_mfma_f32_16x16x32_bf16 v[56:59], v[156:159], v[180:183], v[56:59]
	v_mfma_f32_16x16x32_bf16 v[44:47], v[148:151], v[188:191], v[44:47]
	v_mfma_f32_16x16x32_bf16 v[40:43], v[156:159], v[188:191], v[40:43]
	v_mfma_f32_16x16x32_bf16 v[28:31], v[148:151], v[196:199], v[28:31]
	v_mfma_f32_16x16x32_bf16 v[24:27], v[156:159], v[196:199], v[24:27]
	v_mfma_f32_16x16x32_bf16 v[12:15], v[148:151], v[206:209], v[12:15]
	v_mfma_f32_16x16x32_bf16 v[8:11], v[156:159], v[206:209], v[8:11]
	v_mfma_f32_16x16x32_bf16 v[60:63], v[152:155], v[184:187], v[60:63]
	v_mfma_f32_16x16x32_bf16 v[56:59], v[160:163], v[184:187], v[56:59]
	v_mfma_f32_16x16x32_bf16 v[44:47], v[152:155], v[192:195], v[44:47]
	v_mfma_f32_16x16x32_bf16 v[40:43], v[160:163], v[192:195], v[40:43]
	v_mfma_f32_16x16x32_bf16 v[28:31], v[152:155], v[202:205], v[28:31]
	v_mfma_f32_16x16x32_bf16 v[24:27], v[160:163], v[202:205], v[24:27]
	v_mfma_f32_16x16x32_bf16 v[12:15], v[152:155], v[210:213], v[12:15]
	v_mfma_f32_16x16x32_bf16 v[8:11], v[160:163], v[210:213], v[8:11]
	s_setprio 0
	s_setprio 1
	v_mfma_f32_16x16x32_bf16 v[52:55], v[164:167], v[180:183], v[52:55]
	v_mfma_f32_16x16x32_bf16 v[48:51], v[172:175], v[180:183], v[48:51]
	v_mfma_f32_16x16x32_bf16 v[36:39], v[164:167], v[188:191], v[36:39]
	v_mfma_f32_16x16x32_bf16 v[32:35], v[172:175], v[188:191], v[32:35]
	v_mfma_f32_16x16x32_bf16 v[20:23], v[164:167], v[196:199], v[20:23]
	v_mfma_f32_16x16x32_bf16 v[16:19], v[172:175], v[196:199], v[16:19]
	v_mfma_f32_16x16x32_bf16 v[4:7], v[164:167], v[206:209], v[4:7]
	v_mfma_f32_16x16x32_bf16 v[0:3], v[172:175], v[206:209], v[0:3]
	v_mfma_f32_16x16x32_bf16 v[52:55], v[168:171], v[184:187], v[52:55]
	v_mfma_f32_16x16x32_bf16 v[48:51], v[176:179], v[184:187], v[48:51]
	v_mfma_f32_16x16x32_bf16 v[36:39], v[168:171], v[192:195], v[36:39]
	v_mfma_f32_16x16x32_bf16 v[32:35], v[176:179], v[192:195], v[32:35]
	v_mfma_f32_16x16x32_bf16 v[20:23], v[168:171], v[202:205], v[20:23]
	v_mfma_f32_16x16x32_bf16 v[16:19], v[176:179], v[202:205], v[16:19]
	v_mfma_f32_16x16x32_bf16 v[4:7], v[168:171], v[210:213], v[4:7]
	v_mfma_f32_16x16x32_bf16 v[0:3], v[176:179], v[210:213], v[0:3]
	s_setprio 0
	s_barrier
	s_add_i32 s62, s62, 2
	s_add_u32 s22, s22, 0x100
	s_addc_u32 s23, s23, 0
	s_cmpk_gt_u32 s62, 0x7d
	s_cbranch_scc0 .LBB0_2063
	s_and_b64 vcc, exec, s[10:11]
	s_cbranch_vccz .LBB0_2066
	s_barrier

	.amdhsa_kernel _Z9trunk_fwd4Args
		.amdhsa_group_segment_fixed_size 0
		.amdhsa_private_segment_fixed_size 0
		.amdhsa_kernarg_size 520
		.amdhsa_user_sgpr_count 2
		.amdhsa_user_sgpr_dispatch_ptr 0
		.amdhsa_user_sgpr_queue_ptr 0
		.amdhsa_user_sgpr_kernarg_segment_ptr 1
		.amdhsa_user_sgpr_dispatch_id 0
		.amdhsa_user_sgpr_kernarg_preload_length 0
		.amdhsa_user_sgpr_kernarg_preload_offset 0
		.amdhsa_user_sgpr_private_segment_size 0
		.amdhsa_uses_dynamic_stack 0
		.amdhsa_enable_private_segment 0
		.amdhsa_system_sgpr_workgroup_id_x 1
		.amdhsa_system_sgpr_workgroup_id_y 0
		.amdhsa_system_sgpr_workgroup_id_z 0
		.amdhsa_system_sgpr_workgroup_info 0
		.amdhsa_system_vgpr_workitem_id 0
		.amdhsa_next_free_vgpr 253
		.amdhsa_next_free_sgpr 102
		.amdhsa_accum_offset 256
		.amdhsa_reserve_vcc 1
		.amdhsa_float_round_mode_32 0
		.amdhsa_float_round_mode_16_64 0
		.amdhsa_float_denorm_mode_32 3
		.amdhsa_float_denorm_mode_16_64 3
		.amdhsa_dx10_clamp 1
		.amdhsa_ieee_mode 1
		.amdhsa_fp16_overflow 0
		.amdhsa_tg_split 0
		.amdhsa_exception_fp_ieee_invalid_op 0
		.amdhsa_exception_fp_denorm_src 0
		.amdhsa_exception_fp_ieee_div_zero 0
		.amdhsa_exception_fp_ieee_overflow 0
		.amdhsa_exception_fp_ieee_underflow 0
		.amdhsa_exception_fp_ieee_inexact 0
		.amdhsa_exception_int_div_zero 0
	.end_amdhsa_kernel

amdhsa.kernels:
  - .agpr_count:     0
    .args:
      - .offset:         0
        .size:           264
        .value_kind:     by_value
      - .offset:         264
        .size:           4
        .value_kind:     hidden_block_count_x
      - .offset:         268
        .size:           4
        .value_kind:     hidden_block_count_y
      - .offset:         272
        .size:           4
        .value_kind:     hidden_block_count_z
      - .offset:         276
        .size:           2
        .value_kind:     hidden_group_size_x
      - .offset:         278
        .size:           2
        .value_kind:     hidden_group_size_y
      - .offset:         280
        .size:           2
        .value_kind:     hidden_group_size_z
      - .offset:         282
        .size:           2
        .value_kind:     hidden_remainder_x
      - .offset:         284
        .size:           2
        .value_kind:     hidden_remainder_y
      - .offset:         286
        .size:           2
        .value_kind:     hidden_remainder_z
      - .offset:         304
        .size:           8
        .value_kind:     hidden_global_offset_x
      - .offset:         312
        .size:           8
        .value_kind:     hidden_global_offset_y
      - .offset:         320
        .size:           8
        .value_kind:     hidden_global_offset_z
      - .offset:         328
        .size:           2
        .value_kind:     hidden_grid_dims
      - .offset:         384
        .size:           4
        .value_kind:     hidden_dynamic_lds_size
    .group_segment_fixed_size: 0
    .kernarg_segment_align: 8
    .kernarg_segment_size: 520
    .language:       OpenCL C
    .language_version:
      - 2
      - 0
    .max_flat_workgroup_size: 512
    .name:           _Z9trunk_fwd4Args
    .private_segment_fixed_size: 0
    .sgpr_count:     108
    .sgpr_spill_count: 16
    .symbol:         _Z9trunk_fwd4Args.kd
    .uniform_work_group_size: 1
    .uses_dynamic_stack: false
    .vgpr_count:     253
    .vgpr_spill_count: 0
    .wavefront_size: 64
